# GEMM K-loops: M0-write wait state filled by moving a ds_read instead of s_nop
# speedup vs baseline: 1.0854x; 1.0046x over previous
; #define PG8_STAGE(bufoff, gbase, voff) do { _Pragma("unroll") for (int _i = 0; _i < 2; ++_i) \
;         __builtin_amdgcn_global_load_lds((const unsigned*)((const char*)(gbase) + (voff)[_i]), (PG8_LAS unsigned*)(lds + (bufoff) + ldsw + _i * 8192), 16, 0, 0); } while (0)
; #define PG8_LDA(dst, b, h) do { _Pragma("unroll") for (int m = 0; m < 4; ++m) _Pragma("unroll") for (int k = 0; k < 2; ++k) dst[m][k] = *(const PG8_LAS bf16x8*)(lds + PG8_SA(b, h) + aoff + m * 2048 + k * 1024); } while (0)
; #define PG8_LDB(dst, b, h) do { _Pragma("unroll") for (int n = 0; n < 2; ++n) _Pragma("unroll") for (int k = 0; k < 2; ++k) dst[n][k] = *(const PG8_LAS bf16x8*)(lds + PG8_SB(b, h) + boff + n * 2048 + k * 1024); } while (0)
; #define PG8_MMA(ai, bj, At, Bt) do { __builtin_amdgcn_s_setprio(1); _Pragma("unroll") for (int m = 0; m < 4; ++m) _Pragma("unroll") for (int n = 0; n < 2; ++n) _Pragma("unroll") for (int k = 0; k < 2; ++k) \
;         acc[ai][bj][m][n] = __builtin_amdgcn_mfma_f32_16x16x32_bf16(Bt[n][k], At[m][k], acc[ai][bj][m][n], 0, 0, 0); __builtin_amdgcn_s_setprio(0); } while (0)
; #define PG8_WAIT_V(n) asm volatile("s_waitcnt vmcnt(" #n ")" ::: "memory")
; #define PG8_BAR __builtin_amdgcn_s_barrier()
; template <class Epi, class Sched, bool ALIGN_EPI = false, bool SP2 = false>
; __device__ __forceinline__ void gemm_phase(PG8_LAS unsigned char* lds, const Gemm g, const Sched& S, const Epi& E) {
;     ...
;         for (int t = 0; t < nt; t += 2) {
;             const bool last = (t == nt - 2);
;             const char* a1 = cA + (size_t)(t + 1) * kstep;
;             const char* a2 = last ? nA : cA + (size_t)(t + 2) * kstep; const char* b2 = last ? nB : cB + (size_t)(t + 2) * kstep;
;             const char* a3 = a2 + kstep; const char* b3 = b2 + kstep;
;             if (last && has_next) S.a_ready(nxt);
;             if constexpr (SP2) {
;             PG8_LDB(B0, 0, 0); PG8_LDB(B1, 0, 1); PG8_SCHED; PG8_LDA(At, 0, 0); PG8_STAGE(PG8_SA(1, 1), a1 + hstepA, voffA);
;             PG8_WAIT_V(8); PG8_WAIT_L(0); PG8_BAR; PG8_MMA(0, 0, At, B0); PG8_MMA(0, 1, At, B1); PG8_BAR; PG8_SCHED;
;             PG8_LDA(At, 0, 1); PG8_STAGE(PG8_SB(0, 0), b2, voffB); PG8_STAGE(PG8_SB(0, 1), b2 + hstep, voffB); PG8_STAGE(PG8_SA(0, 0), a2, voffA);
;             PG8_WAIT_V(8); PG8_WAIT_L(0); PG8_BAR; PG8_MMA(1, 0, At, B0); PG8_MMA(1, 1, At, B1); PG8_BAR; PG8_SCHED;
.LBB0_258:
	ds_read_b128 v[164:167], v161
	ds_read_b128 v[168:171], v161 offset:1024
	ds_read_b128 v[172:175], v161 offset:2048
	ds_read_b128 v[176:179], v161 offset:3072
	ds_read_b128 v[180:183], v162
	ds_read_b128 v[184:187], v162 offset:1024
	ds_read_b128 v[190:193], v162 offset:2048
	ds_read_b128 v[194:197], v162 offset:3072
	s_add_i32 s65, s36, 2
	s_add_u32 s66, s10, 0xfffc0080
	s_addc_u32 s37, s11, -1
	s_cmp_eq_u32 s56, s36
	s_cselect_b32 s36, s64, s66
	s_cselect_b32 s37, s29, s37
	s_cselect_b32 s67, s31, s39
	s_cselect_b32 s66, s30, s38
	s_add_i32 m0, s48, 0xc000
	ds_read_b128 v[198:201], v163
	ds_read_b128 v[202:205], v163 offset:1024
	ds_read_b128 v[206:209], v163 offset:2048
	ds_read_b128 v[210:213], v163 offset:3072
	ds_read_b128 v[214:217], v163 offset:4096
	ds_read_b128 v[218:221], v163 offset:5120
	ds_read_b128 v[222:225], v163 offset:6144
	global_load_lds_dwordx4 v138, s[10:11]
	s_add_i32 m0, s48, 0xe000
	ds_read_b128 v[226:229], v163 offset:7168
	global_load_lds_dwordx4 v142, s[10:11]
	s_waitcnt vmcnt(8)
	s_waitcnt lgkmcnt(0)
	s_barrier
	s_setprio 1
	v_mfma_f32_16x16x32_bf16 v[124:127], v[164:167], v[198:201], v[124:127]
	v_mfma_f32_16x16x32_bf16 v[120:123], v[172:175], v[198:201], v[120:123]
	v_mfma_f32_16x16x32_bf16 v[108:111], v[164:167], v[206:209], v[108:111]
	v_mfma_f32_16x16x32_bf16 v[104:107], v[172:175], v[206:209], v[104:107]
	v_mfma_f32_16x16x32_bf16 v[92:95], v[164:167], v[214:217], v[92:95]
	v_mfma_f32_16x16x32_bf16 v[88:91], v[172:175], v[214:217], v[88:91]
	v_mfma_f32_16x16x32_bf16 v[76:79], v[164:167], v[222:225], v[76:79]
	v_mfma_f32_16x16x32_bf16 v[72:75], v[172:175], v[222:225], v[72:75]
	v_mfma_f32_16x16x32_bf16 v[124:127], v[168:171], v[202:205], v[124:127]
	v_mfma_f32_16x16x32_bf16 v[120:123], v[176:179], v[202:205], v[120:123]
	v_mfma_f32_16x16x32_bf16 v[108:111], v[168:171], v[210:213], v[108:111]
	v_mfma_f32_16x16x32_bf16 v[104:107], v[176:179], v[210:213], v[104:107]
	v_mfma_f32_16x16x32_bf16 v[92:95], v[168:171], v[218:221], v[92:95]
	v_mfma_f32_16x16x32_bf16 v[88:91], v[176:179], v[218:221], v[88:91]
	v_mfma_f32_16x16x32_bf16 v[76:79], v[168:171], v[226:229], v[76:79]
	v_mfma_f32_16x16x32_bf16 v[72:75], v[176:179], v[226:229], v[72:75]
	v_mfma_f32_16x16x32_bf16 v[116:119], v[180:183], v[198:201], v[116:119]
	v_mfma_f32_16x16x32_bf16 v[112:115], v[190:193], v[198:201], v[112:115]
	v_mfma_f32_16x16x32_bf16 v[100:103], v[180:183], v[206:209], v[100:103]
	v_mfma_f32_16x16x32_bf16 v[96:99], v[190:193], v[206:209], v[96:99]
	v_mfma_f32_16x16x32_bf16 v[84:87], v[180:183], v[214:217], v[84:87]
	v_mfma_f32_16x16x32_bf16 v[80:83], v[190:193], v[214:217], v[80:83]
	v_mfma_f32_16x16x32_bf16 v[68:71], v[180:183], v[222:225], v[68:71]
	v_mfma_f32_16x16x32_bf16 v[64:67], v[190:193], v[222:225], v[64:67]
	v_mfma_f32_16x16x32_bf16 v[116:119], v[184:187], v[202:205], v[116:119]
	v_mfma_f32_16x16x32_bf16 v[112:115], v[194:197], v[202:205], v[112:115]
	v_mfma_f32_16x16x32_bf16 v[100:103], v[184:187], v[210:213], v[100:103]
	v_mfma_f32_16x16x32_bf16 v[96:99], v[194:197], v[210:213], v[96:99]
	v_mfma_f32_16x16x32_bf16 v[84:87], v[184:187], v[218:221], v[84:87]
	v_mfma_f32_16x16x32_bf16 v[80:83], v[194:197], v[218:221], v[80:83]
	v_mfma_f32_16x16x32_bf16 v[68:71], v[184:187], v[226:229], v[68:71]
	v_mfma_f32_16x16x32_bf16 v[64:67], v[194:197], v[226:229], v[64:67]
	s_setprio 0
	s_barrier
	s_add_i32 s68, s57, s47
	s_mov_b32 m0, s68
	ds_read_b128 v[198:201], v163 offset:16384
	ds_read_b128 v[202:205], v163 offset:17408
	ds_read_b128 v[206:209], v163 offset:18432
	ds_read_b128 v[210:213], v163 offset:19456
	global_load_lds_dwordx4 v136, s[66:67]
	s_add_i32 m0, s68, 0x2000
	s_mov_b64 s[100:101], s[66:67]
	s_add_i32 s68, s58, s47
	global_load_lds_dwordx4 v134, s[66:67]
	s_add_u32 s66, s66, s16
	s_addc_u32 s67, s67, s17
	s_mov_b32 m0, s68
	ds_read_b128 v[226:229], v163 offset:23552
	global_load_lds_dwordx4 v136, s[66:67]
	s_add_i32 m0, s68, 0x2000
	ds_read_b128 v[222:225], v163 offset:22528
	global_load_lds_dwordx4 v134, s[66:67]
	s_mov_b32 m0, s48
	ds_read_b128 v[218:221], v163 offset:21504
	global_load_lds_dwordx4 v128, s[36:37]
	s_mov_b32 m0, s49
	ds_read_b128 v[214:217], v163 offset:20480
	global_load_lds_dwordx4 v130, s[36:37]
	s_waitcnt vmcnt(8)
	s_waitcnt lgkmcnt(0)
	s_barrier
	s_setprio 1
	v_mfma_f32_16x16x32_bf16 v[60:63], v[164:167], v[198:201], v[60:63]
	v_mfma_f32_16x16x32_bf16 v[56:59], v[172:175], v[198:201], v[56:59]
	v_mfma_f32_16x16x32_bf16 v[44:47], v[164:167], v[206:209], v[44:47]
	v_mfma_f32_16x16x32_bf16 v[40:43], v[172:175], v[206:209], v[40:43]
	v_mfma_f32_16x16x32_bf16 v[28:31], v[164:167], v[214:217], v[28:31]
	v_mfma_f32_16x16x32_bf16 v[24:27], v[172:175], v[214:217], v[24:27]
	v_mfma_f32_16x16x32_bf16 v[12:15], v[164:167], v[222:225], v[12:15]
	v_mfma_f32_16x16x32_bf16 v[8:11], v[172:175], v[222:225], v[8:11]
	v_mfma_f32_16x16x32_bf16 v[60:63], v[168:171], v[202:205], v[60:63]
	v_mfma_f32_16x16x32_bf16 v[56:59], v[176:179], v[202:205], v[56:59]
	v_mfma_f32_16x16x32_bf16 v[44:47], v[168:171], v[210:213], v[44:47]
	v_mfma_f32_16x16x32_bf16 v[40:43], v[176:179], v[210:213], v[40:43]
	v_mfma_f32_16x16x32_bf16 v[28:31], v[168:171], v[218:221], v[28:31]
	v_mfma_f32_16x16x32_bf16 v[24:27], v[176:179], v[218:221], v[24:27]
	v_mfma_f32_16x16x32_bf16 v[12:15], v[168:171], v[226:229], v[12:15]
	v_mfma_f32_16x16x32_bf16 v[8:11], v[176:179], v[226:229], v[8:11]
	v_mfma_f32_16x16x32_bf16 v[52:55], v[180:183], v[198:201], v[52:55]
	v_mfma_f32_16x16x32_bf16 v[48:51], v[190:193], v[198:201], v[48:51]
	v_mfma_f32_16x16x32_bf16 v[36:39], v[180:183], v[206:209], v[36:39]
	v_mfma_f32_16x16x32_bf16 v[32:35], v[190:193], v[206:209], v[32:35]
	v_mfma_f32_16x16x32_bf16 v[20:23], v[180:183], v[214:217], v[20:23]
	v_mfma_f32_16x16x32_bf16 v[16:19], v[190:193], v[214:217], v[16:19]
	v_mfma_f32_16x16x32_bf16 v[4:7], v[180:183], v[222:225], v[4:7]
	v_mfma_f32_16x16x32_bf16 v[0:3], v[190:193], v[222:225], v[0:3]
	v_mfma_f32_16x16x32_bf16 v[52:55], v[184:187], v[202:205], v[52:55]
	v_mfma_f32_16x16x32_bf16 v[48:51], v[194:197], v[202:205], v[48:51]
	v_mfma_f32_16x16x32_bf16 v[36:39], v[184:187], v[210:213], v[36:39]
	v_mfma_f32_16x16x32_bf16 v[32:35], v[194:197], v[210:213], v[32:35]
	v_mfma_f32_16x16x32_bf16 v[20:23], v[184:187], v[218:221], v[20:23]
	v_mfma_f32_16x16x32_bf16 v[16:19], v[194:197], v[218:221], v[16:19]
	v_mfma_f32_16x16x32_bf16 v[4:7], v[184:187], v[226:229], v[4:7]
	v_mfma_f32_16x16x32_bf16 v[0:3], v[194:197], v[226:229], v[0:3]
	s_setprio 0
	s_barrier
; #define PG8_STAGE(bufoff, gbase, voff) do { _Pragma("unroll") for (int _i = 0; _i < 2; ++_i) \
;         __builtin_amdgcn_global_load_lds((const unsigned*)((const char*)(gbase) + (voff)[_i]), (PG8_LAS unsigned*)(lds + (bufoff) + ldsw + _i * 8192), 16, 0, 0); } while (0)
; #define PG8_LDA(dst, b, h) do { _Pragma("unroll") for (int m = 0; m < 4; ++m) _Pragma("unroll") for (int k = 0; k < 2; ++k) dst[m][k] = *(const PG8_LAS bf16x8*)(lds + PG8_SA(b, h) + aoff + m * 2048 + k * 1024); } while (0)
; #define PG8_LDB(dst, b, h) do { _Pragma("unroll") for (int n = 0; n < 2; ++n) _Pragma("unroll") for (int k = 0; k < 2; ++k) dst[n][k] = *(const PG8_LAS bf16x8*)(lds + PG8_SB(b, h) + boff + n * 2048 + k * 1024); } while (0)
; #define PG8_MMA(ai, bj, At, Bt) do { __builtin_amdgcn_s_setprio(1); _Pragma("unroll") for (int m = 0; m < 4; ++m) _Pragma("unroll") for (int n = 0; n < 2; ++n) _Pragma("unroll") for (int k = 0; k < 2; ++k) \
;         acc[ai][bj][m][n] = __builtin_amdgcn_mfma_f32_16x16x32_bf16(Bt[n][k], At[m][k], acc[ai][bj][m][n], 0, 0, 0); __builtin_amdgcn_s_setprio(0); } while (0)
; #define PG8_WAIT_V(n) asm volatile("s_waitcnt vmcnt(" #n ")" ::: "memory")
; #define PG8_WAIT_L(n) asm volatile("s_waitcnt lgkmcnt(" #n ")" ::: "memory")
; #define PG8_BAR __builtin_amdgcn_s_barrier()
; template <class Epi, class Sched, bool ALIGN_EPI = false, bool SP2 = false>
; __device__ __forceinline__ void gemm_phase(PG8_LAS unsigned char* lds, const Gemm g, const Sched& S, const Epi& E) {
;     ...
;         for (int t = 0; t < nt; t += 2) {
;             const bool last = (t == nt - 2);
;             const char* a1 = cA + (size_t)(t + 1) * kstep;
;             const char* a2 = last ? nA : cA + (size_t)(t + 2) * kstep; const char* b2 = last ? nB : cB + (size_t)(t + 2) * kstep;
;             const char* a3 = a2 + kstep; const char* b3 = b2 + kstep;
;     ...
;             PG8_LDB(B0, 1, 0); PG8_LDB(B1, 1, 1); PG8_SCHED; PG8_LDA(At, 1, 0); PG8_STAGE(PG8_SA(0, 1), a2 + hstepA, voffA);
;             PG8_WAIT_V(8); PG8_WAIT_L(0); PG8_BAR; PG8_MMA(0, 0, At, B0); PG8_MMA(0, 1, At, B1); PG8_BAR; PG8_SCHED;
;             PG8_LDA(At, 1, 1); PG8_STAGE(PG8_SB(1, 0), b3, voffB); PG8_STAGE(PG8_SB(1, 1), b3 + hstep, voffB); PG8_STAGE(PG8_SA(1, 0), a3, voffA);
;             PG8_WAIT_V(8); PG8_WAIT_L(0); PG8_BAR; PG8_MMA(1, 0, At, B0); PG8_MMA(1, 1, At, B1); PG8_BAR; PG8_SCHED;
	s_add_i32 s66, 0, 0x18000
	s_add_i32 s67, 0, 0x1c000
	v_add_u32_e32 v176, s66, v159
	v_add_u32_e32 v189, s67, v159
	ds_read_b128 v[164:167], v176
	ds_read_b128 v[168:171], v176 offset:1024
	ds_read_b128 v[172:175], v176 offset:2048
	ds_read_b128 v[176:179], v176 offset:3072
	ds_read_b128 v[180:183], v189
	ds_read_b128 v[184:187], v189 offset:1024
	ds_read_b128 v[190:193], v189 offset:2048
	ds_read_b128 v[194:197], v189 offset:3072
	s_mov_b64 vcc, s[36:37]
	s_add_u32 s36, s36, 0x40000
	s_addc_u32 s37, s37, 0
	s_mov_b32 m0, s50
	ds_read_b128 v[198:201], v163 offset:32768
	ds_read_b128 v[202:205], v163 offset:33792
	ds_read_b128 v[206:209], v163 offset:34816
	ds_read_b128 v[210:213], v163 offset:35840
	ds_read_b128 v[214:217], v163 offset:36864
	ds_read_b128 v[218:221], v163 offset:37888
	ds_read_b128 v[222:225], v163 offset:38912
	global_load_lds_dwordx4 v128, s[36:37]
	s_mov_b32 m0, s51
	ds_read_b128 v[226:229], v163 offset:39936
	global_load_lds_dwordx4 v130, s[36:37]
	s_waitcnt vmcnt(8)
	s_waitcnt lgkmcnt(0)
	s_barrier
	s_setprio 1
	v_mfma_f32_16x16x32_bf16 v[124:127], v[164:167], v[198:201], v[124:127]
	v_mfma_f32_16x16x32_bf16 v[120:123], v[172:175], v[198:201], v[120:123]
	v_mfma_f32_16x16x32_bf16 v[108:111], v[164:167], v[206:209], v[108:111]
	v_mfma_f32_16x16x32_bf16 v[104:107], v[172:175], v[206:209], v[104:107]
	v_mfma_f32_16x16x32_bf16 v[92:95], v[164:167], v[214:217], v[92:95]
	v_mfma_f32_16x16x32_bf16 v[88:91], v[172:175], v[214:217], v[88:91]
	v_mfma_f32_16x16x32_bf16 v[76:79], v[164:167], v[222:225], v[76:79]
	v_mfma_f32_16x16x32_bf16 v[72:75], v[172:175], v[222:225], v[72:75]
	v_mfma_f32_16x16x32_bf16 v[124:127], v[168:171], v[202:205], v[124:127]
	v_mfma_f32_16x16x32_bf16 v[120:123], v[176:179], v[202:205], v[120:123]
	v_mfma_f32_16x16x32_bf16 v[108:111], v[168:171], v[210:213], v[108:111]
	v_mfma_f32_16x16x32_bf16 v[104:107], v[176:179], v[210:213], v[104:107]
	v_mfma_f32_16x16x32_bf16 v[92:95], v[168:171], v[218:221], v[92:95]
	v_mfma_f32_16x16x32_bf16 v[88:91], v[176:179], v[218:221], v[88:91]
	v_mfma_f32_16x16x32_bf16 v[76:79], v[168:171], v[226:229], v[76:79]
	v_mfma_f32_16x16x32_bf16 v[72:75], v[176:179], v[226:229], v[72:75]
	v_mfma_f32_16x16x32_bf16 v[116:119], v[180:183], v[198:201], v[116:119]
	v_mfma_f32_16x16x32_bf16 v[112:115], v[190:193], v[198:201], v[112:115]
	v_mfma_f32_16x16x32_bf16 v[100:103], v[180:183], v[206:209], v[100:103]
	v_mfma_f32_16x16x32_bf16 v[96:99], v[190:193], v[206:209], v[96:99]
	v_mfma_f32_16x16x32_bf16 v[84:87], v[180:183], v[214:217], v[84:87]
	v_mfma_f32_16x16x32_bf16 v[80:83], v[190:193], v[214:217], v[80:83]
	v_mfma_f32_16x16x32_bf16 v[68:71], v[180:183], v[222:225], v[68:71]
	v_mfma_f32_16x16x32_bf16 v[64:67], v[190:193], v[222:225], v[64:67]
	v_mfma_f32_16x16x32_bf16 v[116:119], v[184:187], v[202:205], v[116:119]
	v_mfma_f32_16x16x32_bf16 v[112:115], v[194:197], v[202:205], v[112:115]
	v_mfma_f32_16x16x32_bf16 v[100:103], v[184:187], v[210:213], v[100:103]
	v_mfma_f32_16x16x32_bf16 v[96:99], v[194:197], v[210:213], v[96:99]
	v_mfma_f32_16x16x32_bf16 v[84:87], v[184:187], v[218:221], v[84:87]
	v_mfma_f32_16x16x32_bf16 v[80:83], v[194:197], v[218:221], v[80:83]
	v_mfma_f32_16x16x32_bf16 v[68:71], v[184:187], v[226:229], v[68:71]
	v_mfma_f32_16x16x32_bf16 v[64:67], v[194:197], v[226:229], v[64:67]
	s_setprio 0
	s_barrier
	s_add_i32 s36, s66, s47
	s_add_i32 m0, s36, 0xffffff80
	ds_read_b128 v[198:201], v163 offset:49152
	ds_read_b128 v[202:205], v163 offset:50176
	ds_read_b128 v[206:209], v163 offset:51200
	ds_read_b128 v[210:213], v163 offset:52224
	global_load_lds_dwordx4 v136, s[100:101] offset:128
	s_add_i32 m0, s36, 0x1f80
	s_add_i32 s36, s67, s47
	global_load_lds_dwordx4 v134, s[100:101] offset:128
	s_add_u32 s100, s100, s16
	s_addc_u32 s101, s101, s17
	s_add_i32 m0, s36, 0xffffff80
	ds_read_b128 v[226:229], v163 offset:56320
	global_load_lds_dwordx4 v136, s[100:101] offset:128
	s_add_i32 m0, s36, 0x1f80
	ds_read_b128 v[222:225], v163 offset:55296
	global_load_lds_dwordx4 v134, s[100:101] offset:128
	s_add_i32 m0, s52, 0xffffff80
	ds_read_b128 v[218:221], v163 offset:54272
	global_load_lds_dwordx4 v128, vcc offset:128
	s_add_i32 m0, s53, 0xffffff80
	ds_read_b128 v[214:217], v163 offset:53248
	global_load_lds_dwordx4 v130, vcc offset:128
	s_waitcnt vmcnt(8)
	s_waitcnt lgkmcnt(0)
	s_barrier
	s_setprio 1
	v_mfma_f32_16x16x32_bf16 v[60:63], v[164:167], v[198:201], v[60:63]
	v_mfma_f32_16x16x32_bf16 v[56:59], v[172:175], v[198:201], v[56:59]
	v_mfma_f32_16x16x32_bf16 v[44:47], v[164:167], v[206:209], v[44:47]
	v_mfma_f32_16x16x32_bf16 v[40:43], v[172:175], v[206:209], v[40:43]
	v_mfma_f32_16x16x32_bf16 v[28:31], v[164:167], v[214:217], v[28:31]
	v_mfma_f32_16x16x32_bf16 v[24:27], v[172:175], v[214:217], v[24:27]
	v_mfma_f32_16x16x32_bf16 v[12:15], v[164:167], v[222:225], v[12:15]
	v_mfma_f32_16x16x32_bf16 v[8:11], v[172:175], v[222:225], v[8:11]
	v_mfma_f32_16x16x32_bf16 v[60:63], v[168:171], v[202:205], v[60:63]
	v_mfma_f32_16x16x32_bf16 v[56:59], v[176:179], v[202:205], v[56:59]
	v_mfma_f32_16x16x32_bf16 v[44:47], v[168:171], v[210:213], v[44:47]
	v_mfma_f32_16x16x32_bf16 v[40:43], v[176:179], v[210:213], v[40:43]
	v_mfma_f32_16x16x32_bf16 v[28:31], v[168:171], v[218:221], v[28:31]
	v_mfma_f32_16x16x32_bf16 v[24:27], v[176:179], v[218:221], v[24:27]
	v_mfma_f32_16x16x32_bf16 v[12:15], v[168:171], v[226:229], v[12:15]
	v_mfma_f32_16x16x32_bf16 v[8:11], v[176:179], v[226:229], v[8:11]
	v_mfma_f32_16x16x32_bf16 v[52:55], v[180:183], v[198:201], v[52:55]
	v_mfma_f32_16x16x32_bf16 v[48:51], v[190:193], v[198:201], v[48:51]
	v_mfma_f32_16x16x32_bf16 v[36:39], v[180:183], v[206:209], v[36:39]
	v_mfma_f32_16x16x32_bf16 v[32:35], v[190:193], v[206:209], v[32:35]
	v_mfma_f32_16x16x32_bf16 v[20:23], v[180:183], v[214:217], v[20:23]
	v_mfma_f32_16x16x32_bf16 v[16:19], v[190:193], v[214:217], v[16:19]
	v_mfma_f32_16x16x32_bf16 v[4:7], v[180:183], v[222:225], v[4:7]
	v_mfma_f32_16x16x32_bf16 v[0:3], v[190:193], v[222:225], v[0:3]
	v_mfma_f32_16x16x32_bf16 v[52:55], v[184:187], v[202:205], v[52:55]
	v_mfma_f32_16x16x32_bf16 v[48:51], v[194:197], v[202:205], v[48:51]
	v_mfma_f32_16x16x32_bf16 v[36:39], v[184:187], v[210:213], v[36:39]
	v_mfma_f32_16x16x32_bf16 v[32:35], v[194:197], v[210:213], v[32:35]
	v_mfma_f32_16x16x32_bf16 v[20:23], v[184:187], v[218:221], v[20:23]
	v_mfma_f32_16x16x32_bf16 v[16:19], v[194:197], v[218:221], v[16:19]
	v_mfma_f32_16x16x32_bf16 v[4:7], v[184:187], v[226:229], v[4:7]
	v_mfma_f32_16x16x32_bf16 v[0:3], v[194:197], v[226:229], v[0:3]
	s_setprio 0
	s_barrier
	s_add_u32 s10, s10, 0x100
	s_addc_u32 s11, s11, 0
	s_add_u32 s38, s38, 0x100
	s_addc_u32 s39, s39, 0
	s_cmp_ge_i32 s65, s54
	s_mov_b32 s36, s65
	s_cbranch_scc0 .LBB0_258

; #define PG8_STAGE(bufoff, gbase, voff) do { _Pragma("unroll") for (int _i = 0; _i < 2; ++_i) \
;         __builtin_amdgcn_global_load_lds((const unsigned*)((const char*)(gbase) + (voff)[_i]), (PG8_LAS unsigned*)(lds + (bufoff) + ldsw + _i * 8192), 16, 0, 0); } while (0)
; #define PG8_LDA(dst, b, h) do { _Pragma("unroll") for (int m = 0; m < 4; ++m) _Pragma("unroll") for (int k = 0; k < 2; ++k) dst[m][k] = *(const PG8_LAS bf16x8*)(lds + PG8_SA(b, h) + aoff + m * 2048 + k * 1024); } while (0)
; #define PG8_LDB(dst, b, h) do { _Pragma("unroll") for (int n = 0; n < 2; ++n) _Pragma("unroll") for (int k = 0; k < 2; ++k) dst[n][k] = *(const PG8_LAS bf16x8*)(lds + PG8_SB(b, h) + boff + n * 2048 + k * 1024); } while (0)
; #define PG8_MMA(ai, bj, At, Bt) do { __builtin_amdgcn_s_setprio(1); _Pragma("unroll") for (int m = 0; m < 4; ++m) _Pragma("unroll") for (int n = 0; n < 2; ++n) _Pragma("unroll") for (int k = 0; k < 2; ++k) \
;         acc[ai][bj][m][n] = __builtin_amdgcn_mfma_f32_16x16x32_bf16(Bt[n][k], At[m][k], acc[ai][bj][m][n], 0, 0, 0); __builtin_amdgcn_s_setprio(0); } while (0)
; #define PG8_WAIT_V(n) asm volatile("s_waitcnt vmcnt(" #n ")" ::: "memory")
; #define PG8_BAR __builtin_amdgcn_s_barrier()
; template <class Epi, class Sched, bool ALIGN_EPI = false, bool SP2 = false>
; __device__ __forceinline__ void gemm_phase(PG8_LAS unsigned char* lds, const Gemm g, const Sched& S, const Epi& E) {
;     ...
;         for (int t = 0; t < nt; t += 2) {
;             const bool last = (t == nt - 2);
;             const char* a1 = cA + (size_t)(t + 1) * kstep;
;             const char* a2 = last ? nA : cA + (size_t)(t + 2) * kstep; const char* b2 = last ? nB : cB + (size_t)(t + 2) * kstep;
;             const char* a3 = a2 + kstep; const char* b3 = b2 + kstep;
;             if (last && has_next) S.a_ready(nxt);
;             if constexpr (SP2) {
;             PG8_LDB(B0, 0, 0); PG8_LDB(B1, 0, 1); PG8_SCHED; PG8_LDA(At, 0, 0); PG8_STAGE(PG8_SA(1, 1), a1 + hstepA, voffA);
;             PG8_WAIT_V(8); PG8_WAIT_L(0); PG8_BAR; PG8_MMA(0, 0, At, B0); PG8_MMA(0, 1, At, B1); PG8_BAR; PG8_SCHED;
;             PG8_LDA(At, 0, 1); PG8_STAGE(PG8_SB(0, 0), b2, voffB); PG8_STAGE(PG8_SB(0, 1), b2 + hstep, voffB); PG8_STAGE(PG8_SA(0, 0), a2, voffA);
;             PG8_WAIT_V(8); PG8_WAIT_L(0); PG8_BAR; PG8_MMA(1, 0, At, B0); PG8_MMA(1, 1, At, B1); PG8_BAR; PG8_SCHED;
.LBB0_282:
	ds_read_b128 v[148:151], v144
	ds_read_b128 v[152:155], v144 offset:1024
	ds_read_b128 v[156:159], v144 offset:2048
	ds_read_b128 v[160:163], v144 offset:3072
	ds_read_b128 v[164:167], v145
	ds_read_b128 v[168:171], v145 offset:1024
	ds_read_b128 v[172:175], v145 offset:2048
	ds_read_b128 v[176:179], v145 offset:3072
	s_add_i32 s61, s34, 2
	s_add_u32 s62, s30, 0xfffc0080
	s_addc_u32 s35, s31, -1
	s_cmp_eq_u32 s52, s34
	s_cselect_b32 s34, s36, s62
	s_cselect_b32 s35, s5, s35
	s_cselect_b32 s63, s27, s60
	s_cselect_b32 s62, s26, s37
	s_add_i32 m0, s33, 0xc000
	ds_read_b128 v[180:183], v146
	ds_read_b128 v[184:187], v146 offset:1024
	ds_read_b128 v[190:193], v146 offset:2048
	ds_read_b128 v[194:197], v146 offset:3072
	ds_read_b128 v[198:201], v146 offset:4096
	ds_read_b128 v[202:205], v146 offset:5120
	ds_read_b128 v[206:209], v146 offset:6144
	global_load_lds_dwordx4 v138, s[30:31]
	s_add_i32 m0, s33, 0xe000
	ds_read_b128 v[210:213], v146 offset:7168
	global_load_lds_dwordx4 v140, s[30:31]
	s_waitcnt vmcnt(8)
	s_waitcnt lgkmcnt(0)
	s_barrier
	s_setprio 1
	v_mfma_f32_16x16x32_bf16 v[124:127], v[148:151], v[180:183], v[124:127]
	v_mfma_f32_16x16x32_bf16 v[120:123], v[156:159], v[180:183], v[120:123]
	v_mfma_f32_16x16x32_bf16 v[108:111], v[148:151], v[190:193], v[108:111]
	v_mfma_f32_16x16x32_bf16 v[104:107], v[156:159], v[190:193], v[104:107]
	v_mfma_f32_16x16x32_bf16 v[92:95], v[148:151], v[198:201], v[92:95]
	v_mfma_f32_16x16x32_bf16 v[88:91], v[156:159], v[198:201], v[88:91]
	v_mfma_f32_16x16x32_bf16 v[76:79], v[148:151], v[206:209], v[76:79]
	v_mfma_f32_16x16x32_bf16 v[72:75], v[156:159], v[206:209], v[72:75]
	v_mfma_f32_16x16x32_bf16 v[124:127], v[152:155], v[184:187], v[124:127]
	v_mfma_f32_16x16x32_bf16 v[120:123], v[160:163], v[184:187], v[120:123]
	v_mfma_f32_16x16x32_bf16 v[108:111], v[152:155], v[194:197], v[108:111]
	v_mfma_f32_16x16x32_bf16 v[104:107], v[160:163], v[194:197], v[104:107]
	v_mfma_f32_16x16x32_bf16 v[92:95], v[152:155], v[202:205], v[92:95]
	v_mfma_f32_16x16x32_bf16 v[88:91], v[160:163], v[202:205], v[88:91]
	v_mfma_f32_16x16x32_bf16 v[76:79], v[152:155], v[210:213], v[76:79]
	v_mfma_f32_16x16x32_bf16 v[72:75], v[160:163], v[210:213], v[72:75]
	v_mfma_f32_16x16x32_bf16 v[116:119], v[164:167], v[180:183], v[116:119]
	v_mfma_f32_16x16x32_bf16 v[112:115], v[172:175], v[180:183], v[112:115]
	v_mfma_f32_16x16x32_bf16 v[100:103], v[164:167], v[190:193], v[100:103]
	v_mfma_f32_16x16x32_bf16 v[96:99], v[172:175], v[190:193], v[96:99]
	v_mfma_f32_16x16x32_bf16 v[84:87], v[164:167], v[198:201], v[84:87]
	v_mfma_f32_16x16x32_bf16 v[80:83], v[172:175], v[198:201], v[80:83]
	v_mfma_f32_16x16x32_bf16 v[68:71], v[164:167], v[206:209], v[68:71]
	v_mfma_f32_16x16x32_bf16 v[64:67], v[172:175], v[206:209], v[64:67]
	v_mfma_f32_16x16x32_bf16 v[116:119], v[168:171], v[184:187], v[116:119]
	v_mfma_f32_16x16x32_bf16 v[112:115], v[176:179], v[184:187], v[112:115]
	v_mfma_f32_16x16x32_bf16 v[100:103], v[168:171], v[194:197], v[100:103]
	v_mfma_f32_16x16x32_bf16 v[96:99], v[176:179], v[194:197], v[96:99]
	v_mfma_f32_16x16x32_bf16 v[84:87], v[168:171], v[202:205], v[84:87]
	v_mfma_f32_16x16x32_bf16 v[80:83], v[176:179], v[202:205], v[80:83]
	v_mfma_f32_16x16x32_bf16 v[68:71], v[168:171], v[210:213], v[68:71]
	v_mfma_f32_16x16x32_bf16 v[64:67], v[176:179], v[210:213], v[64:67]
	s_setprio 0
	s_barrier
	s_add_i32 s64, s53, s44
	s_mov_b32 m0, s64
	ds_read_b128 v[180:183], v146 offset:16384
	ds_read_b128 v[184:187], v146 offset:17408
	ds_read_b128 v[190:193], v146 offset:18432
	ds_read_b128 v[194:197], v146 offset:19456
	global_load_lds_dwordx4 v132, s[62:63]
	s_add_i32 m0, s64, 0x2000
	s_mov_b64 s[100:101], s[62:63]
	s_add_i32 s64, s54, s44
	global_load_lds_dwordx4 v134, s[62:63]
	s_add_u32 s62, s62, s16
	s_addc_u32 s63, s63, s17
	s_mov_b32 m0, s64
	ds_read_b128 v[210:213], v146 offset:23552
	global_load_lds_dwordx4 v132, s[62:63]
	s_add_i32 m0, s64, 0x2000
	ds_read_b128 v[206:209], v146 offset:22528
	global_load_lds_dwordx4 v134, s[62:63]
	s_mov_b32 m0, s33
	ds_read_b128 v[202:205], v146 offset:21504
	global_load_lds_dwordx4 v128, s[34:35]
	s_mov_b32 m0, s43
	ds_read_b128 v[198:201], v146 offset:20480
	global_load_lds_dwordx4 v130, s[34:35]
	s_waitcnt vmcnt(8)
	s_waitcnt lgkmcnt(0)
	s_barrier
	s_setprio 1
	v_mfma_f32_16x16x32_bf16 v[60:63], v[148:151], v[180:183], v[60:63]
	v_mfma_f32_16x16x32_bf16 v[56:59], v[156:159], v[180:183], v[56:59]
	v_mfma_f32_16x16x32_bf16 v[44:47], v[148:151], v[190:193], v[44:47]
	v_mfma_f32_16x16x32_bf16 v[40:43], v[156:159], v[190:193], v[40:43]
	v_mfma_f32_16x16x32_bf16 v[28:31], v[148:151], v[198:201], v[28:31]
	v_mfma_f32_16x16x32_bf16 v[24:27], v[156:159], v[198:201], v[24:27]
	v_mfma_f32_16x16x32_bf16 v[12:15], v[148:151], v[206:209], v[12:15]
	v_mfma_f32_16x16x32_bf16 v[8:11], v[156:159], v[206:209], v[8:11]
	v_mfma_f32_16x16x32_bf16 v[60:63], v[152:155], v[184:187], v[60:63]
	v_mfma_f32_16x16x32_bf16 v[56:59], v[160:163], v[184:187], v[56:59]
	v_mfma_f32_16x16x32_bf16 v[44:47], v[152:155], v[194:197], v[44:47]
	v_mfma_f32_16x16x32_bf16 v[40:43], v[160:163], v[194:197], v[40:43]
	v_mfma_f32_16x16x32_bf16 v[28:31], v[152:155], v[202:205], v[28:31]
	v_mfma_f32_16x16x32_bf16 v[24:27], v[160:163], v[202:205], v[24:27]
	v_mfma_f32_16x16x32_bf16 v[12:15], v[152:155], v[210:213], v[12:15]
	v_mfma_f32_16x16x32_bf16 v[8:11], v[160:163], v[210:213], v[8:11]
	v_mfma_f32_16x16x32_bf16 v[52:55], v[164:167], v[180:183], v[52:55]
	v_mfma_f32_16x16x32_bf16 v[48:51], v[172:175], v[180:183], v[48:51]
	v_mfma_f32_16x16x32_bf16 v[36:39], v[164:167], v[190:193], v[36:39]
	v_mfma_f32_16x16x32_bf16 v[32:35], v[172:175], v[190:193], v[32:35]
	v_mfma_f32_16x16x32_bf16 v[20:23], v[164:167], v[198:201], v[20:23]
	v_mfma_f32_16x16x32_bf16 v[16:19], v[172:175], v[198:201], v[16:19]
	v_mfma_f32_16x16x32_bf16 v[4:7], v[164:167], v[206:209], v[4:7]
	v_mfma_f32_16x16x32_bf16 v[0:3], v[172:175], v[206:209], v[0:3]
	v_mfma_f32_16x16x32_bf16 v[52:55], v[168:171], v[184:187], v[52:55]
	v_mfma_f32_16x16x32_bf16 v[48:51], v[176:179], v[184:187], v[48:51]
	v_mfma_f32_16x16x32_bf16 v[36:39], v[168:171], v[194:197], v[36:39]
	v_mfma_f32_16x16x32_bf16 v[32:35], v[176:179], v[194:197], v[32:35]
	v_mfma_f32_16x16x32_bf16 v[20:23], v[168:171], v[202:205], v[20:23]
	v_mfma_f32_16x16x32_bf16 v[16:19], v[176:179], v[202:205], v[16:19]
	v_mfma_f32_16x16x32_bf16 v[4:7], v[168:171], v[210:213], v[4:7]
	v_mfma_f32_16x16x32_bf16 v[0:3], v[176:179], v[210:213], v[0:3]
	s_setprio 0
	s_barrier
; #define PG8_STAGE(bufoff, gbase, voff) do { _Pragma("unroll") for (int _i = 0; _i < 2; ++_i) \
;         __builtin_amdgcn_global_load_lds((const unsigned*)((const char*)(gbase) + (voff)[_i]), (PG8_LAS unsigned*)(lds + (bufoff) + ldsw + _i * 8192), 16, 0, 0); } while (0)
; #define PG8_LDA(dst, b, h) do { _Pragma("unroll") for (int m = 0; m < 4; ++m) _Pragma("unroll") for (int k = 0; k < 2; ++k) dst[m][k] = *(const PG8_LAS bf16x8*)(lds + PG8_SA(b, h) + aoff + m * 2048 + k * 1024); } while (0)
; #define PG8_LDB(dst, b, h) do { _Pragma("unroll") for (int n = 0; n < 2; ++n) _Pragma("unroll") for (int k = 0; k < 2; ++k) dst[n][k] = *(const PG8_LAS bf16x8*)(lds + PG8_SB(b, h) + boff + n * 2048 + k * 1024); } while (0)
; #define PG8_MMA(ai, bj, At, Bt) do { __builtin_amdgcn_s_setprio(1); _Pragma("unroll") for (int m = 0; m < 4; ++m) _Pragma("unroll") for (int n = 0; n < 2; ++n) _Pragma("unroll") for (int k = 0; k < 2; ++k) \
;         acc[ai][bj][m][n] = __builtin_amdgcn_mfma_f32_16x16x32_bf16(Bt[n][k], At[m][k], acc[ai][bj][m][n], 0, 0, 0); __builtin_amdgcn_s_setprio(0); } while (0)
; #define PG8_WAIT_V(n) asm volatile("s_waitcnt vmcnt(" #n ")" ::: "memory")
; #define PG8_WAIT_L(n) asm volatile("s_waitcnt lgkmcnt(" #n ")" ::: "memory")
; #define PG8_BAR __builtin_amdgcn_s_barrier()
; template <class Epi, class Sched, bool ALIGN_EPI = false, bool SP2 = false>
; __device__ __forceinline__ void gemm_phase(PG8_LAS unsigned char* lds, const Gemm g, const Sched& S, const Epi& E) {
;     ...
;         for (int t = 0; t < nt; t += 2) {
;             const bool last = (t == nt - 2);
;             const char* a1 = cA + (size_t)(t + 1) * kstep;
;             const char* a2 = last ? nA : cA + (size_t)(t + 2) * kstep; const char* b2 = last ? nB : cB + (size_t)(t + 2) * kstep;
;             const char* a3 = a2 + kstep; const char* b3 = b2 + kstep;
;     ...
;             PG8_LDB(B0, 1, 0); PG8_LDB(B1, 1, 1); PG8_SCHED; PG8_LDA(At, 1, 0); PG8_STAGE(PG8_SA(0, 1), a2 + hstepA, voffA);
;             PG8_WAIT_V(8); PG8_WAIT_L(0); PG8_BAR; PG8_MMA(0, 0, At, B0); PG8_MMA(0, 1, At, B1); PG8_BAR; PG8_SCHED;
;             PG8_LDA(At, 1, 1); PG8_STAGE(PG8_SB(1, 0), b3, voffB); PG8_STAGE(PG8_SB(1, 1), b3 + hstep, voffB); PG8_STAGE(PG8_SA(1, 0), a3, voffA);
;             PG8_WAIT_V(8); PG8_WAIT_L(0); PG8_BAR; PG8_MMA(1, 0, At, B0); PG8_MMA(1, 1, At, B1); PG8_BAR; PG8_SCHED;
	s_add_i32 s62, 0, 0x18000
	v_add_u32_e32 v147, s62, v142
	s_add_i32 s63, 0, 0x1c000
	ds_read_b128 v[148:151], v147
	ds_read_b128 v[152:155], v147 offset:1024
	ds_read_b128 v[156:159], v147 offset:2048
	ds_read_b128 v[160:163], v147 offset:3072
	v_add_u32_e32 v147, s63, v142
	ds_read_b128 v[164:167], v147
	ds_read_b128 v[168:171], v147 offset:1024
	ds_read_b128 v[172:175], v147 offset:2048
	ds_read_b128 v[176:179], v147 offset:3072
	s_mov_b64 vcc, s[34:35]
	s_add_u32 s34, s34, 0x40000
	s_addc_u32 s35, s35, 0
	s_mov_b32 m0, s45
	ds_read_b128 v[180:183], v146 offset:32768
	ds_read_b128 v[184:187], v146 offset:33792
	ds_read_b128 v[190:193], v146 offset:34816
	ds_read_b128 v[194:197], v146 offset:35840
	ds_read_b128 v[198:201], v146 offset:36864
	ds_read_b128 v[202:205], v146 offset:37888
	ds_read_b128 v[206:209], v146 offset:38912
	global_load_lds_dwordx4 v128, s[34:35]
	s_mov_b32 m0, s47
	ds_read_b128 v[210:213], v146 offset:39936
	global_load_lds_dwordx4 v130, s[34:35]
	s_waitcnt vmcnt(8)
	s_waitcnt lgkmcnt(0)
	s_barrier
	s_setprio 1
	v_mfma_f32_16x16x32_bf16 v[124:127], v[148:151], v[180:183], v[124:127]
	v_mfma_f32_16x16x32_bf16 v[120:123], v[156:159], v[180:183], v[120:123]
	v_mfma_f32_16x16x32_bf16 v[108:111], v[148:151], v[190:193], v[108:111]
	v_mfma_f32_16x16x32_bf16 v[104:107], v[156:159], v[190:193], v[104:107]
	v_mfma_f32_16x16x32_bf16 v[92:95], v[148:151], v[198:201], v[92:95]
	v_mfma_f32_16x16x32_bf16 v[88:91], v[156:159], v[198:201], v[88:91]
	v_mfma_f32_16x16x32_bf16 v[76:79], v[148:151], v[206:209], v[76:79]
	v_mfma_f32_16x16x32_bf16 v[72:75], v[156:159], v[206:209], v[72:75]
	v_mfma_f32_16x16x32_bf16 v[124:127], v[152:155], v[184:187], v[124:127]
	v_mfma_f32_16x16x32_bf16 v[120:123], v[160:163], v[184:187], v[120:123]
	v_mfma_f32_16x16x32_bf16 v[108:111], v[152:155], v[194:197], v[108:111]
	v_mfma_f32_16x16x32_bf16 v[104:107], v[160:163], v[194:197], v[104:107]
	v_mfma_f32_16x16x32_bf16 v[92:95], v[152:155], v[202:205], v[92:95]
	v_mfma_f32_16x16x32_bf16 v[88:91], v[160:163], v[202:205], v[88:91]
	v_mfma_f32_16x16x32_bf16 v[76:79], v[152:155], v[210:213], v[76:79]
	v_mfma_f32_16x16x32_bf16 v[72:75], v[160:163], v[210:213], v[72:75]
	v_mfma_f32_16x16x32_bf16 v[116:119], v[164:167], v[180:183], v[116:119]
	v_mfma_f32_16x16x32_bf16 v[112:115], v[172:175], v[180:183], v[112:115]
	v_mfma_f32_16x16x32_bf16 v[100:103], v[164:167], v[190:193], v[100:103]
	v_mfma_f32_16x16x32_bf16 v[96:99], v[172:175], v[190:193], v[96:99]
	v_mfma_f32_16x16x32_bf16 v[84:87], v[164:167], v[198:201], v[84:87]
	v_mfma_f32_16x16x32_bf16 v[80:83], v[172:175], v[198:201], v[80:83]
	v_mfma_f32_16x16x32_bf16 v[68:71], v[164:167], v[206:209], v[68:71]
	v_mfma_f32_16x16x32_bf16 v[64:67], v[172:175], v[206:209], v[64:67]
	v_mfma_f32_16x16x32_bf16 v[116:119], v[168:171], v[184:187], v[116:119]
	v_mfma_f32_16x16x32_bf16 v[112:115], v[176:179], v[184:187], v[112:115]
	v_mfma_f32_16x16x32_bf16 v[100:103], v[168:171], v[194:197], v[100:103]
	v_mfma_f32_16x16x32_bf16 v[96:99], v[176:179], v[194:197], v[96:99]
	v_mfma_f32_16x16x32_bf16 v[84:87], v[168:171], v[202:205], v[84:87]
	v_mfma_f32_16x16x32_bf16 v[80:83], v[176:179], v[202:205], v[80:83]
	v_mfma_f32_16x16x32_bf16 v[68:71], v[168:171], v[210:213], v[68:71]
	v_mfma_f32_16x16x32_bf16 v[64:67], v[176:179], v[210:213], v[64:67]
	s_setprio 0
	s_barrier
	s_add_i32 s34, s62, s44
	s_add_i32 m0, s34, 0xffffff80
	ds_read_b128 v[180:183], v146 offset:49152
	ds_read_b128 v[184:187], v146 offset:50176
	ds_read_b128 v[190:193], v146 offset:51200
	ds_read_b128 v[194:197], v146 offset:52224
	global_load_lds_dwordx4 v132, s[100:101] offset:128
	s_add_i32 m0, s34, 0x1f80
	s_add_i32 s34, s63, s44
	global_load_lds_dwordx4 v134, s[100:101] offset:128
	s_add_u32 s100, s100, s16
	s_addc_u32 s101, s101, s17
	s_add_i32 m0, s34, 0xffffff80
	ds_read_b128 v[210:213], v146 offset:56320
	global_load_lds_dwordx4 v132, s[100:101] offset:128
	s_add_i32 m0, s34, 0x1f80
	ds_read_b128 v[206:209], v146 offset:55296
	global_load_lds_dwordx4 v134, s[100:101] offset:128
	s_add_i32 m0, s48, 0xffffff80
	ds_read_b128 v[202:205], v146 offset:54272
	global_load_lds_dwordx4 v128, vcc offset:128
	s_add_i32 m0, s49, 0xffffff80
	ds_read_b128 v[198:201], v146 offset:53248
	global_load_lds_dwordx4 v130, vcc offset:128
	s_waitcnt vmcnt(8)
	s_waitcnt lgkmcnt(0)
	s_barrier
	s_setprio 1
	v_mfma_f32_16x16x32_bf16 v[60:63], v[148:151], v[180:183], v[60:63]
	v_mfma_f32_16x16x32_bf16 v[56:59], v[156:159], v[180:183], v[56:59]
	v_mfma_f32_16x16x32_bf16 v[44:47], v[148:151], v[190:193], v[44:47]
	v_mfma_f32_16x16x32_bf16 v[40:43], v[156:159], v[190:193], v[40:43]
	v_mfma_f32_16x16x32_bf16 v[28:31], v[148:151], v[198:201], v[28:31]
	v_mfma_f32_16x16x32_bf16 v[24:27], v[156:159], v[198:201], v[24:27]
	v_mfma_f32_16x16x32_bf16 v[12:15], v[148:151], v[206:209], v[12:15]
	v_mfma_f32_16x16x32_bf16 v[8:11], v[156:159], v[206:209], v[8:11]
	v_mfma_f32_16x16x32_bf16 v[60:63], v[152:155], v[184:187], v[60:63]
	v_mfma_f32_16x16x32_bf16 v[56:59], v[160:163], v[184:187], v[56:59]
	v_mfma_f32_16x16x32_bf16 v[44:47], v[152:155], v[194:197], v[44:47]
	v_mfma_f32_16x16x32_bf16 v[40:43], v[160:163], v[194:197], v[40:43]
	v_mfma_f32_16x16x32_bf16 v[28:31], v[152:155], v[202:205], v[28:31]
	v_mfma_f32_16x16x32_bf16 v[24:27], v[160:163], v[202:205], v[24:27]
	v_mfma_f32_16x16x32_bf16 v[12:15], v[152:155], v[210:213], v[12:15]
	v_mfma_f32_16x16x32_bf16 v[8:11], v[160:163], v[210:213], v[8:11]
	v_mfma_f32_16x16x32_bf16 v[52:55], v[164:167], v[180:183], v[52:55]
	v_mfma_f32_16x16x32_bf16 v[48:51], v[172:175], v[180:183], v[48:51]
	v_mfma_f32_16x16x32_bf16 v[36:39], v[164:167], v[190:193], v[36:39]
	v_mfma_f32_16x16x32_bf16 v[32:35], v[172:175], v[190:193], v[32:35]
	v_mfma_f32_16x16x32_bf16 v[20:23], v[164:167], v[198:201], v[20:23]
	v_mfma_f32_16x16x32_bf16 v[16:19], v[172:175], v[198:201], v[16:19]
	v_mfma_f32_16x16x32_bf16 v[4:7], v[164:167], v[206:209], v[4:7]
	v_mfma_f32_16x16x32_bf16 v[0:3], v[172:175], v[206:209], v[0:3]
	v_mfma_f32_16x16x32_bf16 v[52:55], v[168:171], v[184:187], v[52:55]
	v_mfma_f32_16x16x32_bf16 v[48:51], v[176:179], v[184:187], v[48:51]
	v_mfma_f32_16x16x32_bf16 v[36:39], v[168:171], v[194:197], v[36:39]
	v_mfma_f32_16x16x32_bf16 v[32:35], v[176:179], v[194:197], v[32:35]
	v_mfma_f32_16x16x32_bf16 v[20:23], v[168:171], v[202:205], v[20:23]
	v_mfma_f32_16x16x32_bf16 v[16:19], v[176:179], v[202:205], v[16:19]
	v_mfma_f32_16x16x32_bf16 v[4:7], v[168:171], v[210:213], v[4:7]
	v_mfma_f32_16x16x32_bf16 v[0:3], v[176:179], v[210:213], v[0:3]
	s_setprio 0
	s_barrier
	s_add_u32 s30, s30, 0x100
	s_addc_u32 s31, s31, 0
	s_add_u32 s37, s37, 0x100
	s_addc_u32 s60, s60, 0
	s_cmp_ge_i32 s61, s50
	s_mov_b32 s34, s61
	s_cbranch_scc0 .LBB0_282

; #define PG8_STAGE(bufoff, gbase, voff) do { _Pragma("unroll") for (int _i = 0; _i < 2; ++_i) \
;         __builtin_amdgcn_global_load_lds((const unsigned*)((const char*)(gbase) + (voff)[_i]), (PG8_LAS unsigned*)(lds + (bufoff) + ldsw + _i * 8192), 16, 0, 0); } while (0)
; #define PG8_LDA(dst, b, h) do { _Pragma("unroll") for (int m = 0; m < 4; ++m) _Pragma("unroll") for (int k = 0; k < 2; ++k) dst[m][k] = *(const PG8_LAS bf16x8*)(lds + PG8_SA(b, h) + aoff + m * 2048 + k * 1024); } while (0)
; #define PG8_LDB(dst, b, h) do { _Pragma("unroll") for (int n = 0; n < 2; ++n) _Pragma("unroll") for (int k = 0; k < 2; ++k) dst[n][k] = *(const PG8_LAS bf16x8*)(lds + PG8_SB(b, h) + boff + n * 2048 + k * 1024); } while (0)
; #define PG8_MMA(ai, bj, At, Bt) do { __builtin_amdgcn_s_setprio(1); _Pragma("unroll") for (int m = 0; m < 4; ++m) _Pragma("unroll") for (int n = 0; n < 2; ++n) _Pragma("unroll") for (int k = 0; k < 2; ++k) \
;         acc[ai][bj][m][n] = __builtin_amdgcn_mfma_f32_16x16x32_bf16(Bt[n][k], At[m][k], acc[ai][bj][m][n], 0, 0, 0); __builtin_amdgcn_s_setprio(0); } while (0)
; #define PG8_WAIT_V(n) asm volatile("s_waitcnt vmcnt(" #n ")" ::: "memory")
; #define PG8_BAR __builtin_amdgcn_s_barrier()
; template <class Epi, class Sched, bool ALIGN_EPI = false, bool SP2 = false>
; __device__ __forceinline__ void gemm_phase(PG8_LAS unsigned char* lds, const Gemm g, const Sched& S, const Epi& E) {
;     ...
;         for (int t = 0; t < nt; t += 2) {
;             const bool last = (t == nt - 2);
;             const char* a1 = cA + (size_t)(t + 1) * kstep;
;             const char* a2 = last ? nA : cA + (size_t)(t + 2) * kstep; const char* b2 = last ? nB : cB + (size_t)(t + 2) * kstep;
;             const char* a3 = a2 + kstep; const char* b3 = b2 + kstep;
;             if (last && has_next) S.a_ready(nxt);
;             if constexpr (SP2) {
;             PG8_LDB(B0, 0, 0); PG8_LDB(B1, 0, 1); PG8_SCHED; PG8_LDA(At, 0, 0); PG8_STAGE(PG8_SA(1, 1), a1 + hstepA, voffA);
;             PG8_WAIT_V(8); PG8_WAIT_L(0); PG8_BAR; PG8_MMA(0, 0, At, B0); PG8_MMA(0, 1, At, B1); PG8_BAR; PG8_SCHED;
;             PG8_LDA(At, 0, 1); PG8_STAGE(PG8_SB(0, 0), b2, voffB); PG8_STAGE(PG8_SB(0, 1), b2 + hstep, voffB); PG8_STAGE(PG8_SA(0, 0), a2, voffA);
;             PG8_WAIT_V(8); PG8_WAIT_L(0); PG8_BAR; PG8_MMA(1, 0, At, B0); PG8_MMA(1, 1, At, B1); PG8_BAR; PG8_SCHED;
.LBB0_368:
	ds_read_b128 v[154:157], v150
	ds_read_b128 v[158:161], v150 offset:1024
	ds_read_b128 v[162:165], v150 offset:2048
	ds_read_b128 v[166:169], v150 offset:3072
	ds_read_b128 v[170:173], v151
	ds_read_b128 v[174:177], v151 offset:1024
	ds_read_b128 v[178:181], v151 offset:2048
	ds_read_b128 v[182:185], v151 offset:3072
	s_add_i32 s64, s28, 2
	s_add_u32 s65, s26, 0xfffe0080
	s_addc_u32 s29, s27, -1
	s_cmp_eq_u32 s50, s28
	s_cselect_b32 s28, s30, s65
	s_cselect_b32 s29, s13, s29
	s_cselect_b32 s67, s21, s63
	s_cselect_b32 s66, s20, s62
	s_mov_b32 m0, s54
	ds_read_b128 v[190:193], v152
	ds_read_b128 v[194:197], v152 offset:1024
	ds_read_b128 v[198:201], v152 offset:2048
	ds_read_b128 v[202:205], v152 offset:3072
	ds_read_b128 v[206:209], v152 offset:4096
	ds_read_b128 v[210:213], v152 offset:5120
	ds_read_b128 v[214:217], v152 offset:6144
	global_load_lds_dwordx4 v138, s[26:27]
	s_mov_b32 m0, s55
	ds_read_b128 v[218:221], v152 offset:7168
	global_load_lds_dwordx4 v140, s[26:27]
	s_waitcnt vmcnt(8)
	s_waitcnt lgkmcnt(0)
	s_barrier
	s_setprio 1
	v_mfma_f32_16x16x32_bf16 v[124:127], v[154:157], v[190:193], v[124:127]
	v_mfma_f32_16x16x32_bf16 v[120:123], v[162:165], v[190:193], v[120:123]
	v_mfma_f32_16x16x32_bf16 v[108:111], v[154:157], v[198:201], v[108:111]
	v_mfma_f32_16x16x32_bf16 v[104:107], v[162:165], v[198:201], v[104:107]
	v_mfma_f32_16x16x32_bf16 v[92:95], v[154:157], v[206:209], v[92:95]
	v_mfma_f32_16x16x32_bf16 v[88:91], v[162:165], v[206:209], v[88:91]
	v_mfma_f32_16x16x32_bf16 v[76:79], v[154:157], v[214:217], v[76:79]
	v_mfma_f32_16x16x32_bf16 v[72:75], v[162:165], v[214:217], v[72:75]
	v_mfma_f32_16x16x32_bf16 v[124:127], v[158:161], v[194:197], v[124:127]
	v_mfma_f32_16x16x32_bf16 v[120:123], v[166:169], v[194:197], v[120:123]
	v_mfma_f32_16x16x32_bf16 v[108:111], v[158:161], v[202:205], v[108:111]
	v_mfma_f32_16x16x32_bf16 v[104:107], v[166:169], v[202:205], v[104:107]
	v_mfma_f32_16x16x32_bf16 v[92:95], v[158:161], v[210:213], v[92:95]
	v_mfma_f32_16x16x32_bf16 v[88:91], v[166:169], v[210:213], v[88:91]
	v_mfma_f32_16x16x32_bf16 v[76:79], v[158:161], v[218:221], v[76:79]
	v_mfma_f32_16x16x32_bf16 v[72:75], v[166:169], v[218:221], v[72:75]
	v_mfma_f32_16x16x32_bf16 v[116:119], v[170:173], v[190:193], v[116:119]
	v_mfma_f32_16x16x32_bf16 v[112:115], v[178:181], v[190:193], v[112:115]
	v_mfma_f32_16x16x32_bf16 v[100:103], v[170:173], v[198:201], v[100:103]
	v_mfma_f32_16x16x32_bf16 v[96:99], v[178:181], v[198:201], v[96:99]
	v_mfma_f32_16x16x32_bf16 v[84:87], v[170:173], v[206:209], v[84:87]
	v_mfma_f32_16x16x32_bf16 v[80:83], v[178:181], v[206:209], v[80:83]
	v_mfma_f32_16x16x32_bf16 v[68:71], v[170:173], v[214:217], v[68:71]
	v_mfma_f32_16x16x32_bf16 v[64:67], v[178:181], v[214:217], v[64:67]
	v_mfma_f32_16x16x32_bf16 v[116:119], v[174:177], v[194:197], v[116:119]
	v_mfma_f32_16x16x32_bf16 v[112:115], v[182:185], v[194:197], v[112:115]
	v_mfma_f32_16x16x32_bf16 v[100:103], v[174:177], v[202:205], v[100:103]
	v_mfma_f32_16x16x32_bf16 v[96:99], v[182:185], v[202:205], v[96:99]
	v_mfma_f32_16x16x32_bf16 v[84:87], v[174:177], v[210:213], v[84:87]
	v_mfma_f32_16x16x32_bf16 v[80:83], v[182:185], v[210:213], v[80:83]
	v_mfma_f32_16x16x32_bf16 v[68:71], v[174:177], v[218:221], v[68:71]
	v_mfma_f32_16x16x32_bf16 v[64:67], v[182:185], v[218:221], v[64:67]
	s_setprio 0
	s_barrier
	s_mov_b32 m0, s56
	s_mov_b64 s[100:101], s[66:67]
	ds_read_b128 v[190:193], v152 offset:16384
	ds_read_b128 v[194:197], v152 offset:17408
	ds_read_b128 v[198:201], v152 offset:18432
	global_load_lds_dwordx4 v134, s[66:67]
	s_mov_b32 m0, s57
	ds_read_b128 v[218:221], v152 offset:23552
	global_load_lds_dwordx4 v132, s[66:67]
	s_add_u32 s66, s66, s4
	s_addc_u32 s67, s67, s5
	s_mov_b32 m0, s58
	ds_read_b128 v[214:217], v152 offset:22528
	global_load_lds_dwordx4 v134, s[66:67]
	s_mov_b32 m0, s59
	ds_read_b128 v[210:213], v152 offset:21504
	global_load_lds_dwordx4 v132, s[66:67]
	s_mov_b32 m0, s38
	ds_read_b128 v[206:209], v152 offset:20480
	global_load_lds_dwordx4 v130, s[28:29]
	s_mov_b32 m0, s39
	ds_read_b128 v[202:205], v152 offset:19456
	global_load_lds_dwordx4 v128, s[28:29]
	s_waitcnt vmcnt(8)
	s_waitcnt lgkmcnt(0)
	s_barrier
	s_setprio 1
	v_mfma_f32_16x16x32_bf16 v[60:63], v[154:157], v[190:193], v[60:63]
	v_mfma_f32_16x16x32_bf16 v[56:59], v[162:165], v[190:193], v[56:59]
	v_mfma_f32_16x16x32_bf16 v[44:47], v[154:157], v[198:201], v[44:47]
	v_mfma_f32_16x16x32_bf16 v[40:43], v[162:165], v[198:201], v[40:43]
	v_mfma_f32_16x16x32_bf16 v[28:31], v[154:157], v[206:209], v[28:31]
	v_mfma_f32_16x16x32_bf16 v[24:27], v[162:165], v[206:209], v[24:27]
	v_mfma_f32_16x16x32_bf16 v[12:15], v[154:157], v[214:217], v[12:15]
	v_mfma_f32_16x16x32_bf16 v[8:11], v[162:165], v[214:217], v[8:11]
	v_mfma_f32_16x16x32_bf16 v[60:63], v[158:161], v[194:197], v[60:63]
	v_mfma_f32_16x16x32_bf16 v[56:59], v[166:169], v[194:197], v[56:59]
	v_mfma_f32_16x16x32_bf16 v[44:47], v[158:161], v[202:205], v[44:47]
	v_mfma_f32_16x16x32_bf16 v[40:43], v[166:169], v[202:205], v[40:43]
	v_mfma_f32_16x16x32_bf16 v[28:31], v[158:161], v[210:213], v[28:31]
	v_mfma_f32_16x16x32_bf16 v[24:27], v[166:169], v[210:213], v[24:27]
	v_mfma_f32_16x16x32_bf16 v[12:15], v[158:161], v[218:221], v[12:15]
	v_mfma_f32_16x16x32_bf16 v[8:11], v[166:169], v[218:221], v[8:11]
	v_mfma_f32_16x16x32_bf16 v[52:55], v[170:173], v[190:193], v[52:55]
	v_mfma_f32_16x16x32_bf16 v[48:51], v[178:181], v[190:193], v[48:51]
	v_mfma_f32_16x16x32_bf16 v[36:39], v[170:173], v[198:201], v[36:39]
	v_mfma_f32_16x16x32_bf16 v[32:35], v[178:181], v[198:201], v[32:35]
	v_mfma_f32_16x16x32_bf16 v[20:23], v[170:173], v[206:209], v[20:23]
	v_mfma_f32_16x16x32_bf16 v[16:19], v[178:181], v[206:209], v[16:19]
	v_mfma_f32_16x16x32_bf16 v[4:7], v[170:173], v[214:217], v[4:7]
	v_mfma_f32_16x16x32_bf16 v[0:3], v[178:181], v[214:217], v[0:3]
	v_mfma_f32_16x16x32_bf16 v[52:55], v[174:177], v[194:197], v[52:55]
	v_mfma_f32_16x16x32_bf16 v[48:51], v[182:185], v[194:197], v[48:51]
	v_mfma_f32_16x16x32_bf16 v[36:39], v[174:177], v[202:205], v[36:39]
	v_mfma_f32_16x16x32_bf16 v[32:35], v[182:185], v[202:205], v[32:35]
	v_mfma_f32_16x16x32_bf16 v[20:23], v[174:177], v[210:213], v[20:23]
	v_mfma_f32_16x16x32_bf16 v[16:19], v[182:185], v[210:213], v[16:19]
	v_mfma_f32_16x16x32_bf16 v[4:7], v[174:177], v[218:221], v[4:7]
	v_mfma_f32_16x16x32_bf16 v[0:3], v[182:185], v[218:221], v[0:3]
	s_setprio 0
	s_barrier
; #define PG8_STAGE(bufoff, gbase, voff) do { _Pragma("unroll") for (int _i = 0; _i < 2; ++_i) \
;         __builtin_amdgcn_global_load_lds((const unsigned*)((const char*)(gbase) + (voff)[_i]), (PG8_LAS unsigned*)(lds + (bufoff) + ldsw + _i * 8192), 16, 0, 0); } while (0)
; #define PG8_LDA(dst, b, h) do { _Pragma("unroll") for (int m = 0; m < 4; ++m) _Pragma("unroll") for (int k = 0; k < 2; ++k) dst[m][k] = *(const PG8_LAS bf16x8*)(lds + PG8_SA(b, h) + aoff + m * 2048 + k * 1024); } while (0)
; #define PG8_LDB(dst, b, h) do { _Pragma("unroll") for (int n = 0; n < 2; ++n) _Pragma("unroll") for (int k = 0; k < 2; ++k) dst[n][k] = *(const PG8_LAS bf16x8*)(lds + PG8_SB(b, h) + boff + n * 2048 + k * 1024); } while (0)
; #define PG8_MMA(ai, bj, At, Bt) do { __builtin_amdgcn_s_setprio(1); _Pragma("unroll") for (int m = 0; m < 4; ++m) _Pragma("unroll") for (int n = 0; n < 2; ++n) _Pragma("unroll") for (int k = 0; k < 2; ++k) \
;         acc[ai][bj][m][n] = __builtin_amdgcn_mfma_f32_16x16x32_bf16(Bt[n][k], At[m][k], acc[ai][bj][m][n], 0, 0, 0); __builtin_amdgcn_s_setprio(0); } while (0)
; #define PG8_WAIT_V(n) asm volatile("s_waitcnt vmcnt(" #n ")" ::: "memory")
; #define PG8_WAIT_L(n) asm volatile("s_waitcnt lgkmcnt(" #n ")" ::: "memory")
; #define PG8_BAR __builtin_amdgcn_s_barrier()
; template <class Epi, class Sched, bool ALIGN_EPI = false, bool SP2 = false>
; __device__ __forceinline__ void gemm_phase(PG8_LAS unsigned char* lds, const Gemm g, const Sched& S, const Epi& E) {
;     ...
;         for (int t = 0; t < nt; t += 2) {
;             const bool last = (t == nt - 2);
;             const char* a1 = cA + (size_t)(t + 1) * kstep;
;             const char* a2 = last ? nA : cA + (size_t)(t + 2) * kstep; const char* b2 = last ? nB : cB + (size_t)(t + 2) * kstep;
;             const char* a3 = a2 + kstep; const char* b3 = b2 + kstep;
;     ...
;             PG8_LDB(B0, 1, 0); PG8_LDB(B1, 1, 1); PG8_SCHED; PG8_LDA(At, 1, 0); PG8_STAGE(PG8_SA(0, 1), a2 + hstepA, voffA);
;             PG8_WAIT_V(8); PG8_WAIT_L(0); PG8_BAR; PG8_MMA(0, 0, At, B0); PG8_MMA(0, 1, At, B1); PG8_BAR; PG8_SCHED;
;             PG8_LDA(At, 1, 1); PG8_STAGE(PG8_SB(1, 0), b3, voffB); PG8_STAGE(PG8_SB(1, 1), b3 + hstep, voffB); PG8_STAGE(PG8_SA(1, 0), a3, voffA);
;             PG8_WAIT_V(8); PG8_WAIT_L(0); PG8_BAR; PG8_MMA(1, 0, At, B0); PG8_MMA(1, 1, At, B1); PG8_BAR; PG8_SCHED;
	s_add_i32 s65, 0, 0x18000
	s_add_i32 s66, 0, 0x1c000
	v_add_u32_e32 v166, s65, v149
	v_add_u32_e32 v182, s66, v149
	ds_read_b128 v[154:157], v166
	ds_read_b128 v[158:161], v166 offset:1024
	ds_read_b128 v[162:165], v166 offset:2048
	ds_read_b128 v[166:169], v166 offset:3072
	ds_read_b128 v[170:173], v182
	ds_read_b128 v[174:177], v182 offset:1024
	ds_read_b128 v[178:181], v182 offset:2048
	ds_read_b128 v[182:185], v182 offset:3072
	s_mov_b64 vcc, s[28:29]
	s_add_u32 s28, s28, 0x20000
	s_addc_u32 s29, s29, 0
	s_mov_b32 m0, s40
	ds_read_b128 v[190:193], v152 offset:32768
	ds_read_b128 v[194:197], v152 offset:33792
	ds_read_b128 v[198:201], v152 offset:34816
	ds_read_b128 v[202:205], v152 offset:35840
	ds_read_b128 v[206:209], v152 offset:36864
	ds_read_b128 v[210:213], v152 offset:37888
	ds_read_b128 v[214:217], v152 offset:38912
	global_load_lds_dwordx4 v130, s[28:29]
	s_mov_b32 m0, s41
	ds_read_b128 v[218:221], v152 offset:39936
	global_load_lds_dwordx4 v128, s[28:29]
	s_waitcnt vmcnt(8)
	s_waitcnt lgkmcnt(0)
	s_barrier
	s_setprio 1
	v_mfma_f32_16x16x32_bf16 v[124:127], v[154:157], v[190:193], v[124:127]
	v_mfma_f32_16x16x32_bf16 v[120:123], v[162:165], v[190:193], v[120:123]
	v_mfma_f32_16x16x32_bf16 v[108:111], v[154:157], v[198:201], v[108:111]
	v_mfma_f32_16x16x32_bf16 v[104:107], v[162:165], v[198:201], v[104:107]
	v_mfma_f32_16x16x32_bf16 v[92:95], v[154:157], v[206:209], v[92:95]
	v_mfma_f32_16x16x32_bf16 v[88:91], v[162:165], v[206:209], v[88:91]
	v_mfma_f32_16x16x32_bf16 v[76:79], v[154:157], v[214:217], v[76:79]
	v_mfma_f32_16x16x32_bf16 v[72:75], v[162:165], v[214:217], v[72:75]
	v_mfma_f32_16x16x32_bf16 v[124:127], v[158:161], v[194:197], v[124:127]
	v_mfma_f32_16x16x32_bf16 v[120:123], v[166:169], v[194:197], v[120:123]
	v_mfma_f32_16x16x32_bf16 v[108:111], v[158:161], v[202:205], v[108:111]
	v_mfma_f32_16x16x32_bf16 v[104:107], v[166:169], v[202:205], v[104:107]
	v_mfma_f32_16x16x32_bf16 v[92:95], v[158:161], v[210:213], v[92:95]
	v_mfma_f32_16x16x32_bf16 v[88:91], v[166:169], v[210:213], v[88:91]
	v_mfma_f32_16x16x32_bf16 v[76:79], v[158:161], v[218:221], v[76:79]
	v_mfma_f32_16x16x32_bf16 v[72:75], v[166:169], v[218:221], v[72:75]
	v_mfma_f32_16x16x32_bf16 v[116:119], v[170:173], v[190:193], v[116:119]
	v_mfma_f32_16x16x32_bf16 v[112:115], v[178:181], v[190:193], v[112:115]
	v_mfma_f32_16x16x32_bf16 v[100:103], v[170:173], v[198:201], v[100:103]
	v_mfma_f32_16x16x32_bf16 v[96:99], v[178:181], v[198:201], v[96:99]
	v_mfma_f32_16x16x32_bf16 v[84:87], v[170:173], v[206:209], v[84:87]
	v_mfma_f32_16x16x32_bf16 v[80:83], v[178:181], v[206:209], v[80:83]
	v_mfma_f32_16x16x32_bf16 v[68:71], v[170:173], v[214:217], v[68:71]
	v_mfma_f32_16x16x32_bf16 v[64:67], v[178:181], v[214:217], v[64:67]
	v_mfma_f32_16x16x32_bf16 v[116:119], v[174:177], v[194:197], v[116:119]
	v_mfma_f32_16x16x32_bf16 v[112:115], v[182:185], v[194:197], v[112:115]
	v_mfma_f32_16x16x32_bf16 v[100:103], v[174:177], v[202:205], v[100:103]
	v_mfma_f32_16x16x32_bf16 v[96:99], v[182:185], v[202:205], v[96:99]
	v_mfma_f32_16x16x32_bf16 v[84:87], v[174:177], v[210:213], v[84:87]
	v_mfma_f32_16x16x32_bf16 v[80:83], v[182:185], v[210:213], v[80:83]
	v_mfma_f32_16x16x32_bf16 v[68:71], v[174:177], v[218:221], v[68:71]
	v_mfma_f32_16x16x32_bf16 v[64:67], v[182:185], v[218:221], v[64:67]
	s_setprio 0
	s_barrier
	s_add_i32 s28, s65, s37
	s_add_i32 m0, s28, 0xffffff80
	ds_read_b128 v[190:193], v152 offset:49152
	ds_read_b128 v[194:197], v152 offset:50176
	ds_read_b128 v[198:201], v152 offset:51200
	ds_read_b128 v[202:205], v152 offset:52224
	global_load_lds_dwordx4 v134, s[100:101] offset:128
	s_add_i32 m0, s28, 0x1f80
	s_add_i32 s28, s66, s37
	global_load_lds_dwordx4 v132, s[100:101] offset:128
	s_add_u32 s100, s100, s4
	s_addc_u32 s101, s101, s5
	s_add_i32 m0, s28, 0xffffff80
	ds_read_b128 v[218:221], v152 offset:56320
	global_load_lds_dwordx4 v134, s[100:101] offset:128
	s_add_i32 m0, s28, 0x1f80
	ds_read_b128 v[214:217], v152 offset:55296
	global_load_lds_dwordx4 v132, s[100:101] offset:128
	s_add_i32 m0, s43, 0xffffff80
	ds_read_b128 v[210:213], v152 offset:54272
	global_load_lds_dwordx4 v130, vcc offset:128
	s_add_i32 m0, s44, 0xffffff80
	ds_read_b128 v[206:209], v152 offset:53248
	global_load_lds_dwordx4 v128, vcc offset:128
	s_waitcnt vmcnt(8)
	s_waitcnt lgkmcnt(0)
	s_barrier
	s_setprio 1
	v_mfma_f32_16x16x32_bf16 v[60:63], v[154:157], v[190:193], v[60:63]
	v_mfma_f32_16x16x32_bf16 v[56:59], v[162:165], v[190:193], v[56:59]
	v_mfma_f32_16x16x32_bf16 v[44:47], v[154:157], v[198:201], v[44:47]
	v_mfma_f32_16x16x32_bf16 v[40:43], v[162:165], v[198:201], v[40:43]
	v_mfma_f32_16x16x32_bf16 v[28:31], v[154:157], v[206:209], v[28:31]
	v_mfma_f32_16x16x32_bf16 v[24:27], v[162:165], v[206:209], v[24:27]
	v_mfma_f32_16x16x32_bf16 v[12:15], v[154:157], v[214:217], v[12:15]
	v_mfma_f32_16x16x32_bf16 v[8:11], v[162:165], v[214:217], v[8:11]
	v_mfma_f32_16x16x32_bf16 v[60:63], v[158:161], v[194:197], v[60:63]
	v_mfma_f32_16x16x32_bf16 v[56:59], v[166:169], v[194:197], v[56:59]
	v_mfma_f32_16x16x32_bf16 v[44:47], v[158:161], v[202:205], v[44:47]
	v_mfma_f32_16x16x32_bf16 v[40:43], v[166:169], v[202:205], v[40:43]
	v_mfma_f32_16x16x32_bf16 v[28:31], v[158:161], v[210:213], v[28:31]
	v_mfma_f32_16x16x32_bf16 v[24:27], v[166:169], v[210:213], v[24:27]
	v_mfma_f32_16x16x32_bf16 v[12:15], v[158:161], v[218:221], v[12:15]
	v_mfma_f32_16x16x32_bf16 v[8:11], v[166:169], v[218:221], v[8:11]
	v_mfma_f32_16x16x32_bf16 v[52:55], v[170:173], v[190:193], v[52:55]
	v_mfma_f32_16x16x32_bf16 v[48:51], v[178:181], v[190:193], v[48:51]
	v_mfma_f32_16x16x32_bf16 v[36:39], v[170:173], v[198:201], v[36:39]
	v_mfma_f32_16x16x32_bf16 v[32:35], v[178:181], v[198:201], v[32:35]
	v_mfma_f32_16x16x32_bf16 v[20:23], v[170:173], v[206:209], v[20:23]
	v_mfma_f32_16x16x32_bf16 v[16:19], v[178:181], v[206:209], v[16:19]
	v_mfma_f32_16x16x32_bf16 v[4:7], v[170:173], v[214:217], v[4:7]
	v_mfma_f32_16x16x32_bf16 v[0:3], v[178:181], v[214:217], v[0:3]
	v_mfma_f32_16x16x32_bf16 v[52:55], v[174:177], v[194:197], v[52:55]
	v_mfma_f32_16x16x32_bf16 v[48:51], v[182:185], v[194:197], v[48:51]
	v_mfma_f32_16x16x32_bf16 v[36:39], v[174:177], v[202:205], v[36:39]
	v_mfma_f32_16x16x32_bf16 v[32:35], v[182:185], v[202:205], v[32:35]
	v_mfma_f32_16x16x32_bf16 v[20:23], v[174:177], v[210:213], v[20:23]
	v_mfma_f32_16x16x32_bf16 v[16:19], v[182:185], v[210:213], v[16:19]
	v_mfma_f32_16x16x32_bf16 v[4:7], v[174:177], v[218:221], v[4:7]
	v_mfma_f32_16x16x32_bf16 v[0:3], v[182:185], v[218:221], v[0:3]
	s_setprio 0
	s_barrier
	s_add_u32 s26, s26, 0x100
	s_addc_u32 s27, s27, 0
	s_add_u32 s62, s62, 0x100
	s_addc_u32 s63, s63, 0
	s_cmp_ge_i32 s64, s48
	s_mov_b32 s28, s64
	s_cbranch_scc0 .LBB0_368

; #define PG8_STAGE(bufoff, gbase, voff) do { _Pragma("unroll") for (int _i = 0; _i < 2; ++_i) \
;         __builtin_amdgcn_global_load_lds((const unsigned*)((const char*)(gbase) + (voff)[_i]), (PG8_LAS unsigned*)(lds + (bufoff) + ldsw + _i * 8192), 16, 0, 0); } while (0)
; #define PG8_LDA(dst, b, h) do { _Pragma("unroll") for (int m = 0; m < 4; ++m) _Pragma("unroll") for (int k = 0; k < 2; ++k) dst[m][k] = *(const PG8_LAS bf16x8*)(lds + PG8_SA(b, h) + aoff + m * 2048 + k * 1024); } while (0)
; #define PG8_LDB(dst, b, h) do { _Pragma("unroll") for (int n = 0; n < 2; ++n) _Pragma("unroll") for (int k = 0; k < 2; ++k) dst[n][k] = *(const PG8_LAS bf16x8*)(lds + PG8_SB(b, h) + boff + n * 2048 + k * 1024); } while (0)
; #define PG8_MMA(ai, bj, At, Bt) do { __builtin_amdgcn_s_setprio(1); _Pragma("unroll") for (int m = 0; m < 4; ++m) _Pragma("unroll") for (int n = 0; n < 2; ++n) _Pragma("unroll") for (int k = 0; k < 2; ++k) \
;         acc[ai][bj][m][n] = __builtin_amdgcn_mfma_f32_16x16x32_bf16(Bt[n][k], At[m][k], acc[ai][bj][m][n], 0, 0, 0); __builtin_amdgcn_s_setprio(0); } while (0)
; #define PG8_WAIT_V(n) asm volatile("s_waitcnt vmcnt(" #n ")" ::: "memory")
; #define PG8_BAR __builtin_amdgcn_s_barrier()
; template <class Epi, class Sched, bool ALIGN_EPI = false, bool SP2 = false>
; __device__ __forceinline__ void gemm_phase(PG8_LAS unsigned char* lds, const Gemm g, const Sched& S, const Epi& E) {
;     ...
;         for (int t = 0; t < nt; t += 2) {
;             const bool last = (t == nt - 2);
;             const char* a1 = cA + (size_t)(t + 1) * kstep;
;             const char* a2 = last ? nA : cA + (size_t)(t + 2) * kstep; const char* b2 = last ? nB : cB + (size_t)(t + 2) * kstep;
;             const char* a3 = a2 + kstep; const char* b3 = b2 + kstep;
;             if (last && has_next) S.a_ready(nxt);
;             if constexpr (SP2) {
;             PG8_LDB(B0, 0, 0); PG8_LDB(B1, 0, 1); PG8_SCHED; PG8_LDA(At, 0, 0); PG8_STAGE(PG8_SA(1, 1), a1 + hstepA, voffA);
;             PG8_WAIT_V(8); PG8_WAIT_L(0); PG8_BAR; PG8_MMA(0, 0, At, B0); PG8_MMA(0, 1, At, B1); PG8_BAR; PG8_SCHED;
;             PG8_LDA(At, 0, 1); PG8_STAGE(PG8_SB(0, 0), b2, voffB); PG8_STAGE(PG8_SB(0, 1), b2 + hstep, voffB); PG8_STAGE(PG8_SA(0, 0), a2, voffA);
;             PG8_WAIT_V(8); PG8_WAIT_L(0); PG8_BAR; PG8_MMA(1, 0, At, B0); PG8_MMA(1, 1, At, B1); PG8_BAR; PG8_SCHED;
.LBB0_523:
	ds_read_b128 v[154:157], v149
	ds_read_b128 v[158:161], v149 offset:1024
	ds_read_b128 v[162:165], v149 offset:2048
	ds_read_b128 v[166:169], v149 offset:3072
	ds_read_b128 v[170:173], v150
	ds_read_b128 v[174:177], v150 offset:1024
	ds_read_b128 v[178:181], v150 offset:2048
	ds_read_b128 v[182:185], v150 offset:3072
	s_add_i32 s61, s30, 2
	s_add_u32 s62, s4, 0xfffe0080
	s_addc_u32 s31, s5, -1
	s_cmp_eq_u32 s52, s30
	s_cselect_b32 s30, s34, s62
	s_cselect_b32 s31, s15, s31
	s_cselect_b32 s63, s25, s60
	s_cselect_b32 s62, s24, s59
	s_add_i32 m0, s41, 0xc000
	ds_read_b128 v[190:193], v151
	ds_read_b128 v[194:197], v151 offset:1024
	ds_read_b128 v[198:201], v151 offset:2048
	ds_read_b128 v[202:205], v151 offset:3072
	ds_read_b128 v[206:209], v151 offset:4096
	ds_read_b128 v[210:213], v151 offset:5120
	ds_read_b128 v[214:217], v151 offset:6144
	global_load_lds_dwordx4 v138, s[4:5]
	s_add_i32 m0, s41, 0xe000
	ds_read_b128 v[218:221], v151 offset:7168
	global_load_lds_dwordx4 v140, s[4:5]
	s_waitcnt vmcnt(8)
	s_waitcnt lgkmcnt(0)
	s_barrier
	s_setprio 1
	v_mfma_f32_16x16x32_bf16 v[124:127], v[154:157], v[190:193], v[124:127]
	v_mfma_f32_16x16x32_bf16 v[120:123], v[162:165], v[190:193], v[120:123]
	v_mfma_f32_16x16x32_bf16 v[108:111], v[154:157], v[198:201], v[108:111]
	v_mfma_f32_16x16x32_bf16 v[104:107], v[162:165], v[198:201], v[104:107]
	v_mfma_f32_16x16x32_bf16 v[92:95], v[154:157], v[206:209], v[92:95]
	v_mfma_f32_16x16x32_bf16 v[88:91], v[162:165], v[206:209], v[88:91]
	v_mfma_f32_16x16x32_bf16 v[76:79], v[154:157], v[214:217], v[76:79]
	v_mfma_f32_16x16x32_bf16 v[72:75], v[162:165], v[214:217], v[72:75]
	v_mfma_f32_16x16x32_bf16 v[124:127], v[158:161], v[194:197], v[124:127]
	v_mfma_f32_16x16x32_bf16 v[120:123], v[166:169], v[194:197], v[120:123]
	v_mfma_f32_16x16x32_bf16 v[108:111], v[158:161], v[202:205], v[108:111]
	v_mfma_f32_16x16x32_bf16 v[104:107], v[166:169], v[202:205], v[104:107]
	v_mfma_f32_16x16x32_bf16 v[92:95], v[158:161], v[210:213], v[92:95]
	v_mfma_f32_16x16x32_bf16 v[88:91], v[166:169], v[210:213], v[88:91]
	v_mfma_f32_16x16x32_bf16 v[76:79], v[158:161], v[218:221], v[76:79]
	v_mfma_f32_16x16x32_bf16 v[72:75], v[166:169], v[218:221], v[72:75]
	v_mfma_f32_16x16x32_bf16 v[116:119], v[170:173], v[190:193], v[116:119]
	v_mfma_f32_16x16x32_bf16 v[112:115], v[178:181], v[190:193], v[112:115]
	v_mfma_f32_16x16x32_bf16 v[100:103], v[170:173], v[198:201], v[100:103]
	v_mfma_f32_16x16x32_bf16 v[96:99], v[178:181], v[198:201], v[96:99]
	v_mfma_f32_16x16x32_bf16 v[84:87], v[170:173], v[206:209], v[84:87]
	v_mfma_f32_16x16x32_bf16 v[80:83], v[178:181], v[206:209], v[80:83]
	v_mfma_f32_16x16x32_bf16 v[68:71], v[170:173], v[214:217], v[68:71]
	v_mfma_f32_16x16x32_bf16 v[64:67], v[178:181], v[214:217], v[64:67]
	v_mfma_f32_16x16x32_bf16 v[116:119], v[174:177], v[194:197], v[116:119]
	v_mfma_f32_16x16x32_bf16 v[112:115], v[182:185], v[194:197], v[112:115]
	v_mfma_f32_16x16x32_bf16 v[100:103], v[174:177], v[202:205], v[100:103]
	v_mfma_f32_16x16x32_bf16 v[96:99], v[182:185], v[202:205], v[96:99]
	v_mfma_f32_16x16x32_bf16 v[84:87], v[174:177], v[210:213], v[84:87]
	v_mfma_f32_16x16x32_bf16 v[80:83], v[182:185], v[210:213], v[80:83]
	v_mfma_f32_16x16x32_bf16 v[68:71], v[174:177], v[218:221], v[68:71]
	v_mfma_f32_16x16x32_bf16 v[64:67], v[182:185], v[218:221], v[64:67]
	s_setprio 0
	s_barrier
	s_add_i32 s64, s54, s40
	s_mov_b32 m0, s64
	ds_read_b128 v[190:193], v151 offset:16384
	ds_read_b128 v[194:197], v151 offset:17408
	ds_read_b128 v[198:201], v151 offset:18432
	ds_read_b128 v[202:205], v151 offset:19456
	global_load_lds_dwordx4 v134, s[62:63]
	s_add_i32 m0, s64, 0x2000
	s_mov_b64 s[100:101], s[62:63]
	s_add_i32 s64, s55, s40
	global_load_lds_dwordx4 v132, s[62:63]
	s_add_u32 s62, s62, s10
	s_addc_u32 s63, s63, s11
	s_mov_b32 m0, s64
	ds_read_b128 v[218:221], v151 offset:23552
	global_load_lds_dwordx4 v134, s[62:63]
	s_add_i32 m0, s64, 0x2000
	ds_read_b128 v[214:217], v151 offset:22528
	global_load_lds_dwordx4 v132, s[62:63]
	s_mov_b32 m0, s41
	ds_read_b128 v[210:213], v151 offset:21504
	global_load_lds_dwordx4 v130, s[30:31]
	s_mov_b32 m0, s42
	ds_read_b128 v[206:209], v151 offset:20480
	global_load_lds_dwordx4 v128, s[30:31]
	s_waitcnt vmcnt(8)
	s_waitcnt lgkmcnt(0)
	s_barrier
	s_setprio 1
	v_mfma_f32_16x16x32_bf16 v[60:63], v[154:157], v[190:193], v[60:63]
	v_mfma_f32_16x16x32_bf16 v[56:59], v[162:165], v[190:193], v[56:59]
	v_mfma_f32_16x16x32_bf16 v[44:47], v[154:157], v[198:201], v[44:47]
	v_mfma_f32_16x16x32_bf16 v[40:43], v[162:165], v[198:201], v[40:43]
	v_mfma_f32_16x16x32_bf16 v[28:31], v[154:157], v[206:209], v[28:31]
	v_mfma_f32_16x16x32_bf16 v[24:27], v[162:165], v[206:209], v[24:27]
	v_mfma_f32_16x16x32_bf16 v[12:15], v[154:157], v[214:217], v[12:15]
	v_mfma_f32_16x16x32_bf16 v[8:11], v[162:165], v[214:217], v[8:11]
	v_mfma_f32_16x16x32_bf16 v[60:63], v[158:161], v[194:197], v[60:63]
	v_mfma_f32_16x16x32_bf16 v[56:59], v[166:169], v[194:197], v[56:59]
	v_mfma_f32_16x16x32_bf16 v[44:47], v[158:161], v[202:205], v[44:47]
	v_mfma_f32_16x16x32_bf16 v[40:43], v[166:169], v[202:205], v[40:43]
	v_mfma_f32_16x16x32_bf16 v[28:31], v[158:161], v[210:213], v[28:31]
	v_mfma_f32_16x16x32_bf16 v[24:27], v[166:169], v[210:213], v[24:27]
	v_mfma_f32_16x16x32_bf16 v[12:15], v[158:161], v[218:221], v[12:15]
	v_mfma_f32_16x16x32_bf16 v[8:11], v[166:169], v[218:221], v[8:11]
	v_mfma_f32_16x16x32_bf16 v[52:55], v[170:173], v[190:193], v[52:55]
	v_mfma_f32_16x16x32_bf16 v[48:51], v[178:181], v[190:193], v[48:51]
	v_mfma_f32_16x16x32_bf16 v[36:39], v[170:173], v[198:201], v[36:39]
	v_mfma_f32_16x16x32_bf16 v[32:35], v[178:181], v[198:201], v[32:35]
	v_mfma_f32_16x16x32_bf16 v[20:23], v[170:173], v[206:209], v[20:23]
	v_mfma_f32_16x16x32_bf16 v[16:19], v[178:181], v[206:209], v[16:19]
	v_mfma_f32_16x16x32_bf16 v[4:7], v[170:173], v[214:217], v[4:7]
	v_mfma_f32_16x16x32_bf16 v[0:3], v[178:181], v[214:217], v[0:3]
	v_mfma_f32_16x16x32_bf16 v[52:55], v[174:177], v[194:197], v[52:55]
	v_mfma_f32_16x16x32_bf16 v[48:51], v[182:185], v[194:197], v[48:51]
	v_mfma_f32_16x16x32_bf16 v[36:39], v[174:177], v[202:205], v[36:39]
	v_mfma_f32_16x16x32_bf16 v[32:35], v[182:185], v[202:205], v[32:35]
	v_mfma_f32_16x16x32_bf16 v[20:23], v[174:177], v[210:213], v[20:23]
	v_mfma_f32_16x16x32_bf16 v[16:19], v[182:185], v[210:213], v[16:19]
	v_mfma_f32_16x16x32_bf16 v[4:7], v[174:177], v[218:221], v[4:7]
	v_mfma_f32_16x16x32_bf16 v[0:3], v[182:185], v[218:221], v[0:3]
	s_setprio 0
	s_barrier
; #define PG8_STAGE(bufoff, gbase, voff) do { _Pragma("unroll") for (int _i = 0; _i < 2; ++_i) \
;         __builtin_amdgcn_global_load_lds((const unsigned*)((const char*)(gbase) + (voff)[_i]), (PG8_LAS unsigned*)(lds + (bufoff) + ldsw + _i * 8192), 16, 0, 0); } while (0)
; #define PG8_LDA(dst, b, h) do { _Pragma("unroll") for (int m = 0; m < 4; ++m) _Pragma("unroll") for (int k = 0; k < 2; ++k) dst[m][k] = *(const PG8_LAS bf16x8*)(lds + PG8_SA(b, h) + aoff + m * 2048 + k * 1024); } while (0)
; #define PG8_LDB(dst, b, h) do { _Pragma("unroll") for (int n = 0; n < 2; ++n) _Pragma("unroll") for (int k = 0; k < 2; ++k) dst[n][k] = *(const PG8_LAS bf16x8*)(lds + PG8_SB(b, h) + boff + n * 2048 + k * 1024); } while (0)
; #define PG8_MMA(ai, bj, At, Bt) do { __builtin_amdgcn_s_setprio(1); _Pragma("unroll") for (int m = 0; m < 4; ++m) _Pragma("unroll") for (int n = 0; n < 2; ++n) _Pragma("unroll") for (int k = 0; k < 2; ++k) \
;         acc[ai][bj][m][n] = __builtin_amdgcn_mfma_f32_16x16x32_bf16(Bt[n][k], At[m][k], acc[ai][bj][m][n], 0, 0, 0); __builtin_amdgcn_s_setprio(0); } while (0)
; #define PG8_WAIT_V(n) asm volatile("s_waitcnt vmcnt(" #n ")" ::: "memory")
; #define PG8_WAIT_L(n) asm volatile("s_waitcnt lgkmcnt(" #n ")" ::: "memory")
; #define PG8_BAR __builtin_amdgcn_s_barrier()
; template <class Epi, class Sched, bool ALIGN_EPI = false, bool SP2 = false>
; __device__ __forceinline__ void gemm_phase(PG8_LAS unsigned char* lds, const Gemm g, const Sched& S, const Epi& E) {
;     ...
;         for (int t = 0; t < nt; t += 2) {
;             const bool last = (t == nt - 2);
;             const char* a1 = cA + (size_t)(t + 1) * kstep;
;             const char* a2 = last ? nA : cA + (size_t)(t + 2) * kstep; const char* b2 = last ? nB : cB + (size_t)(t + 2) * kstep;
;             const char* a3 = a2 + kstep; const char* b3 = b2 + kstep;
;     ...
;             PG8_LDB(B0, 1, 0); PG8_LDB(B1, 1, 1); PG8_SCHED; PG8_LDA(At, 1, 0); PG8_STAGE(PG8_SA(0, 1), a2 + hstepA, voffA);
;             PG8_WAIT_V(8); PG8_WAIT_L(0); PG8_BAR; PG8_MMA(0, 0, At, B0); PG8_MMA(0, 1, At, B1); PG8_BAR; PG8_SCHED;
;             PG8_LDA(At, 1, 1); PG8_STAGE(PG8_SB(1, 0), b3, voffB); PG8_STAGE(PG8_SB(1, 1), b3 + hstep, voffB); PG8_STAGE(PG8_SA(1, 0), a3, voffA);
;             PG8_WAIT_V(8); PG8_WAIT_L(0); PG8_BAR; PG8_MMA(1, 0, At, B0); PG8_MMA(1, 1, At, B1); PG8_BAR; PG8_SCHED;
	s_add_i32 s62, 0, 0x18000
	s_add_i32 s63, 0, 0x1c000
	v_add_u32_e32 v166, s62, v147
	v_add_u32_e32 v182, s63, v147
	ds_read_b128 v[154:157], v166
	ds_read_b128 v[158:161], v166 offset:1024
	ds_read_b128 v[162:165], v166 offset:2048
	ds_read_b128 v[166:169], v166 offset:3072
	ds_read_b128 v[170:173], v182
	ds_read_b128 v[174:177], v182 offset:1024
	ds_read_b128 v[178:181], v182 offset:2048
	ds_read_b128 v[182:185], v182 offset:3072
	s_mov_b64 vcc, s[30:31]
	s_add_u32 s30, s30, 0x20000
	s_addc_u32 s31, s31, 0
	s_mov_b32 m0, s43
	ds_read_b128 v[190:193], v151 offset:32768
	ds_read_b128 v[194:197], v151 offset:33792
	ds_read_b128 v[198:201], v151 offset:34816
	ds_read_b128 v[202:205], v151 offset:35840
	ds_read_b128 v[206:209], v151 offset:36864
	ds_read_b128 v[210:213], v151 offset:37888
	ds_read_b128 v[214:217], v151 offset:38912
	global_load_lds_dwordx4 v130, s[30:31]
	s_mov_b32 m0, s44
	ds_read_b128 v[218:221], v151 offset:39936
	global_load_lds_dwordx4 v128, s[30:31]
	s_waitcnt vmcnt(8)
	s_waitcnt lgkmcnt(0)
	s_barrier
	s_setprio 1
	v_mfma_f32_16x16x32_bf16 v[124:127], v[154:157], v[190:193], v[124:127]
	v_mfma_f32_16x16x32_bf16 v[120:123], v[162:165], v[190:193], v[120:123]
	v_mfma_f32_16x16x32_bf16 v[108:111], v[154:157], v[198:201], v[108:111]
	v_mfma_f32_16x16x32_bf16 v[104:107], v[162:165], v[198:201], v[104:107]
	v_mfma_f32_16x16x32_bf16 v[92:95], v[154:157], v[206:209], v[92:95]
	v_mfma_f32_16x16x32_bf16 v[88:91], v[162:165], v[206:209], v[88:91]
	v_mfma_f32_16x16x32_bf16 v[76:79], v[154:157], v[214:217], v[76:79]
	v_mfma_f32_16x16x32_bf16 v[72:75], v[162:165], v[214:217], v[72:75]
	v_mfma_f32_16x16x32_bf16 v[124:127], v[158:161], v[194:197], v[124:127]
	v_mfma_f32_16x16x32_bf16 v[120:123], v[166:169], v[194:197], v[120:123]
	v_mfma_f32_16x16x32_bf16 v[108:111], v[158:161], v[202:205], v[108:111]
	v_mfma_f32_16x16x32_bf16 v[104:107], v[166:169], v[202:205], v[104:107]
	v_mfma_f32_16x16x32_bf16 v[92:95], v[158:161], v[210:213], v[92:95]
	v_mfma_f32_16x16x32_bf16 v[88:91], v[166:169], v[210:213], v[88:91]
	v_mfma_f32_16x16x32_bf16 v[76:79], v[158:161], v[218:221], v[76:79]
	v_mfma_f32_16x16x32_bf16 v[72:75], v[166:169], v[218:221], v[72:75]
	v_mfma_f32_16x16x32_bf16 v[116:119], v[170:173], v[190:193], v[116:119]
	v_mfma_f32_16x16x32_bf16 v[112:115], v[178:181], v[190:193], v[112:115]
	v_mfma_f32_16x16x32_bf16 v[100:103], v[170:173], v[198:201], v[100:103]
	v_mfma_f32_16x16x32_bf16 v[96:99], v[178:181], v[198:201], v[96:99]
	v_mfma_f32_16x16x32_bf16 v[84:87], v[170:173], v[206:209], v[84:87]
	v_mfma_f32_16x16x32_bf16 v[80:83], v[178:181], v[206:209], v[80:83]
	v_mfma_f32_16x16x32_bf16 v[68:71], v[170:173], v[214:217], v[68:71]
	v_mfma_f32_16x16x32_bf16 v[64:67], v[178:181], v[214:217], v[64:67]
	v_mfma_f32_16x16x32_bf16 v[116:119], v[174:177], v[194:197], v[116:119]
	v_mfma_f32_16x16x32_bf16 v[112:115], v[182:185], v[194:197], v[112:115]
	v_mfma_f32_16x16x32_bf16 v[100:103], v[174:177], v[202:205], v[100:103]
	v_mfma_f32_16x16x32_bf16 v[96:99], v[182:185], v[202:205], v[96:99]
	v_mfma_f32_16x16x32_bf16 v[84:87], v[174:177], v[210:213], v[84:87]
	v_mfma_f32_16x16x32_bf16 v[80:83], v[182:185], v[210:213], v[80:83]
	v_mfma_f32_16x16x32_bf16 v[68:71], v[174:177], v[218:221], v[68:71]
	v_mfma_f32_16x16x32_bf16 v[64:67], v[182:185], v[218:221], v[64:67]
	s_setprio 0
	s_barrier
	s_add_i32 s30, s62, s40
	s_add_i32 m0, s30, 0xffffff80
	ds_read_b128 v[190:193], v151 offset:49152
	ds_read_b128 v[194:197], v151 offset:50176
	ds_read_b128 v[198:201], v151 offset:51200
	ds_read_b128 v[202:205], v151 offset:52224
	global_load_lds_dwordx4 v134, s[100:101] offset:128
	s_add_i32 m0, s30, 0x1f80
	s_add_i32 s30, s63, s40
	global_load_lds_dwordx4 v132, s[100:101] offset:128
	s_add_u32 s100, s100, s10
	s_addc_u32 s101, s101, s11
	s_add_i32 m0, s30, 0xffffff80
	ds_read_b128 v[218:221], v151 offset:56320
	global_load_lds_dwordx4 v134, s[100:101] offset:128
	s_add_i32 m0, s30, 0x1f80
	ds_read_b128 v[214:217], v151 offset:55296
	global_load_lds_dwordx4 v132, s[100:101] offset:128
	s_add_i32 m0, s48, 0xffffff80
	ds_read_b128 v[210:213], v151 offset:54272
	global_load_lds_dwordx4 v130, vcc offset:128
	s_add_i32 m0, s49, 0xffffff80
	ds_read_b128 v[206:209], v151 offset:53248
	global_load_lds_dwordx4 v128, vcc offset:128
	s_waitcnt vmcnt(8)
	s_waitcnt lgkmcnt(0)
	s_barrier
	s_setprio 1
	v_mfma_f32_16x16x32_bf16 v[60:63], v[154:157], v[190:193], v[60:63]
	v_mfma_f32_16x16x32_bf16 v[56:59], v[162:165], v[190:193], v[56:59]
	v_mfma_f32_16x16x32_bf16 v[44:47], v[154:157], v[198:201], v[44:47]
	v_mfma_f32_16x16x32_bf16 v[40:43], v[162:165], v[198:201], v[40:43]
	v_mfma_f32_16x16x32_bf16 v[28:31], v[154:157], v[206:209], v[28:31]
	v_mfma_f32_16x16x32_bf16 v[24:27], v[162:165], v[206:209], v[24:27]
	v_mfma_f32_16x16x32_bf16 v[12:15], v[154:157], v[214:217], v[12:15]
	v_mfma_f32_16x16x32_bf16 v[8:11], v[162:165], v[214:217], v[8:11]
	v_mfma_f32_16x16x32_bf16 v[60:63], v[158:161], v[194:197], v[60:63]
	v_mfma_f32_16x16x32_bf16 v[56:59], v[166:169], v[194:197], v[56:59]
	v_mfma_f32_16x16x32_bf16 v[44:47], v[158:161], v[202:205], v[44:47]
	v_mfma_f32_16x16x32_bf16 v[40:43], v[166:169], v[202:205], v[40:43]
	v_mfma_f32_16x16x32_bf16 v[28:31], v[158:161], v[210:213], v[28:31]
	v_mfma_f32_16x16x32_bf16 v[24:27], v[166:169], v[210:213], v[24:27]
	v_mfma_f32_16x16x32_bf16 v[12:15], v[158:161], v[218:221], v[12:15]
	v_mfma_f32_16x16x32_bf16 v[8:11], v[166:169], v[218:221], v[8:11]
	v_mfma_f32_16x16x32_bf16 v[52:55], v[170:173], v[190:193], v[52:55]
	v_mfma_f32_16x16x32_bf16 v[48:51], v[178:181], v[190:193], v[48:51]
	v_mfma_f32_16x16x32_bf16 v[36:39], v[170:173], v[198:201], v[36:39]
	v_mfma_f32_16x16x32_bf16 v[32:35], v[178:181], v[198:201], v[32:35]
	v_mfma_f32_16x16x32_bf16 v[20:23], v[170:173], v[206:209], v[20:23]
	v_mfma_f32_16x16x32_bf16 v[16:19], v[178:181], v[206:209], v[16:19]
	v_mfma_f32_16x16x32_bf16 v[4:7], v[170:173], v[214:217], v[4:7]
	v_mfma_f32_16x16x32_bf16 v[0:3], v[178:181], v[214:217], v[0:3]
	v_mfma_f32_16x16x32_bf16 v[52:55], v[174:177], v[194:197], v[52:55]
	v_mfma_f32_16x16x32_bf16 v[48:51], v[182:185], v[194:197], v[48:51]
	v_mfma_f32_16x16x32_bf16 v[36:39], v[174:177], v[202:205], v[36:39]
	v_mfma_f32_16x16x32_bf16 v[32:35], v[182:185], v[202:205], v[32:35]
	v_mfma_f32_16x16x32_bf16 v[20:23], v[174:177], v[210:213], v[20:23]
	v_mfma_f32_16x16x32_bf16 v[16:19], v[182:185], v[210:213], v[16:19]
	v_mfma_f32_16x16x32_bf16 v[4:7], v[174:177], v[218:221], v[4:7]
	v_mfma_f32_16x16x32_bf16 v[0:3], v[182:185], v[218:221], v[0:3]
	s_setprio 0
	s_barrier
	s_add_u32 s4, s4, 0x100
	s_addc_u32 s5, s5, 0
	s_add_u32 s59, s59, 0x100
	s_addc_u32 s60, s60, 0
	s_cmp_ge_i32 s61, s51
	s_mov_b32 s30, s61
	s_cbranch_scc0 .LBB0_523

; #define PG8_STAGE(bufoff, gbase, voff) do { _Pragma("unroll") for (int _i = 0; _i < 2; ++_i) \
;         __builtin_amdgcn_global_load_lds((const unsigned*)((const char*)(gbase) + (voff)[_i]), (PG8_LAS unsigned*)(lds + (bufoff) + ldsw + _i * 8192), 16, 0, 0); } while (0)
; #define PG8_LDA(dst, b, h) do { _Pragma("unroll") for (int m = 0; m < 4; ++m) _Pragma("unroll") for (int k = 0; k < 2; ++k) dst[m][k] = *(const PG8_LAS bf16x8*)(lds + PG8_SA(b, h) + aoff + m * 2048 + k * 1024); } while (0)
; #define PG8_LDB(dst, b, h) do { _Pragma("unroll") for (int n = 0; n < 2; ++n) _Pragma("unroll") for (int k = 0; k < 2; ++k) dst[n][k] = *(const PG8_LAS bf16x8*)(lds + PG8_SB(b, h) + boff + n * 2048 + k * 1024); } while (0)
; #define PG8_MMA(ai, bj, At, Bt) do { __builtin_amdgcn_s_setprio(1); _Pragma("unroll") for (int m = 0; m < 4; ++m) _Pragma("unroll") for (int n = 0; n < 2; ++n) _Pragma("unroll") for (int k = 0; k < 2; ++k) \
;         acc[ai][bj][m][n] = __builtin_amdgcn_mfma_f32_16x16x32_bf16(Bt[n][k], At[m][k], acc[ai][bj][m][n], 0, 0, 0); __builtin_amdgcn_s_setprio(0); } while (0)
; #define PG8_WAIT_V(n) asm volatile("s_waitcnt vmcnt(" #n ")" ::: "memory")
; #define PG8_BAR __builtin_amdgcn_s_barrier()
; template <class Epi, class Sched, bool ALIGN_EPI = false, bool SP2 = false>
; __device__ __forceinline__ void gemm_phase(PG8_LAS unsigned char* lds, const Gemm g, const Sched& S, const Epi& E) {
;     ...
;         for (int t = 0; t < nt; t += 2) {
;             const bool last = (t == nt - 2);
;             const char* a1 = cA + (size_t)(t + 1) * kstep;
;             const char* a2 = last ? nA : cA + (size_t)(t + 2) * kstep; const char* b2 = last ? nB : cB + (size_t)(t + 2) * kstep;
;             const char* a3 = a2 + kstep; const char* b3 = b2 + kstep;
;             if (last && has_next) S.a_ready(nxt);
;             if constexpr (SP2) {
;             PG8_LDB(B0, 0, 0); PG8_LDB(B1, 0, 1); PG8_SCHED; PG8_LDA(At, 0, 0); PG8_STAGE(PG8_SA(1, 1), a1 + hstepA, voffA);
;             PG8_WAIT_V(8); PG8_WAIT_L(0); PG8_BAR; PG8_MMA(0, 0, At, B0); PG8_MMA(0, 1, At, B1); PG8_BAR; PG8_SCHED;
;             PG8_LDA(At, 0, 1); PG8_STAGE(PG8_SB(0, 0), b2, voffB); PG8_STAGE(PG8_SB(0, 1), b2 + hstep, voffB); PG8_STAGE(PG8_SA(0, 0), a2, voffA);
;             PG8_WAIT_V(8); PG8_WAIT_L(0); PG8_BAR; PG8_MMA(1, 0, At, B0); PG8_MMA(1, 1, At, B1); PG8_BAR; PG8_SCHED;
.LBB0_601:
	ds_read_b128 v[150:153], v147
	ds_read_b128 v[154:157], v147 offset:1024
	ds_read_b128 v[158:161], v147 offset:2048
	ds_read_b128 v[162:165], v147 offset:3072
	ds_read_b128 v[166:169], v148
	ds_read_b128 v[170:173], v148 offset:1024
	ds_read_b128 v[174:177], v148 offset:2048
	ds_read_b128 v[178:181], v148 offset:3072
	s_add_i32 s60, s30, 2
	s_add_u32 s61, s10, 0xfffc0080
	s_addc_u32 s31, s11, -1
	s_cmp_eq_u32 s51, s30
	s_cselect_b32 s30, s59, s61
	s_cselect_b32 s31, s23, s31
	s_cselect_b32 s63, s25, s35
	s_cselect_b32 s62, s24, s34
	s_add_i32 m0, s29, 0xc000
	ds_read_b128 v[182:185], v149
	ds_read_b128 v[190:193], v149 offset:1024
	ds_read_b128 v[194:197], v149 offset:2048
	ds_read_b128 v[198:201], v149 offset:3072
	ds_read_b128 v[202:205], v149 offset:4096
	ds_read_b128 v[206:209], v149 offset:5120
	ds_read_b128 v[210:213], v149 offset:6144
	global_load_lds_dwordx4 v136, s[10:11]
	s_add_i32 m0, s29, 0xe000
	ds_read_b128 v[214:217], v149 offset:7168
	global_load_lds_dwordx4 v138, s[10:11]
	s_waitcnt vmcnt(8)
	s_waitcnt lgkmcnt(0)
	s_barrier
	s_setprio 1
	v_mfma_f32_16x16x32_bf16 v[120:123], v[150:153], v[182:185], v[120:123]
	v_mfma_f32_16x16x32_bf16 v[112:115], v[158:161], v[182:185], v[112:115]
	v_mfma_f32_16x16x32_bf16 v[104:107], v[150:153], v[194:197], v[104:107]
	v_mfma_f32_16x16x32_bf16 v[96:99], v[158:161], v[194:197], v[96:99]
	v_mfma_f32_16x16x32_bf16 v[88:91], v[150:153], v[202:205], v[88:91]
	v_mfma_f32_16x16x32_bf16 v[80:83], v[158:161], v[202:205], v[80:83]
	v_mfma_f32_16x16x32_bf16 v[72:75], v[150:153], v[210:213], v[72:75]
	v_mfma_f32_16x16x32_bf16 v[64:67], v[158:161], v[210:213], v[64:67]
	v_mfma_f32_16x16x32_bf16 v[120:123], v[154:157], v[190:193], v[120:123]
	v_mfma_f32_16x16x32_bf16 v[112:115], v[162:165], v[190:193], v[112:115]
	v_mfma_f32_16x16x32_bf16 v[104:107], v[154:157], v[198:201], v[104:107]
	v_mfma_f32_16x16x32_bf16 v[96:99], v[162:165], v[198:201], v[96:99]
	v_mfma_f32_16x16x32_bf16 v[88:91], v[154:157], v[206:209], v[88:91]
	v_mfma_f32_16x16x32_bf16 v[80:83], v[162:165], v[206:209], v[80:83]
	v_mfma_f32_16x16x32_bf16 v[72:75], v[154:157], v[214:217], v[72:75]
	v_mfma_f32_16x16x32_bf16 v[64:67], v[162:165], v[214:217], v[64:67]
	v_mfma_f32_16x16x32_bf16 v[124:127], v[166:169], v[182:185], v[124:127]
	v_mfma_f32_16x16x32_bf16 v[116:119], v[174:177], v[182:185], v[116:119]
	v_mfma_f32_16x16x32_bf16 v[108:111], v[166:169], v[194:197], v[108:111]
	v_mfma_f32_16x16x32_bf16 v[100:103], v[174:177], v[194:197], v[100:103]
	v_mfma_f32_16x16x32_bf16 v[92:95], v[166:169], v[202:205], v[92:95]
	v_mfma_f32_16x16x32_bf16 v[84:87], v[174:177], v[202:205], v[84:87]
	v_mfma_f32_16x16x32_bf16 v[76:79], v[166:169], v[210:213], v[76:79]
	v_mfma_f32_16x16x32_bf16 v[68:71], v[174:177], v[210:213], v[68:71]
	v_mfma_f32_16x16x32_bf16 v[124:127], v[170:173], v[190:193], v[124:127]
	v_mfma_f32_16x16x32_bf16 v[116:119], v[178:181], v[190:193], v[116:119]
	v_mfma_f32_16x16x32_bf16 v[108:111], v[170:173], v[198:201], v[108:111]
	v_mfma_f32_16x16x32_bf16 v[100:103], v[178:181], v[198:201], v[100:103]
	v_mfma_f32_16x16x32_bf16 v[92:95], v[170:173], v[206:209], v[92:95]
	v_mfma_f32_16x16x32_bf16 v[84:87], v[178:181], v[206:209], v[84:87]
	v_mfma_f32_16x16x32_bf16 v[76:79], v[170:173], v[214:217], v[76:79]
	v_mfma_f32_16x16x32_bf16 v[68:71], v[178:181], v[214:217], v[68:71]
	s_setprio 0
	s_barrier
	s_add_i32 s61, s52, s38
	s_mov_b32 m0, s61
	ds_read_b128 v[182:185], v149 offset:16384
	ds_read_b128 v[190:193], v149 offset:17408
	ds_read_b128 v[194:197], v149 offset:18432
	ds_read_b128 v[198:201], v149 offset:19456
	global_load_lds_dwordx4 v134, s[62:63]
	s_add_i32 m0, s61, 0x2000
	s_mov_b64 s[100:101], s[62:63]
	s_add_i32 s61, s53, s38
	global_load_lds_dwordx4 v132, s[62:63]
	s_add_u32 s62, s62, s4
	s_addc_u32 s63, s63, s5
	s_mov_b32 m0, s61
	ds_read_b128 v[214:217], v149 offset:23552
	global_load_lds_dwordx4 v134, s[62:63]
	s_add_i32 m0, s61, 0x2000
	ds_read_b128 v[210:213], v149 offset:22528
	global_load_lds_dwordx4 v132, s[62:63]
	s_mov_b32 m0, s29
	ds_read_b128 v[206:209], v149 offset:21504
	global_load_lds_dwordx4 v128, s[30:31]
	s_mov_b32 m0, s41
	ds_read_b128 v[202:205], v149 offset:20480
	global_load_lds_dwordx4 v130, s[30:31]
	s_waitcnt vmcnt(8)
	s_waitcnt lgkmcnt(0)
	s_barrier
	s_setprio 1
	v_mfma_f32_16x16x32_bf16 v[56:59], v[150:153], v[182:185], v[56:59]
	v_mfma_f32_16x16x32_bf16 v[48:51], v[158:161], v[182:185], v[48:51]
	v_mfma_f32_16x16x32_bf16 v[40:43], v[150:153], v[194:197], v[40:43]
	v_mfma_f32_16x16x32_bf16 v[32:35], v[158:161], v[194:197], v[32:35]
	v_mfma_f32_16x16x32_bf16 v[24:27], v[150:153], v[202:205], v[24:27]
	v_mfma_f32_16x16x32_bf16 v[16:19], v[158:161], v[202:205], v[16:19]
	v_mfma_f32_16x16x32_bf16 v[8:11], v[150:153], v[210:213], v[8:11]
	v_mfma_f32_16x16x32_bf16 v[0:3], v[158:161], v[210:213], v[0:3]
	v_mfma_f32_16x16x32_bf16 v[56:59], v[154:157], v[190:193], v[56:59]
	v_mfma_f32_16x16x32_bf16 v[48:51], v[162:165], v[190:193], v[48:51]
	v_mfma_f32_16x16x32_bf16 v[40:43], v[154:157], v[198:201], v[40:43]
	v_mfma_f32_16x16x32_bf16 v[32:35], v[162:165], v[198:201], v[32:35]
	v_mfma_f32_16x16x32_bf16 v[24:27], v[154:157], v[206:209], v[24:27]
	v_mfma_f32_16x16x32_bf16 v[16:19], v[162:165], v[206:209], v[16:19]
	v_mfma_f32_16x16x32_bf16 v[8:11], v[154:157], v[214:217], v[8:11]
	v_mfma_f32_16x16x32_bf16 v[0:3], v[162:165], v[214:217], v[0:3]
	v_mfma_f32_16x16x32_bf16 v[60:63], v[166:169], v[182:185], v[60:63]
	v_mfma_f32_16x16x32_bf16 v[52:55], v[174:177], v[182:185], v[52:55]
	v_mfma_f32_16x16x32_bf16 v[44:47], v[166:169], v[194:197], v[44:47]
	v_mfma_f32_16x16x32_bf16 v[36:39], v[174:177], v[194:197], v[36:39]
	v_mfma_f32_16x16x32_bf16 v[28:31], v[166:169], v[202:205], v[28:31]
	v_mfma_f32_16x16x32_bf16 v[20:23], v[174:177], v[202:205], v[20:23]
	v_mfma_f32_16x16x32_bf16 v[12:15], v[166:169], v[210:213], v[12:15]
	v_mfma_f32_16x16x32_bf16 v[4:7], v[174:177], v[210:213], v[4:7]
	v_mfma_f32_16x16x32_bf16 v[60:63], v[170:173], v[190:193], v[60:63]
	v_mfma_f32_16x16x32_bf16 v[52:55], v[178:181], v[190:193], v[52:55]
	v_mfma_f32_16x16x32_bf16 v[44:47], v[170:173], v[198:201], v[44:47]
	v_mfma_f32_16x16x32_bf16 v[36:39], v[178:181], v[198:201], v[36:39]
	v_mfma_f32_16x16x32_bf16 v[28:31], v[170:173], v[206:209], v[28:31]
	v_mfma_f32_16x16x32_bf16 v[20:23], v[178:181], v[206:209], v[20:23]
	v_mfma_f32_16x16x32_bf16 v[12:15], v[170:173], v[214:217], v[12:15]
	v_mfma_f32_16x16x32_bf16 v[4:7], v[178:181], v[214:217], v[4:7]
	s_setprio 0
	s_barrier
; #define PG8_STAGE(bufoff, gbase, voff) do { _Pragma("unroll") for (int _i = 0; _i < 2; ++_i) \
;         __builtin_amdgcn_global_load_lds((const unsigned*)((const char*)(gbase) + (voff)[_i]), (PG8_LAS unsigned*)(lds + (bufoff) + ldsw + _i * 8192), 16, 0, 0); } while (0)
; #define PG8_LDA(dst, b, h) do { _Pragma("unroll") for (int m = 0; m < 4; ++m) _Pragma("unroll") for (int k = 0; k < 2; ++k) dst[m][k] = *(const PG8_LAS bf16x8*)(lds + PG8_SA(b, h) + aoff + m * 2048 + k * 1024); } while (0)
; #define PG8_LDB(dst, b, h) do { _Pragma("unroll") for (int n = 0; n < 2; ++n) _Pragma("unroll") for (int k = 0; k < 2; ++k) dst[n][k] = *(const PG8_LAS bf16x8*)(lds + PG8_SB(b, h) + boff + n * 2048 + k * 1024); } while (0)
; #define PG8_MMA(ai, bj, At, Bt) do { __builtin_amdgcn_s_setprio(1); _Pragma("unroll") for (int m = 0; m < 4; ++m) _Pragma("unroll") for (int n = 0; n < 2; ++n) _Pragma("unroll") for (int k = 0; k < 2; ++k) \
;         acc[ai][bj][m][n] = __builtin_amdgcn_mfma_f32_16x16x32_bf16(Bt[n][k], At[m][k], acc[ai][bj][m][n], 0, 0, 0); __builtin_amdgcn_s_setprio(0); } while (0)
; #define PG8_WAIT_V(n) asm volatile("s_waitcnt vmcnt(" #n ")" ::: "memory")
; #define PG8_WAIT_L(n) asm volatile("s_waitcnt lgkmcnt(" #n ")" ::: "memory")
; #define PG8_BAR __builtin_amdgcn_s_barrier()
; template <class Epi, class Sched, bool ALIGN_EPI = false, bool SP2 = false>
; __device__ __forceinline__ void gemm_phase(PG8_LAS unsigned char* lds, const Gemm g, const Sched& S, const Epi& E) {
;     ...
;         for (int t = 0; t < nt; t += 2) {
;             const bool last = (t == nt - 2);
;             const char* a1 = cA + (size_t)(t + 1) * kstep;
;             const char* a2 = last ? nA : cA + (size_t)(t + 2) * kstep; const char* b2 = last ? nB : cB + (size_t)(t + 2) * kstep;
;             const char* a3 = a2 + kstep; const char* b3 = b2 + kstep;
;     ...
;             PG8_LDB(B0, 1, 0); PG8_LDB(B1, 1, 1); PG8_SCHED; PG8_LDA(At, 1, 0); PG8_STAGE(PG8_SA(0, 1), a2 + hstepA, voffA);
;             PG8_WAIT_V(8); PG8_WAIT_L(0); PG8_BAR; PG8_MMA(0, 0, At, B0); PG8_MMA(0, 1, At, B1); PG8_BAR; PG8_SCHED;
;             PG8_LDA(At, 1, 1); PG8_STAGE(PG8_SB(1, 0), b3, voffB); PG8_STAGE(PG8_SB(1, 1), b3 + hstep, voffB); PG8_STAGE(PG8_SA(1, 0), a3, voffA);
;             PG8_WAIT_V(8); PG8_WAIT_L(0); PG8_BAR; PG8_MMA(1, 0, At, B0); PG8_MMA(1, 1, At, B1); PG8_BAR; PG8_SCHED;
	s_add_i32 s61, 0, 0x18000
	s_add_i32 s62, 0, 0x1c000
	v_add_u32_e32 v162, s61, v145
	v_add_u32_e32 v178, s62, v145
	ds_read_b128 v[150:153], v162
	ds_read_b128 v[154:157], v162 offset:1024
	ds_read_b128 v[158:161], v162 offset:2048
	ds_read_b128 v[162:165], v162 offset:3072
	ds_read_b128 v[166:169], v178
	ds_read_b128 v[170:173], v178 offset:1024
	ds_read_b128 v[174:177], v178 offset:2048
	ds_read_b128 v[178:181], v178 offset:3072
	s_mov_b64 vcc, s[30:31]
	s_add_u32 s30, s30, 0x40000
	s_addc_u32 s31, s31, 0
	s_mov_b32 m0, s42
	ds_read_b128 v[182:185], v149 offset:32768
	ds_read_b128 v[190:193], v149 offset:33792
	ds_read_b128 v[194:197], v149 offset:34816
	ds_read_b128 v[198:201], v149 offset:35840
	ds_read_b128 v[202:205], v149 offset:36864
	ds_read_b128 v[206:209], v149 offset:37888
	ds_read_b128 v[210:213], v149 offset:38912
	global_load_lds_dwordx4 v128, s[30:31]
	s_mov_b32 m0, s43
	ds_read_b128 v[214:217], v149 offset:39936
	global_load_lds_dwordx4 v130, s[30:31]
	s_waitcnt vmcnt(8)
	s_waitcnt lgkmcnt(0)
	s_barrier
	s_setprio 1
	v_mfma_f32_16x16x32_bf16 v[120:123], v[150:153], v[182:185], v[120:123]
	v_mfma_f32_16x16x32_bf16 v[112:115], v[158:161], v[182:185], v[112:115]
	v_mfma_f32_16x16x32_bf16 v[104:107], v[150:153], v[194:197], v[104:107]
	v_mfma_f32_16x16x32_bf16 v[96:99], v[158:161], v[194:197], v[96:99]
	v_mfma_f32_16x16x32_bf16 v[88:91], v[150:153], v[202:205], v[88:91]
	v_mfma_f32_16x16x32_bf16 v[80:83], v[158:161], v[202:205], v[80:83]
	v_mfma_f32_16x16x32_bf16 v[72:75], v[150:153], v[210:213], v[72:75]
	v_mfma_f32_16x16x32_bf16 v[64:67], v[158:161], v[210:213], v[64:67]
	v_mfma_f32_16x16x32_bf16 v[120:123], v[154:157], v[190:193], v[120:123]
	v_mfma_f32_16x16x32_bf16 v[112:115], v[162:165], v[190:193], v[112:115]
	v_mfma_f32_16x16x32_bf16 v[104:107], v[154:157], v[198:201], v[104:107]
	v_mfma_f32_16x16x32_bf16 v[96:99], v[162:165], v[198:201], v[96:99]
	v_mfma_f32_16x16x32_bf16 v[88:91], v[154:157], v[206:209], v[88:91]
	v_mfma_f32_16x16x32_bf16 v[80:83], v[162:165], v[206:209], v[80:83]
	v_mfma_f32_16x16x32_bf16 v[72:75], v[154:157], v[214:217], v[72:75]
	v_mfma_f32_16x16x32_bf16 v[64:67], v[162:165], v[214:217], v[64:67]
	v_mfma_f32_16x16x32_bf16 v[124:127], v[166:169], v[182:185], v[124:127]
	v_mfma_f32_16x16x32_bf16 v[116:119], v[174:177], v[182:185], v[116:119]
	v_mfma_f32_16x16x32_bf16 v[108:111], v[166:169], v[194:197], v[108:111]
	v_mfma_f32_16x16x32_bf16 v[100:103], v[174:177], v[194:197], v[100:103]
	v_mfma_f32_16x16x32_bf16 v[92:95], v[166:169], v[202:205], v[92:95]
	v_mfma_f32_16x16x32_bf16 v[84:87], v[174:177], v[202:205], v[84:87]
	v_mfma_f32_16x16x32_bf16 v[76:79], v[166:169], v[210:213], v[76:79]
	v_mfma_f32_16x16x32_bf16 v[68:71], v[174:177], v[210:213], v[68:71]
	v_mfma_f32_16x16x32_bf16 v[124:127], v[170:173], v[190:193], v[124:127]
	v_mfma_f32_16x16x32_bf16 v[116:119], v[178:181], v[190:193], v[116:119]
	v_mfma_f32_16x16x32_bf16 v[108:111], v[170:173], v[198:201], v[108:111]
	v_mfma_f32_16x16x32_bf16 v[100:103], v[178:181], v[198:201], v[100:103]
	v_mfma_f32_16x16x32_bf16 v[92:95], v[170:173], v[206:209], v[92:95]
	v_mfma_f32_16x16x32_bf16 v[84:87], v[178:181], v[206:209], v[84:87]
	v_mfma_f32_16x16x32_bf16 v[76:79], v[170:173], v[214:217], v[76:79]
	v_mfma_f32_16x16x32_bf16 v[68:71], v[178:181], v[214:217], v[68:71]
	s_setprio 0
	s_barrier
	s_add_i32 s30, s61, s38
	s_add_i32 m0, s30, 0xffffff80
	ds_read_b128 v[182:185], v149 offset:49152
	ds_read_b128 v[190:193], v149 offset:50176
	ds_read_b128 v[194:197], v149 offset:51200
	ds_read_b128 v[198:201], v149 offset:52224
	global_load_lds_dwordx4 v134, s[100:101] offset:128
	s_add_i32 m0, s30, 0x1f80
	s_add_i32 s30, s62, s38
	global_load_lds_dwordx4 v132, s[100:101] offset:128
	s_add_u32 s100, s100, s4
	s_addc_u32 s101, s101, s5
	s_add_i32 m0, s30, 0xffffff80
	ds_read_b128 v[214:217], v149 offset:56320
	global_load_lds_dwordx4 v134, s[100:101] offset:128
	s_add_i32 m0, s30, 0x1f80
	ds_read_b128 v[210:213], v149 offset:55296
	global_load_lds_dwordx4 v132, s[100:101] offset:128
	s_add_i32 m0, s47, 0xffffff80
	ds_read_b128 v[206:209], v149 offset:54272
	global_load_lds_dwordx4 v128, vcc offset:128
	s_add_i32 m0, s48, 0xffffff80
	ds_read_b128 v[202:205], v149 offset:53248
	global_load_lds_dwordx4 v130, vcc offset:128
	s_waitcnt vmcnt(8)
	s_waitcnt lgkmcnt(0)
	s_barrier
	s_setprio 1
	v_mfma_f32_16x16x32_bf16 v[56:59], v[150:153], v[182:185], v[56:59]
	v_mfma_f32_16x16x32_bf16 v[48:51], v[158:161], v[182:185], v[48:51]
	v_mfma_f32_16x16x32_bf16 v[40:43], v[150:153], v[194:197], v[40:43]
	v_mfma_f32_16x16x32_bf16 v[32:35], v[158:161], v[194:197], v[32:35]
	v_mfma_f32_16x16x32_bf16 v[24:27], v[150:153], v[202:205], v[24:27]
	v_mfma_f32_16x16x32_bf16 v[16:19], v[158:161], v[202:205], v[16:19]
	v_mfma_f32_16x16x32_bf16 v[8:11], v[150:153], v[210:213], v[8:11]
	v_mfma_f32_16x16x32_bf16 v[0:3], v[158:161], v[210:213], v[0:3]
	v_mfma_f32_16x16x32_bf16 v[56:59], v[154:157], v[190:193], v[56:59]
	v_mfma_f32_16x16x32_bf16 v[48:51], v[162:165], v[190:193], v[48:51]
	v_mfma_f32_16x16x32_bf16 v[40:43], v[154:157], v[198:201], v[40:43]
	v_mfma_f32_16x16x32_bf16 v[32:35], v[162:165], v[198:201], v[32:35]
	v_mfma_f32_16x16x32_bf16 v[24:27], v[154:157], v[206:209], v[24:27]
	v_mfma_f32_16x16x32_bf16 v[16:19], v[162:165], v[206:209], v[16:19]
	v_mfma_f32_16x16x32_bf16 v[8:11], v[154:157], v[214:217], v[8:11]
	v_mfma_f32_16x16x32_bf16 v[0:3], v[162:165], v[214:217], v[0:3]
	v_mfma_f32_16x16x32_bf16 v[60:63], v[166:169], v[182:185], v[60:63]
	v_mfma_f32_16x16x32_bf16 v[52:55], v[174:177], v[182:185], v[52:55]
	v_mfma_f32_16x16x32_bf16 v[44:47], v[166:169], v[194:197], v[44:47]
	v_mfma_f32_16x16x32_bf16 v[36:39], v[174:177], v[194:197], v[36:39]
	v_mfma_f32_16x16x32_bf16 v[28:31], v[166:169], v[202:205], v[28:31]
	v_mfma_f32_16x16x32_bf16 v[20:23], v[174:177], v[202:205], v[20:23]
	v_mfma_f32_16x16x32_bf16 v[12:15], v[166:169], v[210:213], v[12:15]
	v_mfma_f32_16x16x32_bf16 v[4:7], v[174:177], v[210:213], v[4:7]
	v_mfma_f32_16x16x32_bf16 v[60:63], v[170:173], v[190:193], v[60:63]
	v_mfma_f32_16x16x32_bf16 v[52:55], v[178:181], v[190:193], v[52:55]
	v_mfma_f32_16x16x32_bf16 v[44:47], v[170:173], v[198:201], v[44:47]
	v_mfma_f32_16x16x32_bf16 v[36:39], v[178:181], v[198:201], v[36:39]
	v_mfma_f32_16x16x32_bf16 v[28:31], v[170:173], v[206:209], v[28:31]
	v_mfma_f32_16x16x32_bf16 v[20:23], v[178:181], v[206:209], v[20:23]
	v_mfma_f32_16x16x32_bf16 v[12:15], v[170:173], v[214:217], v[12:15]
	v_mfma_f32_16x16x32_bf16 v[4:7], v[178:181], v[214:217], v[4:7]
	s_setprio 0
	s_barrier
	s_add_u32 s10, s10, 0x100
	s_addc_u32 s11, s11, 0
	s_add_u32 s34, s34, 0x100
	s_addc_u32 s35, s35, 0
	s_cmp_ge_i32 s60, s50
	s_mov_b32 s30, s60
	s_cbranch_scc0 .LBB0_601

; #define PG8_STAGE(bufoff, gbase, voff) do { _Pragma("unroll") for (int _i = 0; _i < 2; ++_i) \
;         __builtin_amdgcn_global_load_lds((const unsigned*)((const char*)(gbase) + (voff)[_i]), (PG8_LAS unsigned*)(lds + (bufoff) + ldsw + _i * 8192), 16, 0, 0); } while (0)
; #define PG8_LDA(dst, b, h) do { _Pragma("unroll") for (int m = 0; m < 4; ++m) _Pragma("unroll") for (int k = 0; k < 2; ++k) dst[m][k] = *(const PG8_LAS bf16x8*)(lds + PG8_SA(b, h) + aoff + m * 2048 + k * 1024); } while (0)
; #define PG8_LDB(dst, b, h) do { _Pragma("unroll") for (int n = 0; n < 2; ++n) _Pragma("unroll") for (int k = 0; k < 2; ++k) dst[n][k] = *(const PG8_LAS bf16x8*)(lds + PG8_SB(b, h) + boff + n * 2048 + k * 1024); } while (0)
; #define PG8_MMA(ai, bj, At, Bt) do { __builtin_amdgcn_s_setprio(1); _Pragma("unroll") for (int m = 0; m < 4; ++m) _Pragma("unroll") for (int n = 0; n < 2; ++n) _Pragma("unroll") for (int k = 0; k < 2; ++k) \
;         acc[ai][bj][m][n] = __builtin_amdgcn_mfma_f32_16x16x32_bf16(Bt[n][k], At[m][k], acc[ai][bj][m][n], 0, 0, 0); __builtin_amdgcn_s_setprio(0); } while (0)
; #define PG8_WAIT_V(n) asm volatile("s_waitcnt vmcnt(" #n ")" ::: "memory")
; #define PG8_WAIT_L(n) asm volatile("s_waitcnt lgkmcnt(" #n ")" ::: "memory")
; template <class Epi, class Sched, bool ALIGN_EPI = false, bool SP2 = false>
; __device__ __forceinline__ void gemm_phase(PG8_LAS unsigned char* lds, const Gemm g, const Sched& S, const Epi& E) {
;     ...
;             const bool last = (t == nt - 2);
;             const char* a1 = cA + (size_t)(t + 1) * kstep;
;             const char* a2 = last ? nA : cA + (size_t)(t + 2) * kstep; const char* b2 = last ? nB : cB + (size_t)(t + 2) * kstep;
;             const char* a3 = a2 + kstep; const char* b3 = b2 + kstep;
;             if (last && has_next) S.a_ready(nxt);
;             if constexpr (SP2) {
;             PG8_LDB(B0, 0, 0); PG8_LDB(B1, 0, 1); PG8_SCHED; PG8_LDA(At, 0, 0); PG8_STAGE(PG8_SA(1, 1), a1 + hstepA, voffA);
;             PG8_WAIT_V(8); PG8_WAIT_L(0); PG8_BAR; PG8_MMA(0, 0, At, B0); PG8_MMA(0, 1, At, B1); PG8_BAR; PG8_SCHED;
;             PG8_LDA(At, 0, 1); PG8_STAGE(PG8_SB(0, 0), b2, voffB); PG8_STAGE(PG8_SB(0, 1), b2 + hstep, voffB); PG8_STAGE(PG8_SA(0, 0), a2, voffA);
;             PG8_WAIT_V(8); PG8_WAIT_L(0); PG8_BAR; PG8_MMA(1, 0, At, B0); PG8_MMA(1, 1, At, B1); PG8_BAR; PG8_SCHED;
.LBB0_681:
	ds_read_b128 v[128:131], v175
	ds_read_b128 v[132:135], v175 offset:1024
	ds_read_b128 v[136:139], v175 offset:2048
	ds_read_b128 v[140:143], v175 offset:3072
	ds_read_b128 v[162:165], v176
	ds_read_b128 v[166:169], v176 offset:1024
	ds_read_b128 v[180:183], v176 offset:2048
	ds_read_b128 v[184:187], v176 offset:3072
	s_add_i32 s71, s48, 2
	s_add_u32 s72, s8, 0xfffc0080
	s_addc_u32 s49, s9, -1
	s_cmp_eq_u32 s64, s48
	s_cselect_b32 s48, s70, s72
	s_cselect_b32 s49, s39, s49
	s_cselect_b32 s73, s41, s51
	s_cselect_b32 s72, s40, s50
	s_add_i32 m0, s45, 0xc000
	ds_read_b128 v[190:193], v177
	ds_read_b128 v[194:197], v177 offset:1024
	ds_read_b128 v[198:201], v177 offset:2048
	ds_read_b128 v[202:205], v177 offset:3072
	ds_read_b128 v[206:209], v177 offset:4096
	ds_read_b128 v[210:213], v177 offset:5120
	ds_read_b128 v[214:217], v177 offset:6144
	global_load_lds_dwordx4 v154, s[8:9]
	s_add_i32 m0, s45, 0xe000
	ds_read_b128 v[218:221], v177 offset:7168
	global_load_lds_dwordx4 v156, s[8:9]
	s_waitcnt vmcnt(8)
	s_waitcnt lgkmcnt(0)
	s_barrier
	s_setprio 1
	v_mfma_f32_16x16x32_bf16 v[124:127], v[128:131], v[190:193], v[124:127]
	v_mfma_f32_16x16x32_bf16 v[120:123], v[136:139], v[190:193], v[120:123]
	v_mfma_f32_16x16x32_bf16 v[108:111], v[128:131], v[198:201], v[108:111]
	v_mfma_f32_16x16x32_bf16 v[104:107], v[136:139], v[198:201], v[104:107]
	v_mfma_f32_16x16x32_bf16 v[92:95], v[128:131], v[206:209], v[92:95]
	v_mfma_f32_16x16x32_bf16 v[88:91], v[136:139], v[206:209], v[88:91]
	v_mfma_f32_16x16x32_bf16 v[76:79], v[128:131], v[214:217], v[76:79]
	v_mfma_f32_16x16x32_bf16 v[72:75], v[136:139], v[214:217], v[72:75]
	v_mfma_f32_16x16x32_bf16 v[124:127], v[132:135], v[194:197], v[124:127]
	v_mfma_f32_16x16x32_bf16 v[120:123], v[140:143], v[194:197], v[120:123]
	v_mfma_f32_16x16x32_bf16 v[108:111], v[132:135], v[202:205], v[108:111]
	v_mfma_f32_16x16x32_bf16 v[104:107], v[140:143], v[202:205], v[104:107]
	v_mfma_f32_16x16x32_bf16 v[92:95], v[132:135], v[210:213], v[92:95]
	v_mfma_f32_16x16x32_bf16 v[88:91], v[140:143], v[210:213], v[88:91]
	v_mfma_f32_16x16x32_bf16 v[76:79], v[132:135], v[218:221], v[76:79]
	v_mfma_f32_16x16x32_bf16 v[72:75], v[140:143], v[218:221], v[72:75]
	v_mfma_f32_16x16x32_bf16 v[116:119], v[162:165], v[190:193], v[116:119]
	v_mfma_f32_16x16x32_bf16 v[112:115], v[180:183], v[190:193], v[112:115]
	v_mfma_f32_16x16x32_bf16 v[100:103], v[162:165], v[198:201], v[100:103]
	v_mfma_f32_16x16x32_bf16 v[96:99], v[180:183], v[198:201], v[96:99]
	v_mfma_f32_16x16x32_bf16 v[84:87], v[162:165], v[206:209], v[84:87]
	v_mfma_f32_16x16x32_bf16 v[80:83], v[180:183], v[206:209], v[80:83]
	v_mfma_f32_16x16x32_bf16 v[68:71], v[162:165], v[214:217], v[68:71]
	v_mfma_f32_16x16x32_bf16 v[64:67], v[180:183], v[214:217], v[64:67]
	v_mfma_f32_16x16x32_bf16 v[116:119], v[166:169], v[194:197], v[116:119]
	v_mfma_f32_16x16x32_bf16 v[112:115], v[184:187], v[194:197], v[112:115]
	v_mfma_f32_16x16x32_bf16 v[100:103], v[166:169], v[202:205], v[100:103]
	v_mfma_f32_16x16x32_bf16 v[96:99], v[184:187], v[202:205], v[96:99]
	v_mfma_f32_16x16x32_bf16 v[84:87], v[166:169], v[210:213], v[84:87]
	v_mfma_f32_16x16x32_bf16 v[80:83], v[184:187], v[210:213], v[80:83]
	v_mfma_f32_16x16x32_bf16 v[68:71], v[166:169], v[218:221], v[68:71]
	v_mfma_f32_16x16x32_bf16 v[64:67], v[184:187], v[218:221], v[64:67]
	s_setprio 0
	s_barrier
	s_add_i32 s74, s65, s53
	s_mov_b32 m0, s74
	ds_read_b128 v[190:193], v177 offset:16384
	ds_read_b128 v[194:197], v177 offset:17408
	ds_read_b128 v[198:201], v177 offset:18432
	ds_read_b128 v[202:205], v177 offset:19456
	global_load_lds_dwordx4 v150, s[72:73]
	s_add_i32 m0, s74, 0x2000
	s_mov_b64 s[100:101], s[72:73]
	s_add_i32 s74, s66, s53
	global_load_lds_dwordx4 v148, s[72:73]
	s_add_u32 s72, s72, s10
	s_addc_u32 s73, s73, s11
	s_mov_b32 m0, s74
	ds_read_b128 v[218:221], v177 offset:23552
	global_load_lds_dwordx4 v150, s[72:73]
	s_add_i32 m0, s74, 0x2000
	ds_read_b128 v[214:217], v177 offset:22528
	global_load_lds_dwordx4 v148, s[72:73]
	s_mov_b32 m0, s45
	ds_read_b128 v[210:213], v177 offset:21504
	global_load_lds_dwordx4 v144, s[48:49]
	s_mov_b32 m0, s55
	ds_read_b128 v[206:209], v177 offset:20480
	global_load_lds_dwordx4 v146, s[48:49]
	s_waitcnt vmcnt(8)
	s_waitcnt lgkmcnt(0)
	s_barrier
	s_setprio 1
	v_mfma_f32_16x16x32_bf16 v[60:63], v[128:131], v[190:193], v[60:63]
	v_mfma_f32_16x16x32_bf16 v[56:59], v[136:139], v[190:193], v[56:59]
	v_mfma_f32_16x16x32_bf16 v[44:47], v[128:131], v[198:201], v[44:47]
	v_mfma_f32_16x16x32_bf16 v[40:43], v[136:139], v[198:201], v[40:43]
	v_mfma_f32_16x16x32_bf16 v[28:31], v[128:131], v[206:209], v[28:31]
	v_mfma_f32_16x16x32_bf16 v[24:27], v[136:139], v[206:209], v[24:27]
	v_mfma_f32_16x16x32_bf16 v[12:15], v[128:131], v[214:217], v[12:15]
	v_mfma_f32_16x16x32_bf16 v[8:11], v[136:139], v[214:217], v[8:11]
	v_mfma_f32_16x16x32_bf16 v[60:63], v[132:135], v[194:197], v[60:63]
	v_mfma_f32_16x16x32_bf16 v[56:59], v[140:143], v[194:197], v[56:59]
	v_mfma_f32_16x16x32_bf16 v[44:47], v[132:135], v[202:205], v[44:47]
	v_mfma_f32_16x16x32_bf16 v[40:43], v[140:143], v[202:205], v[40:43]
	v_mfma_f32_16x16x32_bf16 v[28:31], v[132:135], v[210:213], v[28:31]
	v_mfma_f32_16x16x32_bf16 v[24:27], v[140:143], v[210:213], v[24:27]
	v_mfma_f32_16x16x32_bf16 v[12:15], v[132:135], v[218:221], v[12:15]
	v_mfma_f32_16x16x32_bf16 v[8:11], v[140:143], v[218:221], v[8:11]
	v_mfma_f32_16x16x32_bf16 v[52:55], v[162:165], v[190:193], v[52:55]
	v_mfma_f32_16x16x32_bf16 v[48:51], v[180:183], v[190:193], v[48:51]
	v_mfma_f32_16x16x32_bf16 v[36:39], v[162:165], v[198:201], v[36:39]
	v_mfma_f32_16x16x32_bf16 v[32:35], v[180:183], v[198:201], v[32:35]
	v_mfma_f32_16x16x32_bf16 v[20:23], v[162:165], v[206:209], v[20:23]
	v_mfma_f32_16x16x32_bf16 v[16:19], v[180:183], v[206:209], v[16:19]
	v_mfma_f32_16x16x32_bf16 v[4:7], v[162:165], v[214:217], v[4:7]
	v_mfma_f32_16x16x32_bf16 v[0:3], v[180:183], v[214:217], v[0:3]
	v_mfma_f32_16x16x32_bf16 v[52:55], v[166:169], v[194:197], v[52:55]
	v_mfma_f32_16x16x32_bf16 v[48:51], v[184:187], v[194:197], v[48:51]
	v_mfma_f32_16x16x32_bf16 v[36:39], v[166:169], v[202:205], v[36:39]
	v_mfma_f32_16x16x32_bf16 v[32:35], v[184:187], v[202:205], v[32:35]
	v_mfma_f32_16x16x32_bf16 v[20:23], v[166:169], v[210:213], v[20:23]
	v_mfma_f32_16x16x32_bf16 v[16:19], v[184:187], v[210:213], v[16:19]
	v_mfma_f32_16x16x32_bf16 v[4:7], v[166:169], v[218:221], v[4:7]
	v_mfma_f32_16x16x32_bf16 v[0:3], v[184:187], v[218:221], v[0:3]
	s_setprio 0
	s_barrier
; #define PG8_STAGE(bufoff, gbase, voff) do { _Pragma("unroll") for (int _i = 0; _i < 2; ++_i) \
;         __builtin_amdgcn_global_load_lds((const unsigned*)((const char*)(gbase) + (voff)[_i]), (PG8_LAS unsigned*)(lds + (bufoff) + ldsw + _i * 8192), 16, 0, 0); } while (0)
; #define PG8_LDA(dst, b, h) do { _Pragma("unroll") for (int m = 0; m < 4; ++m) _Pragma("unroll") for (int k = 0; k < 2; ++k) dst[m][k] = *(const PG8_LAS bf16x8*)(lds + PG8_SA(b, h) + aoff + m * 2048 + k * 1024); } while (0)
; #define PG8_LDB(dst, b, h) do { _Pragma("unroll") for (int n = 0; n < 2; ++n) _Pragma("unroll") for (int k = 0; k < 2; ++k) dst[n][k] = *(const PG8_LAS bf16x8*)(lds + PG8_SB(b, h) + boff + n * 2048 + k * 1024); } while (0)
; #define PG8_MMA(ai, bj, At, Bt) do { __builtin_amdgcn_s_setprio(1); _Pragma("unroll") for (int m = 0; m < 4; ++m) _Pragma("unroll") for (int n = 0; n < 2; ++n) _Pragma("unroll") for (int k = 0; k < 2; ++k) \
;         acc[ai][bj][m][n] = __builtin_amdgcn_mfma_f32_16x16x32_bf16(Bt[n][k], At[m][k], acc[ai][bj][m][n], 0, 0, 0); __builtin_amdgcn_s_setprio(0); } while (0)
; #define PG8_WAIT_V(n) asm volatile("s_waitcnt vmcnt(" #n ")" ::: "memory")
; #define PG8_WAIT_L(n) asm volatile("s_waitcnt lgkmcnt(" #n ")" ::: "memory")
; #define PG8_BAR __builtin_amdgcn_s_barrier()
; #define PG8_SCHED __builtin_amdgcn_sched_barrier(0)
; template <class Epi, class Sched, bool ALIGN_EPI = false, bool SP2 = false>
; __device__ __forceinline__ void gemm_phase(PG8_LAS unsigned char* lds, const Gemm g, const Sched& S, const Epi& E) {
;     ...
;         for (int t = 0; t < nt; t += 2) {
;             const bool last = (t == nt - 2);
;             const char* a1 = cA + (size_t)(t + 1) * kstep;
;             const char* a2 = last ? nA : cA + (size_t)(t + 2) * kstep; const char* b2 = last ? nB : cB + (size_t)(t + 2) * kstep;
;     ...
;             PG8_LDB(B0, 1, 0); PG8_LDB(B1, 1, 1); PG8_SCHED; PG8_LDA(At, 1, 0); PG8_STAGE(PG8_SA(0, 1), a2 + hstepA, voffA);
;             PG8_WAIT_V(8); PG8_WAIT_L(0); PG8_BAR; PG8_MMA(0, 0, At, B0); PG8_MMA(0, 1, At, B1); PG8_BAR; PG8_SCHED;
;             PG8_LDA(At, 1, 1); PG8_STAGE(PG8_SB(1, 0), b3, voffB); PG8_STAGE(PG8_SB(1, 1), b3 + hstep, voffB); PG8_STAGE(PG8_SA(1, 0), a3, voffA);
;             PG8_WAIT_V(8); PG8_WAIT_L(0); PG8_BAR; PG8_MMA(1, 0, At, B0); PG8_MMA(1, 1, At, B1); PG8_BAR; PG8_SCHED;
	s_add_i32 s72, 0, 0x18000
	s_add_i32 s73, 0, 0x1c000
	v_add_u32_e32 v140, s72, v173
	v_add_u32_e32 v152, s73, v173
	ds_read_b128 v[128:131], v140
	ds_read_b128 v[132:135], v140 offset:1024
	ds_read_b128 v[136:139], v140 offset:2048
	ds_read_b128 v[140:143], v140 offset:3072
	ds_read_b128 v[162:165], v152
	ds_read_b128 v[166:169], v152 offset:1024
	ds_read_b128 v[180:183], v152 offset:2048
	ds_read_b128 v[184:187], v152 offset:3072
	s_mov_b64 vcc, s[48:49]
	s_add_u32 s48, s48, 0x40000
	s_addc_u32 s49, s49, 0
	s_mov_b32 m0, s56
	ds_read_b128 v[190:193], v177 offset:32768
	ds_read_b128 v[194:197], v177 offset:33792
	ds_read_b128 v[198:201], v177 offset:34816
	ds_read_b128 v[202:205], v177 offset:35840
	ds_read_b128 v[206:209], v177 offset:36864
	ds_read_b128 v[210:213], v177 offset:37888
	ds_read_b128 v[214:217], v177 offset:38912
	global_load_lds_dwordx4 v144, s[48:49]
	s_mov_b32 m0, s57
	ds_read_b128 v[218:221], v177 offset:39936
	global_load_lds_dwordx4 v146, s[48:49]
	s_waitcnt vmcnt(8)
	s_waitcnt lgkmcnt(0)
	s_barrier
	s_setprio 1
	v_mfma_f32_16x16x32_bf16 v[124:127], v[128:131], v[190:193], v[124:127]
	v_mfma_f32_16x16x32_bf16 v[120:123], v[136:139], v[190:193], v[120:123]
	v_mfma_f32_16x16x32_bf16 v[108:111], v[128:131], v[198:201], v[108:111]
	v_mfma_f32_16x16x32_bf16 v[104:107], v[136:139], v[198:201], v[104:107]
	v_mfma_f32_16x16x32_bf16 v[92:95], v[128:131], v[206:209], v[92:95]
	v_mfma_f32_16x16x32_bf16 v[88:91], v[136:139], v[206:209], v[88:91]
	v_mfma_f32_16x16x32_bf16 v[76:79], v[128:131], v[214:217], v[76:79]
	v_mfma_f32_16x16x32_bf16 v[72:75], v[136:139], v[214:217], v[72:75]
	v_mfma_f32_16x16x32_bf16 v[124:127], v[132:135], v[194:197], v[124:127]
	v_mfma_f32_16x16x32_bf16 v[120:123], v[140:143], v[194:197], v[120:123]
	v_mfma_f32_16x16x32_bf16 v[108:111], v[132:135], v[202:205], v[108:111]
	v_mfma_f32_16x16x32_bf16 v[104:107], v[140:143], v[202:205], v[104:107]
	v_mfma_f32_16x16x32_bf16 v[92:95], v[132:135], v[210:213], v[92:95]
	v_mfma_f32_16x16x32_bf16 v[88:91], v[140:143], v[210:213], v[88:91]
	v_mfma_f32_16x16x32_bf16 v[76:79], v[132:135], v[218:221], v[76:79]
	v_mfma_f32_16x16x32_bf16 v[72:75], v[140:143], v[218:221], v[72:75]
	v_mfma_f32_16x16x32_bf16 v[116:119], v[162:165], v[190:193], v[116:119]
	v_mfma_f32_16x16x32_bf16 v[112:115], v[180:183], v[190:193], v[112:115]
	v_mfma_f32_16x16x32_bf16 v[100:103], v[162:165], v[198:201], v[100:103]
	v_mfma_f32_16x16x32_bf16 v[96:99], v[180:183], v[198:201], v[96:99]
	v_mfma_f32_16x16x32_bf16 v[84:87], v[162:165], v[206:209], v[84:87]
	v_mfma_f32_16x16x32_bf16 v[80:83], v[180:183], v[206:209], v[80:83]
	v_mfma_f32_16x16x32_bf16 v[68:71], v[162:165], v[214:217], v[68:71]
	v_mfma_f32_16x16x32_bf16 v[64:67], v[180:183], v[214:217], v[64:67]
	v_mfma_f32_16x16x32_bf16 v[116:119], v[166:169], v[194:197], v[116:119]
	v_mfma_f32_16x16x32_bf16 v[112:115], v[184:187], v[194:197], v[112:115]
	v_mfma_f32_16x16x32_bf16 v[100:103], v[166:169], v[202:205], v[100:103]
	v_mfma_f32_16x16x32_bf16 v[96:99], v[184:187], v[202:205], v[96:99]
	v_mfma_f32_16x16x32_bf16 v[84:87], v[166:169], v[210:213], v[84:87]
	v_mfma_f32_16x16x32_bf16 v[80:83], v[184:187], v[210:213], v[80:83]
	v_mfma_f32_16x16x32_bf16 v[68:71], v[166:169], v[218:221], v[68:71]
	v_mfma_f32_16x16x32_bf16 v[64:67], v[184:187], v[218:221], v[64:67]
	s_setprio 0
	s_barrier
	s_add_i32 s48, s72, s53
	s_add_i32 m0, s48, 0xffffff80
	ds_read_b128 v[190:193], v177 offset:49152
	ds_read_b128 v[194:197], v177 offset:50176
	ds_read_b128 v[198:201], v177 offset:51200
	ds_read_b128 v[202:205], v177 offset:52224
	global_load_lds_dwordx4 v150, s[100:101] offset:128
	s_add_i32 m0, s48, 0x1f80
	s_add_i32 s48, s73, s53
	global_load_lds_dwordx4 v148, s[100:101] offset:128
	s_add_u32 s100, s100, s10
	s_addc_u32 s101, s101, s11
	s_add_i32 m0, s48, 0xffffff80
	ds_read_b128 v[218:221], v177 offset:56320
	global_load_lds_dwordx4 v150, s[100:101] offset:128
	s_add_i32 m0, s48, 0x1f80
	ds_read_b128 v[214:217], v177 offset:55296
	global_load_lds_dwordx4 v148, s[100:101] offset:128
	s_add_i32 m0, s60, 0xffffff80
	ds_read_b128 v[210:213], v177 offset:54272
	global_load_lds_dwordx4 v144, vcc offset:128
	s_add_i32 m0, s61, 0xffffff80
	ds_read_b128 v[206:209], v177 offset:53248
	global_load_lds_dwordx4 v146, vcc offset:128
	s_waitcnt vmcnt(8)
	s_waitcnt lgkmcnt(0)
	s_barrier
	s_setprio 1
	v_mfma_f32_16x16x32_bf16 v[60:63], v[128:131], v[190:193], v[60:63]
	v_mfma_f32_16x16x32_bf16 v[56:59], v[136:139], v[190:193], v[56:59]
	v_mfma_f32_16x16x32_bf16 v[44:47], v[128:131], v[198:201], v[44:47]
	v_mfma_f32_16x16x32_bf16 v[40:43], v[136:139], v[198:201], v[40:43]
	v_mfma_f32_16x16x32_bf16 v[28:31], v[128:131], v[206:209], v[28:31]
	v_mfma_f32_16x16x32_bf16 v[24:27], v[136:139], v[206:209], v[24:27]
	v_mfma_f32_16x16x32_bf16 v[12:15], v[128:131], v[214:217], v[12:15]
	v_mfma_f32_16x16x32_bf16 v[8:11], v[136:139], v[214:217], v[8:11]
	v_mfma_f32_16x16x32_bf16 v[60:63], v[132:135], v[194:197], v[60:63]
	v_mfma_f32_16x16x32_bf16 v[56:59], v[140:143], v[194:197], v[56:59]
	v_mfma_f32_16x16x32_bf16 v[44:47], v[132:135], v[202:205], v[44:47]
	v_mfma_f32_16x16x32_bf16 v[40:43], v[140:143], v[202:205], v[40:43]
	v_mfma_f32_16x16x32_bf16 v[28:31], v[132:135], v[210:213], v[28:31]
	v_mfma_f32_16x16x32_bf16 v[24:27], v[140:143], v[210:213], v[24:27]
	v_mfma_f32_16x16x32_bf16 v[12:15], v[132:135], v[218:221], v[12:15]
	v_mfma_f32_16x16x32_bf16 v[8:11], v[140:143], v[218:221], v[8:11]
	v_mfma_f32_16x16x32_bf16 v[52:55], v[162:165], v[190:193], v[52:55]
	v_mfma_f32_16x16x32_bf16 v[48:51], v[180:183], v[190:193], v[48:51]
	v_mfma_f32_16x16x32_bf16 v[36:39], v[162:165], v[198:201], v[36:39]
	v_mfma_f32_16x16x32_bf16 v[32:35], v[180:183], v[198:201], v[32:35]
	v_mfma_f32_16x16x32_bf16 v[20:23], v[162:165], v[206:209], v[20:23]
	v_mfma_f32_16x16x32_bf16 v[16:19], v[180:183], v[206:209], v[16:19]
	v_mfma_f32_16x16x32_bf16 v[4:7], v[162:165], v[214:217], v[4:7]
	v_mfma_f32_16x16x32_bf16 v[0:3], v[180:183], v[214:217], v[0:3]
	v_mfma_f32_16x16x32_bf16 v[52:55], v[166:169], v[194:197], v[52:55]
	v_mfma_f32_16x16x32_bf16 v[48:51], v[184:187], v[194:197], v[48:51]
	v_mfma_f32_16x16x32_bf16 v[36:39], v[166:169], v[202:205], v[36:39]
	v_mfma_f32_16x16x32_bf16 v[32:35], v[184:187], v[202:205], v[32:35]
	v_mfma_f32_16x16x32_bf16 v[20:23], v[166:169], v[210:213], v[20:23]
	v_mfma_f32_16x16x32_bf16 v[16:19], v[184:187], v[210:213], v[16:19]
	v_mfma_f32_16x16x32_bf16 v[4:7], v[166:169], v[218:221], v[4:7]
	v_mfma_f32_16x16x32_bf16 v[0:3], v[184:187], v[218:221], v[0:3]
	s_setprio 0
	s_barrier
	s_add_u32 s8, s8, 0x100
	s_addc_u32 s9, s9, 0
	s_add_u32 s50, s50, 0x100
	s_addc_u32 s51, s51, 0
	s_cmp_ge_i32 s71, s63
	s_mov_b32 s48, s71
	s_cbranch_scc0 .LBB0_681

; #define PG8_STAGE(bufoff, gbase, voff) do { _Pragma("unroll") for (int _i = 0; _i < 2; ++_i) \
;         __builtin_amdgcn_global_load_lds((const unsigned*)((const char*)(gbase) + (voff)[_i]), (PG8_LAS unsigned*)(lds + (bufoff) + ldsw + _i * 8192), 16, 0, 0); } while (0)
; #define PG8_LDA(dst, b, h) do { _Pragma("unroll") for (int m = 0; m < 4; ++m) _Pragma("unroll") for (int k = 0; k < 2; ++k) dst[m][k] = *(const PG8_LAS bf16x8*)(lds + PG8_SA(b, h) + aoff + m * 2048 + k * 1024); } while (0)
; #define PG8_LDB(dst, b, h) do { _Pragma("unroll") for (int n = 0; n < 2; ++n) _Pragma("unroll") for (int k = 0; k < 2; ++k) dst[n][k] = *(const PG8_LAS bf16x8*)(lds + PG8_SB(b, h) + boff + n * 2048 + k * 1024); } while (0)
; #define PG8_MMA(ai, bj, At, Bt) do { __builtin_amdgcn_s_setprio(1); _Pragma("unroll") for (int m = 0; m < 4; ++m) _Pragma("unroll") for (int n = 0; n < 2; ++n) _Pragma("unroll") for (int k = 0; k < 2; ++k) \
;         acc[ai][bj][m][n] = __builtin_amdgcn_mfma_f32_16x16x32_bf16(Bt[n][k], At[m][k], acc[ai][bj][m][n], 0, 0, 0); __builtin_amdgcn_s_setprio(0); } while (0)
; #define PG8_WAIT_V(n) asm volatile("s_waitcnt vmcnt(" #n ")" ::: "memory")
; #define PG8_WAIT_L(n) asm volatile("s_waitcnt lgkmcnt(" #n ")" ::: "memory")
; template <class Epi, class Sched, bool ALIGN_EPI = false, bool SP2 = false>
; __device__ __forceinline__ void gemm_phase(PG8_LAS unsigned char* lds, const Gemm g, const Sched& S, const Epi& E) {
;     ...
;             const bool last = (t == nt - 2);
;             const char* a1 = cA + (size_t)(t + 1) * kstep;
;             const char* a2 = last ? nA : cA + (size_t)(t + 2) * kstep; const char* b2 = last ? nB : cB + (size_t)(t + 2) * kstep;
;             const char* a3 = a2 + kstep; const char* b3 = b2 + kstep;
;             if (last && has_next) S.a_ready(nxt);
;             if constexpr (SP2) {
;             PG8_LDB(B0, 0, 0); PG8_LDB(B1, 0, 1); PG8_SCHED; PG8_LDA(At, 0, 0); PG8_STAGE(PG8_SA(1, 1), a1 + hstepA, voffA);
;             PG8_WAIT_V(8); PG8_WAIT_L(0); PG8_BAR; PG8_MMA(0, 0, At, B0); PG8_MMA(0, 1, At, B1); PG8_BAR; PG8_SCHED;
;             PG8_LDA(At, 0, 1); PG8_STAGE(PG8_SB(0, 0), b2, voffB); PG8_STAGE(PG8_SB(0, 1), b2 + hstep, voffB); PG8_STAGE(PG8_SA(0, 0), a2, voffA);
;             PG8_WAIT_V(8); PG8_WAIT_L(0); PG8_BAR; PG8_MMA(1, 0, At, B0); PG8_MMA(1, 1, At, B1); PG8_BAR; PG8_SCHED;
.LBB0_762:
	ds_read_b128 v[128:131], v169
	ds_read_b128 v[132:135], v169 offset:1024
	ds_read_b128 v[136:139], v169 offset:2048
	ds_read_b128 v[140:143], v169 offset:3072
	ds_read_b128 v[156:159], v170
	ds_read_b128 v[160:163], v170 offset:1024
	ds_read_b128 v[172:175], v170 offset:2048
	ds_read_b128 v[176:179], v170 offset:3072
	s_add_i32 s76, s48, 2
	s_add_u32 s77, s44, 0xfffc0080
	s_addc_u32 s49, s45, -1
	s_cmp_eq_u32 s70, s48
	s_cselect_b32 s48, s50, s77
	s_cselect_b32 s49, s37, s49
	s_cselect_b32 s79, s39, s75
	s_cselect_b32 s78, s38, s51
	s_add_i32 m0, s43, 0xc000
	ds_read_b128 v[180:183], v171
	ds_read_b128 v[184:187], v171 offset:1024
	ds_read_b128 v[190:193], v171 offset:2048
	ds_read_b128 v[194:197], v171 offset:3072
	ds_read_b128 v[198:201], v171 offset:4096
	ds_read_b128 v[202:205], v171 offset:5120
	ds_read_b128 v[206:209], v171 offset:6144
	global_load_lds_dwordx4 v152, s[44:45]
	s_add_i32 m0, s43, 0xe000
	ds_read_b128 v[210:213], v171 offset:7168
	global_load_lds_dwordx4 v154, s[44:45]
	s_waitcnt vmcnt(8)
	s_waitcnt lgkmcnt(0)
	s_barrier
	s_setprio 1
	v_mfma_f32_16x16x32_bf16 v[124:127], v[128:131], v[180:183], v[124:127]
	v_mfma_f32_16x16x32_bf16 v[120:123], v[136:139], v[180:183], v[120:123]
	v_mfma_f32_16x16x32_bf16 v[108:111], v[128:131], v[190:193], v[108:111]
	v_mfma_f32_16x16x32_bf16 v[104:107], v[136:139], v[190:193], v[104:107]
	v_mfma_f32_16x16x32_bf16 v[92:95], v[128:131], v[198:201], v[92:95]
	v_mfma_f32_16x16x32_bf16 v[88:91], v[136:139], v[198:201], v[88:91]
	v_mfma_f32_16x16x32_bf16 v[76:79], v[128:131], v[206:209], v[76:79]
	v_mfma_f32_16x16x32_bf16 v[72:75], v[136:139], v[206:209], v[72:75]
	v_mfma_f32_16x16x32_bf16 v[124:127], v[132:135], v[184:187], v[124:127]
	v_mfma_f32_16x16x32_bf16 v[120:123], v[140:143], v[184:187], v[120:123]
	v_mfma_f32_16x16x32_bf16 v[108:111], v[132:135], v[194:197], v[108:111]
	v_mfma_f32_16x16x32_bf16 v[104:107], v[140:143], v[194:197], v[104:107]
	v_mfma_f32_16x16x32_bf16 v[92:95], v[132:135], v[202:205], v[92:95]
	v_mfma_f32_16x16x32_bf16 v[88:91], v[140:143], v[202:205], v[88:91]
	v_mfma_f32_16x16x32_bf16 v[76:79], v[132:135], v[210:213], v[76:79]
	v_mfma_f32_16x16x32_bf16 v[72:75], v[140:143], v[210:213], v[72:75]
	v_mfma_f32_16x16x32_bf16 v[116:119], v[156:159], v[180:183], v[116:119]
	v_mfma_f32_16x16x32_bf16 v[112:115], v[172:175], v[180:183], v[112:115]
	v_mfma_f32_16x16x32_bf16 v[100:103], v[156:159], v[190:193], v[100:103]
	v_mfma_f32_16x16x32_bf16 v[96:99], v[172:175], v[190:193], v[96:99]
	v_mfma_f32_16x16x32_bf16 v[84:87], v[156:159], v[198:201], v[84:87]
	v_mfma_f32_16x16x32_bf16 v[80:83], v[172:175], v[198:201], v[80:83]
	v_mfma_f32_16x16x32_bf16 v[68:71], v[156:159], v[206:209], v[68:71]
	v_mfma_f32_16x16x32_bf16 v[64:67], v[172:175], v[206:209], v[64:67]
	v_mfma_f32_16x16x32_bf16 v[116:119], v[160:163], v[184:187], v[116:119]
	v_mfma_f32_16x16x32_bf16 v[112:115], v[176:179], v[184:187], v[112:115]
	v_mfma_f32_16x16x32_bf16 v[100:103], v[160:163], v[194:197], v[100:103]
	v_mfma_f32_16x16x32_bf16 v[96:99], v[176:179], v[194:197], v[96:99]
	v_mfma_f32_16x16x32_bf16 v[84:87], v[160:163], v[202:205], v[84:87]
	v_mfma_f32_16x16x32_bf16 v[80:83], v[176:179], v[202:205], v[80:83]
	v_mfma_f32_16x16x32_bf16 v[68:71], v[160:163], v[210:213], v[68:71]
	v_mfma_f32_16x16x32_bf16 v[64:67], v[176:179], v[210:213], v[64:67]
	s_setprio 0
	s_barrier
	s_add_i32 s77, s71, s57
	s_mov_b32 m0, s77
	ds_read_b128 v[180:183], v171 offset:16384
	ds_read_b128 v[184:187], v171 offset:17408
	ds_read_b128 v[190:193], v171 offset:18432
	ds_read_b128 v[194:197], v171 offset:19456
	global_load_lds_dwordx4 v150, s[78:79]
	s_add_i32 m0, s77, 0x2000
	s_mov_b64 s[100:101], s[78:79]
	s_add_i32 s77, s72, s57
	global_load_lds_dwordx4 v148, s[78:79]
	s_add_u32 s78, s78, s8
	s_addc_u32 s79, s79, s9
	s_mov_b32 m0, s77
	ds_read_b128 v[210:213], v171 offset:23552
	global_load_lds_dwordx4 v150, s[78:79]
	s_add_i32 m0, s77, 0x2000
	ds_read_b128 v[206:209], v171 offset:22528
	global_load_lds_dwordx4 v148, s[78:79]
	s_mov_b32 m0, s43
	ds_read_b128 v[202:205], v171 offset:21504
	global_load_lds_dwordx4 v144, s[48:49]
	s_mov_b32 m0, s59
	ds_read_b128 v[198:201], v171 offset:20480
	global_load_lds_dwordx4 v146, s[48:49]
	s_waitcnt vmcnt(8)
	s_waitcnt lgkmcnt(0)
	s_barrier
	s_setprio 1
	v_mfma_f32_16x16x32_bf16 v[60:63], v[128:131], v[180:183], v[60:63]
	v_mfma_f32_16x16x32_bf16 v[56:59], v[136:139], v[180:183], v[56:59]
	v_mfma_f32_16x16x32_bf16 v[44:47], v[128:131], v[190:193], v[44:47]
	v_mfma_f32_16x16x32_bf16 v[40:43], v[136:139], v[190:193], v[40:43]
	v_mfma_f32_16x16x32_bf16 v[28:31], v[128:131], v[198:201], v[28:31]
	v_mfma_f32_16x16x32_bf16 v[24:27], v[136:139], v[198:201], v[24:27]
	v_mfma_f32_16x16x32_bf16 v[12:15], v[128:131], v[206:209], v[12:15]
	v_mfma_f32_16x16x32_bf16 v[8:11], v[136:139], v[206:209], v[8:11]
	v_mfma_f32_16x16x32_bf16 v[60:63], v[132:135], v[184:187], v[60:63]
	v_mfma_f32_16x16x32_bf16 v[56:59], v[140:143], v[184:187], v[56:59]
	v_mfma_f32_16x16x32_bf16 v[44:47], v[132:135], v[194:197], v[44:47]
	v_mfma_f32_16x16x32_bf16 v[40:43], v[140:143], v[194:197], v[40:43]
	v_mfma_f32_16x16x32_bf16 v[28:31], v[132:135], v[202:205], v[28:31]
	v_mfma_f32_16x16x32_bf16 v[24:27], v[140:143], v[202:205], v[24:27]
	v_mfma_f32_16x16x32_bf16 v[12:15], v[132:135], v[210:213], v[12:15]
	v_mfma_f32_16x16x32_bf16 v[8:11], v[140:143], v[210:213], v[8:11]
	v_mfma_f32_16x16x32_bf16 v[52:55], v[156:159], v[180:183], v[52:55]
	v_mfma_f32_16x16x32_bf16 v[48:51], v[172:175], v[180:183], v[48:51]
	v_mfma_f32_16x16x32_bf16 v[36:39], v[156:159], v[190:193], v[36:39]
	v_mfma_f32_16x16x32_bf16 v[32:35], v[172:175], v[190:193], v[32:35]
	v_mfma_f32_16x16x32_bf16 v[20:23], v[156:159], v[198:201], v[20:23]
	v_mfma_f32_16x16x32_bf16 v[16:19], v[172:175], v[198:201], v[16:19]
	v_mfma_f32_16x16x32_bf16 v[4:7], v[156:159], v[206:209], v[4:7]
	v_mfma_f32_16x16x32_bf16 v[0:3], v[172:175], v[206:209], v[0:3]
	v_mfma_f32_16x16x32_bf16 v[52:55], v[160:163], v[184:187], v[52:55]
	v_mfma_f32_16x16x32_bf16 v[48:51], v[176:179], v[184:187], v[48:51]
	v_mfma_f32_16x16x32_bf16 v[36:39], v[160:163], v[194:197], v[36:39]
	v_mfma_f32_16x16x32_bf16 v[32:35], v[176:179], v[194:197], v[32:35]
	v_mfma_f32_16x16x32_bf16 v[20:23], v[160:163], v[202:205], v[20:23]
	v_mfma_f32_16x16x32_bf16 v[16:19], v[176:179], v[202:205], v[16:19]
	v_mfma_f32_16x16x32_bf16 v[4:7], v[160:163], v[210:213], v[4:7]
	v_mfma_f32_16x16x32_bf16 v[0:3], v[176:179], v[210:213], v[0:3]
	s_setprio 0
	s_barrier
; #define PG8_STAGE(bufoff, gbase, voff) do { _Pragma("unroll") for (int _i = 0; _i < 2; ++_i) \
;         __builtin_amdgcn_global_load_lds((const unsigned*)((const char*)(gbase) + (voff)[_i]), (PG8_LAS unsigned*)(lds + (bufoff) + ldsw + _i * 8192), 16, 0, 0); } while (0)
; #define PG8_LDA(dst, b, h) do { _Pragma("unroll") for (int m = 0; m < 4; ++m) _Pragma("unroll") for (int k = 0; k < 2; ++k) dst[m][k] = *(const PG8_LAS bf16x8*)(lds + PG8_SA(b, h) + aoff + m * 2048 + k * 1024); } while (0)
; #define PG8_LDB(dst, b, h) do { _Pragma("unroll") for (int n = 0; n < 2; ++n) _Pragma("unroll") for (int k = 0; k < 2; ++k) dst[n][k] = *(const PG8_LAS bf16x8*)(lds + PG8_SB(b, h) + boff + n * 2048 + k * 1024); } while (0)
; #define PG8_MMA(ai, bj, At, Bt) do { __builtin_amdgcn_s_setprio(1); _Pragma("unroll") for (int m = 0; m < 4; ++m) _Pragma("unroll") for (int n = 0; n < 2; ++n) _Pragma("unroll") for (int k = 0; k < 2; ++k) \
;         acc[ai][bj][m][n] = __builtin_amdgcn_mfma_f32_16x16x32_bf16(Bt[n][k], At[m][k], acc[ai][bj][m][n], 0, 0, 0); __builtin_amdgcn_s_setprio(0); } while (0)
; #define PG8_WAIT_V(n) asm volatile("s_waitcnt vmcnt(" #n ")" ::: "memory")
; #define PG8_WAIT_L(n) asm volatile("s_waitcnt lgkmcnt(" #n ")" ::: "memory")
; #define PG8_BAR __builtin_amdgcn_s_barrier()
; #define PG8_SCHED __builtin_amdgcn_sched_barrier(0)
; template <class Epi, class Sched, bool ALIGN_EPI = false, bool SP2 = false>
; __device__ __forceinline__ void gemm_phase(PG8_LAS unsigned char* lds, const Gemm g, const Sched& S, const Epi& E) {
;     ...
;         for (int t = 0; t < nt; t += 2) {
;             const bool last = (t == nt - 2);
;             const char* a1 = cA + (size_t)(t + 1) * kstep;
;             const char* a2 = last ? nA : cA + (size_t)(t + 2) * kstep; const char* b2 = last ? nB : cB + (size_t)(t + 2) * kstep;
;     ...
;             PG8_LDB(B0, 1, 0); PG8_LDB(B1, 1, 1); PG8_SCHED; PG8_LDA(At, 1, 0); PG8_STAGE(PG8_SA(0, 1), a2 + hstepA, voffA);
;             PG8_WAIT_V(8); PG8_WAIT_L(0); PG8_BAR; PG8_MMA(0, 0, At, B0); PG8_MMA(0, 1, At, B1); PG8_BAR; PG8_SCHED;
;             PG8_LDA(At, 1, 1); PG8_STAGE(PG8_SB(1, 0), b3, voffB); PG8_STAGE(PG8_SB(1, 1), b3 + hstep, voffB); PG8_STAGE(PG8_SA(1, 0), a3, voffA);
;             PG8_WAIT_V(8); PG8_WAIT_L(0); PG8_BAR; PG8_MMA(1, 0, At, B0); PG8_MMA(1, 1, At, B1); PG8_BAR; PG8_SCHED;
	s_add_i32 s77, 0, 0x18000
	s_add_i32 s78, 0, 0x1c000
	v_add_u32_e32 v140, s77, v167
	v_add_u32_e32 v176, s78, v167
	ds_read_b128 v[128:131], v140
	ds_read_b128 v[132:135], v140 offset:1024
	ds_read_b128 v[136:139], v140 offset:2048
	ds_read_b128 v[140:143], v140 offset:3072
	ds_read_b128 v[156:159], v176
	ds_read_b128 v[160:163], v176 offset:1024
	ds_read_b128 v[172:175], v176 offset:2048
	ds_read_b128 v[176:179], v176 offset:3072
	s_mov_b64 vcc, s[48:49]
	s_add_u32 s48, s48, 0x40000
	s_addc_u32 s49, s49, 0
	s_mov_b32 m0, s60
	ds_read_b128 v[180:183], v171 offset:32768
	ds_read_b128 v[184:187], v171 offset:33792
	ds_read_b128 v[190:193], v171 offset:34816
	ds_read_b128 v[194:197], v171 offset:35840
	ds_read_b128 v[198:201], v171 offset:36864
	ds_read_b128 v[202:205], v171 offset:37888
	ds_read_b128 v[206:209], v171 offset:38912
	global_load_lds_dwordx4 v144, s[48:49]
	s_mov_b32 m0, s61
	ds_read_b128 v[210:213], v171 offset:39936
	global_load_lds_dwordx4 v146, s[48:49]
	s_waitcnt vmcnt(8)
	s_waitcnt lgkmcnt(0)
	s_barrier
	s_setprio 1
	v_mfma_f32_16x16x32_bf16 v[124:127], v[128:131], v[180:183], v[124:127]
	v_mfma_f32_16x16x32_bf16 v[120:123], v[136:139], v[180:183], v[120:123]
	v_mfma_f32_16x16x32_bf16 v[108:111], v[128:131], v[190:193], v[108:111]
	v_mfma_f32_16x16x32_bf16 v[104:107], v[136:139], v[190:193], v[104:107]
	v_mfma_f32_16x16x32_bf16 v[92:95], v[128:131], v[198:201], v[92:95]
	v_mfma_f32_16x16x32_bf16 v[88:91], v[136:139], v[198:201], v[88:91]
	v_mfma_f32_16x16x32_bf16 v[76:79], v[128:131], v[206:209], v[76:79]
	v_mfma_f32_16x16x32_bf16 v[72:75], v[136:139], v[206:209], v[72:75]
	v_mfma_f32_16x16x32_bf16 v[124:127], v[132:135], v[184:187], v[124:127]
	v_mfma_f32_16x16x32_bf16 v[120:123], v[140:143], v[184:187], v[120:123]
	v_mfma_f32_16x16x32_bf16 v[108:111], v[132:135], v[194:197], v[108:111]
	v_mfma_f32_16x16x32_bf16 v[104:107], v[140:143], v[194:197], v[104:107]
	v_mfma_f32_16x16x32_bf16 v[92:95], v[132:135], v[202:205], v[92:95]
	v_mfma_f32_16x16x32_bf16 v[88:91], v[140:143], v[202:205], v[88:91]
	v_mfma_f32_16x16x32_bf16 v[76:79], v[132:135], v[210:213], v[76:79]
	v_mfma_f32_16x16x32_bf16 v[72:75], v[140:143], v[210:213], v[72:75]
	v_mfma_f32_16x16x32_bf16 v[116:119], v[156:159], v[180:183], v[116:119]
	v_mfma_f32_16x16x32_bf16 v[112:115], v[172:175], v[180:183], v[112:115]
	v_mfma_f32_16x16x32_bf16 v[100:103], v[156:159], v[190:193], v[100:103]
	v_mfma_f32_16x16x32_bf16 v[96:99], v[172:175], v[190:193], v[96:99]
	v_mfma_f32_16x16x32_bf16 v[84:87], v[156:159], v[198:201], v[84:87]
	v_mfma_f32_16x16x32_bf16 v[80:83], v[172:175], v[198:201], v[80:83]
	v_mfma_f32_16x16x32_bf16 v[68:71], v[156:159], v[206:209], v[68:71]
	v_mfma_f32_16x16x32_bf16 v[64:67], v[172:175], v[206:209], v[64:67]
	v_mfma_f32_16x16x32_bf16 v[116:119], v[160:163], v[184:187], v[116:119]
	v_mfma_f32_16x16x32_bf16 v[112:115], v[176:179], v[184:187], v[112:115]
	v_mfma_f32_16x16x32_bf16 v[100:103], v[160:163], v[194:197], v[100:103]
	v_mfma_f32_16x16x32_bf16 v[96:99], v[176:179], v[194:197], v[96:99]
	v_mfma_f32_16x16x32_bf16 v[84:87], v[160:163], v[202:205], v[84:87]
	v_mfma_f32_16x16x32_bf16 v[80:83], v[176:179], v[202:205], v[80:83]
	v_mfma_f32_16x16x32_bf16 v[68:71], v[160:163], v[210:213], v[68:71]
	v_mfma_f32_16x16x32_bf16 v[64:67], v[176:179], v[210:213], v[64:67]
	s_setprio 0
	s_barrier
	s_add_i32 s48, s77, s57
	s_add_i32 m0, s48, 0xffffff80
	ds_read_b128 v[180:183], v171 offset:49152
	ds_read_b128 v[184:187], v171 offset:50176
	ds_read_b128 v[190:193], v171 offset:51200
	ds_read_b128 v[194:197], v171 offset:52224
	global_load_lds_dwordx4 v150, s[100:101] offset:128
	s_add_i32 m0, s48, 0x1f80
	s_add_i32 s48, s78, s57
	global_load_lds_dwordx4 v148, s[100:101] offset:128
	s_add_u32 s100, s100, s8
	s_addc_u32 s101, s101, s9
	s_add_i32 m0, s48, 0xffffff80
	ds_read_b128 v[210:213], v171 offset:56320
	global_load_lds_dwordx4 v150, s[100:101] offset:128
	s_add_i32 m0, s48, 0x1f80
	ds_read_b128 v[206:209], v171 offset:55296
	global_load_lds_dwordx4 v148, s[100:101] offset:128
	s_add_i32 m0, s65, 0xffffff80
	ds_read_b128 v[202:205], v171 offset:54272
	global_load_lds_dwordx4 v144, vcc offset:128
	s_add_i32 m0, s66, 0xffffff80
	ds_read_b128 v[198:201], v171 offset:53248
	global_load_lds_dwordx4 v146, vcc offset:128
	s_waitcnt vmcnt(8)
	s_waitcnt lgkmcnt(0)
	s_barrier
	s_setprio 1
	v_mfma_f32_16x16x32_bf16 v[60:63], v[128:131], v[180:183], v[60:63]
	v_mfma_f32_16x16x32_bf16 v[56:59], v[136:139], v[180:183], v[56:59]
	v_mfma_f32_16x16x32_bf16 v[44:47], v[128:131], v[190:193], v[44:47]
	v_mfma_f32_16x16x32_bf16 v[40:43], v[136:139], v[190:193], v[40:43]
	v_mfma_f32_16x16x32_bf16 v[28:31], v[128:131], v[198:201], v[28:31]
	v_mfma_f32_16x16x32_bf16 v[24:27], v[136:139], v[198:201], v[24:27]
	v_mfma_f32_16x16x32_bf16 v[12:15], v[128:131], v[206:209], v[12:15]
	v_mfma_f32_16x16x32_bf16 v[8:11], v[136:139], v[206:209], v[8:11]
	v_mfma_f32_16x16x32_bf16 v[60:63], v[132:135], v[184:187], v[60:63]
	v_mfma_f32_16x16x32_bf16 v[56:59], v[140:143], v[184:187], v[56:59]
	v_mfma_f32_16x16x32_bf16 v[44:47], v[132:135], v[194:197], v[44:47]
	v_mfma_f32_16x16x32_bf16 v[40:43], v[140:143], v[194:197], v[40:43]
	v_mfma_f32_16x16x32_bf16 v[28:31], v[132:135], v[202:205], v[28:31]
	v_mfma_f32_16x16x32_bf16 v[24:27], v[140:143], v[202:205], v[24:27]
	v_mfma_f32_16x16x32_bf16 v[12:15], v[132:135], v[210:213], v[12:15]
	v_mfma_f32_16x16x32_bf16 v[8:11], v[140:143], v[210:213], v[8:11]
	v_mfma_f32_16x16x32_bf16 v[52:55], v[156:159], v[180:183], v[52:55]
	v_mfma_f32_16x16x32_bf16 v[48:51], v[172:175], v[180:183], v[48:51]
	v_mfma_f32_16x16x32_bf16 v[36:39], v[156:159], v[190:193], v[36:39]
	v_mfma_f32_16x16x32_bf16 v[32:35], v[172:175], v[190:193], v[32:35]
	v_mfma_f32_16x16x32_bf16 v[20:23], v[156:159], v[198:201], v[20:23]
	v_mfma_f32_16x16x32_bf16 v[16:19], v[172:175], v[198:201], v[16:19]
	v_mfma_f32_16x16x32_bf16 v[4:7], v[156:159], v[206:209], v[4:7]
	v_mfma_f32_16x16x32_bf16 v[0:3], v[172:175], v[206:209], v[0:3]
	v_mfma_f32_16x16x32_bf16 v[52:55], v[160:163], v[184:187], v[52:55]
	v_mfma_f32_16x16x32_bf16 v[48:51], v[176:179], v[184:187], v[48:51]
	v_mfma_f32_16x16x32_bf16 v[36:39], v[160:163], v[194:197], v[36:39]
	v_mfma_f32_16x16x32_bf16 v[32:35], v[176:179], v[194:197], v[32:35]
	v_mfma_f32_16x16x32_bf16 v[20:23], v[160:163], v[202:205], v[20:23]
	v_mfma_f32_16x16x32_bf16 v[16:19], v[176:179], v[202:205], v[16:19]
	v_mfma_f32_16x16x32_bf16 v[4:7], v[160:163], v[210:213], v[4:7]
	v_mfma_f32_16x16x32_bf16 v[0:3], v[176:179], v[210:213], v[0:3]
	s_setprio 0
	s_barrier
	s_add_u32 s44, s44, 0x100
	s_addc_u32 s45, s45, 0
	s_add_u32 s51, s51, 0x100
	s_addc_u32 s75, s75, 0
	s_cmp_ge_i32 s76, s67
	s_mov_b32 s48, s76
	s_cbranch_scc0 .LBB0_762

; #define PG8_STAGE(bufoff, gbase, voff) do { _Pragma("unroll") for (int _i = 0; _i < 2; ++_i) \
;         __builtin_amdgcn_global_load_lds((const unsigned*)((const char*)(gbase) + (voff)[_i]), (PG8_LAS unsigned*)(lds + (bufoff) + ldsw + _i * 8192), 16, 0, 0); } while (0)
; #define PG8_LDA(dst, b, h) do { _Pragma("unroll") for (int m = 0; m < 4; ++m) _Pragma("unroll") for (int k = 0; k < 2; ++k) dst[m][k] = *(const PG8_LAS bf16x8*)(lds + PG8_SA(b, h) + aoff + m * 2048 + k * 1024); } while (0)
; #define PG8_LDB(dst, b, h) do { _Pragma("unroll") for (int n = 0; n < 2; ++n) _Pragma("unroll") for (int k = 0; k < 2; ++k) dst[n][k] = *(const PG8_LAS bf16x8*)(lds + PG8_SB(b, h) + boff + n * 2048 + k * 1024); } while (0)
; #define PG8_MMA(ai, bj, At, Bt) do { __builtin_amdgcn_s_setprio(1); _Pragma("unroll") for (int m = 0; m < 4; ++m) _Pragma("unroll") for (int n = 0; n < 2; ++n) _Pragma("unroll") for (int k = 0; k < 2; ++k) \
;         acc[ai][bj][m][n] = __builtin_amdgcn_mfma_f32_16x16x32_bf16(Bt[n][k], At[m][k], acc[ai][bj][m][n], 0, 0, 0); __builtin_amdgcn_s_setprio(0); } while (0)
; #define PG8_WAIT_V(n) asm volatile("s_waitcnt vmcnt(" #n ")" ::: "memory")
; #define PG8_WAIT_L(n) asm volatile("s_waitcnt lgkmcnt(" #n ")" ::: "memory")
; template <class Epi, class Sched, bool ALIGN_EPI = false, bool SP2 = false>
; __device__ __forceinline__ void gemm_phase(PG8_LAS unsigned char* lds, const Gemm g, const Sched& S, const Epi& E) {
;     ...
;             const bool last = (t == nt - 2);
;             const char* a1 = cA + (size_t)(t + 1) * kstep;
;             const char* a2 = last ? nA : cA + (size_t)(t + 2) * kstep; const char* b2 = last ? nB : cB + (size_t)(t + 2) * kstep;
;             const char* a3 = a2 + kstep; const char* b3 = b2 + kstep;
;             if (last && has_next) S.a_ready(nxt);
;             if constexpr (SP2) {
;             PG8_LDB(B0, 0, 0); PG8_LDB(B1, 0, 1); PG8_SCHED; PG8_LDA(At, 0, 0); PG8_STAGE(PG8_SA(1, 1), a1 + hstepA, voffA);
;             PG8_WAIT_V(8); PG8_WAIT_L(0); PG8_BAR; PG8_MMA(0, 0, At, B0); PG8_MMA(0, 1, At, B1); PG8_BAR; PG8_SCHED;
;             PG8_LDA(At, 0, 1); PG8_STAGE(PG8_SB(0, 0), b2, voffB); PG8_STAGE(PG8_SB(0, 1), b2 + hstep, voffB); PG8_STAGE(PG8_SA(0, 0), a2, voffA);
;             PG8_WAIT_V(8); PG8_WAIT_L(0); PG8_BAR; PG8_MMA(1, 0, At, B0); PG8_MMA(1, 1, At, B1); PG8_BAR; PG8_SCHED;
.LBB0_898:
	ds_read_b128 v[150:153], v147
	ds_read_b128 v[154:157], v147 offset:1024
	ds_read_b128 v[158:161], v147 offset:2048
	ds_read_b128 v[162:165], v147 offset:3072
	ds_read_b128 v[166:169], v148
	ds_read_b128 v[170:173], v148 offset:1024
	ds_read_b128 v[174:177], v148 offset:2048
	ds_read_b128 v[178:181], v148 offset:3072
	s_add_i32 s58, s30, 2
	s_add_u32 s59, s10, 0xfffc0080
	s_addc_u32 s31, s11, -1
	s_cmp_eq_u32 s51, s30
	s_cselect_b32 s30, s57, s59
	s_cselect_b32 s31, s23, s31
	s_cselect_b32 s61, s25, s35
	s_cselect_b32 s60, s24, s34
	s_add_i32 m0, s29, 0xc000
	ds_read_b128 v[182:185], v149
	ds_read_b128 v[190:193], v149 offset:1024
	ds_read_b128 v[194:197], v149 offset:2048
	ds_read_b128 v[198:201], v149 offset:3072
	ds_read_b128 v[202:205], v149 offset:4096
	ds_read_b128 v[206:209], v149 offset:5120
	ds_read_b128 v[210:213], v149 offset:6144
	global_load_lds_dwordx4 v136, s[10:11]
	s_add_i32 m0, s29, 0xe000
	ds_read_b128 v[214:217], v149 offset:7168
	global_load_lds_dwordx4 v138, s[10:11]
	s_waitcnt vmcnt(8)
	s_waitcnt lgkmcnt(0)
	s_barrier
	s_setprio 1
	v_mfma_f32_16x16x32_bf16 v[124:127], v[150:153], v[182:185], v[124:127]
	v_mfma_f32_16x16x32_bf16 v[116:119], v[158:161], v[182:185], v[116:119]
	v_mfma_f32_16x16x32_bf16 v[108:111], v[150:153], v[194:197], v[108:111]
	v_mfma_f32_16x16x32_bf16 v[100:103], v[158:161], v[194:197], v[100:103]
	v_mfma_f32_16x16x32_bf16 v[92:95], v[150:153], v[202:205], v[92:95]
	v_mfma_f32_16x16x32_bf16 v[84:87], v[158:161], v[202:205], v[84:87]
	v_mfma_f32_16x16x32_bf16 v[76:79], v[150:153], v[210:213], v[76:79]
	v_mfma_f32_16x16x32_bf16 v[68:71], v[158:161], v[210:213], v[68:71]
	v_mfma_f32_16x16x32_bf16 v[124:127], v[154:157], v[190:193], v[124:127]
	v_mfma_f32_16x16x32_bf16 v[116:119], v[162:165], v[190:193], v[116:119]
	v_mfma_f32_16x16x32_bf16 v[108:111], v[154:157], v[198:201], v[108:111]
	v_mfma_f32_16x16x32_bf16 v[100:103], v[162:165], v[198:201], v[100:103]
	v_mfma_f32_16x16x32_bf16 v[92:95], v[154:157], v[206:209], v[92:95]
	v_mfma_f32_16x16x32_bf16 v[84:87], v[162:165], v[206:209], v[84:87]
	v_mfma_f32_16x16x32_bf16 v[76:79], v[154:157], v[214:217], v[76:79]
	v_mfma_f32_16x16x32_bf16 v[68:71], v[162:165], v[214:217], v[68:71]
	v_mfma_f32_16x16x32_bf16 v[120:123], v[166:169], v[182:185], v[120:123]
	v_mfma_f32_16x16x32_bf16 v[112:115], v[174:177], v[182:185], v[112:115]
	v_mfma_f32_16x16x32_bf16 v[104:107], v[166:169], v[194:197], v[104:107]
	v_mfma_f32_16x16x32_bf16 v[96:99], v[174:177], v[194:197], v[96:99]
	v_mfma_f32_16x16x32_bf16 v[88:91], v[166:169], v[202:205], v[88:91]
	v_mfma_f32_16x16x32_bf16 v[80:83], v[174:177], v[202:205], v[80:83]
	v_mfma_f32_16x16x32_bf16 v[72:75], v[166:169], v[210:213], v[72:75]
	v_mfma_f32_16x16x32_bf16 v[64:67], v[174:177], v[210:213], v[64:67]
	v_mfma_f32_16x16x32_bf16 v[120:123], v[170:173], v[190:193], v[120:123]
	v_mfma_f32_16x16x32_bf16 v[112:115], v[178:181], v[190:193], v[112:115]
	v_mfma_f32_16x16x32_bf16 v[104:107], v[170:173], v[198:201], v[104:107]
	v_mfma_f32_16x16x32_bf16 v[96:99], v[178:181], v[198:201], v[96:99]
	v_mfma_f32_16x16x32_bf16 v[88:91], v[170:173], v[206:209], v[88:91]
	v_mfma_f32_16x16x32_bf16 v[80:83], v[178:181], v[206:209], v[80:83]
	v_mfma_f32_16x16x32_bf16 v[72:75], v[170:173], v[214:217], v[72:75]
	v_mfma_f32_16x16x32_bf16 v[64:67], v[178:181], v[214:217], v[64:67]
	s_setprio 0
	s_barrier
	s_add_i32 s59, s52, s38
	s_mov_b32 m0, s59
	ds_read_b128 v[182:185], v149 offset:16384
	ds_read_b128 v[190:193], v149 offset:17408
	ds_read_b128 v[194:197], v149 offset:18432
	ds_read_b128 v[198:201], v149 offset:19456
	global_load_lds_dwordx4 v134, s[60:61]
	s_add_i32 m0, s59, 0x2000
	s_mov_b64 s[100:101], s[60:61]
	s_add_i32 s59, s53, s38
	global_load_lds_dwordx4 v132, s[60:61]
	s_add_u32 s60, s60, s4
	s_addc_u32 s61, s61, s5
	s_mov_b32 m0, s59
	ds_read_b128 v[214:217], v149 offset:23552
	global_load_lds_dwordx4 v134, s[60:61]
	s_add_i32 m0, s59, 0x2000
	ds_read_b128 v[210:213], v149 offset:22528
	global_load_lds_dwordx4 v132, s[60:61]
	s_mov_b32 m0, s29
	ds_read_b128 v[206:209], v149 offset:21504
	global_load_lds_dwordx4 v128, s[30:31]
	s_mov_b32 m0, s41
	ds_read_b128 v[202:205], v149 offset:20480
	global_load_lds_dwordx4 v130, s[30:31]
	s_waitcnt vmcnt(8)
	s_waitcnt lgkmcnt(0)
	s_barrier
	s_setprio 1
	v_mfma_f32_16x16x32_bf16 v[60:63], v[150:153], v[182:185], v[60:63]
	v_mfma_f32_16x16x32_bf16 v[52:55], v[158:161], v[182:185], v[52:55]
	v_mfma_f32_16x16x32_bf16 v[44:47], v[150:153], v[194:197], v[44:47]
	v_mfma_f32_16x16x32_bf16 v[36:39], v[158:161], v[194:197], v[36:39]
	v_mfma_f32_16x16x32_bf16 v[28:31], v[150:153], v[202:205], v[28:31]
	v_mfma_f32_16x16x32_bf16 v[20:23], v[158:161], v[202:205], v[20:23]
	v_mfma_f32_16x16x32_bf16 v[12:15], v[150:153], v[210:213], v[12:15]
	v_mfma_f32_16x16x32_bf16 v[4:7], v[158:161], v[210:213], v[4:7]
	v_mfma_f32_16x16x32_bf16 v[60:63], v[154:157], v[190:193], v[60:63]
	v_mfma_f32_16x16x32_bf16 v[52:55], v[162:165], v[190:193], v[52:55]
	v_mfma_f32_16x16x32_bf16 v[44:47], v[154:157], v[198:201], v[44:47]
	v_mfma_f32_16x16x32_bf16 v[36:39], v[162:165], v[198:201], v[36:39]
	v_mfma_f32_16x16x32_bf16 v[28:31], v[154:157], v[206:209], v[28:31]
	v_mfma_f32_16x16x32_bf16 v[20:23], v[162:165], v[206:209], v[20:23]
	v_mfma_f32_16x16x32_bf16 v[12:15], v[154:157], v[214:217], v[12:15]
	v_mfma_f32_16x16x32_bf16 v[4:7], v[162:165], v[214:217], v[4:7]
	v_mfma_f32_16x16x32_bf16 v[56:59], v[166:169], v[182:185], v[56:59]
	v_mfma_f32_16x16x32_bf16 v[48:51], v[174:177], v[182:185], v[48:51]
	v_mfma_f32_16x16x32_bf16 v[40:43], v[166:169], v[194:197], v[40:43]
	v_mfma_f32_16x16x32_bf16 v[32:35], v[174:177], v[194:197], v[32:35]
	v_mfma_f32_16x16x32_bf16 v[24:27], v[166:169], v[202:205], v[24:27]
	v_mfma_f32_16x16x32_bf16 v[16:19], v[174:177], v[202:205], v[16:19]
	v_mfma_f32_16x16x32_bf16 v[8:11], v[166:169], v[210:213], v[8:11]
	v_mfma_f32_16x16x32_bf16 v[0:3], v[174:177], v[210:213], v[0:3]
	v_mfma_f32_16x16x32_bf16 v[56:59], v[170:173], v[190:193], v[56:59]
	v_mfma_f32_16x16x32_bf16 v[48:51], v[178:181], v[190:193], v[48:51]
	v_mfma_f32_16x16x32_bf16 v[40:43], v[170:173], v[198:201], v[40:43]
	v_mfma_f32_16x16x32_bf16 v[32:35], v[178:181], v[198:201], v[32:35]
	v_mfma_f32_16x16x32_bf16 v[24:27], v[170:173], v[206:209], v[24:27]
	v_mfma_f32_16x16x32_bf16 v[16:19], v[178:181], v[206:209], v[16:19]
	v_mfma_f32_16x16x32_bf16 v[8:11], v[170:173], v[214:217], v[8:11]
	v_mfma_f32_16x16x32_bf16 v[0:3], v[178:181], v[214:217], v[0:3]
	s_setprio 0
	s_barrier
; #define PG8_STAGE(bufoff, gbase, voff) do { _Pragma("unroll") for (int _i = 0; _i < 2; ++_i) \
;         __builtin_amdgcn_global_load_lds((const unsigned*)((const char*)(gbase) + (voff)[_i]), (PG8_LAS unsigned*)(lds + (bufoff) + ldsw + _i * 8192), 16, 0, 0); } while (0)
; #define PG8_LDA(dst, b, h) do { _Pragma("unroll") for (int m = 0; m < 4; ++m) _Pragma("unroll") for (int k = 0; k < 2; ++k) dst[m][k] = *(const PG8_LAS bf16x8*)(lds + PG8_SA(b, h) + aoff + m * 2048 + k * 1024); } while (0)
; #define PG8_LDB(dst, b, h) do { _Pragma("unroll") for (int n = 0; n < 2; ++n) _Pragma("unroll") for (int k = 0; k < 2; ++k) dst[n][k] = *(const PG8_LAS bf16x8*)(lds + PG8_SB(b, h) + boff + n * 2048 + k * 1024); } while (0)
; #define PG8_MMA(ai, bj, At, Bt) do { __builtin_amdgcn_s_setprio(1); _Pragma("unroll") for (int m = 0; m < 4; ++m) _Pragma("unroll") for (int n = 0; n < 2; ++n) _Pragma("unroll") for (int k = 0; k < 2; ++k) \
;         acc[ai][bj][m][n] = __builtin_amdgcn_mfma_f32_16x16x32_bf16(Bt[n][k], At[m][k], acc[ai][bj][m][n], 0, 0, 0); __builtin_amdgcn_s_setprio(0); } while (0)
; #define PG8_WAIT_V(n) asm volatile("s_waitcnt vmcnt(" #n ")" ::: "memory")
; #define PG8_WAIT_L(n) asm volatile("s_waitcnt lgkmcnt(" #n ")" ::: "memory")
; #define PG8_BAR __builtin_amdgcn_s_barrier()
; #define PG8_SCHED __builtin_amdgcn_sched_barrier(0)
; template <class Epi, class Sched, bool ALIGN_EPI = false, bool SP2 = false>
; __device__ __forceinline__ void gemm_phase(PG8_LAS unsigned char* lds, const Gemm g, const Sched& S, const Epi& E) {
;     ...
;         for (int t = 0; t < nt; t += 2) {
;             const bool last = (t == nt - 2);
;             const char* a1 = cA + (size_t)(t + 1) * kstep;
;             const char* a2 = last ? nA : cA + (size_t)(t + 2) * kstep; const char* b2 = last ? nB : cB + (size_t)(t + 2) * kstep;
;     ...
;             PG8_LDB(B0, 1, 0); PG8_LDB(B1, 1, 1); PG8_SCHED; PG8_LDA(At, 1, 0); PG8_STAGE(PG8_SA(0, 1), a2 + hstepA, voffA);
;             PG8_WAIT_V(8); PG8_WAIT_L(0); PG8_BAR; PG8_MMA(0, 0, At, B0); PG8_MMA(0, 1, At, B1); PG8_BAR; PG8_SCHED;
;             PG8_LDA(At, 1, 1); PG8_STAGE(PG8_SB(1, 0), b3, voffB); PG8_STAGE(PG8_SB(1, 1), b3 + hstep, voffB); PG8_STAGE(PG8_SA(1, 0), a3, voffA);
;             PG8_WAIT_V(8); PG8_WAIT_L(0); PG8_BAR; PG8_MMA(1, 0, At, B0); PG8_MMA(1, 1, At, B1); PG8_BAR; PG8_SCHED;
	s_add_i32 s59, 0, 0x18000
	s_add_i32 s60, 0, 0x1c000
	v_add_u32_e32 v162, s59, v145
	v_add_u32_e32 v178, s60, v145
	ds_read_b128 v[150:153], v162
	ds_read_b128 v[154:157], v162 offset:1024
	ds_read_b128 v[158:161], v162 offset:2048
	ds_read_b128 v[162:165], v162 offset:3072
	ds_read_b128 v[166:169], v178
	ds_read_b128 v[170:173], v178 offset:1024
	ds_read_b128 v[174:177], v178 offset:2048
	ds_read_b128 v[178:181], v178 offset:3072
	s_mov_b64 vcc, s[30:31]
	s_add_u32 s30, s30, 0x40000
	s_addc_u32 s31, s31, 0
	s_mov_b32 m0, s42
	ds_read_b128 v[182:185], v149 offset:32768
	ds_read_b128 v[190:193], v149 offset:33792
	ds_read_b128 v[194:197], v149 offset:34816
	ds_read_b128 v[198:201], v149 offset:35840
	ds_read_b128 v[202:205], v149 offset:36864
	ds_read_b128 v[206:209], v149 offset:37888
	ds_read_b128 v[210:213], v149 offset:38912
	global_load_lds_dwordx4 v128, s[30:31]
	s_mov_b32 m0, s43
	ds_read_b128 v[214:217], v149 offset:39936
	global_load_lds_dwordx4 v130, s[30:31]
	s_waitcnt vmcnt(8)
	s_waitcnt lgkmcnt(0)
	s_barrier
	s_setprio 1
	v_mfma_f32_16x16x32_bf16 v[124:127], v[150:153], v[182:185], v[124:127]
	v_mfma_f32_16x16x32_bf16 v[116:119], v[158:161], v[182:185], v[116:119]
	v_mfma_f32_16x16x32_bf16 v[108:111], v[150:153], v[194:197], v[108:111]
	v_mfma_f32_16x16x32_bf16 v[100:103], v[158:161], v[194:197], v[100:103]
	v_mfma_f32_16x16x32_bf16 v[92:95], v[150:153], v[202:205], v[92:95]
	v_mfma_f32_16x16x32_bf16 v[84:87], v[158:161], v[202:205], v[84:87]
	v_mfma_f32_16x16x32_bf16 v[76:79], v[150:153], v[210:213], v[76:79]
	v_mfma_f32_16x16x32_bf16 v[68:71], v[158:161], v[210:213], v[68:71]
	v_mfma_f32_16x16x32_bf16 v[124:127], v[154:157], v[190:193], v[124:127]
	v_mfma_f32_16x16x32_bf16 v[116:119], v[162:165], v[190:193], v[116:119]
	v_mfma_f32_16x16x32_bf16 v[108:111], v[154:157], v[198:201], v[108:111]
	v_mfma_f32_16x16x32_bf16 v[100:103], v[162:165], v[198:201], v[100:103]
	v_mfma_f32_16x16x32_bf16 v[92:95], v[154:157], v[206:209], v[92:95]
	v_mfma_f32_16x16x32_bf16 v[84:87], v[162:165], v[206:209], v[84:87]
	v_mfma_f32_16x16x32_bf16 v[76:79], v[154:157], v[214:217], v[76:79]
	v_mfma_f32_16x16x32_bf16 v[68:71], v[162:165], v[214:217], v[68:71]
	v_mfma_f32_16x16x32_bf16 v[120:123], v[166:169], v[182:185], v[120:123]
	v_mfma_f32_16x16x32_bf16 v[112:115], v[174:177], v[182:185], v[112:115]
	v_mfma_f32_16x16x32_bf16 v[104:107], v[166:169], v[194:197], v[104:107]
	v_mfma_f32_16x16x32_bf16 v[96:99], v[174:177], v[194:197], v[96:99]
	v_mfma_f32_16x16x32_bf16 v[88:91], v[166:169], v[202:205], v[88:91]
	v_mfma_f32_16x16x32_bf16 v[80:83], v[174:177], v[202:205], v[80:83]
	v_mfma_f32_16x16x32_bf16 v[72:75], v[166:169], v[210:213], v[72:75]
	v_mfma_f32_16x16x32_bf16 v[64:67], v[174:177], v[210:213], v[64:67]
	v_mfma_f32_16x16x32_bf16 v[120:123], v[170:173], v[190:193], v[120:123]
	v_mfma_f32_16x16x32_bf16 v[112:115], v[178:181], v[190:193], v[112:115]
	v_mfma_f32_16x16x32_bf16 v[104:107], v[170:173], v[198:201], v[104:107]
	v_mfma_f32_16x16x32_bf16 v[96:99], v[178:181], v[198:201], v[96:99]
	v_mfma_f32_16x16x32_bf16 v[88:91], v[170:173], v[206:209], v[88:91]
	v_mfma_f32_16x16x32_bf16 v[80:83], v[178:181], v[206:209], v[80:83]
	v_mfma_f32_16x16x32_bf16 v[72:75], v[170:173], v[214:217], v[72:75]
	v_mfma_f32_16x16x32_bf16 v[64:67], v[178:181], v[214:217], v[64:67]
	s_setprio 0
	s_barrier
	s_add_i32 s30, s59, s38
	s_add_i32 m0, s30, 0xffffff80
	ds_read_b128 v[182:185], v149 offset:49152
	ds_read_b128 v[190:193], v149 offset:50176
	ds_read_b128 v[194:197], v149 offset:51200
	ds_read_b128 v[198:201], v149 offset:52224
	global_load_lds_dwordx4 v134, s[100:101] offset:128
	s_add_i32 m0, s30, 0x1f80
	s_add_i32 s30, s60, s38
	global_load_lds_dwordx4 v132, s[100:101] offset:128
	s_add_u32 s100, s100, s4
	s_addc_u32 s101, s101, s5
	s_add_i32 m0, s30, 0xffffff80
	ds_read_b128 v[214:217], v149 offset:56320
	global_load_lds_dwordx4 v134, s[100:101] offset:128
	s_add_i32 m0, s30, 0x1f80
	ds_read_b128 v[210:213], v149 offset:55296
	global_load_lds_dwordx4 v132, s[100:101] offset:128
	s_add_i32 m0, s47, 0xffffff80
	ds_read_b128 v[206:209], v149 offset:54272
	global_load_lds_dwordx4 v128, vcc offset:128
	s_add_i32 m0, s48, 0xffffff80
	ds_read_b128 v[202:205], v149 offset:53248
	global_load_lds_dwordx4 v130, vcc offset:128
	s_waitcnt vmcnt(8)
	s_waitcnt lgkmcnt(0)
	s_barrier
	s_setprio 1
	v_mfma_f32_16x16x32_bf16 v[60:63], v[150:153], v[182:185], v[60:63]
	v_mfma_f32_16x16x32_bf16 v[52:55], v[158:161], v[182:185], v[52:55]
	v_mfma_f32_16x16x32_bf16 v[44:47], v[150:153], v[194:197], v[44:47]
	v_mfma_f32_16x16x32_bf16 v[36:39], v[158:161], v[194:197], v[36:39]
	v_mfma_f32_16x16x32_bf16 v[28:31], v[150:153], v[202:205], v[28:31]
	v_mfma_f32_16x16x32_bf16 v[20:23], v[158:161], v[202:205], v[20:23]
	v_mfma_f32_16x16x32_bf16 v[12:15], v[150:153], v[210:213], v[12:15]
	v_mfma_f32_16x16x32_bf16 v[4:7], v[158:161], v[210:213], v[4:7]
	v_mfma_f32_16x16x32_bf16 v[60:63], v[154:157], v[190:193], v[60:63]
	v_mfma_f32_16x16x32_bf16 v[52:55], v[162:165], v[190:193], v[52:55]
	v_mfma_f32_16x16x32_bf16 v[44:47], v[154:157], v[198:201], v[44:47]
	v_mfma_f32_16x16x32_bf16 v[36:39], v[162:165], v[198:201], v[36:39]
	v_mfma_f32_16x16x32_bf16 v[28:31], v[154:157], v[206:209], v[28:31]
	v_mfma_f32_16x16x32_bf16 v[20:23], v[162:165], v[206:209], v[20:23]
	v_mfma_f32_16x16x32_bf16 v[12:15], v[154:157], v[214:217], v[12:15]
	v_mfma_f32_16x16x32_bf16 v[4:7], v[162:165], v[214:217], v[4:7]
	v_mfma_f32_16x16x32_bf16 v[56:59], v[166:169], v[182:185], v[56:59]
	v_mfma_f32_16x16x32_bf16 v[48:51], v[174:177], v[182:185], v[48:51]
	v_mfma_f32_16x16x32_bf16 v[40:43], v[166:169], v[194:197], v[40:43]
	v_mfma_f32_16x16x32_bf16 v[32:35], v[174:177], v[194:197], v[32:35]
	v_mfma_f32_16x16x32_bf16 v[24:27], v[166:169], v[202:205], v[24:27]
	v_mfma_f32_16x16x32_bf16 v[16:19], v[174:177], v[202:205], v[16:19]
	v_mfma_f32_16x16x32_bf16 v[8:11], v[166:169], v[210:213], v[8:11]
	v_mfma_f32_16x16x32_bf16 v[0:3], v[174:177], v[210:213], v[0:3]
	v_mfma_f32_16x16x32_bf16 v[56:59], v[170:173], v[190:193], v[56:59]
	v_mfma_f32_16x16x32_bf16 v[48:51], v[178:181], v[190:193], v[48:51]
	v_mfma_f32_16x16x32_bf16 v[40:43], v[170:173], v[198:201], v[40:43]
	v_mfma_f32_16x16x32_bf16 v[32:35], v[178:181], v[198:201], v[32:35]
	v_mfma_f32_16x16x32_bf16 v[24:27], v[170:173], v[206:209], v[24:27]
	v_mfma_f32_16x16x32_bf16 v[16:19], v[178:181], v[206:209], v[16:19]
	v_mfma_f32_16x16x32_bf16 v[8:11], v[170:173], v[214:217], v[8:11]
	v_mfma_f32_16x16x32_bf16 v[0:3], v[178:181], v[214:217], v[0:3]
	s_setprio 0
	s_barrier
	s_add_u32 s10, s10, 0x100
	s_addc_u32 s11, s11, 0
	s_add_u32 s34, s34, 0x100
	s_addc_u32 s35, s35, 0
	s_cmp_ge_i32 s58, s50
	s_mov_b32 s30, s58
	s_cbranch_scc0 .LBB0_898

; #define PG8_STAGE(bufoff, gbase, voff) do { _Pragma("unroll") for (int _i = 0; _i < 2; ++_i) \
;         __builtin_amdgcn_global_load_lds((const unsigned*)((const char*)(gbase) + (voff)[_i]), (PG8_LAS unsigned*)(lds + (bufoff) + ldsw + _i * 8192), 16, 0, 0); } while (0)
; #define PG8_LDA(dst, b, h) do { _Pragma("unroll") for (int m = 0; m < 4; ++m) _Pragma("unroll") for (int k = 0; k < 2; ++k) dst[m][k] = *(const PG8_LAS bf16x8*)(lds + PG8_SA(b, h) + aoff + m * 2048 + k * 1024); } while (0)
; #define PG8_LDB(dst, b, h) do { _Pragma("unroll") for (int n = 0; n < 2; ++n) _Pragma("unroll") for (int k = 0; k < 2; ++k) dst[n][k] = *(const PG8_LAS bf16x8*)(lds + PG8_SB(b, h) + boff + n * 2048 + k * 1024); } while (0)
; #define PG8_MMA(ai, bj, At, Bt) do { __builtin_amdgcn_s_setprio(1); _Pragma("unroll") for (int m = 0; m < 4; ++m) _Pragma("unroll") for (int n = 0; n < 2; ++n) _Pragma("unroll") for (int k = 0; k < 2; ++k) \
;         acc[ai][bj][m][n] = __builtin_amdgcn_mfma_f32_16x16x32_bf16(Bt[n][k], At[m][k], acc[ai][bj][m][n], 0, 0, 0); __builtin_amdgcn_s_setprio(0); } while (0)
; #define PG8_WAIT_V(n) asm volatile("s_waitcnt vmcnt(" #n ")" ::: "memory")
; #define PG8_WAIT_L(n) asm volatile("s_waitcnt lgkmcnt(" #n ")" ::: "memory")
; template <class Epi, class Sched, bool ALIGN_EPI = false, bool SP2 = false>
; __device__ __forceinline__ void gemm_phase(PG8_LAS unsigned char* lds, const Gemm g, const Sched& S, const Epi& E) {
;     ...
;             const bool last = (t == nt - 2);
;             const char* a1 = cA + (size_t)(t + 1) * kstep;
;             const char* a2 = last ? nA : cA + (size_t)(t + 2) * kstep; const char* b2 = last ? nB : cB + (size_t)(t + 2) * kstep;
;             const char* a3 = a2 + kstep; const char* b3 = b2 + kstep;
;             if (last && has_next) S.a_ready(nxt);
;             if constexpr (SP2) {
;             PG8_LDB(B0, 0, 0); PG8_LDB(B1, 0, 1); PG8_SCHED; PG8_LDA(At, 0, 0); PG8_STAGE(PG8_SA(1, 1), a1 + hstepA, voffA);
;             PG8_WAIT_V(8); PG8_WAIT_L(0); PG8_BAR; PG8_MMA(0, 0, At, B0); PG8_MMA(0, 1, At, B1); PG8_BAR; PG8_SCHED;
;             PG8_LDA(At, 0, 1); PG8_STAGE(PG8_SB(0, 0), b2, voffB); PG8_STAGE(PG8_SB(0, 1), b2 + hstep, voffB); PG8_STAGE(PG8_SA(0, 0), a2, voffA);
;             PG8_WAIT_V(8); PG8_WAIT_L(0); PG8_BAR; PG8_MMA(1, 0, At, B0); PG8_MMA(1, 1, At, B1); PG8_BAR; PG8_SCHED;
.LBB0_980:
	ds_read_b128 v[128:131], v169
	ds_read_b128 v[132:135], v169 offset:1024
	ds_read_b128 v[136:139], v169 offset:2048
	ds_read_b128 v[140:143], v169 offset:3072
	ds_read_b128 v[160:163], v170
	ds_read_b128 v[172:175], v170 offset:1024
	ds_read_b128 v[176:179], v170 offset:2048
	ds_read_b128 v[180:183], v170 offset:3072
	s_add_i32 s69, s38, 2
	s_add_u32 s70, s36, 0xfff50080
	s_addc_u32 s39, s37, -1
	s_cmp_eq_u32 s55, s38
	s_cselect_b32 s38, s8, s70
	s_cselect_b32 s39, s9, s39
	s_cselect_b32 s71, s35, s68
	s_cselect_b32 s70, s34, s67
	s_add_i32 m0, s44, 0xc000
	ds_read_b128 v[184:187], v171
	ds_read_b128 v[190:193], v171 offset:1024
	ds_read_b128 v[194:197], v171 offset:2048
	ds_read_b128 v[198:201], v171 offset:3072
	ds_read_b128 v[202:205], v171 offset:4096
	ds_read_b128 v[206:209], v171 offset:5120
	ds_read_b128 v[210:213], v171 offset:6144
	global_load_lds_dwordx4 v152, s[36:37]
	s_add_i32 m0, s44, 0xe000
	ds_read_b128 v[214:217], v171 offset:7168
	global_load_lds_dwordx4 v154, s[36:37]
	s_waitcnt vmcnt(8)
	s_waitcnt lgkmcnt(0)
	s_barrier
	s_setprio 1
	v_mfma_f32_16x16x32_bf16 v[124:127], v[128:131], v[184:187], v[124:127]
	v_mfma_f32_16x16x32_bf16 v[120:123], v[136:139], v[184:187], v[120:123]
	v_mfma_f32_16x16x32_bf16 v[108:111], v[128:131], v[194:197], v[108:111]
	v_mfma_f32_16x16x32_bf16 v[104:107], v[136:139], v[194:197], v[104:107]
	v_mfma_f32_16x16x32_bf16 v[92:95], v[128:131], v[202:205], v[92:95]
	v_mfma_f32_16x16x32_bf16 v[88:91], v[136:139], v[202:205], v[88:91]
	v_mfma_f32_16x16x32_bf16 v[76:79], v[128:131], v[210:213], v[76:79]
	v_mfma_f32_16x16x32_bf16 v[72:75], v[136:139], v[210:213], v[72:75]
	v_mfma_f32_16x16x32_bf16 v[124:127], v[132:135], v[190:193], v[124:127]
	v_mfma_f32_16x16x32_bf16 v[120:123], v[140:143], v[190:193], v[120:123]
	v_mfma_f32_16x16x32_bf16 v[108:111], v[132:135], v[198:201], v[108:111]
	v_mfma_f32_16x16x32_bf16 v[104:107], v[140:143], v[198:201], v[104:107]
	v_mfma_f32_16x16x32_bf16 v[92:95], v[132:135], v[206:209], v[92:95]
	v_mfma_f32_16x16x32_bf16 v[88:91], v[140:143], v[206:209], v[88:91]
	v_mfma_f32_16x16x32_bf16 v[76:79], v[132:135], v[214:217], v[76:79]
	v_mfma_f32_16x16x32_bf16 v[72:75], v[140:143], v[214:217], v[72:75]
	v_mfma_f32_16x16x32_bf16 v[116:119], v[160:163], v[184:187], v[116:119]
	v_mfma_f32_16x16x32_bf16 v[112:115], v[176:179], v[184:187], v[112:115]
	v_mfma_f32_16x16x32_bf16 v[100:103], v[160:163], v[194:197], v[100:103]
	v_mfma_f32_16x16x32_bf16 v[96:99], v[176:179], v[194:197], v[96:99]
	v_mfma_f32_16x16x32_bf16 v[84:87], v[160:163], v[202:205], v[84:87]
	v_mfma_f32_16x16x32_bf16 v[80:83], v[176:179], v[202:205], v[80:83]
	v_mfma_f32_16x16x32_bf16 v[68:71], v[160:163], v[210:213], v[68:71]
	v_mfma_f32_16x16x32_bf16 v[64:67], v[176:179], v[210:213], v[64:67]
	v_mfma_f32_16x16x32_bf16 v[116:119], v[172:175], v[190:193], v[116:119]
	v_mfma_f32_16x16x32_bf16 v[112:115], v[180:183], v[190:193], v[112:115]
	v_mfma_f32_16x16x32_bf16 v[100:103], v[172:175], v[198:201], v[100:103]
	v_mfma_f32_16x16x32_bf16 v[96:99], v[180:183], v[198:201], v[96:99]
	v_mfma_f32_16x16x32_bf16 v[84:87], v[172:175], v[206:209], v[84:87]
	v_mfma_f32_16x16x32_bf16 v[80:83], v[180:183], v[206:209], v[80:83]
	v_mfma_f32_16x16x32_bf16 v[68:71], v[172:175], v[214:217], v[68:71]
	v_mfma_f32_16x16x32_bf16 v[64:67], v[180:183], v[214:217], v[64:67]
	s_setprio 0
	s_barrier
	s_add_i32 s72, s56, s42
	s_mov_b32 m0, s72
	ds_read_b128 v[184:187], v171 offset:16384
	ds_read_b128 v[190:193], v171 offset:17408
	ds_read_b128 v[194:197], v171 offset:18432
	ds_read_b128 v[198:201], v171 offset:19456
	global_load_lds_dwordx4 v150, s[70:71]
	s_add_i32 m0, s72, 0x2000
	s_mov_b64 s[100:101], s[70:71]
	s_add_i32 s72, s57, s42
	global_load_lds_dwordx4 v148, s[70:71]
	s_add_u32 s70, s70, s4
	s_addc_u32 s71, s71, s5
	s_mov_b32 m0, s72
	ds_read_b128 v[214:217], v171 offset:23552
	global_load_lds_dwordx4 v150, s[70:71]
	s_add_i32 m0, s72, 0x2000
	ds_read_b128 v[210:213], v171 offset:22528
	global_load_lds_dwordx4 v148, s[70:71]
	s_mov_b32 m0, s44
	ds_read_b128 v[206:209], v171 offset:21504
	global_load_lds_dwordx4 v144, s[38:39]
	s_mov_b32 m0, s45
	ds_read_b128 v[202:205], v171 offset:20480
	global_load_lds_dwordx4 v146, s[38:39]
	s_waitcnt vmcnt(8)
	s_waitcnt lgkmcnt(0)
	s_barrier
	s_setprio 1
	v_mfma_f32_16x16x32_bf16 v[60:63], v[128:131], v[184:187], v[60:63]
	v_mfma_f32_16x16x32_bf16 v[56:59], v[136:139], v[184:187], v[56:59]
	v_mfma_f32_16x16x32_bf16 v[44:47], v[128:131], v[194:197], v[44:47]
	v_mfma_f32_16x16x32_bf16 v[40:43], v[136:139], v[194:197], v[40:43]
	v_mfma_f32_16x16x32_bf16 v[28:31], v[128:131], v[202:205], v[28:31]
	v_mfma_f32_16x16x32_bf16 v[24:27], v[136:139], v[202:205], v[24:27]
	v_mfma_f32_16x16x32_bf16 v[12:15], v[128:131], v[210:213], v[12:15]
	v_mfma_f32_16x16x32_bf16 v[8:11], v[136:139], v[210:213], v[8:11]
	v_mfma_f32_16x16x32_bf16 v[60:63], v[132:135], v[190:193], v[60:63]
	v_mfma_f32_16x16x32_bf16 v[56:59], v[140:143], v[190:193], v[56:59]
	v_mfma_f32_16x16x32_bf16 v[44:47], v[132:135], v[198:201], v[44:47]
	v_mfma_f32_16x16x32_bf16 v[40:43], v[140:143], v[198:201], v[40:43]
	v_mfma_f32_16x16x32_bf16 v[28:31], v[132:135], v[206:209], v[28:31]
	v_mfma_f32_16x16x32_bf16 v[24:27], v[140:143], v[206:209], v[24:27]
	v_mfma_f32_16x16x32_bf16 v[12:15], v[132:135], v[214:217], v[12:15]
	v_mfma_f32_16x16x32_bf16 v[8:11], v[140:143], v[214:217], v[8:11]
	v_mfma_f32_16x16x32_bf16 v[52:55], v[160:163], v[184:187], v[52:55]
	v_mfma_f32_16x16x32_bf16 v[48:51], v[176:179], v[184:187], v[48:51]
	v_mfma_f32_16x16x32_bf16 v[36:39], v[160:163], v[194:197], v[36:39]
	v_mfma_f32_16x16x32_bf16 v[32:35], v[176:179], v[194:197], v[32:35]
	v_mfma_f32_16x16x32_bf16 v[20:23], v[160:163], v[202:205], v[20:23]
	v_mfma_f32_16x16x32_bf16 v[16:19], v[176:179], v[202:205], v[16:19]
	v_mfma_f32_16x16x32_bf16 v[4:7], v[160:163], v[210:213], v[4:7]
	v_mfma_f32_16x16x32_bf16 v[0:3], v[176:179], v[210:213], v[0:3]
	v_mfma_f32_16x16x32_bf16 v[52:55], v[172:175], v[190:193], v[52:55]
	v_mfma_f32_16x16x32_bf16 v[48:51], v[180:183], v[190:193], v[48:51]
	v_mfma_f32_16x16x32_bf16 v[36:39], v[172:175], v[198:201], v[36:39]
	v_mfma_f32_16x16x32_bf16 v[32:35], v[180:183], v[198:201], v[32:35]
	v_mfma_f32_16x16x32_bf16 v[20:23], v[172:175], v[206:209], v[20:23]
	v_mfma_f32_16x16x32_bf16 v[16:19], v[180:183], v[206:209], v[16:19]
	v_mfma_f32_16x16x32_bf16 v[4:7], v[172:175], v[214:217], v[4:7]
	v_mfma_f32_16x16x32_bf16 v[0:3], v[180:183], v[214:217], v[0:3]
	s_setprio 0
	s_barrier
; #define PG8_STAGE(bufoff, gbase, voff) do { _Pragma("unroll") for (int _i = 0; _i < 2; ++_i) \
;         __builtin_amdgcn_global_load_lds((const unsigned*)((const char*)(gbase) + (voff)[_i]), (PG8_LAS unsigned*)(lds + (bufoff) + ldsw + _i * 8192), 16, 0, 0); } while (0)
; #define PG8_LDA(dst, b, h) do { _Pragma("unroll") for (int m = 0; m < 4; ++m) _Pragma("unroll") for (int k = 0; k < 2; ++k) dst[m][k] = *(const PG8_LAS bf16x8*)(lds + PG8_SA(b, h) + aoff + m * 2048 + k * 1024); } while (0)
; #define PG8_LDB(dst, b, h) do { _Pragma("unroll") for (int n = 0; n < 2; ++n) _Pragma("unroll") for (int k = 0; k < 2; ++k) dst[n][k] = *(const PG8_LAS bf16x8*)(lds + PG8_SB(b, h) + boff + n * 2048 + k * 1024); } while (0)
; #define PG8_MMA(ai, bj, At, Bt) do { __builtin_amdgcn_s_setprio(1); _Pragma("unroll") for (int m = 0; m < 4; ++m) _Pragma("unroll") for (int n = 0; n < 2; ++n) _Pragma("unroll") for (int k = 0; k < 2; ++k) \
;         acc[ai][bj][m][n] = __builtin_amdgcn_mfma_f32_16x16x32_bf16(Bt[n][k], At[m][k], acc[ai][bj][m][n], 0, 0, 0); __builtin_amdgcn_s_setprio(0); } while (0)
; #define PG8_WAIT_V(n) asm volatile("s_waitcnt vmcnt(" #n ")" ::: "memory")
; #define PG8_WAIT_L(n) asm volatile("s_waitcnt lgkmcnt(" #n ")" ::: "memory")
; #define PG8_BAR __builtin_amdgcn_s_barrier()
; #define PG8_SCHED __builtin_amdgcn_sched_barrier(0)
; template <class Epi, class Sched, bool ALIGN_EPI = false, bool SP2 = false>
; __device__ __forceinline__ void gemm_phase(PG8_LAS unsigned char* lds, const Gemm g, const Sched& S, const Epi& E) {
;     ...
;         for (int t = 0; t < nt; t += 2) {
;             const bool last = (t == nt - 2);
;             const char* a1 = cA + (size_t)(t + 1) * kstep;
;             const char* a2 = last ? nA : cA + (size_t)(t + 2) * kstep; const char* b2 = last ? nB : cB + (size_t)(t + 2) * kstep;
;     ...
;             PG8_LDB(B0, 1, 0); PG8_LDB(B1, 1, 1); PG8_SCHED; PG8_LDA(At, 1, 0); PG8_STAGE(PG8_SA(0, 1), a2 + hstepA, voffA);
;             PG8_WAIT_V(8); PG8_WAIT_L(0); PG8_BAR; PG8_MMA(0, 0, At, B0); PG8_MMA(0, 1, At, B1); PG8_BAR; PG8_SCHED;
;             PG8_LDA(At, 1, 1); PG8_STAGE(PG8_SB(1, 0), b3, voffB); PG8_STAGE(PG8_SB(1, 1), b3 + hstep, voffB); PG8_STAGE(PG8_SA(1, 0), a3, voffA);
;             PG8_WAIT_V(8); PG8_WAIT_L(0); PG8_BAR; PG8_MMA(1, 0, At, B0); PG8_MMA(1, 1, At, B1); PG8_BAR; PG8_SCHED;
	s_add_i32 s70, 0, 0x18000
	s_add_i32 s71, 0, 0x1c000
	v_add_u32_e32 v140, s70, v167
	v_add_u32_e32 v180, s71, v167
	ds_read_b128 v[128:131], v140
	ds_read_b128 v[132:135], v140 offset:1024
	ds_read_b128 v[136:139], v140 offset:2048
	ds_read_b128 v[140:143], v140 offset:3072
	ds_read_b128 v[160:163], v180
	ds_read_b128 v[172:175], v180 offset:1024
	ds_read_b128 v[176:179], v180 offset:2048
	ds_read_b128 v[180:183], v180 offset:3072
	s_mov_b64 vcc, s[38:39]
	s_add_u32 s38, s38, 0xb0000
	s_addc_u32 s39, s39, 0
	s_mov_b32 m0, s47
	ds_read_b128 v[184:187], v171 offset:32768
	ds_read_b128 v[190:193], v171 offset:33792
	ds_read_b128 v[194:197], v171 offset:34816
	ds_read_b128 v[198:201], v171 offset:35840
	ds_read_b128 v[202:205], v171 offset:36864
	ds_read_b128 v[206:209], v171 offset:37888
	ds_read_b128 v[210:213], v171 offset:38912
	global_load_lds_dwordx4 v144, s[38:39]
	s_mov_b32 m0, s48
	ds_read_b128 v[214:217], v171 offset:39936
	global_load_lds_dwordx4 v146, s[38:39]
	s_waitcnt vmcnt(8)
	s_waitcnt lgkmcnt(0)
	s_barrier
	s_setprio 1
	v_mfma_f32_16x16x32_bf16 v[124:127], v[128:131], v[184:187], v[124:127]
	v_mfma_f32_16x16x32_bf16 v[120:123], v[136:139], v[184:187], v[120:123]
	v_mfma_f32_16x16x32_bf16 v[108:111], v[128:131], v[194:197], v[108:111]
	v_mfma_f32_16x16x32_bf16 v[104:107], v[136:139], v[194:197], v[104:107]
	v_mfma_f32_16x16x32_bf16 v[92:95], v[128:131], v[202:205], v[92:95]
	v_mfma_f32_16x16x32_bf16 v[88:91], v[136:139], v[202:205], v[88:91]
	v_mfma_f32_16x16x32_bf16 v[76:79], v[128:131], v[210:213], v[76:79]
	v_mfma_f32_16x16x32_bf16 v[72:75], v[136:139], v[210:213], v[72:75]
	v_mfma_f32_16x16x32_bf16 v[124:127], v[132:135], v[190:193], v[124:127]
	v_mfma_f32_16x16x32_bf16 v[120:123], v[140:143], v[190:193], v[120:123]
	v_mfma_f32_16x16x32_bf16 v[108:111], v[132:135], v[198:201], v[108:111]
	v_mfma_f32_16x16x32_bf16 v[104:107], v[140:143], v[198:201], v[104:107]
	v_mfma_f32_16x16x32_bf16 v[92:95], v[132:135], v[206:209], v[92:95]
	v_mfma_f32_16x16x32_bf16 v[88:91], v[140:143], v[206:209], v[88:91]
	v_mfma_f32_16x16x32_bf16 v[76:79], v[132:135], v[214:217], v[76:79]
	v_mfma_f32_16x16x32_bf16 v[72:75], v[140:143], v[214:217], v[72:75]
	v_mfma_f32_16x16x32_bf16 v[116:119], v[160:163], v[184:187], v[116:119]
	v_mfma_f32_16x16x32_bf16 v[112:115], v[176:179], v[184:187], v[112:115]
	v_mfma_f32_16x16x32_bf16 v[100:103], v[160:163], v[194:197], v[100:103]
	v_mfma_f32_16x16x32_bf16 v[96:99], v[176:179], v[194:197], v[96:99]
	v_mfma_f32_16x16x32_bf16 v[84:87], v[160:163], v[202:205], v[84:87]
	v_mfma_f32_16x16x32_bf16 v[80:83], v[176:179], v[202:205], v[80:83]
	v_mfma_f32_16x16x32_bf16 v[68:71], v[160:163], v[210:213], v[68:71]
	v_mfma_f32_16x16x32_bf16 v[64:67], v[176:179], v[210:213], v[64:67]
	v_mfma_f32_16x16x32_bf16 v[116:119], v[172:175], v[190:193], v[116:119]
	v_mfma_f32_16x16x32_bf16 v[112:115], v[180:183], v[190:193], v[112:115]
	v_mfma_f32_16x16x32_bf16 v[100:103], v[172:175], v[198:201], v[100:103]
	v_mfma_f32_16x16x32_bf16 v[96:99], v[180:183], v[198:201], v[96:99]
	v_mfma_f32_16x16x32_bf16 v[84:87], v[172:175], v[206:209], v[84:87]
	v_mfma_f32_16x16x32_bf16 v[80:83], v[180:183], v[206:209], v[80:83]
	v_mfma_f32_16x16x32_bf16 v[68:71], v[172:175], v[214:217], v[68:71]
	v_mfma_f32_16x16x32_bf16 v[64:67], v[180:183], v[214:217], v[64:67]
	s_setprio 0
	s_barrier
	s_add_i32 s38, s70, s42
	s_add_i32 m0, s38, 0xffffff80
	ds_read_b128 v[184:187], v171 offset:49152
	ds_read_b128 v[190:193], v171 offset:50176
	ds_read_b128 v[194:197], v171 offset:51200
	ds_read_b128 v[198:201], v171 offset:52224
	global_load_lds_dwordx4 v150, s[100:101] offset:128
	s_add_i32 m0, s38, 0x1f80
	s_add_i32 s38, s71, s42
	global_load_lds_dwordx4 v148, s[100:101] offset:128
	s_add_u32 s100, s100, s4
	s_addc_u32 s101, s101, s5
	s_add_i32 m0, s38, 0xffffff80
	ds_read_b128 v[214:217], v171 offset:56320
	global_load_lds_dwordx4 v150, s[100:101] offset:128
	s_add_i32 m0, s38, 0x1f80
	ds_read_b128 v[210:213], v171 offset:55296
	global_load_lds_dwordx4 v148, s[100:101] offset:128
	s_add_i32 m0, s51, 0xffffff80
	ds_read_b128 v[206:209], v171 offset:54272
	global_load_lds_dwordx4 v144, vcc offset:128
	s_add_i32 m0, s52, 0xffffff80
	ds_read_b128 v[202:205], v171 offset:53248
	global_load_lds_dwordx4 v146, vcc offset:128
	s_waitcnt vmcnt(8)
	s_waitcnt lgkmcnt(0)
	s_barrier
	s_setprio 1
	v_mfma_f32_16x16x32_bf16 v[60:63], v[128:131], v[184:187], v[60:63]
	v_mfma_f32_16x16x32_bf16 v[56:59], v[136:139], v[184:187], v[56:59]
	v_mfma_f32_16x16x32_bf16 v[44:47], v[128:131], v[194:197], v[44:47]
	v_mfma_f32_16x16x32_bf16 v[40:43], v[136:139], v[194:197], v[40:43]
	v_mfma_f32_16x16x32_bf16 v[28:31], v[128:131], v[202:205], v[28:31]
	v_mfma_f32_16x16x32_bf16 v[24:27], v[136:139], v[202:205], v[24:27]
	v_mfma_f32_16x16x32_bf16 v[12:15], v[128:131], v[210:213], v[12:15]
	v_mfma_f32_16x16x32_bf16 v[8:11], v[136:139], v[210:213], v[8:11]
	v_mfma_f32_16x16x32_bf16 v[60:63], v[132:135], v[190:193], v[60:63]
	v_mfma_f32_16x16x32_bf16 v[56:59], v[140:143], v[190:193], v[56:59]
	v_mfma_f32_16x16x32_bf16 v[44:47], v[132:135], v[198:201], v[44:47]
	v_mfma_f32_16x16x32_bf16 v[40:43], v[140:143], v[198:201], v[40:43]
	v_mfma_f32_16x16x32_bf16 v[28:31], v[132:135], v[206:209], v[28:31]
	v_mfma_f32_16x16x32_bf16 v[24:27], v[140:143], v[206:209], v[24:27]
	v_mfma_f32_16x16x32_bf16 v[12:15], v[132:135], v[214:217], v[12:15]
	v_mfma_f32_16x16x32_bf16 v[8:11], v[140:143], v[214:217], v[8:11]
	v_mfma_f32_16x16x32_bf16 v[52:55], v[160:163], v[184:187], v[52:55]
	v_mfma_f32_16x16x32_bf16 v[48:51], v[176:179], v[184:187], v[48:51]
	v_mfma_f32_16x16x32_bf16 v[36:39], v[160:163], v[194:197], v[36:39]
	v_mfma_f32_16x16x32_bf16 v[32:35], v[176:179], v[194:197], v[32:35]
	v_mfma_f32_16x16x32_bf16 v[20:23], v[160:163], v[202:205], v[20:23]
	v_mfma_f32_16x16x32_bf16 v[16:19], v[176:179], v[202:205], v[16:19]
	v_mfma_f32_16x16x32_bf16 v[4:7], v[160:163], v[210:213], v[4:7]
	v_mfma_f32_16x16x32_bf16 v[0:3], v[176:179], v[210:213], v[0:3]
	v_mfma_f32_16x16x32_bf16 v[52:55], v[172:175], v[190:193], v[52:55]
	v_mfma_f32_16x16x32_bf16 v[48:51], v[180:183], v[190:193], v[48:51]
	v_mfma_f32_16x16x32_bf16 v[36:39], v[172:175], v[198:201], v[36:39]
	v_mfma_f32_16x16x32_bf16 v[32:35], v[180:183], v[198:201], v[32:35]
	v_mfma_f32_16x16x32_bf16 v[20:23], v[172:175], v[206:209], v[20:23]
	v_mfma_f32_16x16x32_bf16 v[16:19], v[180:183], v[206:209], v[16:19]
	v_mfma_f32_16x16x32_bf16 v[4:7], v[172:175], v[214:217], v[4:7]
	v_mfma_f32_16x16x32_bf16 v[0:3], v[180:183], v[214:217], v[0:3]
	s_setprio 0
	s_barrier
	s_add_u32 s36, s36, 0x100
	s_addc_u32 s37, s37, 0
	s_add_u32 s67, s67, 0x100
	s_addc_u32 s68, s68, 0
	s_cmp_ge_i32 s69, s54
	s_mov_b32 s38, s69
	s_cbranch_scc0 .LBB0_980

; #define PG8_STAGE(bufoff, gbase, voff) do { _Pragma("unroll") for (int _i = 0; _i < 2; ++_i) \
;         __builtin_amdgcn_global_load_lds((const unsigned*)((const char*)(gbase) + (voff)[_i]), (PG8_LAS unsigned*)(lds + (bufoff) + ldsw + _i * 8192), 16, 0, 0); } while (0)
; #define PG8_LDA(dst, b, h) do { _Pragma("unroll") for (int m = 0; m < 4; ++m) _Pragma("unroll") for (int k = 0; k < 2; ++k) dst[m][k] = *(const PG8_LAS bf16x8*)(lds + PG8_SA(b, h) + aoff + m * 2048 + k * 1024); } while (0)
; #define PG8_LDB(dst, b, h) do { _Pragma("unroll") for (int n = 0; n < 2; ++n) _Pragma("unroll") for (int k = 0; k < 2; ++k) dst[n][k] = *(const PG8_LAS bf16x8*)(lds + PG8_SB(b, h) + boff + n * 2048 + k * 1024); } while (0)
; #define PG8_MMA(ai, bj, At, Bt) do { __builtin_amdgcn_s_setprio(1); _Pragma("unroll") for (int m = 0; m < 4; ++m) _Pragma("unroll") for (int n = 0; n < 2; ++n) _Pragma("unroll") for (int k = 0; k < 2; ++k) \
;         acc[ai][bj][m][n] = __builtin_amdgcn_mfma_f32_16x16x32_bf16(Bt[n][k], At[m][k], acc[ai][bj][m][n], 0, 0, 0); __builtin_amdgcn_s_setprio(0); } while (0)
; #define PG8_WAIT_V(n) asm volatile("s_waitcnt vmcnt(" #n ")" ::: "memory")
; #define PG8_WAIT_L(n) asm volatile("s_waitcnt lgkmcnt(" #n ")" ::: "memory")
; template <class Epi, class Sched, bool ALIGN_EPI = false, bool SP2 = false>
; __device__ __forceinline__ void gemm_phase(PG8_LAS unsigned char* lds, const Gemm g, const Sched& S, const Epi& E) {
;     ...
;             const bool last = (t == nt - 2);
;             const char* a1 = cA + (size_t)(t + 1) * kstep;
;             const char* a2 = last ? nA : cA + (size_t)(t + 2) * kstep; const char* b2 = last ? nB : cB + (size_t)(t + 2) * kstep;
;             const char* a3 = a2 + kstep; const char* b3 = b2 + kstep;
;             if (last && has_next) S.a_ready(nxt);
;             if constexpr (SP2) {
;             PG8_LDB(B0, 0, 0); PG8_LDB(B1, 0, 1); PG8_SCHED; PG8_LDA(At, 0, 0); PG8_STAGE(PG8_SA(1, 1), a1 + hstepA, voffA);
;             PG8_WAIT_V(8); PG8_WAIT_L(0); PG8_BAR; PG8_MMA(0, 0, At, B0); PG8_MMA(0, 1, At, B1); PG8_BAR; PG8_SCHED;
;             PG8_LDA(At, 0, 1); PG8_STAGE(PG8_SB(0, 0), b2, voffB); PG8_STAGE(PG8_SB(0, 1), b2 + hstep, voffB); PG8_STAGE(PG8_SA(0, 0), a2, voffA);
;             PG8_WAIT_V(8); PG8_WAIT_L(0); PG8_BAR; PG8_MMA(1, 0, At, B0); PG8_MMA(1, 1, At, B1); PG8_BAR; PG8_SCHED;
.LBB0_1068:
	ds_read_b128 v[152:155], v148
	ds_read_b128 v[156:159], v148 offset:1024
	ds_read_b128 v[160:163], v148 offset:2048
	ds_read_b128 v[164:167], v148 offset:3072
	ds_read_b128 v[168:171], v149
	ds_read_b128 v[172:175], v149 offset:1024
	ds_read_b128 v[176:179], v149 offset:2048
	ds_read_b128 v[180:183], v149 offset:3072
	s_add_i32 s69, s26, 2
	s_add_u32 s27, s24, 0xfff50080
	s_addc_u32 s28, s25, -1
	s_cmp_eq_u32 s51, s26
	s_cselect_b32 s26, s22, s67
	s_cselect_b32 s29, s21, s28
	s_cselect_b32 s28, s20, s27
	s_cselect_b32 s27, s23, s68
	s_add_i32 m0, s42, 0xc000
	ds_read_b128 v[184:187], v150
	ds_read_b128 v[190:193], v150 offset:1024
	ds_read_b128 v[194:197], v150 offset:2048
	ds_read_b128 v[198:201], v150 offset:3072
	ds_read_b128 v[202:205], v150 offset:4096
	ds_read_b128 v[206:209], v150 offset:5120
	ds_read_b128 v[210:213], v150 offset:6144
	global_load_lds_dwordx4 v132, s[24:25]
	s_add_i32 m0, s42, 0xe000
	ds_read_b128 v[214:217], v150 offset:7168
	global_load_lds_dwordx4 v136, s[24:25]
	s_waitcnt vmcnt(8)
	s_waitcnt lgkmcnt(0)
	s_barrier
	s_setprio 1
	v_mfma_f32_16x16x32_bf16 v[124:127], v[152:155], v[184:187], v[124:127]
	v_mfma_f32_16x16x32_bf16 v[120:123], v[160:163], v[184:187], v[120:123]
	v_mfma_f32_16x16x32_bf16 v[108:111], v[152:155], v[194:197], v[108:111]
	v_mfma_f32_16x16x32_bf16 v[104:107], v[160:163], v[194:197], v[104:107]
	v_mfma_f32_16x16x32_bf16 v[92:95], v[152:155], v[202:205], v[92:95]
	v_mfma_f32_16x16x32_bf16 v[88:91], v[160:163], v[202:205], v[88:91]
	v_mfma_f32_16x16x32_bf16 v[76:79], v[152:155], v[210:213], v[76:79]
	v_mfma_f32_16x16x32_bf16 v[72:75], v[160:163], v[210:213], v[72:75]
	v_mfma_f32_16x16x32_bf16 v[124:127], v[156:159], v[190:193], v[124:127]
	v_mfma_f32_16x16x32_bf16 v[120:123], v[164:167], v[190:193], v[120:123]
	v_mfma_f32_16x16x32_bf16 v[108:111], v[156:159], v[198:201], v[108:111]
	v_mfma_f32_16x16x32_bf16 v[104:107], v[164:167], v[198:201], v[104:107]
	v_mfma_f32_16x16x32_bf16 v[92:95], v[156:159], v[206:209], v[92:95]
	v_mfma_f32_16x16x32_bf16 v[88:91], v[164:167], v[206:209], v[88:91]
	v_mfma_f32_16x16x32_bf16 v[76:79], v[156:159], v[214:217], v[76:79]
	v_mfma_f32_16x16x32_bf16 v[72:75], v[164:167], v[214:217], v[72:75]
	v_mfma_f32_16x16x32_bf16 v[116:119], v[168:171], v[184:187], v[116:119]
	v_mfma_f32_16x16x32_bf16 v[112:115], v[176:179], v[184:187], v[112:115]
	v_mfma_f32_16x16x32_bf16 v[100:103], v[168:171], v[194:197], v[100:103]
	v_mfma_f32_16x16x32_bf16 v[96:99], v[176:179], v[194:197], v[96:99]
	v_mfma_f32_16x16x32_bf16 v[84:87], v[168:171], v[202:205], v[84:87]
	v_mfma_f32_16x16x32_bf16 v[80:83], v[176:179], v[202:205], v[80:83]
	v_mfma_f32_16x16x32_bf16 v[68:71], v[168:171], v[210:213], v[68:71]
	v_mfma_f32_16x16x32_bf16 v[64:67], v[176:179], v[210:213], v[64:67]
	v_mfma_f32_16x16x32_bf16 v[116:119], v[172:175], v[190:193], v[116:119]
	v_mfma_f32_16x16x32_bf16 v[112:115], v[180:183], v[190:193], v[112:115]
	v_mfma_f32_16x16x32_bf16 v[100:103], v[172:175], v[198:201], v[100:103]
	v_mfma_f32_16x16x32_bf16 v[96:99], v[180:183], v[198:201], v[96:99]
	v_mfma_f32_16x16x32_bf16 v[84:87], v[172:175], v[206:209], v[84:87]
	v_mfma_f32_16x16x32_bf16 v[80:83], v[180:183], v[206:209], v[80:83]
	v_mfma_f32_16x16x32_bf16 v[68:71], v[172:175], v[214:217], v[68:71]
	v_mfma_f32_16x16x32_bf16 v[64:67], v[180:183], v[214:217], v[64:67]
	s_setprio 0
	s_barrier
	s_add_i32 s70, s54, s41
	s_mov_b32 m0, s70
	ds_read_b128 v[184:187], v150 offset:16384
	ds_read_b128 v[190:193], v150 offset:17408
	ds_read_b128 v[194:197], v150 offset:18432
	ds_read_b128 v[198:201], v150 offset:19456
	global_load_lds_dwordx4 v128, s[26:27]
	s_add_i32 m0, s70, 0x2000
	s_add_u32 s70, s26, 0xb0000
	s_addc_u32 s71, s27, 0
	s_add_i32 s72, s55, s41
	global_load_lds_dwordx4 v130, s[26:27]
	s_mov_b32 m0, s72
	ds_read_b128 v[214:217], v150 offset:23552
	global_load_lds_dwordx4 v128, s[70:71]
	s_add_i32 m0, s72, 0x2000
	ds_read_b128 v[210:213], v150 offset:22528
	global_load_lds_dwordx4 v130, s[70:71]
	s_mov_b32 m0, s42
	ds_read_b128 v[206:209], v150 offset:21504
	global_load_lds_dwordx4 v128, s[28:29]
	s_mov_b32 m0, s43
	ds_read_b128 v[202:205], v150 offset:20480
	global_load_lds_dwordx4 v130, s[28:29]
	s_waitcnt vmcnt(8)
	s_waitcnt lgkmcnt(0)
	s_barrier
	s_setprio 1
	v_mfma_f32_16x16x32_bf16 v[60:63], v[152:155], v[184:187], v[60:63]
	v_mfma_f32_16x16x32_bf16 v[56:59], v[160:163], v[184:187], v[56:59]
	v_mfma_f32_16x16x32_bf16 v[44:47], v[152:155], v[194:197], v[44:47]
	v_mfma_f32_16x16x32_bf16 v[40:43], v[160:163], v[194:197], v[40:43]
	v_mfma_f32_16x16x32_bf16 v[28:31], v[152:155], v[202:205], v[28:31]
	v_mfma_f32_16x16x32_bf16 v[24:27], v[160:163], v[202:205], v[24:27]
	v_mfma_f32_16x16x32_bf16 v[12:15], v[152:155], v[210:213], v[12:15]
	v_mfma_f32_16x16x32_bf16 v[8:11], v[160:163], v[210:213], v[8:11]
	v_mfma_f32_16x16x32_bf16 v[60:63], v[156:159], v[190:193], v[60:63]
	v_mfma_f32_16x16x32_bf16 v[56:59], v[164:167], v[190:193], v[56:59]
	v_mfma_f32_16x16x32_bf16 v[44:47], v[156:159], v[198:201], v[44:47]
	v_mfma_f32_16x16x32_bf16 v[40:43], v[164:167], v[198:201], v[40:43]
	v_mfma_f32_16x16x32_bf16 v[28:31], v[156:159], v[206:209], v[28:31]
	v_mfma_f32_16x16x32_bf16 v[24:27], v[164:167], v[206:209], v[24:27]
	v_mfma_f32_16x16x32_bf16 v[12:15], v[156:159], v[214:217], v[12:15]
	v_mfma_f32_16x16x32_bf16 v[8:11], v[164:167], v[214:217], v[8:11]
	v_mfma_f32_16x16x32_bf16 v[52:55], v[168:171], v[184:187], v[52:55]
	v_mfma_f32_16x16x32_bf16 v[48:51], v[176:179], v[184:187], v[48:51]
	v_mfma_f32_16x16x32_bf16 v[36:39], v[168:171], v[194:197], v[36:39]
	v_mfma_f32_16x16x32_bf16 v[32:35], v[176:179], v[194:197], v[32:35]
	v_mfma_f32_16x16x32_bf16 v[20:23], v[168:171], v[202:205], v[20:23]
	v_mfma_f32_16x16x32_bf16 v[16:19], v[176:179], v[202:205], v[16:19]
	v_mfma_f32_16x16x32_bf16 v[4:7], v[168:171], v[210:213], v[4:7]
	v_mfma_f32_16x16x32_bf16 v[0:3], v[176:179], v[210:213], v[0:3]
	v_mfma_f32_16x16x32_bf16 v[52:55], v[172:175], v[190:193], v[52:55]
	v_mfma_f32_16x16x32_bf16 v[48:51], v[180:183], v[190:193], v[48:51]
	v_mfma_f32_16x16x32_bf16 v[36:39], v[172:175], v[198:201], v[36:39]
	v_mfma_f32_16x16x32_bf16 v[32:35], v[180:183], v[198:201], v[32:35]
	v_mfma_f32_16x16x32_bf16 v[20:23], v[172:175], v[206:209], v[20:23]
	v_mfma_f32_16x16x32_bf16 v[16:19], v[180:183], v[206:209], v[16:19]
	v_mfma_f32_16x16x32_bf16 v[4:7], v[172:175], v[214:217], v[4:7]
	v_mfma_f32_16x16x32_bf16 v[0:3], v[180:183], v[214:217], v[0:3]
	s_setprio 0
	s_barrier
; #define PG8_STAGE(bufoff, gbase, voff) do { _Pragma("unroll") for (int _i = 0; _i < 2; ++_i) \
;         __builtin_amdgcn_global_load_lds((const unsigned*)((const char*)(gbase) + (voff)[_i]), (PG8_LAS unsigned*)(lds + (bufoff) + ldsw + _i * 8192), 16, 0, 0); } while (0)
; #define PG8_LDA(dst, b, h) do { _Pragma("unroll") for (int m = 0; m < 4; ++m) _Pragma("unroll") for (int k = 0; k < 2; ++k) dst[m][k] = *(const PG8_LAS bf16x8*)(lds + PG8_SA(b, h) + aoff + m * 2048 + k * 1024); } while (0)
; #define PG8_LDB(dst, b, h) do { _Pragma("unroll") for (int n = 0; n < 2; ++n) _Pragma("unroll") for (int k = 0; k < 2; ++k) dst[n][k] = *(const PG8_LAS bf16x8*)(lds + PG8_SB(b, h) + boff + n * 2048 + k * 1024); } while (0)
; #define PG8_MMA(ai, bj, At, Bt) do { __builtin_amdgcn_s_setprio(1); _Pragma("unroll") for (int m = 0; m < 4; ++m) _Pragma("unroll") for (int n = 0; n < 2; ++n) _Pragma("unroll") for (int k = 0; k < 2; ++k) \
;         acc[ai][bj][m][n] = __builtin_amdgcn_mfma_f32_16x16x32_bf16(Bt[n][k], At[m][k], acc[ai][bj][m][n], 0, 0, 0); __builtin_amdgcn_s_setprio(0); } while (0)
; #define PG8_WAIT_V(n) asm volatile("s_waitcnt vmcnt(" #n ")" ::: "memory")
; #define PG8_WAIT_L(n) asm volatile("s_waitcnt lgkmcnt(" #n ")" ::: "memory")
; #define PG8_BAR __builtin_amdgcn_s_barrier()
; #define PG8_SCHED __builtin_amdgcn_sched_barrier(0)
; template <class Epi, class Sched, bool ALIGN_EPI = false, bool SP2 = false>
; __device__ __forceinline__ void gemm_phase(PG8_LAS unsigned char* lds, const Gemm g, const Sched& S, const Epi& E) {
;     ...
;         for (int t = 0; t < nt; t += 2) {
;             const bool last = (t == nt - 2);
;             const char* a1 = cA + (size_t)(t + 1) * kstep;
;             const char* a2 = last ? nA : cA + (size_t)(t + 2) * kstep; const char* b2 = last ? nB : cB + (size_t)(t + 2) * kstep;
;     ...
;             PG8_LDB(B0, 1, 0); PG8_LDB(B1, 1, 1); PG8_SCHED; PG8_LDA(At, 1, 0); PG8_STAGE(PG8_SA(0, 1), a2 + hstepA, voffA);
;             PG8_WAIT_V(8); PG8_WAIT_L(0); PG8_BAR; PG8_MMA(0, 0, At, B0); PG8_MMA(0, 1, At, B1); PG8_BAR; PG8_SCHED;
;             PG8_LDA(At, 1, 1); PG8_STAGE(PG8_SB(1, 0), b3, voffB); PG8_STAGE(PG8_SB(1, 1), b3 + hstep, voffB); PG8_STAGE(PG8_SA(1, 0), a3, voffA);
;             PG8_WAIT_V(8); PG8_WAIT_L(0); PG8_BAR; PG8_MMA(1, 0, At, B0); PG8_MMA(1, 1, At, B1); PG8_BAR; PG8_SCHED;
	s_add_i32 s70, 0, 0x18000
	v_add_u32_e32 v151, s70, v147
	s_add_i32 s71, 0, 0x1c000
	ds_read_b128 v[152:155], v151
	ds_read_b128 v[156:159], v151 offset:1024
	ds_read_b128 v[160:163], v151 offset:2048
	ds_read_b128 v[164:167], v151 offset:3072
	v_add_u32_e32 v151, s71, v147
	ds_read_b128 v[168:171], v151
	ds_read_b128 v[172:175], v151 offset:1024
	ds_read_b128 v[176:179], v151 offset:2048
	ds_read_b128 v[180:183], v151 offset:3072
	s_mov_b64 vcc, s[28:29]
	s_add_u32 s28, s28, 0xb0000
	s_addc_u32 s29, s29, 0
	s_mov_b32 m0, s44
	ds_read_b128 v[184:187], v150 offset:32768
	ds_read_b128 v[190:193], v150 offset:33792
	ds_read_b128 v[194:197], v150 offset:34816
	ds_read_b128 v[198:201], v150 offset:35840
	ds_read_b128 v[202:205], v150 offset:36864
	ds_read_b128 v[206:209], v150 offset:37888
	ds_read_b128 v[210:213], v150 offset:38912
	global_load_lds_dwordx4 v128, s[28:29]
	s_mov_b32 m0, s45
	ds_read_b128 v[214:217], v150 offset:39936
	global_load_lds_dwordx4 v130, s[28:29]
	s_waitcnt vmcnt(8)
	s_waitcnt lgkmcnt(0)
	s_barrier
	s_setprio 1
	v_mfma_f32_16x16x32_bf16 v[124:127], v[152:155], v[184:187], v[124:127]
	v_mfma_f32_16x16x32_bf16 v[120:123], v[160:163], v[184:187], v[120:123]
	v_mfma_f32_16x16x32_bf16 v[108:111], v[152:155], v[194:197], v[108:111]
	v_mfma_f32_16x16x32_bf16 v[104:107], v[160:163], v[194:197], v[104:107]
	v_mfma_f32_16x16x32_bf16 v[92:95], v[152:155], v[202:205], v[92:95]
	v_mfma_f32_16x16x32_bf16 v[88:91], v[160:163], v[202:205], v[88:91]
	v_mfma_f32_16x16x32_bf16 v[76:79], v[152:155], v[210:213], v[76:79]
	v_mfma_f32_16x16x32_bf16 v[72:75], v[160:163], v[210:213], v[72:75]
	v_mfma_f32_16x16x32_bf16 v[124:127], v[156:159], v[190:193], v[124:127]
	v_mfma_f32_16x16x32_bf16 v[120:123], v[164:167], v[190:193], v[120:123]
	v_mfma_f32_16x16x32_bf16 v[108:111], v[156:159], v[198:201], v[108:111]
	v_mfma_f32_16x16x32_bf16 v[104:107], v[164:167], v[198:201], v[104:107]
	v_mfma_f32_16x16x32_bf16 v[92:95], v[156:159], v[206:209], v[92:95]
	v_mfma_f32_16x16x32_bf16 v[88:91], v[164:167], v[206:209], v[88:91]
	v_mfma_f32_16x16x32_bf16 v[76:79], v[156:159], v[214:217], v[76:79]
	v_mfma_f32_16x16x32_bf16 v[72:75], v[164:167], v[214:217], v[72:75]
	v_mfma_f32_16x16x32_bf16 v[116:119], v[168:171], v[184:187], v[116:119]
	v_mfma_f32_16x16x32_bf16 v[112:115], v[176:179], v[184:187], v[112:115]
	v_mfma_f32_16x16x32_bf16 v[100:103], v[168:171], v[194:197], v[100:103]
	v_mfma_f32_16x16x32_bf16 v[96:99], v[176:179], v[194:197], v[96:99]
	v_mfma_f32_16x16x32_bf16 v[84:87], v[168:171], v[202:205], v[84:87]
	v_mfma_f32_16x16x32_bf16 v[80:83], v[176:179], v[202:205], v[80:83]
	v_mfma_f32_16x16x32_bf16 v[68:71], v[168:171], v[210:213], v[68:71]
	v_mfma_f32_16x16x32_bf16 v[64:67], v[176:179], v[210:213], v[64:67]
	v_mfma_f32_16x16x32_bf16 v[116:119], v[172:175], v[190:193], v[116:119]
	v_mfma_f32_16x16x32_bf16 v[112:115], v[180:183], v[190:193], v[112:115]
	v_mfma_f32_16x16x32_bf16 v[100:103], v[172:175], v[198:201], v[100:103]
	v_mfma_f32_16x16x32_bf16 v[96:99], v[180:183], v[198:201], v[96:99]
	v_mfma_f32_16x16x32_bf16 v[84:87], v[172:175], v[206:209], v[84:87]
	v_mfma_f32_16x16x32_bf16 v[80:83], v[180:183], v[206:209], v[80:83]
	v_mfma_f32_16x16x32_bf16 v[68:71], v[172:175], v[214:217], v[68:71]
	v_mfma_f32_16x16x32_bf16 v[64:67], v[180:183], v[214:217], v[64:67]
	s_setprio 0
	s_barrier
	s_add_i32 s28, s70, s41
	s_add_i32 m0, s28, 0xffffff80
	ds_read_b128 v[184:187], v150 offset:49152
	ds_read_b128 v[190:193], v150 offset:50176
	ds_read_b128 v[194:197], v150 offset:51200
	ds_read_b128 v[198:201], v150 offset:52224
	global_load_lds_dwordx4 v128, s[26:27] offset:128
	s_add_i32 m0, s28, 0x1f80
	s_mov_b64 s[100:101], s[26:27]
	s_add_u32 s26, s26, 0xb0080
	s_addc_u32 s27, s27, 0
	s_add_i32 s28, s71, s41
	global_load_lds_dwordx4 v130, s[100:101] offset:128
	s_mov_b32 m0, s28
	ds_read_b128 v[214:217], v150 offset:56320
	global_load_lds_dwordx4 v128, s[26:27]
	s_add_i32 m0, s28, 0x2000
	ds_read_b128 v[210:213], v150 offset:55296
	global_load_lds_dwordx4 v130, s[26:27]
	s_add_i32 m0, s49, 0xffffff80
	ds_read_b128 v[206:209], v150 offset:54272
	global_load_lds_dwordx4 v128, vcc offset:128
	s_add_i32 m0, s50, 0xffffff80
	ds_read_b128 v[202:205], v150 offset:53248
	global_load_lds_dwordx4 v130, vcc offset:128
	s_waitcnt vmcnt(8)
	s_waitcnt lgkmcnt(0)
	s_barrier
	s_setprio 1
	v_mfma_f32_16x16x32_bf16 v[60:63], v[152:155], v[184:187], v[60:63]
	v_mfma_f32_16x16x32_bf16 v[56:59], v[160:163], v[184:187], v[56:59]
	v_mfma_f32_16x16x32_bf16 v[44:47], v[152:155], v[194:197], v[44:47]
	v_mfma_f32_16x16x32_bf16 v[40:43], v[160:163], v[194:197], v[40:43]
	v_mfma_f32_16x16x32_bf16 v[28:31], v[152:155], v[202:205], v[28:31]
	v_mfma_f32_16x16x32_bf16 v[24:27], v[160:163], v[202:205], v[24:27]
	v_mfma_f32_16x16x32_bf16 v[12:15], v[152:155], v[210:213], v[12:15]
	v_mfma_f32_16x16x32_bf16 v[8:11], v[160:163], v[210:213], v[8:11]
	v_mfma_f32_16x16x32_bf16 v[60:63], v[156:159], v[190:193], v[60:63]
	v_mfma_f32_16x16x32_bf16 v[56:59], v[164:167], v[190:193], v[56:59]
	v_mfma_f32_16x16x32_bf16 v[44:47], v[156:159], v[198:201], v[44:47]
	v_mfma_f32_16x16x32_bf16 v[40:43], v[164:167], v[198:201], v[40:43]
	v_mfma_f32_16x16x32_bf16 v[28:31], v[156:159], v[206:209], v[28:31]
	v_mfma_f32_16x16x32_bf16 v[24:27], v[164:167], v[206:209], v[24:27]
	v_mfma_f32_16x16x32_bf16 v[12:15], v[156:159], v[214:217], v[12:15]
	v_mfma_f32_16x16x32_bf16 v[8:11], v[164:167], v[214:217], v[8:11]
	v_mfma_f32_16x16x32_bf16 v[52:55], v[168:171], v[184:187], v[52:55]
	v_mfma_f32_16x16x32_bf16 v[48:51], v[176:179], v[184:187], v[48:51]
	v_mfma_f32_16x16x32_bf16 v[36:39], v[168:171], v[194:197], v[36:39]
	v_mfma_f32_16x16x32_bf16 v[32:35], v[176:179], v[194:197], v[32:35]
	v_mfma_f32_16x16x32_bf16 v[20:23], v[168:171], v[202:205], v[20:23]
	v_mfma_f32_16x16x32_bf16 v[16:19], v[176:179], v[202:205], v[16:19]
	v_mfma_f32_16x16x32_bf16 v[4:7], v[168:171], v[210:213], v[4:7]
	v_mfma_f32_16x16x32_bf16 v[0:3], v[176:179], v[210:213], v[0:3]
	v_mfma_f32_16x16x32_bf16 v[52:55], v[172:175], v[190:193], v[52:55]
	v_mfma_f32_16x16x32_bf16 v[48:51], v[180:183], v[190:193], v[48:51]
	v_mfma_f32_16x16x32_bf16 v[36:39], v[172:175], v[198:201], v[36:39]
	v_mfma_f32_16x16x32_bf16 v[32:35], v[180:183], v[198:201], v[32:35]
	v_mfma_f32_16x16x32_bf16 v[20:23], v[172:175], v[206:209], v[20:23]
	v_mfma_f32_16x16x32_bf16 v[16:19], v[180:183], v[206:209], v[16:19]
	v_mfma_f32_16x16x32_bf16 v[4:7], v[172:175], v[214:217], v[4:7]
	v_mfma_f32_16x16x32_bf16 v[0:3], v[180:183], v[214:217], v[0:3]
	s_setprio 0
	s_barrier
	s_add_u32 s24, s24, 0x100
	s_addc_u32 s25, s25, 0
	s_add_u32 s67, s67, 0x100
	s_addc_u32 s68, s68, 0
	s_cmp_ge_i32 s69, s48
	s_mov_b32 s26, s69
	s_cbranch_scc0 .LBB0_1068

; #define PG8_STAGE(bufoff, gbase, voff) do { _Pragma("unroll") for (int _i = 0; _i < 2; ++_i) \
;         __builtin_amdgcn_global_load_lds((const unsigned*)((const char*)(gbase) + (voff)[_i]), (PG8_LAS unsigned*)(lds + (bufoff) + ldsw + _i * 8192), 16, 0, 0); } while (0)
; #define PG8_LDA(dst, b, h) do { _Pragma("unroll") for (int m = 0; m < 4; ++m) _Pragma("unroll") for (int k = 0; k < 2; ++k) dst[m][k] = *(const PG8_LAS bf16x8*)(lds + PG8_SA(b, h) + aoff + m * 2048 + k * 1024); } while (0)
; #define PG8_LDB(dst, b, h) do { _Pragma("unroll") for (int n = 0; n < 2; ++n) _Pragma("unroll") for (int k = 0; k < 2; ++k) dst[n][k] = *(const PG8_LAS bf16x8*)(lds + PG8_SB(b, h) + boff + n * 2048 + k * 1024); } while (0)
; #define PG8_MMA(ai, bj, At, Bt) do { __builtin_amdgcn_s_setprio(1); _Pragma("unroll") for (int m = 0; m < 4; ++m) _Pragma("unroll") for (int n = 0; n < 2; ++n) _Pragma("unroll") for (int k = 0; k < 2; ++k) \
;         acc[ai][bj][m][n] = __builtin_amdgcn_mfma_f32_16x16x32_bf16(Bt[n][k], At[m][k], acc[ai][bj][m][n], 0, 0, 0); __builtin_amdgcn_s_setprio(0); } while (0)
; #define PG8_WAIT_V(n) asm volatile("s_waitcnt vmcnt(" #n ")" ::: "memory")
; #define PG8_WAIT_L(n) asm volatile("s_waitcnt lgkmcnt(" #n ")" ::: "memory")
; template <class Epi, class Sched, bool ALIGN_EPI = false, bool SP2 = false>
; __device__ __forceinline__ void gemm_phase(PG8_LAS unsigned char* lds, const Gemm g, const Sched& S, const Epi& E) {
;     ...
;             const bool last = (t == nt - 2);
;             const char* a1 = cA + (size_t)(t + 1) * kstep;
;             const char* a2 = last ? nA : cA + (size_t)(t + 2) * kstep; const char* b2 = last ? nB : cB + (size_t)(t + 2) * kstep;
;             const char* a3 = a2 + kstep; const char* b3 = b2 + kstep;
;             if (last && has_next) S.a_ready(nxt);
;             if constexpr (SP2) {
;             PG8_LDB(B0, 0, 0); PG8_LDB(B1, 0, 1); PG8_SCHED; PG8_LDA(At, 0, 0); PG8_STAGE(PG8_SA(1, 1), a1 + hstepA, voffA);
;             PG8_WAIT_V(8); PG8_WAIT_L(0); PG8_BAR; PG8_MMA(0, 0, At, B0); PG8_MMA(0, 1, At, B1); PG8_BAR; PG8_SCHED;
;             PG8_LDA(At, 0, 1); PG8_STAGE(PG8_SB(0, 0), b2, voffB); PG8_STAGE(PG8_SB(0, 1), b2 + hstep, voffB); PG8_STAGE(PG8_SA(0, 0), a2, voffA);
;             PG8_WAIT_V(8); PG8_WAIT_L(0); PG8_BAR; PG8_MMA(1, 0, At, B0); PG8_MMA(1, 1, At, B1); PG8_BAR; PG8_SCHED;
.LBB0_1236:
	ds_read_b128 v[150:153], v147
	ds_read_b128 v[154:157], v147 offset:1024
	ds_read_b128 v[158:161], v147 offset:2048
	ds_read_b128 v[162:165], v147 offset:3072
	ds_read_b128 v[166:169], v148
	ds_read_b128 v[170:173], v148 offset:1024
	ds_read_b128 v[174:177], v148 offset:2048
	ds_read_b128 v[178:181], v148 offset:3072
	s_add_i32 s68, s40, 2
	s_add_u32 s69, s8, 0xfffc0080
	s_addc_u32 s41, s9, -1
	s_cmp_eq_u32 s59, s40
	s_cselect_b32 s40, s67, s69
	s_cselect_b32 s41, s35, s41
	s_cselect_b32 s71, s37, s43
	s_cselect_b32 s70, s36, s42
	s_add_i32 m0, s31, 0xc000
	ds_read_b128 v[182:185], v149
	ds_read_b128 v[190:193], v149 offset:1024
	ds_read_b128 v[194:197], v149 offset:2048
	ds_read_b128 v[198:201], v149 offset:3072
	ds_read_b128 v[202:205], v149 offset:4096
	ds_read_b128 v[206:209], v149 offset:5120
	ds_read_b128 v[210:213], v149 offset:6144
	global_load_lds_dwordx4 v136, s[8:9]
	s_add_i32 m0, s31, 0xe000
	ds_read_b128 v[214:217], v149 offset:7168
	global_load_lds_dwordx4 v138, s[8:9]
	s_waitcnt vmcnt(8)
	s_waitcnt lgkmcnt(0)
	s_barrier
	s_setprio 1
	v_mfma_f32_16x16x32_bf16 v[120:123], v[150:153], v[182:185], v[120:123]
	v_mfma_f32_16x16x32_bf16 v[124:127], v[158:161], v[182:185], v[124:127]
	v_mfma_f32_16x16x32_bf16 v[108:111], v[150:153], v[194:197], v[108:111]
	v_mfma_f32_16x16x32_bf16 v[104:107], v[158:161], v[194:197], v[104:107]
	v_mfma_f32_16x16x32_bf16 v[92:95], v[150:153], v[202:205], v[92:95]
	v_mfma_f32_16x16x32_bf16 v[88:91], v[158:161], v[202:205], v[88:91]
	v_mfma_f32_16x16x32_bf16 v[76:79], v[150:153], v[210:213], v[76:79]
	v_mfma_f32_16x16x32_bf16 v[72:75], v[158:161], v[210:213], v[72:75]
	v_mfma_f32_16x16x32_bf16 v[120:123], v[154:157], v[190:193], v[120:123]
	v_mfma_f32_16x16x32_bf16 v[124:127], v[162:165], v[190:193], v[124:127]
	v_mfma_f32_16x16x32_bf16 v[108:111], v[154:157], v[198:201], v[108:111]
	v_mfma_f32_16x16x32_bf16 v[104:107], v[162:165], v[198:201], v[104:107]
	v_mfma_f32_16x16x32_bf16 v[92:95], v[154:157], v[206:209], v[92:95]
	v_mfma_f32_16x16x32_bf16 v[88:91], v[162:165], v[206:209], v[88:91]
	v_mfma_f32_16x16x32_bf16 v[76:79], v[154:157], v[214:217], v[76:79]
	v_mfma_f32_16x16x32_bf16 v[72:75], v[162:165], v[214:217], v[72:75]
	v_mfma_f32_16x16x32_bf16 v[116:119], v[166:169], v[182:185], v[116:119]
	v_mfma_f32_16x16x32_bf16 v[112:115], v[174:177], v[182:185], v[112:115]
	v_mfma_f32_16x16x32_bf16 v[100:103], v[166:169], v[194:197], v[100:103]
	v_mfma_f32_16x16x32_bf16 v[96:99], v[174:177], v[194:197], v[96:99]
	v_mfma_f32_16x16x32_bf16 v[84:87], v[166:169], v[202:205], v[84:87]
	v_mfma_f32_16x16x32_bf16 v[80:83], v[174:177], v[202:205], v[80:83]
	v_mfma_f32_16x16x32_bf16 v[68:71], v[166:169], v[210:213], v[68:71]
	v_mfma_f32_16x16x32_bf16 v[64:67], v[174:177], v[210:213], v[64:67]
	v_mfma_f32_16x16x32_bf16 v[116:119], v[170:173], v[190:193], v[116:119]
	v_mfma_f32_16x16x32_bf16 v[112:115], v[178:181], v[190:193], v[112:115]
	v_mfma_f32_16x16x32_bf16 v[100:103], v[170:173], v[198:201], v[100:103]
	v_mfma_f32_16x16x32_bf16 v[96:99], v[178:181], v[198:201], v[96:99]
	v_mfma_f32_16x16x32_bf16 v[84:87], v[170:173], v[206:209], v[84:87]
	v_mfma_f32_16x16x32_bf16 v[80:83], v[178:181], v[206:209], v[80:83]
	v_mfma_f32_16x16x32_bf16 v[68:71], v[170:173], v[214:217], v[68:71]
	v_mfma_f32_16x16x32_bf16 v[64:67], v[178:181], v[214:217], v[64:67]
	s_setprio 0
	s_barrier
	s_add_i32 s69, s60, s47
	s_mov_b32 m0, s69
	ds_read_b128 v[182:185], v149 offset:16384
	ds_read_b128 v[190:193], v149 offset:17408
	ds_read_b128 v[194:197], v149 offset:18432
	ds_read_b128 v[198:201], v149 offset:19456
	global_load_lds_dwordx4 v134, s[70:71]
	s_add_i32 m0, s69, 0x2000
	s_mov_b64 s[100:101], s[70:71]
	s_add_i32 s69, s61, s47
	global_load_lds_dwordx4 v132, s[70:71]
	s_add_u32 s70, s70, s4
	s_addc_u32 s71, s71, s5
	s_mov_b32 m0, s69
	ds_read_b128 v[214:217], v149 offset:23552
	global_load_lds_dwordx4 v134, s[70:71]
	s_add_i32 m0, s69, 0x2000
	ds_read_b128 v[210:213], v149 offset:22528
	global_load_lds_dwordx4 v132, s[70:71]
	s_mov_b32 m0, s31
	ds_read_b128 v[206:209], v149 offset:21504
	global_load_lds_dwordx4 v128, s[40:41]
	s_mov_b32 m0, s50
	ds_read_b128 v[202:205], v149 offset:20480
	global_load_lds_dwordx4 v130, s[40:41]
	s_waitcnt vmcnt(8)
	s_waitcnt lgkmcnt(0)
	s_barrier
	s_setprio 1
	v_mfma_f32_16x16x32_bf16 v[60:63], v[150:153], v[182:185], v[60:63]
	v_mfma_f32_16x16x32_bf16 v[56:59], v[158:161], v[182:185], v[56:59]
	v_mfma_f32_16x16x32_bf16 v[44:47], v[150:153], v[194:197], v[44:47]
	v_mfma_f32_16x16x32_bf16 v[40:43], v[158:161], v[194:197], v[40:43]
	v_mfma_f32_16x16x32_bf16 v[28:31], v[150:153], v[202:205], v[28:31]
	v_mfma_f32_16x16x32_bf16 v[24:27], v[158:161], v[202:205], v[24:27]
	v_mfma_f32_16x16x32_bf16 v[12:15], v[150:153], v[210:213], v[12:15]
	v_mfma_f32_16x16x32_bf16 v[8:11], v[158:161], v[210:213], v[8:11]
	v_mfma_f32_16x16x32_bf16 v[60:63], v[154:157], v[190:193], v[60:63]
	v_mfma_f32_16x16x32_bf16 v[56:59], v[162:165], v[190:193], v[56:59]
	v_mfma_f32_16x16x32_bf16 v[44:47], v[154:157], v[198:201], v[44:47]
	v_mfma_f32_16x16x32_bf16 v[40:43], v[162:165], v[198:201], v[40:43]
	v_mfma_f32_16x16x32_bf16 v[28:31], v[154:157], v[206:209], v[28:31]
	v_mfma_f32_16x16x32_bf16 v[24:27], v[162:165], v[206:209], v[24:27]
	v_mfma_f32_16x16x32_bf16 v[12:15], v[154:157], v[214:217], v[12:15]
	v_mfma_f32_16x16x32_bf16 v[8:11], v[162:165], v[214:217], v[8:11]
	v_mfma_f32_16x16x32_bf16 v[52:55], v[166:169], v[182:185], v[52:55]
	v_mfma_f32_16x16x32_bf16 v[48:51], v[174:177], v[182:185], v[48:51]
	v_mfma_f32_16x16x32_bf16 v[36:39], v[166:169], v[194:197], v[36:39]
	v_mfma_f32_16x16x32_bf16 v[32:35], v[174:177], v[194:197], v[32:35]
	v_mfma_f32_16x16x32_bf16 v[20:23], v[166:169], v[202:205], v[20:23]
	v_mfma_f32_16x16x32_bf16 v[16:19], v[174:177], v[202:205], v[16:19]
	v_mfma_f32_16x16x32_bf16 v[4:7], v[166:169], v[210:213], v[4:7]
	v_mfma_f32_16x16x32_bf16 v[0:3], v[174:177], v[210:213], v[0:3]
	v_mfma_f32_16x16x32_bf16 v[52:55], v[170:173], v[190:193], v[52:55]
	v_mfma_f32_16x16x32_bf16 v[48:51], v[178:181], v[190:193], v[48:51]
	v_mfma_f32_16x16x32_bf16 v[36:39], v[170:173], v[198:201], v[36:39]
	v_mfma_f32_16x16x32_bf16 v[32:35], v[178:181], v[198:201], v[32:35]
	v_mfma_f32_16x16x32_bf16 v[20:23], v[170:173], v[206:209], v[20:23]
	v_mfma_f32_16x16x32_bf16 v[16:19], v[178:181], v[206:209], v[16:19]
	v_mfma_f32_16x16x32_bf16 v[4:7], v[170:173], v[214:217], v[4:7]
	v_mfma_f32_16x16x32_bf16 v[0:3], v[178:181], v[214:217], v[0:3]
	s_setprio 0
	s_barrier
; #define PG8_STAGE(bufoff, gbase, voff) do { _Pragma("unroll") for (int _i = 0; _i < 2; ++_i) \
;         __builtin_amdgcn_global_load_lds((const unsigned*)((const char*)(gbase) + (voff)[_i]), (PG8_LAS unsigned*)(lds + (bufoff) + ldsw + _i * 8192), 16, 0, 0); } while (0)
; #define PG8_LDA(dst, b, h) do { _Pragma("unroll") for (int m = 0; m < 4; ++m) _Pragma("unroll") for (int k = 0; k < 2; ++k) dst[m][k] = *(const PG8_LAS bf16x8*)(lds + PG8_SA(b, h) + aoff + m * 2048 + k * 1024); } while (0)
; #define PG8_LDB(dst, b, h) do { _Pragma("unroll") for (int n = 0; n < 2; ++n) _Pragma("unroll") for (int k = 0; k < 2; ++k) dst[n][k] = *(const PG8_LAS bf16x8*)(lds + PG8_SB(b, h) + boff + n * 2048 + k * 1024); } while (0)
; #define PG8_MMA(ai, bj, At, Bt) do { __builtin_amdgcn_s_setprio(1); _Pragma("unroll") for (int m = 0; m < 4; ++m) _Pragma("unroll") for (int n = 0; n < 2; ++n) _Pragma("unroll") for (int k = 0; k < 2; ++k) \
;         acc[ai][bj][m][n] = __builtin_amdgcn_mfma_f32_16x16x32_bf16(Bt[n][k], At[m][k], acc[ai][bj][m][n], 0, 0, 0); __builtin_amdgcn_s_setprio(0); } while (0)
; #define PG8_WAIT_V(n) asm volatile("s_waitcnt vmcnt(" #n ")" ::: "memory")
; #define PG8_WAIT_L(n) asm volatile("s_waitcnt lgkmcnt(" #n ")" ::: "memory")
; #define PG8_BAR __builtin_amdgcn_s_barrier()
; #define PG8_SCHED __builtin_amdgcn_sched_barrier(0)
; template <class Epi, class Sched, bool ALIGN_EPI = false, bool SP2 = false>
; __device__ __forceinline__ void gemm_phase(PG8_LAS unsigned char* lds, const Gemm g, const Sched& S, const Epi& E) {
;     ...
;         for (int t = 0; t < nt; t += 2) {
;             const bool last = (t == nt - 2);
;             const char* a1 = cA + (size_t)(t + 1) * kstep;
;             const char* a2 = last ? nA : cA + (size_t)(t + 2) * kstep; const char* b2 = last ? nB : cB + (size_t)(t + 2) * kstep;
;     ...
;             PG8_LDB(B0, 1, 0); PG8_LDB(B1, 1, 1); PG8_SCHED; PG8_LDA(At, 1, 0); PG8_STAGE(PG8_SA(0, 1), a2 + hstepA, voffA);
;             PG8_WAIT_V(8); PG8_WAIT_L(0); PG8_BAR; PG8_MMA(0, 0, At, B0); PG8_MMA(0, 1, At, B1); PG8_BAR; PG8_SCHED;
;             PG8_LDA(At, 1, 1); PG8_STAGE(PG8_SB(1, 0), b3, voffB); PG8_STAGE(PG8_SB(1, 1), b3 + hstep, voffB); PG8_STAGE(PG8_SA(1, 0), a3, voffA);
;             PG8_WAIT_V(8); PG8_WAIT_L(0); PG8_BAR; PG8_MMA(1, 0, At, B0); PG8_MMA(1, 1, At, B1); PG8_BAR; PG8_SCHED;
	s_add_i32 s69, 0, 0x18000
	s_add_i32 s70, 0, 0x1c000
	v_add_u32_e32 v162, s69, v145
	v_add_u32_e32 v178, s70, v145
	ds_read_b128 v[150:153], v162
	ds_read_b128 v[154:157], v162 offset:1024
	ds_read_b128 v[158:161], v162 offset:2048
	ds_read_b128 v[162:165], v162 offset:3072
	ds_read_b128 v[166:169], v178
	ds_read_b128 v[170:173], v178 offset:1024
	ds_read_b128 v[174:177], v178 offset:2048
	ds_read_b128 v[178:181], v178 offset:3072
	s_mov_b64 vcc, s[40:41]
	s_add_u32 s40, s40, 0x40000
	s_addc_u32 s41, s41, 0
	s_mov_b32 m0, s51
	ds_read_b128 v[182:185], v149 offset:32768
	ds_read_b128 v[190:193], v149 offset:33792
	ds_read_b128 v[194:197], v149 offset:34816
	ds_read_b128 v[198:201], v149 offset:35840
	ds_read_b128 v[202:205], v149 offset:36864
	ds_read_b128 v[206:209], v149 offset:37888
	ds_read_b128 v[210:213], v149 offset:38912
	global_load_lds_dwordx4 v128, s[40:41]
	s_mov_b32 m0, s52
	ds_read_b128 v[214:217], v149 offset:39936
	global_load_lds_dwordx4 v130, s[40:41]
	s_waitcnt vmcnt(8)
	s_waitcnt lgkmcnt(0)
	s_barrier
	s_setprio 1
	v_mfma_f32_16x16x32_bf16 v[120:123], v[150:153], v[182:185], v[120:123]
	v_mfma_f32_16x16x32_bf16 v[124:127], v[158:161], v[182:185], v[124:127]
	v_mfma_f32_16x16x32_bf16 v[108:111], v[150:153], v[194:197], v[108:111]
	v_mfma_f32_16x16x32_bf16 v[104:107], v[158:161], v[194:197], v[104:107]
	v_mfma_f32_16x16x32_bf16 v[92:95], v[150:153], v[202:205], v[92:95]
	v_mfma_f32_16x16x32_bf16 v[88:91], v[158:161], v[202:205], v[88:91]
	v_mfma_f32_16x16x32_bf16 v[76:79], v[150:153], v[210:213], v[76:79]
	v_mfma_f32_16x16x32_bf16 v[72:75], v[158:161], v[210:213], v[72:75]
	v_mfma_f32_16x16x32_bf16 v[120:123], v[154:157], v[190:193], v[120:123]
	v_mfma_f32_16x16x32_bf16 v[124:127], v[162:165], v[190:193], v[124:127]
	v_mfma_f32_16x16x32_bf16 v[108:111], v[154:157], v[198:201], v[108:111]
	v_mfma_f32_16x16x32_bf16 v[104:107], v[162:165], v[198:201], v[104:107]
	v_mfma_f32_16x16x32_bf16 v[92:95], v[154:157], v[206:209], v[92:95]
	v_mfma_f32_16x16x32_bf16 v[88:91], v[162:165], v[206:209], v[88:91]
	v_mfma_f32_16x16x32_bf16 v[76:79], v[154:157], v[214:217], v[76:79]
	v_mfma_f32_16x16x32_bf16 v[72:75], v[162:165], v[214:217], v[72:75]
	v_mfma_f32_16x16x32_bf16 v[116:119], v[166:169], v[182:185], v[116:119]
	v_mfma_f32_16x16x32_bf16 v[112:115], v[174:177], v[182:185], v[112:115]
	v_mfma_f32_16x16x32_bf16 v[100:103], v[166:169], v[194:197], v[100:103]
	v_mfma_f32_16x16x32_bf16 v[96:99], v[174:177], v[194:197], v[96:99]
	v_mfma_f32_16x16x32_bf16 v[84:87], v[166:169], v[202:205], v[84:87]
	v_mfma_f32_16x16x32_bf16 v[80:83], v[174:177], v[202:205], v[80:83]
	v_mfma_f32_16x16x32_bf16 v[68:71], v[166:169], v[210:213], v[68:71]
	v_mfma_f32_16x16x32_bf16 v[64:67], v[174:177], v[210:213], v[64:67]
	v_mfma_f32_16x16x32_bf16 v[116:119], v[170:173], v[190:193], v[116:119]
	v_mfma_f32_16x16x32_bf16 v[112:115], v[178:181], v[190:193], v[112:115]
	v_mfma_f32_16x16x32_bf16 v[100:103], v[170:173], v[198:201], v[100:103]
	v_mfma_f32_16x16x32_bf16 v[96:99], v[178:181], v[198:201], v[96:99]
	v_mfma_f32_16x16x32_bf16 v[84:87], v[170:173], v[206:209], v[84:87]
	v_mfma_f32_16x16x32_bf16 v[80:83], v[178:181], v[206:209], v[80:83]
	v_mfma_f32_16x16x32_bf16 v[68:71], v[170:173], v[214:217], v[68:71]
	v_mfma_f32_16x16x32_bf16 v[64:67], v[178:181], v[214:217], v[64:67]
	s_setprio 0
	s_barrier
	s_add_i32 s40, s69, s47
	s_add_i32 m0, s40, 0xffffff80
	ds_read_b128 v[182:185], v149 offset:49152
	ds_read_b128 v[190:193], v149 offset:50176
	ds_read_b128 v[194:197], v149 offset:51200
	ds_read_b128 v[198:201], v149 offset:52224
	global_load_lds_dwordx4 v134, s[100:101] offset:128
	s_add_i32 m0, s40, 0x1f80
	s_add_i32 s40, s70, s47
	global_load_lds_dwordx4 v132, s[100:101] offset:128
	s_add_u32 s100, s100, s4
	s_addc_u32 s101, s101, s5
	s_add_i32 m0, s40, 0xffffff80
	ds_read_b128 v[214:217], v149 offset:56320
	global_load_lds_dwordx4 v134, s[100:101] offset:128
	s_add_i32 m0, s40, 0x1f80
	ds_read_b128 v[210:213], v149 offset:55296
	global_load_lds_dwordx4 v132, s[100:101] offset:128
	s_add_i32 m0, s55, 0xffffff80
	ds_read_b128 v[206:209], v149 offset:54272
	global_load_lds_dwordx4 v128, vcc offset:128
	s_add_i32 m0, s56, 0xffffff80
	ds_read_b128 v[202:205], v149 offset:53248
	global_load_lds_dwordx4 v130, vcc offset:128
	s_waitcnt vmcnt(8)
	s_waitcnt lgkmcnt(0)
	s_barrier
	s_setprio 1
	v_mfma_f32_16x16x32_bf16 v[60:63], v[150:153], v[182:185], v[60:63]
	v_mfma_f32_16x16x32_bf16 v[56:59], v[158:161], v[182:185], v[56:59]
	v_mfma_f32_16x16x32_bf16 v[44:47], v[150:153], v[194:197], v[44:47]
	v_mfma_f32_16x16x32_bf16 v[40:43], v[158:161], v[194:197], v[40:43]
	v_mfma_f32_16x16x32_bf16 v[28:31], v[150:153], v[202:205], v[28:31]
	v_mfma_f32_16x16x32_bf16 v[24:27], v[158:161], v[202:205], v[24:27]
	v_mfma_f32_16x16x32_bf16 v[12:15], v[150:153], v[210:213], v[12:15]
	v_mfma_f32_16x16x32_bf16 v[8:11], v[158:161], v[210:213], v[8:11]
	v_mfma_f32_16x16x32_bf16 v[60:63], v[154:157], v[190:193], v[60:63]
	v_mfma_f32_16x16x32_bf16 v[56:59], v[162:165], v[190:193], v[56:59]
	v_mfma_f32_16x16x32_bf16 v[44:47], v[154:157], v[198:201], v[44:47]
	v_mfma_f32_16x16x32_bf16 v[40:43], v[162:165], v[198:201], v[40:43]
	v_mfma_f32_16x16x32_bf16 v[28:31], v[154:157], v[206:209], v[28:31]
	v_mfma_f32_16x16x32_bf16 v[24:27], v[162:165], v[206:209], v[24:27]
	v_mfma_f32_16x16x32_bf16 v[12:15], v[154:157], v[214:217], v[12:15]
	v_mfma_f32_16x16x32_bf16 v[8:11], v[162:165], v[214:217], v[8:11]
	v_mfma_f32_16x16x32_bf16 v[52:55], v[166:169], v[182:185], v[52:55]
	v_mfma_f32_16x16x32_bf16 v[48:51], v[174:177], v[182:185], v[48:51]
	v_mfma_f32_16x16x32_bf16 v[36:39], v[166:169], v[194:197], v[36:39]
	v_mfma_f32_16x16x32_bf16 v[32:35], v[174:177], v[194:197], v[32:35]
	v_mfma_f32_16x16x32_bf16 v[20:23], v[166:169], v[202:205], v[20:23]
	v_mfma_f32_16x16x32_bf16 v[16:19], v[174:177], v[202:205], v[16:19]
	v_mfma_f32_16x16x32_bf16 v[4:7], v[166:169], v[210:213], v[4:7]
	v_mfma_f32_16x16x32_bf16 v[0:3], v[174:177], v[210:213], v[0:3]
	v_mfma_f32_16x16x32_bf16 v[52:55], v[170:173], v[190:193], v[52:55]
	v_mfma_f32_16x16x32_bf16 v[48:51], v[178:181], v[190:193], v[48:51]
	v_mfma_f32_16x16x32_bf16 v[36:39], v[170:173], v[198:201], v[36:39]
	v_mfma_f32_16x16x32_bf16 v[32:35], v[178:181], v[198:201], v[32:35]
	v_mfma_f32_16x16x32_bf16 v[20:23], v[170:173], v[206:209], v[20:23]
	v_mfma_f32_16x16x32_bf16 v[16:19], v[178:181], v[206:209], v[16:19]
	v_mfma_f32_16x16x32_bf16 v[4:7], v[170:173], v[214:217], v[4:7]
	v_mfma_f32_16x16x32_bf16 v[0:3], v[178:181], v[214:217], v[0:3]
	s_setprio 0
	s_barrier
	s_add_u32 s8, s8, 0x100
	s_addc_u32 s9, s9, 0
	s_add_u32 s42, s42, 0x100
	s_addc_u32 s43, s43, 0
	s_cmp_ge_i32 s68, s58
	s_mov_b32 s40, s68
	s_cbranch_scc0 .LBB0_1236

; #define PG8_STAGE(bufoff, gbase, voff) do { _Pragma("unroll") for (int _i = 0; _i < 2; ++_i) \
;         __builtin_amdgcn_global_load_lds((const unsigned*)((const char*)(gbase) + (voff)[_i]), (PG8_LAS unsigned*)(lds + (bufoff) + ldsw + _i * 8192), 16, 0, 0); } while (0)
; #define PG8_LDA(dst, b, h) do { _Pragma("unroll") for (int m = 0; m < 4; ++m) _Pragma("unroll") for (int k = 0; k < 2; ++k) dst[m][k] = *(const PG8_LAS bf16x8*)(lds + PG8_SA(b, h) + aoff + m * 2048 + k * 1024); } while (0)
; #define PG8_LDB(dst, b, h) do { _Pragma("unroll") for (int n = 0; n < 2; ++n) _Pragma("unroll") for (int k = 0; k < 2; ++k) dst[n][k] = *(const PG8_LAS bf16x8*)(lds + PG8_SB(b, h) + boff + n * 2048 + k * 1024); } while (0)
; #define PG8_MMA(ai, bj, At, Bt) do { __builtin_amdgcn_s_setprio(1); _Pragma("unroll") for (int m = 0; m < 4; ++m) _Pragma("unroll") for (int n = 0; n < 2; ++n) _Pragma("unroll") for (int k = 0; k < 2; ++k) \
;         acc[ai][bj][m][n] = __builtin_amdgcn_mfma_f32_16x16x32_bf16(Bt[n][k], At[m][k], acc[ai][bj][m][n], 0, 0, 0); __builtin_amdgcn_s_setprio(0); } while (0)
; #define PG8_WAIT_V(n) asm volatile("s_waitcnt vmcnt(" #n ")" ::: "memory")
; #define PG8_WAIT_L(n) asm volatile("s_waitcnt lgkmcnt(" #n ")" ::: "memory")
; template <class Epi, class Sched, bool ALIGN_EPI = false, bool SP2 = false>
; __device__ __forceinline__ void gemm_phase(PG8_LAS unsigned char* lds, const Gemm g, const Sched& S, const Epi& E) {
;     ...
;             const bool last = (t == nt - 2);
;             const char* a1 = cA + (size_t)(t + 1) * kstep;
;             const char* a2 = last ? nA : cA + (size_t)(t + 2) * kstep; const char* b2 = last ? nB : cB + (size_t)(t + 2) * kstep;
;             const char* a3 = a2 + kstep; const char* b3 = b2 + kstep;
;             if (last && has_next) S.a_ready(nxt);
;             if constexpr (SP2) {
;             PG8_LDB(B0, 0, 0); PG8_LDB(B1, 0, 1); PG8_SCHED; PG8_LDA(At, 0, 0); PG8_STAGE(PG8_SA(1, 1), a1 + hstepA, voffA);
;             PG8_WAIT_V(8); PG8_WAIT_L(0); PG8_BAR; PG8_MMA(0, 0, At, B0); PG8_MMA(0, 1, At, B1); PG8_BAR; PG8_SCHED;
;             PG8_LDA(At, 0, 1); PG8_STAGE(PG8_SB(0, 0), b2, voffB); PG8_STAGE(PG8_SB(0, 1), b2 + hstep, voffB); PG8_STAGE(PG8_SA(0, 0), a2, voffA);
;             PG8_WAIT_V(8); PG8_WAIT_L(0); PG8_BAR; PG8_MMA(1, 0, At, B0); PG8_MMA(1, 1, At, B1); PG8_BAR; PG8_SCHED;
.LBB0_1480:
	ds_read_b128 v[162:165], v159
	ds_read_b128 v[166:169], v159 offset:1024
	ds_read_b128 v[170:173], v159 offset:2048
	ds_read_b128 v[174:177], v159 offset:3072
	ds_read_b128 v[178:181], v160
	ds_read_b128 v[182:185], v160 offset:1024
	ds_read_b128 v[190:193], v160 offset:2048
	ds_read_b128 v[194:197], v160 offset:3072
	s_add_i32 s63, s36, 2
	s_add_u32 s64, s10, 0xfffe0080
	s_addc_u32 s37, s11, -1
	s_cmp_eq_u32 s56, s36
	s_cselect_b32 s36, s62, s64
	s_cselect_b32 s37, s29, s37
	s_cselect_b32 s65, s31, s39
	s_cselect_b32 s64, s30, s38
	s_add_i32 m0, s27, 0xc000
	ds_read_b128 v[198:201], v161
	ds_read_b128 v[202:205], v161 offset:1024
	ds_read_b128 v[206:209], v161 offset:2048
	ds_read_b128 v[210:213], v161 offset:3072
	ds_read_b128 v[214:217], v161 offset:4096
	ds_read_b128 v[218:221], v161 offset:5120
	ds_read_b128 v[222:225], v161 offset:6144
	global_load_lds_dwordx4 v138, s[10:11]
	s_add_i32 m0, s27, 0xe000
	ds_read_b128 v[226:229], v161 offset:7168
	global_load_lds_dwordx4 v140, s[10:11]
	s_waitcnt vmcnt(8)
	s_waitcnt lgkmcnt(0)
	s_barrier
	s_setprio 1
	v_mfma_f32_16x16x32_bf16 v[124:127], v[162:165], v[198:201], v[124:127]
	v_mfma_f32_16x16x32_bf16 v[120:123], v[170:173], v[198:201], v[120:123]
	v_mfma_f32_16x16x32_bf16 v[108:111], v[162:165], v[206:209], v[108:111]
	v_mfma_f32_16x16x32_bf16 v[104:107], v[170:173], v[206:209], v[104:107]
	v_mfma_f32_16x16x32_bf16 v[92:95], v[162:165], v[214:217], v[92:95]
	v_mfma_f32_16x16x32_bf16 v[88:91], v[170:173], v[214:217], v[88:91]
	v_mfma_f32_16x16x32_bf16 v[76:79], v[162:165], v[222:225], v[76:79]
	v_mfma_f32_16x16x32_bf16 v[72:75], v[170:173], v[222:225], v[72:75]
	v_mfma_f32_16x16x32_bf16 v[124:127], v[166:169], v[202:205], v[124:127]
	v_mfma_f32_16x16x32_bf16 v[120:123], v[174:177], v[202:205], v[120:123]
	v_mfma_f32_16x16x32_bf16 v[108:111], v[166:169], v[210:213], v[108:111]
	v_mfma_f32_16x16x32_bf16 v[104:107], v[174:177], v[210:213], v[104:107]
	v_mfma_f32_16x16x32_bf16 v[92:95], v[166:169], v[218:221], v[92:95]
	v_mfma_f32_16x16x32_bf16 v[88:91], v[174:177], v[218:221], v[88:91]
	v_mfma_f32_16x16x32_bf16 v[76:79], v[166:169], v[226:229], v[76:79]
	v_mfma_f32_16x16x32_bf16 v[72:75], v[174:177], v[226:229], v[72:75]
	v_mfma_f32_16x16x32_bf16 v[116:119], v[178:181], v[198:201], v[116:119]
	v_mfma_f32_16x16x32_bf16 v[112:115], v[190:193], v[198:201], v[112:115]
	v_mfma_f32_16x16x32_bf16 v[100:103], v[178:181], v[206:209], v[100:103]
	v_mfma_f32_16x16x32_bf16 v[96:99], v[190:193], v[206:209], v[96:99]
	v_mfma_f32_16x16x32_bf16 v[84:87], v[178:181], v[214:217], v[84:87]
	v_mfma_f32_16x16x32_bf16 v[80:83], v[190:193], v[214:217], v[80:83]
	v_mfma_f32_16x16x32_bf16 v[68:71], v[178:181], v[222:225], v[68:71]
	v_mfma_f32_16x16x32_bf16 v[64:67], v[190:193], v[222:225], v[64:67]
	v_mfma_f32_16x16x32_bf16 v[116:119], v[182:185], v[202:205], v[116:119]
	v_mfma_f32_16x16x32_bf16 v[112:115], v[194:197], v[202:205], v[112:115]
	v_mfma_f32_16x16x32_bf16 v[100:103], v[182:185], v[210:213], v[100:103]
	v_mfma_f32_16x16x32_bf16 v[96:99], v[194:197], v[210:213], v[96:99]
	v_mfma_f32_16x16x32_bf16 v[84:87], v[182:185], v[218:221], v[84:87]
	v_mfma_f32_16x16x32_bf16 v[80:83], v[194:197], v[218:221], v[80:83]
	v_mfma_f32_16x16x32_bf16 v[68:71], v[182:185], v[226:229], v[68:71]
	v_mfma_f32_16x16x32_bf16 v[64:67], v[194:197], v[226:229], v[64:67]
	s_setprio 0
	s_barrier
	s_add_i32 s66, s57, s47
	s_mov_b32 m0, s66
	ds_read_b128 v[198:201], v161 offset:16384
	ds_read_b128 v[202:205], v161 offset:17408
	ds_read_b128 v[206:209], v161 offset:18432
	ds_read_b128 v[210:213], v161 offset:19456
	global_load_lds_dwordx4 v136, s[64:65]
	s_add_i32 m0, s66, 0x2000
	s_mov_b64 s[100:101], s[64:65]
	s_add_i32 s66, s58, s47
	global_load_lds_dwordx4 v134, s[64:65]
	s_add_u32 s64, s64, s16
	s_addc_u32 s65, s65, s17
	s_mov_b32 m0, s66
	ds_read_b128 v[226:229], v161 offset:23552
	global_load_lds_dwordx4 v136, s[64:65]
	s_add_i32 m0, s66, 0x2000
	ds_read_b128 v[222:225], v161 offset:22528
	global_load_lds_dwordx4 v134, s[64:65]
	s_mov_b32 m0, s27
	ds_read_b128 v[218:221], v161 offset:21504
	global_load_lds_dwordx4 v130, s[36:37]
	s_mov_b32 m0, s48
	ds_read_b128 v[214:217], v161 offset:20480
	global_load_lds_dwordx4 v132, s[36:37]
	s_waitcnt vmcnt(8)
	s_waitcnt lgkmcnt(0)
	s_barrier
	s_setprio 1
	v_mfma_f32_16x16x32_bf16 v[60:63], v[162:165], v[198:201], v[60:63]
	v_mfma_f32_16x16x32_bf16 v[56:59], v[170:173], v[198:201], v[56:59]
	v_mfma_f32_16x16x32_bf16 v[44:47], v[162:165], v[206:209], v[44:47]
	v_mfma_f32_16x16x32_bf16 v[40:43], v[170:173], v[206:209], v[40:43]
	v_mfma_f32_16x16x32_bf16 v[28:31], v[162:165], v[214:217], v[28:31]
	v_mfma_f32_16x16x32_bf16 v[24:27], v[170:173], v[214:217], v[24:27]
	v_mfma_f32_16x16x32_bf16 v[12:15], v[162:165], v[222:225], v[12:15]
	v_mfma_f32_16x16x32_bf16 v[8:11], v[170:173], v[222:225], v[8:11]
	v_mfma_f32_16x16x32_bf16 v[60:63], v[166:169], v[202:205], v[60:63]
	v_mfma_f32_16x16x32_bf16 v[56:59], v[174:177], v[202:205], v[56:59]
	v_mfma_f32_16x16x32_bf16 v[44:47], v[166:169], v[210:213], v[44:47]
	v_mfma_f32_16x16x32_bf16 v[40:43], v[174:177], v[210:213], v[40:43]
	v_mfma_f32_16x16x32_bf16 v[28:31], v[166:169], v[218:221], v[28:31]
	v_mfma_f32_16x16x32_bf16 v[24:27], v[174:177], v[218:221], v[24:27]
	v_mfma_f32_16x16x32_bf16 v[12:15], v[166:169], v[226:229], v[12:15]
	v_mfma_f32_16x16x32_bf16 v[8:11], v[174:177], v[226:229], v[8:11]
	v_mfma_f32_16x16x32_bf16 v[52:55], v[178:181], v[198:201], v[52:55]
	v_mfma_f32_16x16x32_bf16 v[48:51], v[190:193], v[198:201], v[48:51]
	v_mfma_f32_16x16x32_bf16 v[36:39], v[178:181], v[206:209], v[36:39]
	v_mfma_f32_16x16x32_bf16 v[32:35], v[190:193], v[206:209], v[32:35]
	v_mfma_f32_16x16x32_bf16 v[20:23], v[178:181], v[214:217], v[20:23]
	v_mfma_f32_16x16x32_bf16 v[16:19], v[190:193], v[214:217], v[16:19]
	v_mfma_f32_16x16x32_bf16 v[4:7], v[178:181], v[222:225], v[4:7]
	v_mfma_f32_16x16x32_bf16 v[0:3], v[190:193], v[222:225], v[0:3]
	v_mfma_f32_16x16x32_bf16 v[52:55], v[182:185], v[202:205], v[52:55]
	v_mfma_f32_16x16x32_bf16 v[48:51], v[194:197], v[202:205], v[48:51]
	v_mfma_f32_16x16x32_bf16 v[36:39], v[182:185], v[210:213], v[36:39]
	v_mfma_f32_16x16x32_bf16 v[32:35], v[194:197], v[210:213], v[32:35]
	v_mfma_f32_16x16x32_bf16 v[20:23], v[182:185], v[218:221], v[20:23]
	v_mfma_f32_16x16x32_bf16 v[16:19], v[194:197], v[218:221], v[16:19]
	v_mfma_f32_16x16x32_bf16 v[4:7], v[182:185], v[226:229], v[4:7]
	v_mfma_f32_16x16x32_bf16 v[0:3], v[194:197], v[226:229], v[0:3]
	s_setprio 0
	s_barrier
; #define PG8_STAGE(bufoff, gbase, voff) do { _Pragma("unroll") for (int _i = 0; _i < 2; ++_i) \
;         __builtin_amdgcn_global_load_lds((const unsigned*)((const char*)(gbase) + (voff)[_i]), (PG8_LAS unsigned*)(lds + (bufoff) + ldsw + _i * 8192), 16, 0, 0); } while (0)
; #define PG8_LDA(dst, b, h) do { _Pragma("unroll") for (int m = 0; m < 4; ++m) _Pragma("unroll") for (int k = 0; k < 2; ++k) dst[m][k] = *(const PG8_LAS bf16x8*)(lds + PG8_SA(b, h) + aoff + m * 2048 + k * 1024); } while (0)
; #define PG8_LDB(dst, b, h) do { _Pragma("unroll") for (int n = 0; n < 2; ++n) _Pragma("unroll") for (int k = 0; k < 2; ++k) dst[n][k] = *(const PG8_LAS bf16x8*)(lds + PG8_SB(b, h) + boff + n * 2048 + k * 1024); } while (0)
; #define PG8_MMA(ai, bj, At, Bt) do { __builtin_amdgcn_s_setprio(1); _Pragma("unroll") for (int m = 0; m < 4; ++m) _Pragma("unroll") for (int n = 0; n < 2; ++n) _Pragma("unroll") for (int k = 0; k < 2; ++k) \
;         acc[ai][bj][m][n] = __builtin_amdgcn_mfma_f32_16x16x32_bf16(Bt[n][k], At[m][k], acc[ai][bj][m][n], 0, 0, 0); __builtin_amdgcn_s_setprio(0); } while (0)
; #define PG8_WAIT_V(n) asm volatile("s_waitcnt vmcnt(" #n ")" ::: "memory")
; #define PG8_WAIT_L(n) asm volatile("s_waitcnt lgkmcnt(" #n ")" ::: "memory")
; #define PG8_BAR __builtin_amdgcn_s_barrier()
; #define PG8_SCHED __builtin_amdgcn_sched_barrier(0)
; template <class Epi, class Sched, bool ALIGN_EPI = false, bool SP2 = false>
; __device__ __forceinline__ void gemm_phase(PG8_LAS unsigned char* lds, const Gemm g, const Sched& S, const Epi& E) {
;     ...
;         for (int t = 0; t < nt; t += 2) {
;             const bool last = (t == nt - 2);
;             const char* a1 = cA + (size_t)(t + 1) * kstep;
;             const char* a2 = last ? nA : cA + (size_t)(t + 2) * kstep; const char* b2 = last ? nB : cB + (size_t)(t + 2) * kstep;
;     ...
;             PG8_LDB(B0, 1, 0); PG8_LDB(B1, 1, 1); PG8_SCHED; PG8_LDA(At, 1, 0); PG8_STAGE(PG8_SA(0, 1), a2 + hstepA, voffA);
;             PG8_WAIT_V(8); PG8_WAIT_L(0); PG8_BAR; PG8_MMA(0, 0, At, B0); PG8_MMA(0, 1, At, B1); PG8_BAR; PG8_SCHED;
;             PG8_LDA(At, 1, 1); PG8_STAGE(PG8_SB(1, 0), b3, voffB); PG8_STAGE(PG8_SB(1, 1), b3 + hstep, voffB); PG8_STAGE(PG8_SA(1, 0), a3, voffA);
;             PG8_WAIT_V(8); PG8_WAIT_L(0); PG8_BAR; PG8_MMA(1, 0, At, B0); PG8_MMA(1, 1, At, B1); PG8_BAR; PG8_SCHED;
	s_add_i32 s64, 0, 0x18000
	s_add_i32 s65, 0, 0x1c000
	v_add_u32_e32 v174, s64, v157
	v_add_u32_e32 v194, s65, v157
	ds_read_b128 v[162:165], v174
	ds_read_b128 v[166:169], v174 offset:1024
	ds_read_b128 v[170:173], v174 offset:2048
	ds_read_b128 v[174:177], v174 offset:3072
	ds_read_b128 v[178:181], v194
	ds_read_b128 v[182:185], v194 offset:1024
	ds_read_b128 v[190:193], v194 offset:2048
	ds_read_b128 v[194:197], v194 offset:3072
	s_mov_b64 vcc, s[36:37]
	s_add_u32 s36, s36, 0x20000
	s_addc_u32 s37, s37, 0
	s_mov_b32 m0, s49
	ds_read_b128 v[198:201], v161 offset:32768
	ds_read_b128 v[202:205], v161 offset:33792
	ds_read_b128 v[206:209], v161 offset:34816
	ds_read_b128 v[210:213], v161 offset:35840
	ds_read_b128 v[214:217], v161 offset:36864
	ds_read_b128 v[218:221], v161 offset:37888
	ds_read_b128 v[222:225], v161 offset:38912
	global_load_lds_dwordx4 v130, s[36:37]
	s_mov_b32 m0, s50
	ds_read_b128 v[226:229], v161 offset:39936
	global_load_lds_dwordx4 v132, s[36:37]
	s_waitcnt vmcnt(8)
	s_waitcnt lgkmcnt(0)
	s_barrier
	s_setprio 1
	v_mfma_f32_16x16x32_bf16 v[124:127], v[162:165], v[198:201], v[124:127]
	v_mfma_f32_16x16x32_bf16 v[120:123], v[170:173], v[198:201], v[120:123]
	v_mfma_f32_16x16x32_bf16 v[108:111], v[162:165], v[206:209], v[108:111]
	v_mfma_f32_16x16x32_bf16 v[104:107], v[170:173], v[206:209], v[104:107]
	v_mfma_f32_16x16x32_bf16 v[92:95], v[162:165], v[214:217], v[92:95]
	v_mfma_f32_16x16x32_bf16 v[88:91], v[170:173], v[214:217], v[88:91]
	v_mfma_f32_16x16x32_bf16 v[76:79], v[162:165], v[222:225], v[76:79]
	v_mfma_f32_16x16x32_bf16 v[72:75], v[170:173], v[222:225], v[72:75]
	v_mfma_f32_16x16x32_bf16 v[124:127], v[166:169], v[202:205], v[124:127]
	v_mfma_f32_16x16x32_bf16 v[120:123], v[174:177], v[202:205], v[120:123]
	v_mfma_f32_16x16x32_bf16 v[108:111], v[166:169], v[210:213], v[108:111]
	v_mfma_f32_16x16x32_bf16 v[104:107], v[174:177], v[210:213], v[104:107]
	v_mfma_f32_16x16x32_bf16 v[92:95], v[166:169], v[218:221], v[92:95]
	v_mfma_f32_16x16x32_bf16 v[88:91], v[174:177], v[218:221], v[88:91]
	v_mfma_f32_16x16x32_bf16 v[76:79], v[166:169], v[226:229], v[76:79]
	v_mfma_f32_16x16x32_bf16 v[72:75], v[174:177], v[226:229], v[72:75]
	v_mfma_f32_16x16x32_bf16 v[116:119], v[178:181], v[198:201], v[116:119]
	v_mfma_f32_16x16x32_bf16 v[112:115], v[190:193], v[198:201], v[112:115]
	v_mfma_f32_16x16x32_bf16 v[100:103], v[178:181], v[206:209], v[100:103]
	v_mfma_f32_16x16x32_bf16 v[96:99], v[190:193], v[206:209], v[96:99]
	v_mfma_f32_16x16x32_bf16 v[84:87], v[178:181], v[214:217], v[84:87]
	v_mfma_f32_16x16x32_bf16 v[80:83], v[190:193], v[214:217], v[80:83]
	v_mfma_f32_16x16x32_bf16 v[68:71], v[178:181], v[222:225], v[68:71]
	v_mfma_f32_16x16x32_bf16 v[64:67], v[190:193], v[222:225], v[64:67]
	v_mfma_f32_16x16x32_bf16 v[116:119], v[182:185], v[202:205], v[116:119]
	v_mfma_f32_16x16x32_bf16 v[112:115], v[194:197], v[202:205], v[112:115]
	v_mfma_f32_16x16x32_bf16 v[100:103], v[182:185], v[210:213], v[100:103]
	v_mfma_f32_16x16x32_bf16 v[96:99], v[194:197], v[210:213], v[96:99]
	v_mfma_f32_16x16x32_bf16 v[84:87], v[182:185], v[218:221], v[84:87]
	v_mfma_f32_16x16x32_bf16 v[80:83], v[194:197], v[218:221], v[80:83]
	v_mfma_f32_16x16x32_bf16 v[68:71], v[182:185], v[226:229], v[68:71]
	v_mfma_f32_16x16x32_bf16 v[64:67], v[194:197], v[226:229], v[64:67]
	s_setprio 0
	s_barrier
	s_add_i32 s36, s64, s47
	s_add_i32 m0, s36, 0xffffff80
	ds_read_b128 v[198:201], v161 offset:49152
	ds_read_b128 v[202:205], v161 offset:50176
	ds_read_b128 v[206:209], v161 offset:51200
	ds_read_b128 v[210:213], v161 offset:52224
	global_load_lds_dwordx4 v136, s[100:101] offset:128
	s_add_i32 m0, s36, 0x1f80
	s_add_i32 s36, s65, s47
	global_load_lds_dwordx4 v134, s[100:101] offset:128
	s_add_u32 s100, s100, s16
	s_addc_u32 s101, s101, s17
	s_add_i32 m0, s36, 0xffffff80
	ds_read_b128 v[226:229], v161 offset:56320
	global_load_lds_dwordx4 v136, s[100:101] offset:128
	s_add_i32 m0, s36, 0x1f80
	ds_read_b128 v[222:225], v161 offset:55296
	global_load_lds_dwordx4 v134, s[100:101] offset:128
	s_add_i32 m0, s51, 0xffffff80
	ds_read_b128 v[218:221], v161 offset:54272
	global_load_lds_dwordx4 v130, vcc offset:128
	s_add_i32 m0, s52, 0xffffff80
	ds_read_b128 v[214:217], v161 offset:53248
	global_load_lds_dwordx4 v132, vcc offset:128
	s_waitcnt vmcnt(8)
	s_waitcnt lgkmcnt(0)
	s_barrier
	s_setprio 1
	v_mfma_f32_16x16x32_bf16 v[60:63], v[162:165], v[198:201], v[60:63]
	v_mfma_f32_16x16x32_bf16 v[56:59], v[170:173], v[198:201], v[56:59]
	v_mfma_f32_16x16x32_bf16 v[44:47], v[162:165], v[206:209], v[44:47]
	v_mfma_f32_16x16x32_bf16 v[40:43], v[170:173], v[206:209], v[40:43]
	v_mfma_f32_16x16x32_bf16 v[28:31], v[162:165], v[214:217], v[28:31]
	v_mfma_f32_16x16x32_bf16 v[24:27], v[170:173], v[214:217], v[24:27]
	v_mfma_f32_16x16x32_bf16 v[12:15], v[162:165], v[222:225], v[12:15]
	v_mfma_f32_16x16x32_bf16 v[8:11], v[170:173], v[222:225], v[8:11]
	v_mfma_f32_16x16x32_bf16 v[60:63], v[166:169], v[202:205], v[60:63]
	v_mfma_f32_16x16x32_bf16 v[56:59], v[174:177], v[202:205], v[56:59]
	v_mfma_f32_16x16x32_bf16 v[44:47], v[166:169], v[210:213], v[44:47]
	v_mfma_f32_16x16x32_bf16 v[40:43], v[174:177], v[210:213], v[40:43]
	v_mfma_f32_16x16x32_bf16 v[28:31], v[166:169], v[218:221], v[28:31]
	v_mfma_f32_16x16x32_bf16 v[24:27], v[174:177], v[218:221], v[24:27]
	v_mfma_f32_16x16x32_bf16 v[12:15], v[166:169], v[226:229], v[12:15]
	v_mfma_f32_16x16x32_bf16 v[8:11], v[174:177], v[226:229], v[8:11]
	v_mfma_f32_16x16x32_bf16 v[52:55], v[178:181], v[198:201], v[52:55]
	v_mfma_f32_16x16x32_bf16 v[48:51], v[190:193], v[198:201], v[48:51]
	v_mfma_f32_16x16x32_bf16 v[36:39], v[178:181], v[206:209], v[36:39]
	v_mfma_f32_16x16x32_bf16 v[32:35], v[190:193], v[206:209], v[32:35]
	v_mfma_f32_16x16x32_bf16 v[20:23], v[178:181], v[214:217], v[20:23]
	v_mfma_f32_16x16x32_bf16 v[16:19], v[190:193], v[214:217], v[16:19]
	v_mfma_f32_16x16x32_bf16 v[4:7], v[178:181], v[222:225], v[4:7]
	v_mfma_f32_16x16x32_bf16 v[0:3], v[190:193], v[222:225], v[0:3]
	v_mfma_f32_16x16x32_bf16 v[52:55], v[182:185], v[202:205], v[52:55]
	v_mfma_f32_16x16x32_bf16 v[48:51], v[194:197], v[202:205], v[48:51]
	v_mfma_f32_16x16x32_bf16 v[36:39], v[182:185], v[210:213], v[36:39]
	v_mfma_f32_16x16x32_bf16 v[32:35], v[194:197], v[210:213], v[32:35]
	v_mfma_f32_16x16x32_bf16 v[20:23], v[182:185], v[218:221], v[20:23]
	v_mfma_f32_16x16x32_bf16 v[16:19], v[194:197], v[218:221], v[16:19]
	v_mfma_f32_16x16x32_bf16 v[4:7], v[182:185], v[226:229], v[4:7]
	v_mfma_f32_16x16x32_bf16 v[0:3], v[194:197], v[226:229], v[0:3]
	s_setprio 0
	s_barrier
	s_add_u32 s10, s10, 0x100
	s_addc_u32 s11, s11, 0
	s_add_u32 s38, s38, 0x100
	s_addc_u32 s39, s39, 0
	s_cmp_ge_i32 s63, s53
	s_mov_b32 s36, s63
	s_cbranch_scc0 .LBB0_1480

; #define PG8_STAGE(bufoff, gbase, voff) do { _Pragma("unroll") for (int _i = 0; _i < 2; ++_i) \
;         __builtin_amdgcn_global_load_lds((const unsigned*)((const char*)(gbase) + (voff)[_i]), (PG8_LAS unsigned*)(lds + (bufoff) + ldsw + _i * 8192), 16, 0, 0); } while (0)
; #define PG8_LDA(dst, b, h) do { _Pragma("unroll") for (int m = 0; m < 4; ++m) _Pragma("unroll") for (int k = 0; k < 2; ++k) dst[m][k] = *(const PG8_LAS bf16x8*)(lds + PG8_SA(b, h) + aoff + m * 2048 + k * 1024); } while (0)
; #define PG8_LDB(dst, b, h) do { _Pragma("unroll") for (int n = 0; n < 2; ++n) _Pragma("unroll") for (int k = 0; k < 2; ++k) dst[n][k] = *(const PG8_LAS bf16x8*)(lds + PG8_SB(b, h) + boff + n * 2048 + k * 1024); } while (0)
; #define PG8_MMA(ai, bj, At, Bt) do { __builtin_amdgcn_s_setprio(1); _Pragma("unroll") for (int m = 0; m < 4; ++m) _Pragma("unroll") for (int n = 0; n < 2; ++n) _Pragma("unroll") for (int k = 0; k < 2; ++k) \
;         acc[ai][bj][m][n] = __builtin_amdgcn_mfma_f32_16x16x32_bf16(Bt[n][k], At[m][k], acc[ai][bj][m][n], 0, 0, 0); __builtin_amdgcn_s_setprio(0); } while (0)
; #define PG8_WAIT_V(n) asm volatile("s_waitcnt vmcnt(" #n ")" ::: "memory")
; #define PG8_WAIT_L(n) asm volatile("s_waitcnt lgkmcnt(" #n ")" ::: "memory")
; template <class Epi, class Sched, bool ALIGN_EPI = false, bool SP2 = false>
; __device__ __forceinline__ void gemm_phase(PG8_LAS unsigned char* lds, const Gemm g, const Sched& S, const Epi& E) {
;     ...
;             const bool last = (t == nt - 2);
;             const char* a1 = cA + (size_t)(t + 1) * kstep;
;             const char* a2 = last ? nA : cA + (size_t)(t + 2) * kstep; const char* b2 = last ? nB : cB + (size_t)(t + 2) * kstep;
;             const char* a3 = a2 + kstep; const char* b3 = b2 + kstep;
;             if (last && has_next) S.a_ready(nxt);
;             if constexpr (SP2) {
;             PG8_LDB(B0, 0, 0); PG8_LDB(B1, 0, 1); PG8_SCHED; PG8_LDA(At, 0, 0); PG8_STAGE(PG8_SA(1, 1), a1 + hstepA, voffA);
;             PG8_WAIT_V(8); PG8_WAIT_L(0); PG8_BAR; PG8_MMA(0, 0, At, B0); PG8_MMA(0, 1, At, B1); PG8_BAR; PG8_SCHED;
;             PG8_LDA(At, 0, 1); PG8_STAGE(PG8_SB(0, 0), b2, voffB); PG8_STAGE(PG8_SB(0, 1), b2 + hstep, voffB); PG8_STAGE(PG8_SA(0, 0), a2, voffA);
;             PG8_WAIT_V(8); PG8_WAIT_L(0); PG8_BAR; PG8_MMA(1, 0, At, B0); PG8_MMA(1, 1, At, B1); PG8_BAR; PG8_SCHED;
.LBB0_1501:
	ds_read_b128 v[68:71], v196
	ds_read_b128 v[72:75], v196 offset:1024
	ds_read_b128 v[76:79], v196 offset:2048
	ds_read_b128 v[80:83], v196 offset:3072
	ds_read_b128 v[84:87], v197
	ds_read_b128 v[88:91], v197 offset:1024
	ds_read_b128 v[182:185], v197 offset:2048
	ds_read_b128 v[202:205], v197 offset:3072
	s_add_i32 s38, s14, 2
	s_add_u32 s39, s4, 0xffff0080
	s_addc_u32 s15, s5, -1
	s_cmp_eq_u32 s58, s14
	s_cselect_b32 s14, s35, s39
	s_cselect_b32 s15, s27, s15
	s_cselect_b32 s73, s29, s37
	s_cselect_b32 s72, s28, s36
	s_add_i32 m0, s47, 0xc000
	ds_read_b128 v[206:209], v198
	ds_read_b128 v[210:213], v198 offset:1024
	ds_read_b128 v[214:217], v198 offset:2048
	ds_read_b128 v[218:221], v198 offset:3072
	ds_read_b128 v[222:225], v198 offset:4096
	ds_read_b128 v[226:229], v198 offset:5120
	ds_read_b128 v[230:233], v198 offset:6144
	global_load_lds_dwordx4 v174, s[4:5]
	s_add_i32 m0, s47, 0xe000
	ds_read_b128 v[234:237], v198 offset:7168
	global_load_lds_dwordx4 v176, s[4:5]
	s_waitcnt vmcnt(8)
	s_waitcnt lgkmcnt(0)
	s_barrier
	s_setprio 1
	v_mfma_f32_16x16x32_bf16 v[152:155], v[68:71], v[206:209], v[152:155]
	v_mfma_f32_16x16x32_bf16 v[148:151], v[76:79], v[206:209], v[148:151]
	v_mfma_f32_16x16x32_bf16 v[136:139], v[68:71], v[214:217], v[136:139]
	v_mfma_f32_16x16x32_bf16 v[132:135], v[76:79], v[214:217], v[132:135]
	v_mfma_f32_16x16x32_bf16 v[120:123], v[68:71], v[222:225], v[120:123]
	v_mfma_f32_16x16x32_bf16 v[116:119], v[76:79], v[222:225], v[116:119]
	v_mfma_f32_16x16x32_bf16 v[104:107], v[68:71], v[230:233], v[104:107]
	v_mfma_f32_16x16x32_bf16 v[100:103], v[76:79], v[230:233], v[100:103]
	v_mfma_f32_16x16x32_bf16 v[152:155], v[72:75], v[210:213], v[152:155]
	v_mfma_f32_16x16x32_bf16 v[148:151], v[80:83], v[210:213], v[148:151]
	v_mfma_f32_16x16x32_bf16 v[136:139], v[72:75], v[218:221], v[136:139]
	v_mfma_f32_16x16x32_bf16 v[132:135], v[80:83], v[218:221], v[132:135]
	v_mfma_f32_16x16x32_bf16 v[120:123], v[72:75], v[226:229], v[120:123]
	v_mfma_f32_16x16x32_bf16 v[116:119], v[80:83], v[226:229], v[116:119]
	v_mfma_f32_16x16x32_bf16 v[104:107], v[72:75], v[234:237], v[104:107]
	v_mfma_f32_16x16x32_bf16 v[100:103], v[80:83], v[234:237], v[100:103]
	v_mfma_f32_16x16x32_bf16 v[144:147], v[84:87], v[206:209], v[144:147]
	v_mfma_f32_16x16x32_bf16 v[140:143], v[182:185], v[206:209], v[140:143]
	v_mfma_f32_16x16x32_bf16 v[128:131], v[84:87], v[214:217], v[128:131]
	v_mfma_f32_16x16x32_bf16 v[124:127], v[182:185], v[214:217], v[124:127]
	v_mfma_f32_16x16x32_bf16 v[112:115], v[84:87], v[222:225], v[112:115]
	v_mfma_f32_16x16x32_bf16 v[108:111], v[182:185], v[222:225], v[108:111]
	v_mfma_f32_16x16x32_bf16 v[96:99], v[84:87], v[230:233], v[96:99]
	v_mfma_f32_16x16x32_bf16 v[92:95], v[182:185], v[230:233], v[92:95]
	v_mfma_f32_16x16x32_bf16 v[144:147], v[88:91], v[210:213], v[144:147]
	v_mfma_f32_16x16x32_bf16 v[140:143], v[202:205], v[210:213], v[140:143]
	v_mfma_f32_16x16x32_bf16 v[128:131], v[88:91], v[218:221], v[128:131]
	v_mfma_f32_16x16x32_bf16 v[124:127], v[202:205], v[218:221], v[124:127]
	v_mfma_f32_16x16x32_bf16 v[112:115], v[88:91], v[226:229], v[112:115]
	v_mfma_f32_16x16x32_bf16 v[108:111], v[202:205], v[226:229], v[108:111]
	v_mfma_f32_16x16x32_bf16 v[96:99], v[88:91], v[234:237], v[96:99]
	v_mfma_f32_16x16x32_bf16 v[92:95], v[202:205], v[234:237], v[92:95]
	s_setprio 0
	s_barrier
	s_add_i32 s39, s61, s45
	s_mov_b32 m0, s39
	ds_read_b128 v[206:209], v198 offset:16384
	ds_read_b128 v[210:213], v198 offset:17408
	ds_read_b128 v[214:217], v198 offset:18432
	ds_read_b128 v[218:221], v198 offset:19456
	global_load_lds_dwordx4 v156, s[72:73]
	s_add_i32 m0, s39, 0x2000
	s_mov_b64 s[100:101], s[72:73]
	s_add_i32 s39, s62, s45
	global_load_lds_dwordx4 v158, s[72:73]
	s_add_u32 s72, s72, s16
	s_addc_u32 s73, s73, s17
	s_mov_b32 m0, s39
	ds_read_b128 v[234:237], v198 offset:23552
	global_load_lds_dwordx4 v156, s[72:73]
	s_add_i32 m0, s39, 0x2000
	ds_read_b128 v[230:233], v198 offset:22528
	global_load_lds_dwordx4 v158, s[72:73]
	s_mov_b32 m0, s47
	ds_read_b128 v[226:229], v198 offset:21504
	global_load_lds_dwordx4 v160, s[14:15]
	s_mov_b32 m0, s48
	ds_read_b128 v[222:225], v198 offset:20480
	global_load_lds_dwordx4 v162, s[14:15]
	s_waitcnt vmcnt(8)
	s_waitcnt lgkmcnt(0)
	s_barrier
	s_setprio 1
	v_mfma_f32_16x16x32_bf16 v[64:67], v[68:71], v[206:209], v[64:67]
	v_mfma_f32_16x16x32_bf16 v[60:63], v[76:79], v[206:209], v[60:63]
	v_mfma_f32_16x16x32_bf16 v[48:51], v[68:71], v[214:217], v[48:51]
	v_mfma_f32_16x16x32_bf16 v[44:47], v[76:79], v[214:217], v[44:47]
	v_mfma_f32_16x16x32_bf16 v[32:35], v[68:71], v[222:225], v[32:35]
	v_mfma_f32_16x16x32_bf16 v[28:31], v[76:79], v[222:225], v[28:31]
	v_mfma_f32_16x16x32_bf16 v[16:19], v[68:71], v[230:233], v[16:19]
	v_mfma_f32_16x16x32_bf16 v[12:15], v[76:79], v[230:233], v[12:15]
	v_mfma_f32_16x16x32_bf16 v[64:67], v[72:75], v[210:213], v[64:67]
	v_mfma_f32_16x16x32_bf16 v[60:63], v[80:83], v[210:213], v[60:63]
	v_mfma_f32_16x16x32_bf16 v[48:51], v[72:75], v[218:221], v[48:51]
	v_mfma_f32_16x16x32_bf16 v[44:47], v[80:83], v[218:221], v[44:47]
	v_mfma_f32_16x16x32_bf16 v[32:35], v[72:75], v[226:229], v[32:35]
	v_mfma_f32_16x16x32_bf16 v[28:31], v[80:83], v[226:229], v[28:31]
	v_mfma_f32_16x16x32_bf16 v[16:19], v[72:75], v[234:237], v[16:19]
	v_mfma_f32_16x16x32_bf16 v[12:15], v[80:83], v[234:237], v[12:15]
	v_mfma_f32_16x16x32_bf16 v[56:59], v[84:87], v[206:209], v[56:59]
	v_mfma_f32_16x16x32_bf16 v[52:55], v[182:185], v[206:209], v[52:55]
	v_mfma_f32_16x16x32_bf16 v[40:43], v[84:87], v[214:217], v[40:43]
	v_mfma_f32_16x16x32_bf16 v[36:39], v[182:185], v[214:217], v[36:39]
	v_mfma_f32_16x16x32_bf16 v[24:27], v[84:87], v[222:225], v[24:27]
	v_mfma_f32_16x16x32_bf16 v[20:23], v[182:185], v[222:225], v[20:23]
	v_mfma_f32_16x16x32_bf16 v[8:11], v[84:87], v[230:233], v[8:11]
	v_mfma_f32_16x16x32_bf16 v[4:7], v[182:185], v[230:233], v[4:7]
	v_mfma_f32_16x16x32_bf16 v[56:59], v[88:91], v[210:213], v[56:59]
	v_mfma_f32_16x16x32_bf16 v[52:55], v[202:205], v[210:213], v[52:55]
	v_mfma_f32_16x16x32_bf16 v[40:43], v[88:91], v[218:221], v[40:43]
	v_mfma_f32_16x16x32_bf16 v[36:39], v[202:205], v[218:221], v[36:39]
	v_mfma_f32_16x16x32_bf16 v[24:27], v[88:91], v[226:229], v[24:27]
	v_mfma_f32_16x16x32_bf16 v[20:23], v[202:205], v[226:229], v[20:23]
	v_mfma_f32_16x16x32_bf16 v[8:11], v[88:91], v[234:237], v[8:11]
	v_mfma_f32_16x16x32_bf16 v[4:7], v[202:205], v[234:237], v[4:7]
	s_setprio 0
	s_barrier
; #define PG8_STAGE(bufoff, gbase, voff) do { _Pragma("unroll") for (int _i = 0; _i < 2; ++_i) \
;         __builtin_amdgcn_global_load_lds((const unsigned*)((const char*)(gbase) + (voff)[_i]), (PG8_LAS unsigned*)(lds + (bufoff) + ldsw + _i * 8192), 16, 0, 0); } while (0)
; #define PG8_LDA(dst, b, h) do { _Pragma("unroll") for (int m = 0; m < 4; ++m) _Pragma("unroll") for (int k = 0; k < 2; ++k) dst[m][k] = *(const PG8_LAS bf16x8*)(lds + PG8_SA(b, h) + aoff + m * 2048 + k * 1024); } while (0)
; #define PG8_LDB(dst, b, h) do { _Pragma("unroll") for (int n = 0; n < 2; ++n) _Pragma("unroll") for (int k = 0; k < 2; ++k) dst[n][k] = *(const PG8_LAS bf16x8*)(lds + PG8_SB(b, h) + boff + n * 2048 + k * 1024); } while (0)
; #define PG8_MMA(ai, bj, At, Bt) do { __builtin_amdgcn_s_setprio(1); _Pragma("unroll") for (int m = 0; m < 4; ++m) _Pragma("unroll") for (int n = 0; n < 2; ++n) _Pragma("unroll") for (int k = 0; k < 2; ++k) \
;         acc[ai][bj][m][n] = __builtin_amdgcn_mfma_f32_16x16x32_bf16(Bt[n][k], At[m][k], acc[ai][bj][m][n], 0, 0, 0); __builtin_amdgcn_s_setprio(0); } while (0)
; #define PG8_WAIT_V(n) asm volatile("s_waitcnt vmcnt(" #n ")" ::: "memory")
; #define PG8_WAIT_L(n) asm volatile("s_waitcnt lgkmcnt(" #n ")" ::: "memory")
; #define PG8_BAR __builtin_amdgcn_s_barrier()
; #define PG8_SCHED __builtin_amdgcn_sched_barrier(0)
; template <class Epi, class Sched, bool ALIGN_EPI = false, bool SP2 = false>
; __device__ __forceinline__ void gemm_phase(PG8_LAS unsigned char* lds, const Gemm g, const Sched& S, const Epi& E) {
;     ...
;         for (int t = 0; t < nt; t += 2) {
;             const bool last = (t == nt - 2);
;             const char* a1 = cA + (size_t)(t + 1) * kstep;
;             const char* a2 = last ? nA : cA + (size_t)(t + 2) * kstep; const char* b2 = last ? nB : cB + (size_t)(t + 2) * kstep;
;     ...
;             PG8_LDB(B0, 1, 0); PG8_LDB(B1, 1, 1); PG8_SCHED; PG8_LDA(At, 1, 0); PG8_STAGE(PG8_SA(0, 1), a2 + hstepA, voffA);
;             PG8_WAIT_V(8); PG8_WAIT_L(0); PG8_BAR; PG8_MMA(0, 0, At, B0); PG8_MMA(0, 1, At, B1); PG8_BAR; PG8_SCHED;
;             PG8_LDA(At, 1, 1); PG8_STAGE(PG8_SB(1, 0), b3, voffB); PG8_STAGE(PG8_SB(1, 1), b3 + hstep, voffB); PG8_STAGE(PG8_SA(1, 0), a3, voffA);
;             PG8_WAIT_V(8); PG8_WAIT_L(0); PG8_BAR; PG8_MMA(1, 0, At, B0); PG8_MMA(1, 1, At, B1); PG8_BAR; PG8_SCHED;
	s_add_i32 s39, 0, 0x18000
	s_add_i32 s71, 0, 0x1c000
	v_add_u32_e32 v80, s39, v191
	v_add_u32_e32 v164, s71, v191
	ds_read_b128 v[68:71], v80
	ds_read_b128 v[72:75], v80 offset:1024
	ds_read_b128 v[76:79], v80 offset:2048
	ds_read_b128 v[80:83], v80 offset:3072
	ds_read_b128 v[84:87], v164
	ds_read_b128 v[88:91], v164 offset:1024
	ds_read_b128 v[182:185], v164 offset:2048
	ds_read_b128 v[202:205], v164 offset:3072
	s_mov_b64 vcc, s[14:15]
	s_add_u32 s14, s14, 0x10000
	s_addc_u32 s15, s15, 0
	s_mov_b32 m0, s49
	ds_read_b128 v[206:209], v198 offset:32768
	ds_read_b128 v[210:213], v198 offset:33792
	ds_read_b128 v[214:217], v198 offset:34816
	ds_read_b128 v[218:221], v198 offset:35840
	ds_read_b128 v[222:225], v198 offset:36864
	ds_read_b128 v[226:229], v198 offset:37888
	ds_read_b128 v[230:233], v198 offset:38912
	global_load_lds_dwordx4 v160, s[14:15]
	s_mov_b32 m0, s50
	ds_read_b128 v[234:237], v198 offset:39936
	global_load_lds_dwordx4 v162, s[14:15]
	s_waitcnt vmcnt(8)
	s_waitcnt lgkmcnt(0)
	s_barrier
	s_setprio 1
	v_mfma_f32_16x16x32_bf16 v[152:155], v[68:71], v[206:209], v[152:155]
	v_mfma_f32_16x16x32_bf16 v[148:151], v[76:79], v[206:209], v[148:151]
	v_mfma_f32_16x16x32_bf16 v[136:139], v[68:71], v[214:217], v[136:139]
	v_mfma_f32_16x16x32_bf16 v[132:135], v[76:79], v[214:217], v[132:135]
	v_mfma_f32_16x16x32_bf16 v[120:123], v[68:71], v[222:225], v[120:123]
	v_mfma_f32_16x16x32_bf16 v[116:119], v[76:79], v[222:225], v[116:119]
	v_mfma_f32_16x16x32_bf16 v[104:107], v[68:71], v[230:233], v[104:107]
	v_mfma_f32_16x16x32_bf16 v[100:103], v[76:79], v[230:233], v[100:103]
	v_mfma_f32_16x16x32_bf16 v[152:155], v[72:75], v[210:213], v[152:155]
	v_mfma_f32_16x16x32_bf16 v[148:151], v[80:83], v[210:213], v[148:151]
	v_mfma_f32_16x16x32_bf16 v[136:139], v[72:75], v[218:221], v[136:139]
	v_mfma_f32_16x16x32_bf16 v[132:135], v[80:83], v[218:221], v[132:135]
	v_mfma_f32_16x16x32_bf16 v[120:123], v[72:75], v[226:229], v[120:123]
	v_mfma_f32_16x16x32_bf16 v[116:119], v[80:83], v[226:229], v[116:119]
	v_mfma_f32_16x16x32_bf16 v[104:107], v[72:75], v[234:237], v[104:107]
	v_mfma_f32_16x16x32_bf16 v[100:103], v[80:83], v[234:237], v[100:103]
	v_mfma_f32_16x16x32_bf16 v[144:147], v[84:87], v[206:209], v[144:147]
	v_mfma_f32_16x16x32_bf16 v[140:143], v[182:185], v[206:209], v[140:143]
	v_mfma_f32_16x16x32_bf16 v[128:131], v[84:87], v[214:217], v[128:131]
	v_mfma_f32_16x16x32_bf16 v[124:127], v[182:185], v[214:217], v[124:127]
	v_mfma_f32_16x16x32_bf16 v[112:115], v[84:87], v[222:225], v[112:115]
	v_mfma_f32_16x16x32_bf16 v[108:111], v[182:185], v[222:225], v[108:111]
	v_mfma_f32_16x16x32_bf16 v[96:99], v[84:87], v[230:233], v[96:99]
	v_mfma_f32_16x16x32_bf16 v[92:95], v[182:185], v[230:233], v[92:95]
	v_mfma_f32_16x16x32_bf16 v[144:147], v[88:91], v[210:213], v[144:147]
	v_mfma_f32_16x16x32_bf16 v[140:143], v[202:205], v[210:213], v[140:143]
	v_mfma_f32_16x16x32_bf16 v[128:131], v[88:91], v[218:221], v[128:131]
	v_mfma_f32_16x16x32_bf16 v[124:127], v[202:205], v[218:221], v[124:127]
	v_mfma_f32_16x16x32_bf16 v[112:115], v[88:91], v[226:229], v[112:115]
	v_mfma_f32_16x16x32_bf16 v[108:111], v[202:205], v[226:229], v[108:111]
	v_mfma_f32_16x16x32_bf16 v[96:99], v[88:91], v[234:237], v[96:99]
	v_mfma_f32_16x16x32_bf16 v[92:95], v[202:205], v[234:237], v[92:95]
	s_setprio 0
	s_barrier
	s_add_i32 s14, s39, s45
	s_add_i32 m0, s14, 0xffffff80
	ds_read_b128 v[206:209], v198 offset:49152
	ds_read_b128 v[210:213], v198 offset:50176
	ds_read_b128 v[214:217], v198 offset:51200
	ds_read_b128 v[218:221], v198 offset:52224
	global_load_lds_dwordx4 v156, s[100:101] offset:128
	s_add_i32 m0, s14, 0x1f80
	s_add_i32 s14, s71, s45
	global_load_lds_dwordx4 v158, s[100:101] offset:128
	s_add_i32 m0, s14, 0xffffff80
	ds_read_b128 v[234:237], v198 offset:56320
	global_load_lds_dwordx4 v156, s[72:73] offset:128
	s_add_i32 m0, s14, 0x1f80
	ds_read_b128 v[230:233], v198 offset:55296
	global_load_lds_dwordx4 v158, s[72:73] offset:128
	s_add_i32 m0, s56, 0xffffff80
	ds_read_b128 v[226:229], v198 offset:54272
	global_load_lds_dwordx4 v160, vcc offset:128
	s_add_i32 m0, s57, 0xffffff80
	ds_read_b128 v[222:225], v198 offset:53248
	global_load_lds_dwordx4 v162, vcc offset:128
	s_waitcnt vmcnt(8)
	s_waitcnt lgkmcnt(0)
	s_barrier
	s_setprio 1
	v_mfma_f32_16x16x32_bf16 v[64:67], v[68:71], v[206:209], v[64:67]
	v_mfma_f32_16x16x32_bf16 v[60:63], v[76:79], v[206:209], v[60:63]
	v_mfma_f32_16x16x32_bf16 v[48:51], v[68:71], v[214:217], v[48:51]
	v_mfma_f32_16x16x32_bf16 v[44:47], v[76:79], v[214:217], v[44:47]
	v_mfma_f32_16x16x32_bf16 v[32:35], v[68:71], v[222:225], v[32:35]
	v_mfma_f32_16x16x32_bf16 v[28:31], v[76:79], v[222:225], v[28:31]
	v_mfma_f32_16x16x32_bf16 v[16:19], v[68:71], v[230:233], v[16:19]
	v_mfma_f32_16x16x32_bf16 v[12:15], v[76:79], v[230:233], v[12:15]
	v_mfma_f32_16x16x32_bf16 v[64:67], v[72:75], v[210:213], v[64:67]
	v_mfma_f32_16x16x32_bf16 v[60:63], v[80:83], v[210:213], v[60:63]
	v_mfma_f32_16x16x32_bf16 v[48:51], v[72:75], v[218:221], v[48:51]
	v_mfma_f32_16x16x32_bf16 v[44:47], v[80:83], v[218:221], v[44:47]
	v_mfma_f32_16x16x32_bf16 v[32:35], v[72:75], v[226:229], v[32:35]
	v_mfma_f32_16x16x32_bf16 v[28:31], v[80:83], v[226:229], v[28:31]
	v_mfma_f32_16x16x32_bf16 v[16:19], v[72:75], v[234:237], v[16:19]
	v_mfma_f32_16x16x32_bf16 v[12:15], v[80:83], v[234:237], v[12:15]
	v_mfma_f32_16x16x32_bf16 v[56:59], v[84:87], v[206:209], v[56:59]
	v_mfma_f32_16x16x32_bf16 v[52:55], v[182:185], v[206:209], v[52:55]
	v_mfma_f32_16x16x32_bf16 v[40:43], v[84:87], v[214:217], v[40:43]
	v_mfma_f32_16x16x32_bf16 v[36:39], v[182:185], v[214:217], v[36:39]
	v_mfma_f32_16x16x32_bf16 v[24:27], v[84:87], v[222:225], v[24:27]
	v_mfma_f32_16x16x32_bf16 v[20:23], v[182:185], v[222:225], v[20:23]
	v_mfma_f32_16x16x32_bf16 v[8:11], v[84:87], v[230:233], v[8:11]
	v_mfma_f32_16x16x32_bf16 v[4:7], v[182:185], v[230:233], v[4:7]
	v_mfma_f32_16x16x32_bf16 v[56:59], v[88:91], v[210:213], v[56:59]
	v_mfma_f32_16x16x32_bf16 v[52:55], v[202:205], v[210:213], v[52:55]
	v_mfma_f32_16x16x32_bf16 v[40:43], v[88:91], v[218:221], v[40:43]
	v_mfma_f32_16x16x32_bf16 v[36:39], v[202:205], v[218:221], v[36:39]
	v_mfma_f32_16x16x32_bf16 v[24:27], v[88:91], v[226:229], v[24:27]
	v_mfma_f32_16x16x32_bf16 v[20:23], v[202:205], v[226:229], v[20:23]
	v_mfma_f32_16x16x32_bf16 v[8:11], v[88:91], v[234:237], v[8:11]
	v_mfma_f32_16x16x32_bf16 v[4:7], v[202:205], v[234:237], v[4:7]
	s_setprio 0
	s_barrier
	s_add_u32 s4, s4, 0x100
	s_addc_u32 s5, s5, 0
	s_add_u32 s36, s36, 0x100
	s_addc_u32 s37, s37, 0
	s_cmp_ge_i32 s38, s54
	s_mov_b32 s14, s38
	s_cbranch_scc0 .LBB0_1501

; #define PG8_STAGE(bufoff, gbase, voff) do { _Pragma("unroll") for (int _i = 0; _i < 2; ++_i) \
;         __builtin_amdgcn_global_load_lds((const unsigned*)((const char*)(gbase) + (voff)[_i]), (PG8_LAS unsigned*)(lds + (bufoff) + ldsw + _i * 8192), 16, 0, 0); } while (0)
; #define PG8_LDA(dst, b, h) do { _Pragma("unroll") for (int m = 0; m < 4; ++m) _Pragma("unroll") for (int k = 0; k < 2; ++k) dst[m][k] = *(const PG8_LAS bf16x8*)(lds + PG8_SA(b, h) + aoff + m * 2048 + k * 1024); } while (0)
; #define PG8_LDB(dst, b, h) do { _Pragma("unroll") for (int n = 0; n < 2; ++n) _Pragma("unroll") for (int k = 0; k < 2; ++k) dst[n][k] = *(const PG8_LAS bf16x8*)(lds + PG8_SB(b, h) + boff + n * 2048 + k * 1024); } while (0)
; #define PG8_MMA(ai, bj, At, Bt) do { __builtin_amdgcn_s_setprio(1); _Pragma("unroll") for (int m = 0; m < 4; ++m) _Pragma("unroll") for (int n = 0; n < 2; ++n) _Pragma("unroll") for (int k = 0; k < 2; ++k) \
;         acc[ai][bj][m][n] = __builtin_amdgcn_mfma_f32_16x16x32_bf16(Bt[n][k], At[m][k], acc[ai][bj][m][n], 0, 0, 0); __builtin_amdgcn_s_setprio(0); } while (0)
; #define PG8_WAIT_V(n) asm volatile("s_waitcnt vmcnt(" #n ")" ::: "memory")
; #define PG8_WAIT_L(n) asm volatile("s_waitcnt lgkmcnt(" #n ")" ::: "memory")
; template <class Epi, class Sched, bool ALIGN_EPI = false, bool SP2 = false>
; __device__ __forceinline__ void gemm_phase(PG8_LAS unsigned char* lds, const Gemm g, const Sched& S, const Epi& E) {
;     ...
;             const bool last = (t == nt - 2);
;             const char* a1 = cA + (size_t)(t + 1) * kstep;
;             const char* a2 = last ? nA : cA + (size_t)(t + 2) * kstep; const char* b2 = last ? nB : cB + (size_t)(t + 2) * kstep;
;             const char* a3 = a2 + kstep; const char* b3 = b2 + kstep;
;             if (last && has_next) S.a_ready(nxt);
;             if constexpr (SP2) {
;             PG8_LDB(B0, 0, 0); PG8_LDB(B1, 0, 1); PG8_SCHED; PG8_LDA(At, 0, 0); PG8_STAGE(PG8_SA(1, 1), a1 + hstepA, voffA);
;             PG8_WAIT_V(8); PG8_WAIT_L(0); PG8_BAR; PG8_MMA(0, 0, At, B0); PG8_MMA(0, 1, At, B1); PG8_BAR; PG8_SCHED;
;             PG8_LDA(At, 0, 1); PG8_STAGE(PG8_SB(0, 0), b2, voffB); PG8_STAGE(PG8_SB(0, 1), b2 + hstep, voffB); PG8_STAGE(PG8_SA(0, 0), a2, voffA);
;             PG8_WAIT_V(8); PG8_WAIT_L(0); PG8_BAR; PG8_MMA(1, 0, At, B0); PG8_MMA(1, 1, At, B1); PG8_BAR; PG8_SCHED;
.LBB0_1679:
	ds_read_b128 v[120:123], v169
	ds_read_b128 v[128:131], v169 offset:1024
	ds_read_b128 v[136:139], v169 offset:2048
	ds_read_b128 v[140:143], v169 offset:3072
	ds_read_b128 v[160:163], v170
	ds_read_b128 v[172:175], v170 offset:1024
	ds_read_b128 v[176:179], v170 offset:2048
	ds_read_b128 v[180:183], v170 offset:3072
	s_add_i32 s90, s68, 2
	s_add_u32 s91, s8, 0xfffc0080
	s_addc_u32 s69, s9, -1
	s_cmp_eq_u32 s84, s68
	s_cselect_b32 s68, s89, s91
	s_cselect_b32 s69, s61, s69
	s_cselect_b32 s93, s63, s71
	s_cselect_b32 s92, s62, s70
	s_add_i32 m0, s67, 0xc000
	ds_read_b128 v[184:187], v171
	ds_read_b128 v[190:193], v171 offset:1024
	ds_read_b128 v[194:197], v171 offset:2048
	ds_read_b128 v[198:201], v171 offset:3072
	ds_read_b128 v[202:205], v171 offset:4096
	ds_read_b128 v[206:209], v171 offset:5120
	ds_read_b128 v[210:213], v171 offset:6144
	global_load_lds_dwordx4 v152, s[8:9]
	s_add_i32 m0, s67, 0xe000
	ds_read_b128 v[214:217], v171 offset:7168
	global_load_lds_dwordx4 v154, s[8:9]
	s_waitcnt vmcnt(8)
	s_waitcnt lgkmcnt(0)
	s_barrier
	s_setprio 1
	v_mfma_f32_16x16x32_bf16 v[132:135], v[120:123], v[184:187], v[132:135]
	v_mfma_f32_16x16x32_bf16 v[124:127], v[136:139], v[184:187], v[124:127]
	v_mfma_f32_16x16x32_bf16 v[108:111], v[120:123], v[194:197], v[108:111]
	v_mfma_f32_16x16x32_bf16 v[104:107], v[136:139], v[194:197], v[104:107]
	v_mfma_f32_16x16x32_bf16 v[92:95], v[120:123], v[202:205], v[92:95]
	v_mfma_f32_16x16x32_bf16 v[88:91], v[136:139], v[202:205], v[88:91]
	v_mfma_f32_16x16x32_bf16 v[76:79], v[120:123], v[210:213], v[76:79]
	v_mfma_f32_16x16x32_bf16 v[72:75], v[136:139], v[210:213], v[72:75]
	v_mfma_f32_16x16x32_bf16 v[132:135], v[128:131], v[190:193], v[132:135]
	v_mfma_f32_16x16x32_bf16 v[124:127], v[140:143], v[190:193], v[124:127]
	v_mfma_f32_16x16x32_bf16 v[108:111], v[128:131], v[198:201], v[108:111]
	v_mfma_f32_16x16x32_bf16 v[104:107], v[140:143], v[198:201], v[104:107]
	v_mfma_f32_16x16x32_bf16 v[92:95], v[128:131], v[206:209], v[92:95]
	v_mfma_f32_16x16x32_bf16 v[88:91], v[140:143], v[206:209], v[88:91]
	v_mfma_f32_16x16x32_bf16 v[76:79], v[128:131], v[214:217], v[76:79]
	v_mfma_f32_16x16x32_bf16 v[72:75], v[140:143], v[214:217], v[72:75]
	v_mfma_f32_16x16x32_bf16 v[116:119], v[160:163], v[184:187], v[116:119]
	v_mfma_f32_16x16x32_bf16 v[112:115], v[176:179], v[184:187], v[112:115]
	v_mfma_f32_16x16x32_bf16 v[100:103], v[160:163], v[194:197], v[100:103]
	v_mfma_f32_16x16x32_bf16 v[96:99], v[176:179], v[194:197], v[96:99]
	v_mfma_f32_16x16x32_bf16 v[84:87], v[160:163], v[202:205], v[84:87]
	v_mfma_f32_16x16x32_bf16 v[80:83], v[176:179], v[202:205], v[80:83]
	v_mfma_f32_16x16x32_bf16 v[68:71], v[160:163], v[210:213], v[68:71]
	v_mfma_f32_16x16x32_bf16 v[64:67], v[176:179], v[210:213], v[64:67]
	v_mfma_f32_16x16x32_bf16 v[116:119], v[172:175], v[190:193], v[116:119]
	v_mfma_f32_16x16x32_bf16 v[112:115], v[180:183], v[190:193], v[112:115]
	v_mfma_f32_16x16x32_bf16 v[100:103], v[172:175], v[198:201], v[100:103]
	v_mfma_f32_16x16x32_bf16 v[96:99], v[180:183], v[198:201], v[96:99]
	v_mfma_f32_16x16x32_bf16 v[84:87], v[172:175], v[206:209], v[84:87]
	v_mfma_f32_16x16x32_bf16 v[80:83], v[180:183], v[206:209], v[80:83]
	v_mfma_f32_16x16x32_bf16 v[68:71], v[172:175], v[214:217], v[68:71]
	v_mfma_f32_16x16x32_bf16 v[64:67], v[180:183], v[214:217], v[64:67]
	s_setprio 0
	s_barrier
	s_add_i32 s91, s85, s73
	s_mov_b32 m0, s91
	ds_read_b128 v[184:187], v171 offset:16384
	ds_read_b128 v[190:193], v171 offset:17408
	ds_read_b128 v[194:197], v171 offset:18432
	ds_read_b128 v[198:201], v171 offset:19456
	global_load_lds_dwordx4 v150, s[92:93]
	s_add_i32 m0, s91, 0x2000
	s_mov_b64 s[100:101], s[92:93]
	s_add_i32 s91, s86, s73
	global_load_lds_dwordx4 v148, s[92:93]
	s_add_u32 s92, s92, s10
	s_addc_u32 s93, s93, s11
	s_mov_b32 m0, s91
	ds_read_b128 v[214:217], v171 offset:23552
	global_load_lds_dwordx4 v150, s[92:93]
	s_add_i32 m0, s91, 0x2000
	ds_read_b128 v[210:213], v171 offset:22528
	global_load_lds_dwordx4 v148, s[92:93]
	s_mov_b32 m0, s67
	ds_read_b128 v[206:209], v171 offset:21504
	global_load_lds_dwordx4 v144, s[68:69]
	s_mov_b32 m0, s75
	ds_read_b128 v[202:205], v171 offset:20480
	global_load_lds_dwordx4 v146, s[68:69]
	s_waitcnt vmcnt(8)
	s_waitcnt lgkmcnt(0)
	s_barrier
	s_setprio 1
	v_mfma_f32_16x16x32_bf16 v[60:63], v[120:123], v[184:187], v[60:63]
	v_mfma_f32_16x16x32_bf16 v[56:59], v[136:139], v[184:187], v[56:59]
	v_mfma_f32_16x16x32_bf16 v[44:47], v[120:123], v[194:197], v[44:47]
	v_mfma_f32_16x16x32_bf16 v[40:43], v[136:139], v[194:197], v[40:43]
	v_mfma_f32_16x16x32_bf16 v[28:31], v[120:123], v[202:205], v[28:31]
	v_mfma_f32_16x16x32_bf16 v[24:27], v[136:139], v[202:205], v[24:27]
	v_mfma_f32_16x16x32_bf16 v[12:15], v[120:123], v[210:213], v[12:15]
	v_mfma_f32_16x16x32_bf16 v[8:11], v[136:139], v[210:213], v[8:11]
	v_mfma_f32_16x16x32_bf16 v[60:63], v[128:131], v[190:193], v[60:63]
	v_mfma_f32_16x16x32_bf16 v[56:59], v[140:143], v[190:193], v[56:59]
	v_mfma_f32_16x16x32_bf16 v[44:47], v[128:131], v[198:201], v[44:47]
	v_mfma_f32_16x16x32_bf16 v[40:43], v[140:143], v[198:201], v[40:43]
	v_mfma_f32_16x16x32_bf16 v[28:31], v[128:131], v[206:209], v[28:31]
	v_mfma_f32_16x16x32_bf16 v[24:27], v[140:143], v[206:209], v[24:27]
	v_mfma_f32_16x16x32_bf16 v[12:15], v[128:131], v[214:217], v[12:15]
	v_mfma_f32_16x16x32_bf16 v[8:11], v[140:143], v[214:217], v[8:11]
	v_mfma_f32_16x16x32_bf16 v[52:55], v[160:163], v[184:187], v[52:55]
	v_mfma_f32_16x16x32_bf16 v[48:51], v[176:179], v[184:187], v[48:51]
	v_mfma_f32_16x16x32_bf16 v[36:39], v[160:163], v[194:197], v[36:39]
	v_mfma_f32_16x16x32_bf16 v[32:35], v[176:179], v[194:197], v[32:35]
	v_mfma_f32_16x16x32_bf16 v[20:23], v[160:163], v[202:205], v[20:23]
	v_mfma_f32_16x16x32_bf16 v[16:19], v[176:179], v[202:205], v[16:19]
	v_mfma_f32_16x16x32_bf16 v[4:7], v[160:163], v[210:213], v[4:7]
	v_mfma_f32_16x16x32_bf16 v[0:3], v[176:179], v[210:213], v[0:3]
	v_mfma_f32_16x16x32_bf16 v[52:55], v[172:175], v[190:193], v[52:55]
	v_mfma_f32_16x16x32_bf16 v[48:51], v[180:183], v[190:193], v[48:51]
	v_mfma_f32_16x16x32_bf16 v[36:39], v[172:175], v[198:201], v[36:39]
	v_mfma_f32_16x16x32_bf16 v[32:35], v[180:183], v[198:201], v[32:35]
	v_mfma_f32_16x16x32_bf16 v[20:23], v[172:175], v[206:209], v[20:23]
	v_mfma_f32_16x16x32_bf16 v[16:19], v[180:183], v[206:209], v[16:19]
	v_mfma_f32_16x16x32_bf16 v[4:7], v[172:175], v[214:217], v[4:7]
	v_mfma_f32_16x16x32_bf16 v[0:3], v[180:183], v[214:217], v[0:3]
	s_setprio 0
	s_barrier
; #define PG8_STAGE(bufoff, gbase, voff) do { _Pragma("unroll") for (int _i = 0; _i < 2; ++_i) \
;         __builtin_amdgcn_global_load_lds((const unsigned*)((const char*)(gbase) + (voff)[_i]), (PG8_LAS unsigned*)(lds + (bufoff) + ldsw + _i * 8192), 16, 0, 0); } while (0)
; #define PG8_LDA(dst, b, h) do { _Pragma("unroll") for (int m = 0; m < 4; ++m) _Pragma("unroll") for (int k = 0; k < 2; ++k) dst[m][k] = *(const PG8_LAS bf16x8*)(lds + PG8_SA(b, h) + aoff + m * 2048 + k * 1024); } while (0)
; #define PG8_LDB(dst, b, h) do { _Pragma("unroll") for (int n = 0; n < 2; ++n) _Pragma("unroll") for (int k = 0; k < 2; ++k) dst[n][k] = *(const PG8_LAS bf16x8*)(lds + PG8_SB(b, h) + boff + n * 2048 + k * 1024); } while (0)
; #define PG8_MMA(ai, bj, At, Bt) do { __builtin_amdgcn_s_setprio(1); _Pragma("unroll") for (int m = 0; m < 4; ++m) _Pragma("unroll") for (int n = 0; n < 2; ++n) _Pragma("unroll") for (int k = 0; k < 2; ++k) \
;         acc[ai][bj][m][n] = __builtin_amdgcn_mfma_f32_16x16x32_bf16(Bt[n][k], At[m][k], acc[ai][bj][m][n], 0, 0, 0); __builtin_amdgcn_s_setprio(0); } while (0)
; #define PG8_WAIT_V(n) asm volatile("s_waitcnt vmcnt(" #n ")" ::: "memory")
; #define PG8_WAIT_L(n) asm volatile("s_waitcnt lgkmcnt(" #n ")" ::: "memory")
; #define PG8_BAR __builtin_amdgcn_s_barrier()
; #define PG8_SCHED __builtin_amdgcn_sched_barrier(0)
; template <class Epi, class Sched, bool ALIGN_EPI = false, bool SP2 = false>
; __device__ __forceinline__ void gemm_phase(PG8_LAS unsigned char* lds, const Gemm g, const Sched& S, const Epi& E) {
;     ...
;         for (int t = 0; t < nt; t += 2) {
;             const bool last = (t == nt - 2);
;             const char* a1 = cA + (size_t)(t + 1) * kstep;
;             const char* a2 = last ? nA : cA + (size_t)(t + 2) * kstep; const char* b2 = last ? nB : cB + (size_t)(t + 2) * kstep;
;     ...
;             PG8_LDB(B0, 1, 0); PG8_LDB(B1, 1, 1); PG8_SCHED; PG8_LDA(At, 1, 0); PG8_STAGE(PG8_SA(0, 1), a2 + hstepA, voffA);
;             PG8_WAIT_V(8); PG8_WAIT_L(0); PG8_BAR; PG8_MMA(0, 0, At, B0); PG8_MMA(0, 1, At, B1); PG8_BAR; PG8_SCHED;
;             PG8_LDA(At, 1, 1); PG8_STAGE(PG8_SB(1, 0), b3, voffB); PG8_STAGE(PG8_SB(1, 1), b3 + hstep, voffB); PG8_STAGE(PG8_SA(1, 0), a3, voffA);
;             PG8_WAIT_V(8); PG8_WAIT_L(0); PG8_BAR; PG8_MMA(1, 0, At, B0); PG8_MMA(1, 1, At, B1); PG8_BAR; PG8_SCHED;
	s_add_i32 s91, 0, 0x18000
	s_add_i32 s92, 0, 0x1c000
	v_add_u32_e32 v140, s91, v167
	v_add_u32_e32 v180, s92, v167
	ds_read_b128 v[120:123], v140
	ds_read_b128 v[128:131], v140 offset:1024
	ds_read_b128 v[136:139], v140 offset:2048
	ds_read_b128 v[140:143], v140 offset:3072
	ds_read_b128 v[160:163], v180
	ds_read_b128 v[172:175], v180 offset:1024
	ds_read_b128 v[176:179], v180 offset:2048
	ds_read_b128 v[180:183], v180 offset:3072
	s_mov_b64 vcc, s[68:69]
	s_add_u32 s68, s68, 0x40000
	s_addc_u32 s69, s69, 0
	s_mov_b32 m0, s76
	ds_read_b128 v[184:187], v171 offset:32768
	ds_read_b128 v[190:193], v171 offset:33792
	ds_read_b128 v[194:197], v171 offset:34816
	ds_read_b128 v[198:201], v171 offset:35840
	ds_read_b128 v[202:205], v171 offset:36864
	ds_read_b128 v[206:209], v171 offset:37888
	ds_read_b128 v[210:213], v171 offset:38912
	global_load_lds_dwordx4 v144, s[68:69]
	s_mov_b32 m0, s77
	ds_read_b128 v[214:217], v171 offset:39936
	global_load_lds_dwordx4 v146, s[68:69]
	s_waitcnt vmcnt(8)
	s_waitcnt lgkmcnt(0)
	s_barrier
	s_setprio 1
	v_mfma_f32_16x16x32_bf16 v[132:135], v[120:123], v[184:187], v[132:135]
	v_mfma_f32_16x16x32_bf16 v[124:127], v[136:139], v[184:187], v[124:127]
	v_mfma_f32_16x16x32_bf16 v[108:111], v[120:123], v[194:197], v[108:111]
	v_mfma_f32_16x16x32_bf16 v[104:107], v[136:139], v[194:197], v[104:107]
	v_mfma_f32_16x16x32_bf16 v[92:95], v[120:123], v[202:205], v[92:95]
	v_mfma_f32_16x16x32_bf16 v[88:91], v[136:139], v[202:205], v[88:91]
	v_mfma_f32_16x16x32_bf16 v[76:79], v[120:123], v[210:213], v[76:79]
	v_mfma_f32_16x16x32_bf16 v[72:75], v[136:139], v[210:213], v[72:75]
	v_mfma_f32_16x16x32_bf16 v[132:135], v[128:131], v[190:193], v[132:135]
	v_mfma_f32_16x16x32_bf16 v[124:127], v[140:143], v[190:193], v[124:127]
	v_mfma_f32_16x16x32_bf16 v[108:111], v[128:131], v[198:201], v[108:111]
	v_mfma_f32_16x16x32_bf16 v[104:107], v[140:143], v[198:201], v[104:107]
	v_mfma_f32_16x16x32_bf16 v[92:95], v[128:131], v[206:209], v[92:95]
	v_mfma_f32_16x16x32_bf16 v[88:91], v[140:143], v[206:209], v[88:91]
	v_mfma_f32_16x16x32_bf16 v[76:79], v[128:131], v[214:217], v[76:79]
	v_mfma_f32_16x16x32_bf16 v[72:75], v[140:143], v[214:217], v[72:75]
	v_mfma_f32_16x16x32_bf16 v[116:119], v[160:163], v[184:187], v[116:119]
	v_mfma_f32_16x16x32_bf16 v[112:115], v[176:179], v[184:187], v[112:115]
	v_mfma_f32_16x16x32_bf16 v[100:103], v[160:163], v[194:197], v[100:103]
	v_mfma_f32_16x16x32_bf16 v[96:99], v[176:179], v[194:197], v[96:99]
	v_mfma_f32_16x16x32_bf16 v[84:87], v[160:163], v[202:205], v[84:87]
	v_mfma_f32_16x16x32_bf16 v[80:83], v[176:179], v[202:205], v[80:83]
	v_mfma_f32_16x16x32_bf16 v[68:71], v[160:163], v[210:213], v[68:71]
	v_mfma_f32_16x16x32_bf16 v[64:67], v[176:179], v[210:213], v[64:67]
	v_mfma_f32_16x16x32_bf16 v[116:119], v[172:175], v[190:193], v[116:119]
	v_mfma_f32_16x16x32_bf16 v[112:115], v[180:183], v[190:193], v[112:115]
	v_mfma_f32_16x16x32_bf16 v[100:103], v[172:175], v[198:201], v[100:103]
	v_mfma_f32_16x16x32_bf16 v[96:99], v[180:183], v[198:201], v[96:99]
	v_mfma_f32_16x16x32_bf16 v[84:87], v[172:175], v[206:209], v[84:87]
	v_mfma_f32_16x16x32_bf16 v[80:83], v[180:183], v[206:209], v[80:83]
	v_mfma_f32_16x16x32_bf16 v[68:71], v[172:175], v[214:217], v[68:71]
	v_mfma_f32_16x16x32_bf16 v[64:67], v[180:183], v[214:217], v[64:67]
	s_setprio 0
	s_barrier
	s_add_i32 s68, s91, s73
	s_add_i32 m0, s68, 0xffffff80
	ds_read_b128 v[184:187], v171 offset:49152
	ds_read_b128 v[190:193], v171 offset:50176
	ds_read_b128 v[194:197], v171 offset:51200
	ds_read_b128 v[198:201], v171 offset:52224
	global_load_lds_dwordx4 v150, s[100:101] offset:128
	s_add_i32 m0, s68, 0x1f80
	s_add_i32 s68, s92, s73
	global_load_lds_dwordx4 v148, s[100:101] offset:128
	s_add_u32 s100, s100, s10
	s_addc_u32 s101, s101, s11
	s_add_i32 m0, s68, 0xffffff80
	ds_read_b128 v[214:217], v171 offset:56320
	global_load_lds_dwordx4 v150, s[100:101] offset:128
	s_add_i32 m0, s68, 0x1f80
	ds_read_b128 v[210:213], v171 offset:55296
	global_load_lds_dwordx4 v148, s[100:101] offset:128
	s_add_i32 m0, s80, 0xffffff80
	ds_read_b128 v[206:209], v171 offset:54272
	global_load_lds_dwordx4 v144, vcc offset:128
	s_add_i32 m0, s81, 0xffffff80
	ds_read_b128 v[202:205], v171 offset:53248
	global_load_lds_dwordx4 v146, vcc offset:128
	s_waitcnt vmcnt(8)
	s_waitcnt lgkmcnt(0)
	s_barrier
	s_setprio 1
	v_mfma_f32_16x16x32_bf16 v[60:63], v[120:123], v[184:187], v[60:63]
	v_mfma_f32_16x16x32_bf16 v[56:59], v[136:139], v[184:187], v[56:59]
	v_mfma_f32_16x16x32_bf16 v[44:47], v[120:123], v[194:197], v[44:47]
	v_mfma_f32_16x16x32_bf16 v[40:43], v[136:139], v[194:197], v[40:43]
	v_mfma_f32_16x16x32_bf16 v[28:31], v[120:123], v[202:205], v[28:31]
	v_mfma_f32_16x16x32_bf16 v[24:27], v[136:139], v[202:205], v[24:27]
	v_mfma_f32_16x16x32_bf16 v[12:15], v[120:123], v[210:213], v[12:15]
	v_mfma_f32_16x16x32_bf16 v[8:11], v[136:139], v[210:213], v[8:11]
	v_mfma_f32_16x16x32_bf16 v[60:63], v[128:131], v[190:193], v[60:63]
	v_mfma_f32_16x16x32_bf16 v[56:59], v[140:143], v[190:193], v[56:59]
	v_mfma_f32_16x16x32_bf16 v[44:47], v[128:131], v[198:201], v[44:47]
	v_mfma_f32_16x16x32_bf16 v[40:43], v[140:143], v[198:201], v[40:43]
	v_mfma_f32_16x16x32_bf16 v[28:31], v[128:131], v[206:209], v[28:31]
	v_mfma_f32_16x16x32_bf16 v[24:27], v[140:143], v[206:209], v[24:27]
	v_mfma_f32_16x16x32_bf16 v[12:15], v[128:131], v[214:217], v[12:15]
	v_mfma_f32_16x16x32_bf16 v[8:11], v[140:143], v[214:217], v[8:11]
	v_mfma_f32_16x16x32_bf16 v[52:55], v[160:163], v[184:187], v[52:55]
	v_mfma_f32_16x16x32_bf16 v[48:51], v[176:179], v[184:187], v[48:51]
	v_mfma_f32_16x16x32_bf16 v[36:39], v[160:163], v[194:197], v[36:39]
	v_mfma_f32_16x16x32_bf16 v[32:35], v[176:179], v[194:197], v[32:35]
	v_mfma_f32_16x16x32_bf16 v[20:23], v[160:163], v[202:205], v[20:23]
	v_mfma_f32_16x16x32_bf16 v[16:19], v[176:179], v[202:205], v[16:19]
	v_mfma_f32_16x16x32_bf16 v[4:7], v[160:163], v[210:213], v[4:7]
	v_mfma_f32_16x16x32_bf16 v[0:3], v[176:179], v[210:213], v[0:3]
	v_mfma_f32_16x16x32_bf16 v[52:55], v[172:175], v[190:193], v[52:55]
	v_mfma_f32_16x16x32_bf16 v[48:51], v[180:183], v[190:193], v[48:51]
	v_mfma_f32_16x16x32_bf16 v[36:39], v[172:175], v[198:201], v[36:39]
	v_mfma_f32_16x16x32_bf16 v[32:35], v[180:183], v[198:201], v[32:35]
	v_mfma_f32_16x16x32_bf16 v[20:23], v[172:175], v[206:209], v[20:23]
	v_mfma_f32_16x16x32_bf16 v[16:19], v[180:183], v[206:209], v[16:19]
	v_mfma_f32_16x16x32_bf16 v[4:7], v[172:175], v[214:217], v[4:7]
	v_mfma_f32_16x16x32_bf16 v[0:3], v[180:183], v[214:217], v[0:3]
	s_setprio 0
	s_barrier
	s_add_u32 s8, s8, 0x100
	s_addc_u32 s9, s9, 0
	s_add_u32 s70, s70, 0x100
	s_addc_u32 s71, s71, 0
	s_cmp_ge_i32 s90, s83
	s_mov_b32 s68, s90
	s_cbranch_scc0 .LBB0_1679

; #define PG8_STAGE(bufoff, gbase, voff) do { _Pragma("unroll") for (int _i = 0; _i < 2; ++_i) \
;         __builtin_amdgcn_global_load_lds((const unsigned*)((const char*)(gbase) + (voff)[_i]), (PG8_LAS unsigned*)(lds + (bufoff) + ldsw + _i * 8192), 16, 0, 0); } while (0)
; #define PG8_LDA(dst, b, h) do { _Pragma("unroll") for (int m = 0; m < 4; ++m) _Pragma("unroll") for (int k = 0; k < 2; ++k) dst[m][k] = *(const PG8_LAS bf16x8*)(lds + PG8_SA(b, h) + aoff + m * 2048 + k * 1024); } while (0)
; #define PG8_LDB(dst, b, h) do { _Pragma("unroll") for (int n = 0; n < 2; ++n) _Pragma("unroll") for (int k = 0; k < 2; ++k) dst[n][k] = *(const PG8_LAS bf16x8*)(lds + PG8_SB(b, h) + boff + n * 2048 + k * 1024); } while (0)
; #define PG8_MMA(ai, bj, At, Bt) do { __builtin_amdgcn_s_setprio(1); _Pragma("unroll") for (int m = 0; m < 4; ++m) _Pragma("unroll") for (int n = 0; n < 2; ++n) _Pragma("unroll") for (int k = 0; k < 2; ++k) \
;         acc[ai][bj][m][n] = __builtin_amdgcn_mfma_f32_16x16x32_bf16(Bt[n][k], At[m][k], acc[ai][bj][m][n], 0, 0, 0); __builtin_amdgcn_s_setprio(0); } while (0)
; #define PG8_WAIT_V(n) asm volatile("s_waitcnt vmcnt(" #n ")" ::: "memory")
; #define PG8_BAR __builtin_amdgcn_s_barrier()
; template <class Epi, class Sched, bool ALIGN_EPI = false, bool SP2 = false>
; __device__ __forceinline__ void gemm_phase(PG8_LAS unsigned char* lds, const Gemm g, const Sched& S, const Epi& E) {
;     ...
;         for (int t = 0; t < nt; t += 2) {
;             const bool last = (t == nt - 2);
;             const char* a1 = cA + (size_t)(t + 1) * kstep;
;             const char* a2 = last ? nA : cA + (size_t)(t + 2) * kstep; const char* b2 = last ? nB : cB + (size_t)(t + 2) * kstep;
;             const char* a3 = a2 + kstep; const char* b3 = b2 + kstep;
;             if (last && has_next) S.a_ready(nxt);
;             if constexpr (SP2) {
;             PG8_LDB(B0, 0, 0); PG8_LDB(B1, 0, 1); PG8_SCHED; PG8_LDA(At, 0, 0); PG8_STAGE(PG8_SA(1, 1), a1 + hstepA, voffA);
;             PG8_WAIT_V(8); PG8_WAIT_L(0); PG8_BAR; PG8_MMA(0, 0, At, B0); PG8_MMA(0, 1, At, B1); PG8_BAR; PG8_SCHED;
;             PG8_LDA(At, 0, 1); PG8_STAGE(PG8_SB(0, 0), b2, voffB); PG8_STAGE(PG8_SB(0, 1), b2 + hstep, voffB); PG8_STAGE(PG8_SA(0, 0), a2, voffA);
;             PG8_WAIT_V(8); PG8_WAIT_L(0); PG8_BAR; PG8_MMA(1, 0, At, B0); PG8_MMA(1, 1, At, B1); PG8_BAR; PG8_SCHED;
.LBB0_1815:
	ds_read_b128 v[150:153], v147
	ds_read_b128 v[154:157], v147 offset:1024
	ds_read_b128 v[158:161], v147 offset:2048
	ds_read_b128 v[162:165], v147 offset:3072
	ds_read_b128 v[166:169], v148
	ds_read_b128 v[170:173], v148 offset:1024
	ds_read_b128 v[174:177], v148 offset:2048
	ds_read_b128 v[178:181], v148 offset:3072
	s_add_i32 s57, s30, 2
	s_add_u32 s58, s10, 0xfffc0080
	s_addc_u32 s31, s11, -1
	s_cmp_eq_u32 s50, s30
	s_cselect_b32 s30, s56, s58
	s_cselect_b32 s31, s23, s31
	s_cselect_b32 s59, s25, s35
	s_cselect_b32 s58, s24, s34
	s_add_i32 m0, s29, 0xc000
	ds_read_b128 v[182:185], v149
	ds_read_b128 v[190:193], v149 offset:1024
	ds_read_b128 v[194:197], v149 offset:2048
	ds_read_b128 v[198:201], v149 offset:3072
	ds_read_b128 v[202:205], v149 offset:4096
	ds_read_b128 v[206:209], v149 offset:5120
	ds_read_b128 v[210:213], v149 offset:6144
	global_load_lds_dwordx4 v136, s[10:11]
	s_add_i32 m0, s29, 0xe000
	ds_read_b128 v[214:217], v149 offset:7168
	global_load_lds_dwordx4 v138, s[10:11]
	s_waitcnt vmcnt(8)
	s_waitcnt lgkmcnt(0)
	s_barrier
	s_setprio 1
	v_mfma_f32_16x16x32_bf16 v[124:127], v[150:153], v[182:185], v[124:127]
	v_mfma_f32_16x16x32_bf16 v[116:119], v[158:161], v[182:185], v[116:119]
	v_mfma_f32_16x16x32_bf16 v[108:111], v[150:153], v[194:197], v[108:111]
	v_mfma_f32_16x16x32_bf16 v[100:103], v[158:161], v[194:197], v[100:103]
	v_mfma_f32_16x16x32_bf16 v[92:95], v[150:153], v[202:205], v[92:95]
	v_mfma_f32_16x16x32_bf16 v[84:87], v[158:161], v[202:205], v[84:87]
	v_mfma_f32_16x16x32_bf16 v[76:79], v[150:153], v[210:213], v[76:79]
	v_mfma_f32_16x16x32_bf16 v[68:71], v[158:161], v[210:213], v[68:71]
	v_mfma_f32_16x16x32_bf16 v[124:127], v[154:157], v[190:193], v[124:127]
	v_mfma_f32_16x16x32_bf16 v[116:119], v[162:165], v[190:193], v[116:119]
	v_mfma_f32_16x16x32_bf16 v[108:111], v[154:157], v[198:201], v[108:111]
	v_mfma_f32_16x16x32_bf16 v[100:103], v[162:165], v[198:201], v[100:103]
	v_mfma_f32_16x16x32_bf16 v[92:95], v[154:157], v[206:209], v[92:95]
	v_mfma_f32_16x16x32_bf16 v[84:87], v[162:165], v[206:209], v[84:87]
	v_mfma_f32_16x16x32_bf16 v[76:79], v[154:157], v[214:217], v[76:79]
	v_mfma_f32_16x16x32_bf16 v[68:71], v[162:165], v[214:217], v[68:71]
	v_mfma_f32_16x16x32_bf16 v[120:123], v[166:169], v[182:185], v[120:123]
	v_mfma_f32_16x16x32_bf16 v[112:115], v[174:177], v[182:185], v[112:115]
	v_mfma_f32_16x16x32_bf16 v[104:107], v[166:169], v[194:197], v[104:107]
	v_mfma_f32_16x16x32_bf16 v[96:99], v[174:177], v[194:197], v[96:99]
	v_mfma_f32_16x16x32_bf16 v[88:91], v[166:169], v[202:205], v[88:91]
	v_mfma_f32_16x16x32_bf16 v[80:83], v[174:177], v[202:205], v[80:83]
	v_mfma_f32_16x16x32_bf16 v[72:75], v[166:169], v[210:213], v[72:75]
	v_mfma_f32_16x16x32_bf16 v[64:67], v[174:177], v[210:213], v[64:67]
	v_mfma_f32_16x16x32_bf16 v[120:123], v[170:173], v[190:193], v[120:123]
	v_mfma_f32_16x16x32_bf16 v[112:115], v[178:181], v[190:193], v[112:115]
	v_mfma_f32_16x16x32_bf16 v[104:107], v[170:173], v[198:201], v[104:107]
	v_mfma_f32_16x16x32_bf16 v[96:99], v[178:181], v[198:201], v[96:99]
	v_mfma_f32_16x16x32_bf16 v[88:91], v[170:173], v[206:209], v[88:91]
	v_mfma_f32_16x16x32_bf16 v[80:83], v[178:181], v[206:209], v[80:83]
	v_mfma_f32_16x16x32_bf16 v[72:75], v[170:173], v[214:217], v[72:75]
	v_mfma_f32_16x16x32_bf16 v[64:67], v[178:181], v[214:217], v[64:67]
	s_setprio 0
	s_barrier
	s_add_i32 s60, s51, s38
	s_mov_b32 m0, s60
	ds_read_b128 v[182:185], v149 offset:16384
	ds_read_b128 v[190:193], v149 offset:17408
	ds_read_b128 v[194:197], v149 offset:18432
	ds_read_b128 v[198:201], v149 offset:19456
	global_load_lds_dwordx4 v134, s[58:59]
	s_add_i32 m0, s60, 0x2000
	s_mov_b64 s[100:101], s[58:59]
	s_add_i32 s60, s52, s38
	global_load_lds_dwordx4 v132, s[58:59]
	s_add_u32 s58, s58, s4
	s_addc_u32 s59, s59, s5
	s_mov_b32 m0, s60
	ds_read_b128 v[214:217], v149 offset:23552
	global_load_lds_dwordx4 v134, s[58:59]
	s_add_i32 m0, s60, 0x2000
	ds_read_b128 v[210:213], v149 offset:22528
	global_load_lds_dwordx4 v132, s[58:59]
	s_mov_b32 m0, s29
	ds_read_b128 v[206:209], v149 offset:21504
	global_load_lds_dwordx4 v128, s[30:31]
	s_mov_b32 m0, s41
	ds_read_b128 v[202:205], v149 offset:20480
	global_load_lds_dwordx4 v130, s[30:31]
	s_waitcnt vmcnt(8)
	s_waitcnt lgkmcnt(0)
	s_barrier
	s_setprio 1
	v_mfma_f32_16x16x32_bf16 v[60:63], v[150:153], v[182:185], v[60:63]
	v_mfma_f32_16x16x32_bf16 v[52:55], v[158:161], v[182:185], v[52:55]
	v_mfma_f32_16x16x32_bf16 v[44:47], v[150:153], v[194:197], v[44:47]
	v_mfma_f32_16x16x32_bf16 v[36:39], v[158:161], v[194:197], v[36:39]
	v_mfma_f32_16x16x32_bf16 v[28:31], v[150:153], v[202:205], v[28:31]
	v_mfma_f32_16x16x32_bf16 v[20:23], v[158:161], v[202:205], v[20:23]
	v_mfma_f32_16x16x32_bf16 v[12:15], v[150:153], v[210:213], v[12:15]
	v_mfma_f32_16x16x32_bf16 v[4:7], v[158:161], v[210:213], v[4:7]
	v_mfma_f32_16x16x32_bf16 v[60:63], v[154:157], v[190:193], v[60:63]
	v_mfma_f32_16x16x32_bf16 v[52:55], v[162:165], v[190:193], v[52:55]
	v_mfma_f32_16x16x32_bf16 v[44:47], v[154:157], v[198:201], v[44:47]
	v_mfma_f32_16x16x32_bf16 v[36:39], v[162:165], v[198:201], v[36:39]
	v_mfma_f32_16x16x32_bf16 v[28:31], v[154:157], v[206:209], v[28:31]
	v_mfma_f32_16x16x32_bf16 v[20:23], v[162:165], v[206:209], v[20:23]
	v_mfma_f32_16x16x32_bf16 v[12:15], v[154:157], v[214:217], v[12:15]
	v_mfma_f32_16x16x32_bf16 v[4:7], v[162:165], v[214:217], v[4:7]
	v_mfma_f32_16x16x32_bf16 v[56:59], v[166:169], v[182:185], v[56:59]
	v_mfma_f32_16x16x32_bf16 v[48:51], v[174:177], v[182:185], v[48:51]
	v_mfma_f32_16x16x32_bf16 v[40:43], v[166:169], v[194:197], v[40:43]
	v_mfma_f32_16x16x32_bf16 v[32:35], v[174:177], v[194:197], v[32:35]
	v_mfma_f32_16x16x32_bf16 v[24:27], v[166:169], v[202:205], v[24:27]
	v_mfma_f32_16x16x32_bf16 v[16:19], v[174:177], v[202:205], v[16:19]
	v_mfma_f32_16x16x32_bf16 v[8:11], v[166:169], v[210:213], v[8:11]
	v_mfma_f32_16x16x32_bf16 v[0:3], v[174:177], v[210:213], v[0:3]
	v_mfma_f32_16x16x32_bf16 v[56:59], v[170:173], v[190:193], v[56:59]
	v_mfma_f32_16x16x32_bf16 v[48:51], v[178:181], v[190:193], v[48:51]
	v_mfma_f32_16x16x32_bf16 v[40:43], v[170:173], v[198:201], v[40:43]
	v_mfma_f32_16x16x32_bf16 v[32:35], v[178:181], v[198:201], v[32:35]
	v_mfma_f32_16x16x32_bf16 v[24:27], v[170:173], v[206:209], v[24:27]
	v_mfma_f32_16x16x32_bf16 v[16:19], v[178:181], v[206:209], v[16:19]
	v_mfma_f32_16x16x32_bf16 v[8:11], v[170:173], v[214:217], v[8:11]
	v_mfma_f32_16x16x32_bf16 v[0:3], v[178:181], v[214:217], v[0:3]
	s_setprio 0
	s_barrier
; #define PG8_STAGE(bufoff, gbase, voff) do { _Pragma("unroll") for (int _i = 0; _i < 2; ++_i) \
;         __builtin_amdgcn_global_load_lds((const unsigned*)((const char*)(gbase) + (voff)[_i]), (PG8_LAS unsigned*)(lds + (bufoff) + ldsw + _i * 8192), 16, 0, 0); } while (0)
; #define PG8_LDA(dst, b, h) do { _Pragma("unroll") for (int m = 0; m < 4; ++m) _Pragma("unroll") for (int k = 0; k < 2; ++k) dst[m][k] = *(const PG8_LAS bf16x8*)(lds + PG8_SA(b, h) + aoff + m * 2048 + k * 1024); } while (0)
; #define PG8_LDB(dst, b, h) do { _Pragma("unroll") for (int n = 0; n < 2; ++n) _Pragma("unroll") for (int k = 0; k < 2; ++k) dst[n][k] = *(const PG8_LAS bf16x8*)(lds + PG8_SB(b, h) + boff + n * 2048 + k * 1024); } while (0)
; #define PG8_MMA(ai, bj, At, Bt) do { __builtin_amdgcn_s_setprio(1); _Pragma("unroll") for (int m = 0; m < 4; ++m) _Pragma("unroll") for (int n = 0; n < 2; ++n) _Pragma("unroll") for (int k = 0; k < 2; ++k) \
;         acc[ai][bj][m][n] = __builtin_amdgcn_mfma_f32_16x16x32_bf16(Bt[n][k], At[m][k], acc[ai][bj][m][n], 0, 0, 0); __builtin_amdgcn_s_setprio(0); } while (0)
; #define PG8_WAIT_V(n) asm volatile("s_waitcnt vmcnt(" #n ")" ::: "memory")
; #define PG8_WAIT_L(n) asm volatile("s_waitcnt lgkmcnt(" #n ")" ::: "memory")
; #define PG8_BAR __builtin_amdgcn_s_barrier()
; template <class Epi, class Sched, bool ALIGN_EPI = false, bool SP2 = false>
; __device__ __forceinline__ void gemm_phase(PG8_LAS unsigned char* lds, const Gemm g, const Sched& S, const Epi& E) {
;     ...
;         for (int t = 0; t < nt; t += 2) {
;             const bool last = (t == nt - 2);
;             const char* a1 = cA + (size_t)(t + 1) * kstep;
;             const char* a2 = last ? nA : cA + (size_t)(t + 2) * kstep; const char* b2 = last ? nB : cB + (size_t)(t + 2) * kstep;
;             const char* a3 = a2 + kstep; const char* b3 = b2 + kstep;
;     ...
;             PG8_LDB(B0, 1, 0); PG8_LDB(B1, 1, 1); PG8_SCHED; PG8_LDA(At, 1, 0); PG8_STAGE(PG8_SA(0, 1), a2 + hstepA, voffA);
;             PG8_WAIT_V(8); PG8_WAIT_L(0); PG8_BAR; PG8_MMA(0, 0, At, B0); PG8_MMA(0, 1, At, B1); PG8_BAR; PG8_SCHED;
;             PG8_LDA(At, 1, 1); PG8_STAGE(PG8_SB(1, 0), b3, voffB); PG8_STAGE(PG8_SB(1, 1), b3 + hstep, voffB); PG8_STAGE(PG8_SA(1, 0), a3, voffA);
;             PG8_WAIT_V(8); PG8_WAIT_L(0); PG8_BAR; PG8_MMA(1, 0, At, B0); PG8_MMA(1, 1, At, B1); PG8_BAR; PG8_SCHED;
	s_add_i32 s58, 0, 0x18000
	s_add_i32 s59, 0, 0x1c000
	v_add_u32_e32 v162, s58, v145
	v_add_u32_e32 v178, s59, v145
	ds_read_b128 v[150:153], v162
	ds_read_b128 v[154:157], v162 offset:1024
	ds_read_b128 v[158:161], v162 offset:2048
	ds_read_b128 v[162:165], v162 offset:3072
	ds_read_b128 v[166:169], v178
	ds_read_b128 v[170:173], v178 offset:1024
	ds_read_b128 v[174:177], v178 offset:2048
	ds_read_b128 v[178:181], v178 offset:3072
	s_mov_b64 vcc, s[30:31]
	s_add_u32 s30, s30, 0x40000
	s_addc_u32 s31, s31, 0
	s_mov_b32 m0, s42
	ds_read_b128 v[182:185], v149 offset:32768
	ds_read_b128 v[190:193], v149 offset:33792
	ds_read_b128 v[194:197], v149 offset:34816
	ds_read_b128 v[198:201], v149 offset:35840
	ds_read_b128 v[202:205], v149 offset:36864
	ds_read_b128 v[206:209], v149 offset:37888
	ds_read_b128 v[210:213], v149 offset:38912
	global_load_lds_dwordx4 v128, s[30:31]
	s_mov_b32 m0, s43
	ds_read_b128 v[214:217], v149 offset:39936
	global_load_lds_dwordx4 v130, s[30:31]
	s_waitcnt vmcnt(8)
	s_waitcnt lgkmcnt(0)
	s_barrier
	s_setprio 1
	v_mfma_f32_16x16x32_bf16 v[124:127], v[150:153], v[182:185], v[124:127]
	v_mfma_f32_16x16x32_bf16 v[116:119], v[158:161], v[182:185], v[116:119]
	v_mfma_f32_16x16x32_bf16 v[108:111], v[150:153], v[194:197], v[108:111]
	v_mfma_f32_16x16x32_bf16 v[100:103], v[158:161], v[194:197], v[100:103]
	v_mfma_f32_16x16x32_bf16 v[92:95], v[150:153], v[202:205], v[92:95]
	v_mfma_f32_16x16x32_bf16 v[84:87], v[158:161], v[202:205], v[84:87]
	v_mfma_f32_16x16x32_bf16 v[76:79], v[150:153], v[210:213], v[76:79]
	v_mfma_f32_16x16x32_bf16 v[68:71], v[158:161], v[210:213], v[68:71]
	v_mfma_f32_16x16x32_bf16 v[124:127], v[154:157], v[190:193], v[124:127]
	v_mfma_f32_16x16x32_bf16 v[116:119], v[162:165], v[190:193], v[116:119]
	v_mfma_f32_16x16x32_bf16 v[108:111], v[154:157], v[198:201], v[108:111]
	v_mfma_f32_16x16x32_bf16 v[100:103], v[162:165], v[198:201], v[100:103]
	v_mfma_f32_16x16x32_bf16 v[92:95], v[154:157], v[206:209], v[92:95]
	v_mfma_f32_16x16x32_bf16 v[84:87], v[162:165], v[206:209], v[84:87]
	v_mfma_f32_16x16x32_bf16 v[76:79], v[154:157], v[214:217], v[76:79]
	v_mfma_f32_16x16x32_bf16 v[68:71], v[162:165], v[214:217], v[68:71]
	v_mfma_f32_16x16x32_bf16 v[120:123], v[166:169], v[182:185], v[120:123]
	v_mfma_f32_16x16x32_bf16 v[112:115], v[174:177], v[182:185], v[112:115]
	v_mfma_f32_16x16x32_bf16 v[104:107], v[166:169], v[194:197], v[104:107]
	v_mfma_f32_16x16x32_bf16 v[96:99], v[174:177], v[194:197], v[96:99]
	v_mfma_f32_16x16x32_bf16 v[88:91], v[166:169], v[202:205], v[88:91]
	v_mfma_f32_16x16x32_bf16 v[80:83], v[174:177], v[202:205], v[80:83]
	v_mfma_f32_16x16x32_bf16 v[72:75], v[166:169], v[210:213], v[72:75]
	v_mfma_f32_16x16x32_bf16 v[64:67], v[174:177], v[210:213], v[64:67]
	v_mfma_f32_16x16x32_bf16 v[120:123], v[170:173], v[190:193], v[120:123]
	v_mfma_f32_16x16x32_bf16 v[112:115], v[178:181], v[190:193], v[112:115]
	v_mfma_f32_16x16x32_bf16 v[104:107], v[170:173], v[198:201], v[104:107]
	v_mfma_f32_16x16x32_bf16 v[96:99], v[178:181], v[198:201], v[96:99]
	v_mfma_f32_16x16x32_bf16 v[88:91], v[170:173], v[206:209], v[88:91]
	v_mfma_f32_16x16x32_bf16 v[80:83], v[178:181], v[206:209], v[80:83]
	v_mfma_f32_16x16x32_bf16 v[72:75], v[170:173], v[214:217], v[72:75]
	v_mfma_f32_16x16x32_bf16 v[64:67], v[178:181], v[214:217], v[64:67]
	s_setprio 0
	s_barrier
	s_add_i32 s30, s58, s38
	s_add_i32 m0, s30, 0xffffff80
	ds_read_b128 v[182:185], v149 offset:49152
	ds_read_b128 v[190:193], v149 offset:50176
	ds_read_b128 v[194:197], v149 offset:51200
	ds_read_b128 v[198:201], v149 offset:52224
	global_load_lds_dwordx4 v134, s[100:101] offset:128
	s_add_i32 m0, s30, 0x1f80
	s_add_i32 s30, s59, s38
	global_load_lds_dwordx4 v132, s[100:101] offset:128
	s_add_u32 s100, s100, s4
	s_addc_u32 s101, s101, s5
	s_add_i32 m0, s30, 0xffffff80
	ds_read_b128 v[214:217], v149 offset:56320
	global_load_lds_dwordx4 v134, s[100:101] offset:128
	s_add_i32 m0, s30, 0x1f80
	ds_read_b128 v[210:213], v149 offset:55296
	global_load_lds_dwordx4 v132, s[100:101] offset:128
	s_add_i32 m0, s46, 0xffffff80
	ds_read_b128 v[206:209], v149 offset:54272
	global_load_lds_dwordx4 v128, vcc offset:128
	s_add_i32 m0, s47, 0xffffff80
	ds_read_b128 v[202:205], v149 offset:53248
	global_load_lds_dwordx4 v130, vcc offset:128
	s_waitcnt vmcnt(8)
	s_waitcnt lgkmcnt(0)
	s_barrier
	s_setprio 1
	v_mfma_f32_16x16x32_bf16 v[60:63], v[150:153], v[182:185], v[60:63]
	v_mfma_f32_16x16x32_bf16 v[52:55], v[158:161], v[182:185], v[52:55]
	v_mfma_f32_16x16x32_bf16 v[44:47], v[150:153], v[194:197], v[44:47]
	v_mfma_f32_16x16x32_bf16 v[36:39], v[158:161], v[194:197], v[36:39]
	v_mfma_f32_16x16x32_bf16 v[28:31], v[150:153], v[202:205], v[28:31]
	v_mfma_f32_16x16x32_bf16 v[20:23], v[158:161], v[202:205], v[20:23]
	v_mfma_f32_16x16x32_bf16 v[12:15], v[150:153], v[210:213], v[12:15]
	v_mfma_f32_16x16x32_bf16 v[4:7], v[158:161], v[210:213], v[4:7]
	v_mfma_f32_16x16x32_bf16 v[60:63], v[154:157], v[190:193], v[60:63]
	v_mfma_f32_16x16x32_bf16 v[52:55], v[162:165], v[190:193], v[52:55]
	v_mfma_f32_16x16x32_bf16 v[44:47], v[154:157], v[198:201], v[44:47]
	v_mfma_f32_16x16x32_bf16 v[36:39], v[162:165], v[198:201], v[36:39]
	v_mfma_f32_16x16x32_bf16 v[28:31], v[154:157], v[206:209], v[28:31]
	v_mfma_f32_16x16x32_bf16 v[20:23], v[162:165], v[206:209], v[20:23]
	v_mfma_f32_16x16x32_bf16 v[12:15], v[154:157], v[214:217], v[12:15]
	v_mfma_f32_16x16x32_bf16 v[4:7], v[162:165], v[214:217], v[4:7]
	v_mfma_f32_16x16x32_bf16 v[56:59], v[166:169], v[182:185], v[56:59]
	v_mfma_f32_16x16x32_bf16 v[48:51], v[174:177], v[182:185], v[48:51]
	v_mfma_f32_16x16x32_bf16 v[40:43], v[166:169], v[194:197], v[40:43]
	v_mfma_f32_16x16x32_bf16 v[32:35], v[174:177], v[194:197], v[32:35]
	v_mfma_f32_16x16x32_bf16 v[24:27], v[166:169], v[202:205], v[24:27]
	v_mfma_f32_16x16x32_bf16 v[16:19], v[174:177], v[202:205], v[16:19]
	v_mfma_f32_16x16x32_bf16 v[8:11], v[166:169], v[210:213], v[8:11]
	v_mfma_f32_16x16x32_bf16 v[0:3], v[174:177], v[210:213], v[0:3]
	v_mfma_f32_16x16x32_bf16 v[56:59], v[170:173], v[190:193], v[56:59]
	v_mfma_f32_16x16x32_bf16 v[48:51], v[178:181], v[190:193], v[48:51]
	v_mfma_f32_16x16x32_bf16 v[40:43], v[170:173], v[198:201], v[40:43]
	v_mfma_f32_16x16x32_bf16 v[32:35], v[178:181], v[198:201], v[32:35]
	v_mfma_f32_16x16x32_bf16 v[24:27], v[170:173], v[206:209], v[24:27]
	v_mfma_f32_16x16x32_bf16 v[16:19], v[178:181], v[206:209], v[16:19]
	v_mfma_f32_16x16x32_bf16 v[8:11], v[170:173], v[214:217], v[8:11]
	v_mfma_f32_16x16x32_bf16 v[0:3], v[178:181], v[214:217], v[0:3]
	s_setprio 0
	s_barrier
	s_add_u32 s10, s10, 0x100
	s_addc_u32 s11, s11, 0
	s_add_u32 s34, s34, 0x100
	s_addc_u32 s35, s35, 0
	s_cmp_ge_i32 s57, s49
	s_mov_b32 s30, s57
	s_cbranch_scc0 .LBB0_1815

; #define PG8_STAGE(bufoff, gbase, voff) do { _Pragma("unroll") for (int _i = 0; _i < 2; ++_i) \
;         __builtin_amdgcn_global_load_lds((const unsigned*)((const char*)(gbase) + (voff)[_i]), (PG8_LAS unsigned*)(lds + (bufoff) + ldsw + _i * 8192), 16, 0, 0); } while (0)
; #define PG8_LDA(dst, b, h) do { _Pragma("unroll") for (int m = 0; m < 4; ++m) _Pragma("unroll") for (int k = 0; k < 2; ++k) dst[m][k] = *(const PG8_LAS bf16x8*)(lds + PG8_SA(b, h) + aoff + m * 2048 + k * 1024); } while (0)
; #define PG8_LDB(dst, b, h) do { _Pragma("unroll") for (int n = 0; n < 2; ++n) _Pragma("unroll") for (int k = 0; k < 2; ++k) dst[n][k] = *(const PG8_LAS bf16x8*)(lds + PG8_SB(b, h) + boff + n * 2048 + k * 1024); } while (0)
; #define PG8_MMA(ai, bj, At, Bt) do { __builtin_amdgcn_s_setprio(1); _Pragma("unroll") for (int m = 0; m < 4; ++m) _Pragma("unroll") for (int n = 0; n < 2; ++n) _Pragma("unroll") for (int k = 0; k < 2; ++k) \
;         acc[ai][bj][m][n] = __builtin_amdgcn_mfma_f32_16x16x32_bf16(Bt[n][k], At[m][k], acc[ai][bj][m][n], 0, 0, 0); __builtin_amdgcn_s_setprio(0); } while (0)
; #define PG8_WAIT_V(n) asm volatile("s_waitcnt vmcnt(" #n ")" ::: "memory")
; #define PG8_BAR __builtin_amdgcn_s_barrier()
; template <class Epi, class Sched, bool ALIGN_EPI = false, bool SP2 = false>
; __device__ __forceinline__ void gemm_phase(PG8_LAS unsigned char* lds, const Gemm g, const Sched& S, const Epi& E) {
;     ...
;         for (int t = 0; t < nt; t += 2) {
;             const bool last = (t == nt - 2);
;             const char* a1 = cA + (size_t)(t + 1) * kstep;
;             const char* a2 = last ? nA : cA + (size_t)(t + 2) * kstep; const char* b2 = last ? nB : cB + (size_t)(t + 2) * kstep;
;             const char* a3 = a2 + kstep; const char* b3 = b2 + kstep;
;             if (last && has_next) S.a_ready(nxt);
;             if constexpr (SP2) {
;             PG8_LDB(B0, 0, 0); PG8_LDB(B1, 0, 1); PG8_SCHED; PG8_LDA(At, 0, 0); PG8_STAGE(PG8_SA(1, 1), a1 + hstepA, voffA);
;             PG8_WAIT_V(8); PG8_WAIT_L(0); PG8_BAR; PG8_MMA(0, 0, At, B0); PG8_MMA(0, 1, At, B1); PG8_BAR; PG8_SCHED;
;             PG8_LDA(At, 0, 1); PG8_STAGE(PG8_SB(0, 0), b2, voffB); PG8_STAGE(PG8_SB(0, 1), b2 + hstep, voffB); PG8_STAGE(PG8_SA(0, 0), a2, voffA);
;             PG8_WAIT_V(8); PG8_WAIT_L(0); PG8_BAR; PG8_MMA(1, 0, At, B0); PG8_MMA(1, 1, At, B1); PG8_BAR; PG8_SCHED;
.LBB0_1897:
	ds_read_b128 v[128:131], v169
	ds_read_b128 v[132:135], v169 offset:1024
	ds_read_b128 v[136:139], v169 offset:2048
	ds_read_b128 v[140:143], v169 offset:3072
	ds_read_b128 v[160:163], v170
	ds_read_b128 v[172:175], v170 offset:1024
	ds_read_b128 v[176:179], v170 offset:2048
	ds_read_b128 v[180:183], v170 offset:3072
	s_add_i32 s63, s38, 2
	s_add_u32 s64, s36, 0xfff50080
	s_addc_u32 s39, s37, -1
	s_cmp_eq_u32 s53, s38
	s_cselect_b32 s38, s4, s64
	s_cselect_b32 s39, s5, s39
	s_cselect_b32 s65, s35, s62
	s_cselect_b32 s64, s34, s61
	s_add_i32 m0, s44, 0xc000
	ds_read_b128 v[184:187], v171
	ds_read_b128 v[188:191], v171 offset:1024
	ds_read_b128 v[192:195], v171 offset:2048
	ds_read_b128 v[196:199], v171 offset:3072
	ds_read_b128 v[200:203], v171 offset:4096
	ds_read_b128 v[204:207], v171 offset:5120
	ds_read_b128 v[208:211], v171 offset:6144
	global_load_lds_dwordx4 v152, s[36:37]
	s_add_i32 m0, s44, 0xe000
	ds_read_b128 v[212:215], v171 offset:7168
	global_load_lds_dwordx4 v154, s[36:37]
	s_waitcnt vmcnt(8)
	s_waitcnt lgkmcnt(0)
	s_barrier
	s_setprio 1
	v_mfma_f32_16x16x32_bf16 v[124:127], v[128:131], v[184:187], v[124:127]
	v_mfma_f32_16x16x32_bf16 v[120:123], v[136:139], v[184:187], v[120:123]
	v_mfma_f32_16x16x32_bf16 v[108:111], v[128:131], v[192:195], v[108:111]
	v_mfma_f32_16x16x32_bf16 v[104:107], v[136:139], v[192:195], v[104:107]
	v_mfma_f32_16x16x32_bf16 v[92:95], v[128:131], v[200:203], v[92:95]
	v_mfma_f32_16x16x32_bf16 v[88:91], v[136:139], v[200:203], v[88:91]
	v_mfma_f32_16x16x32_bf16 v[76:79], v[128:131], v[208:211], v[76:79]
	v_mfma_f32_16x16x32_bf16 v[72:75], v[136:139], v[208:211], v[72:75]
	v_mfma_f32_16x16x32_bf16 v[124:127], v[132:135], v[188:191], v[124:127]
	v_mfma_f32_16x16x32_bf16 v[120:123], v[140:143], v[188:191], v[120:123]
	v_mfma_f32_16x16x32_bf16 v[108:111], v[132:135], v[196:199], v[108:111]
	v_mfma_f32_16x16x32_bf16 v[104:107], v[140:143], v[196:199], v[104:107]
	v_mfma_f32_16x16x32_bf16 v[92:95], v[132:135], v[204:207], v[92:95]
	v_mfma_f32_16x16x32_bf16 v[88:91], v[140:143], v[204:207], v[88:91]
	v_mfma_f32_16x16x32_bf16 v[76:79], v[132:135], v[212:215], v[76:79]
	v_mfma_f32_16x16x32_bf16 v[72:75], v[140:143], v[212:215], v[72:75]
	v_mfma_f32_16x16x32_bf16 v[116:119], v[160:163], v[184:187], v[116:119]
	v_mfma_f32_16x16x32_bf16 v[112:115], v[176:179], v[184:187], v[112:115]
	v_mfma_f32_16x16x32_bf16 v[100:103], v[160:163], v[192:195], v[100:103]
	v_mfma_f32_16x16x32_bf16 v[96:99], v[176:179], v[192:195], v[96:99]
	v_mfma_f32_16x16x32_bf16 v[84:87], v[160:163], v[200:203], v[84:87]
	v_mfma_f32_16x16x32_bf16 v[80:83], v[176:179], v[200:203], v[80:83]
	v_mfma_f32_16x16x32_bf16 v[68:71], v[160:163], v[208:211], v[68:71]
	v_mfma_f32_16x16x32_bf16 v[64:67], v[176:179], v[208:211], v[64:67]
	v_mfma_f32_16x16x32_bf16 v[116:119], v[172:175], v[188:191], v[116:119]
	v_mfma_f32_16x16x32_bf16 v[112:115], v[180:183], v[188:191], v[112:115]
	v_mfma_f32_16x16x32_bf16 v[100:103], v[172:175], v[196:199], v[100:103]
	v_mfma_f32_16x16x32_bf16 v[96:99], v[180:183], v[196:199], v[96:99]
	v_mfma_f32_16x16x32_bf16 v[84:87], v[172:175], v[204:207], v[84:87]
	v_mfma_f32_16x16x32_bf16 v[80:83], v[180:183], v[204:207], v[80:83]
	v_mfma_f32_16x16x32_bf16 v[68:71], v[172:175], v[212:215], v[68:71]
	v_mfma_f32_16x16x32_bf16 v[64:67], v[180:183], v[212:215], v[64:67]
	s_setprio 0
	s_barrier
	s_add_i32 s66, s54, s42
	s_mov_b32 m0, s66
	ds_read_b128 v[184:187], v171 offset:16384
	ds_read_b128 v[188:191], v171 offset:17408
	ds_read_b128 v[192:195], v171 offset:18432
	ds_read_b128 v[196:199], v171 offset:19456
	global_load_lds_dwordx4 v150, s[64:65]
	s_add_i32 m0, s66, 0x2000
	s_mov_b64 s[100:101], s[64:65]
	s_add_i32 s66, s55, s42
	global_load_lds_dwordx4 v148, s[64:65]
	s_add_u32 s64, s64, s6
	s_addc_u32 s65, s65, s7
	s_mov_b32 m0, s66
	ds_read_b128 v[212:215], v171 offset:23552
	global_load_lds_dwordx4 v150, s[64:65]
	s_add_i32 m0, s66, 0x2000
	ds_read_b128 v[208:211], v171 offset:22528
	global_load_lds_dwordx4 v148, s[64:65]
	s_mov_b32 m0, s44
	ds_read_b128 v[204:207], v171 offset:21504
	global_load_lds_dwordx4 v144, s[38:39]
	s_mov_b32 m0, s45
	ds_read_b128 v[200:203], v171 offset:20480
	global_load_lds_dwordx4 v146, s[38:39]
	s_waitcnt vmcnt(8)
	s_waitcnt lgkmcnt(0)
	s_barrier
	s_setprio 1
	v_mfma_f32_16x16x32_bf16 v[60:63], v[128:131], v[184:187], v[60:63]
	v_mfma_f32_16x16x32_bf16 v[56:59], v[136:139], v[184:187], v[56:59]
	v_mfma_f32_16x16x32_bf16 v[44:47], v[128:131], v[192:195], v[44:47]
	v_mfma_f32_16x16x32_bf16 v[40:43], v[136:139], v[192:195], v[40:43]
	v_mfma_f32_16x16x32_bf16 v[28:31], v[128:131], v[200:203], v[28:31]
	v_mfma_f32_16x16x32_bf16 v[24:27], v[136:139], v[200:203], v[24:27]
	v_mfma_f32_16x16x32_bf16 v[12:15], v[128:131], v[208:211], v[12:15]
	v_mfma_f32_16x16x32_bf16 v[8:11], v[136:139], v[208:211], v[8:11]
	v_mfma_f32_16x16x32_bf16 v[60:63], v[132:135], v[188:191], v[60:63]
	v_mfma_f32_16x16x32_bf16 v[56:59], v[140:143], v[188:191], v[56:59]
	v_mfma_f32_16x16x32_bf16 v[44:47], v[132:135], v[196:199], v[44:47]
	v_mfma_f32_16x16x32_bf16 v[40:43], v[140:143], v[196:199], v[40:43]
	v_mfma_f32_16x16x32_bf16 v[28:31], v[132:135], v[204:207], v[28:31]
	v_mfma_f32_16x16x32_bf16 v[24:27], v[140:143], v[204:207], v[24:27]
	v_mfma_f32_16x16x32_bf16 v[12:15], v[132:135], v[212:215], v[12:15]
	v_mfma_f32_16x16x32_bf16 v[8:11], v[140:143], v[212:215], v[8:11]
	v_mfma_f32_16x16x32_bf16 v[52:55], v[160:163], v[184:187], v[52:55]
	v_mfma_f32_16x16x32_bf16 v[48:51], v[176:179], v[184:187], v[48:51]
	v_mfma_f32_16x16x32_bf16 v[36:39], v[160:163], v[192:195], v[36:39]
	v_mfma_f32_16x16x32_bf16 v[32:35], v[176:179], v[192:195], v[32:35]
	v_mfma_f32_16x16x32_bf16 v[20:23], v[160:163], v[200:203], v[20:23]
	v_mfma_f32_16x16x32_bf16 v[16:19], v[176:179], v[200:203], v[16:19]
	v_mfma_f32_16x16x32_bf16 v[4:7], v[160:163], v[208:211], v[4:7]
	v_mfma_f32_16x16x32_bf16 v[0:3], v[176:179], v[208:211], v[0:3]
	v_mfma_f32_16x16x32_bf16 v[52:55], v[172:175], v[188:191], v[52:55]
	v_mfma_f32_16x16x32_bf16 v[48:51], v[180:183], v[188:191], v[48:51]
	v_mfma_f32_16x16x32_bf16 v[36:39], v[172:175], v[196:199], v[36:39]
	v_mfma_f32_16x16x32_bf16 v[32:35], v[180:183], v[196:199], v[32:35]
	v_mfma_f32_16x16x32_bf16 v[20:23], v[172:175], v[204:207], v[20:23]
	v_mfma_f32_16x16x32_bf16 v[16:19], v[180:183], v[204:207], v[16:19]
	v_mfma_f32_16x16x32_bf16 v[4:7], v[172:175], v[212:215], v[4:7]
	v_mfma_f32_16x16x32_bf16 v[0:3], v[180:183], v[212:215], v[0:3]
	s_setprio 0
	s_barrier
; #define PG8_STAGE(bufoff, gbase, voff) do { _Pragma("unroll") for (int _i = 0; _i < 2; ++_i) \
;         __builtin_amdgcn_global_load_lds((const unsigned*)((const char*)(gbase) + (voff)[_i]), (PG8_LAS unsigned*)(lds + (bufoff) + ldsw + _i * 8192), 16, 0, 0); } while (0)
; #define PG8_LDA(dst, b, h) do { _Pragma("unroll") for (int m = 0; m < 4; ++m) _Pragma("unroll") for (int k = 0; k < 2; ++k) dst[m][k] = *(const PG8_LAS bf16x8*)(lds + PG8_SA(b, h) + aoff + m * 2048 + k * 1024); } while (0)
; #define PG8_LDB(dst, b, h) do { _Pragma("unroll") for (int n = 0; n < 2; ++n) _Pragma("unroll") for (int k = 0; k < 2; ++k) dst[n][k] = *(const PG8_LAS bf16x8*)(lds + PG8_SB(b, h) + boff + n * 2048 + k * 1024); } while (0)
; #define PG8_MMA(ai, bj, At, Bt) do { __builtin_amdgcn_s_setprio(1); _Pragma("unroll") for (int m = 0; m < 4; ++m) _Pragma("unroll") for (int n = 0; n < 2; ++n) _Pragma("unroll") for (int k = 0; k < 2; ++k) \
;         acc[ai][bj][m][n] = __builtin_amdgcn_mfma_f32_16x16x32_bf16(Bt[n][k], At[m][k], acc[ai][bj][m][n], 0, 0, 0); __builtin_amdgcn_s_setprio(0); } while (0)
; #define PG8_WAIT_V(n) asm volatile("s_waitcnt vmcnt(" #n ")" ::: "memory")
; #define PG8_WAIT_L(n) asm volatile("s_waitcnt lgkmcnt(" #n ")" ::: "memory")
; #define PG8_BAR __builtin_amdgcn_s_barrier()
; template <class Epi, class Sched, bool ALIGN_EPI = false, bool SP2 = false>
; __device__ __forceinline__ void gemm_phase(PG8_LAS unsigned char* lds, const Gemm g, const Sched& S, const Epi& E) {
;     ...
;         for (int t = 0; t < nt; t += 2) {
;             const bool last = (t == nt - 2);
;             const char* a1 = cA + (size_t)(t + 1) * kstep;
;             const char* a2 = last ? nA : cA + (size_t)(t + 2) * kstep; const char* b2 = last ? nB : cB + (size_t)(t + 2) * kstep;
;             const char* a3 = a2 + kstep; const char* b3 = b2 + kstep;
;     ...
;             PG8_LDB(B0, 1, 0); PG8_LDB(B1, 1, 1); PG8_SCHED; PG8_LDA(At, 1, 0); PG8_STAGE(PG8_SA(0, 1), a2 + hstepA, voffA);
;             PG8_WAIT_V(8); PG8_WAIT_L(0); PG8_BAR; PG8_MMA(0, 0, At, B0); PG8_MMA(0, 1, At, B1); PG8_BAR; PG8_SCHED;
;             PG8_LDA(At, 1, 1); PG8_STAGE(PG8_SB(1, 0), b3, voffB); PG8_STAGE(PG8_SB(1, 1), b3 + hstep, voffB); PG8_STAGE(PG8_SA(1, 0), a3, voffA);
;             PG8_WAIT_V(8); PG8_WAIT_L(0); PG8_BAR; PG8_MMA(1, 0, At, B0); PG8_MMA(1, 1, At, B1); PG8_BAR; PG8_SCHED;
	s_add_i32 s64, 0, 0x18000
	s_add_i32 s65, 0, 0x1c000
	v_add_u32_e32 v140, s64, v167
	v_add_u32_e32 v180, s65, v167
	ds_read_b128 v[128:131], v140
	ds_read_b128 v[132:135], v140 offset:1024
	ds_read_b128 v[136:139], v140 offset:2048
	ds_read_b128 v[140:143], v140 offset:3072
	ds_read_b128 v[160:163], v180
	ds_read_b128 v[172:175], v180 offset:1024
	ds_read_b128 v[176:179], v180 offset:2048
	ds_read_b128 v[180:183], v180 offset:3072
	s_mov_b64 vcc, s[38:39]
	s_add_u32 s38, s38, 0xb0000
	s_addc_u32 s39, s39, 0
	s_mov_b32 m0, s46
	ds_read_b128 v[184:187], v171 offset:32768
	ds_read_b128 v[188:191], v171 offset:33792
	ds_read_b128 v[192:195], v171 offset:34816
	ds_read_b128 v[196:199], v171 offset:35840
	ds_read_b128 v[200:203], v171 offset:36864
	ds_read_b128 v[204:207], v171 offset:37888
	ds_read_b128 v[208:211], v171 offset:38912
	global_load_lds_dwordx4 v144, s[38:39]
	s_mov_b32 m0, s47
	ds_read_b128 v[212:215], v171 offset:39936
	global_load_lds_dwordx4 v146, s[38:39]
	s_waitcnt vmcnt(8)
	s_waitcnt lgkmcnt(0)
	s_barrier
	s_setprio 1
	v_mfma_f32_16x16x32_bf16 v[124:127], v[128:131], v[184:187], v[124:127]
	v_mfma_f32_16x16x32_bf16 v[120:123], v[136:139], v[184:187], v[120:123]
	v_mfma_f32_16x16x32_bf16 v[108:111], v[128:131], v[192:195], v[108:111]
	v_mfma_f32_16x16x32_bf16 v[104:107], v[136:139], v[192:195], v[104:107]
	v_mfma_f32_16x16x32_bf16 v[92:95], v[128:131], v[200:203], v[92:95]
	v_mfma_f32_16x16x32_bf16 v[88:91], v[136:139], v[200:203], v[88:91]
	v_mfma_f32_16x16x32_bf16 v[76:79], v[128:131], v[208:211], v[76:79]
	v_mfma_f32_16x16x32_bf16 v[72:75], v[136:139], v[208:211], v[72:75]
	v_mfma_f32_16x16x32_bf16 v[124:127], v[132:135], v[188:191], v[124:127]
	v_mfma_f32_16x16x32_bf16 v[120:123], v[140:143], v[188:191], v[120:123]
	v_mfma_f32_16x16x32_bf16 v[108:111], v[132:135], v[196:199], v[108:111]
	v_mfma_f32_16x16x32_bf16 v[104:107], v[140:143], v[196:199], v[104:107]
	v_mfma_f32_16x16x32_bf16 v[92:95], v[132:135], v[204:207], v[92:95]
	v_mfma_f32_16x16x32_bf16 v[88:91], v[140:143], v[204:207], v[88:91]
	v_mfma_f32_16x16x32_bf16 v[76:79], v[132:135], v[212:215], v[76:79]
	v_mfma_f32_16x16x32_bf16 v[72:75], v[140:143], v[212:215], v[72:75]
	v_mfma_f32_16x16x32_bf16 v[116:119], v[160:163], v[184:187], v[116:119]
	v_mfma_f32_16x16x32_bf16 v[112:115], v[176:179], v[184:187], v[112:115]
	v_mfma_f32_16x16x32_bf16 v[100:103], v[160:163], v[192:195], v[100:103]
	v_mfma_f32_16x16x32_bf16 v[96:99], v[176:179], v[192:195], v[96:99]
	v_mfma_f32_16x16x32_bf16 v[84:87], v[160:163], v[200:203], v[84:87]
	v_mfma_f32_16x16x32_bf16 v[80:83], v[176:179], v[200:203], v[80:83]
	v_mfma_f32_16x16x32_bf16 v[68:71], v[160:163], v[208:211], v[68:71]
	v_mfma_f32_16x16x32_bf16 v[64:67], v[176:179], v[208:211], v[64:67]
	v_mfma_f32_16x16x32_bf16 v[116:119], v[172:175], v[188:191], v[116:119]
	v_mfma_f32_16x16x32_bf16 v[112:115], v[180:183], v[188:191], v[112:115]
	v_mfma_f32_16x16x32_bf16 v[100:103], v[172:175], v[196:199], v[100:103]
	v_mfma_f32_16x16x32_bf16 v[96:99], v[180:183], v[196:199], v[96:99]
	v_mfma_f32_16x16x32_bf16 v[84:87], v[172:175], v[204:207], v[84:87]
	v_mfma_f32_16x16x32_bf16 v[80:83], v[180:183], v[204:207], v[80:83]
	v_mfma_f32_16x16x32_bf16 v[68:71], v[172:175], v[212:215], v[68:71]
	v_mfma_f32_16x16x32_bf16 v[64:67], v[180:183], v[212:215], v[64:67]
	s_setprio 0
	s_barrier
	s_add_i32 s38, s64, s42
	s_add_i32 m0, s38, 0xffffff80
	ds_read_b128 v[184:187], v171 offset:49152
	ds_read_b128 v[188:191], v171 offset:50176
	ds_read_b128 v[192:195], v171 offset:51200
	ds_read_b128 v[196:199], v171 offset:52224
	global_load_lds_dwordx4 v150, s[100:101] offset:128
	s_add_i32 m0, s38, 0x1f80
	s_add_i32 s38, s65, s42
	global_load_lds_dwordx4 v148, s[100:101] offset:128
	s_add_u32 s100, s100, s6
	s_addc_u32 s101, s101, s7
	s_add_i32 m0, s38, 0xffffff80
	ds_read_b128 v[212:215], v171 offset:56320
	global_load_lds_dwordx4 v150, s[100:101] offset:128
	s_add_i32 m0, s38, 0x1f80
	ds_read_b128 v[208:211], v171 offset:55296
	global_load_lds_dwordx4 v148, s[100:101] offset:128
	s_add_i32 m0, s50, 0xffffff80
	ds_read_b128 v[204:207], v171 offset:54272
	global_load_lds_dwordx4 v144, vcc offset:128
	s_add_i32 m0, s51, 0xffffff80
	ds_read_b128 v[200:203], v171 offset:53248
	global_load_lds_dwordx4 v146, vcc offset:128
	s_waitcnt vmcnt(8)
	s_waitcnt lgkmcnt(0)
	s_barrier
	s_setprio 1
	v_mfma_f32_16x16x32_bf16 v[60:63], v[128:131], v[184:187], v[60:63]
	v_mfma_f32_16x16x32_bf16 v[56:59], v[136:139], v[184:187], v[56:59]
	v_mfma_f32_16x16x32_bf16 v[44:47], v[128:131], v[192:195], v[44:47]
	v_mfma_f32_16x16x32_bf16 v[40:43], v[136:139], v[192:195], v[40:43]
	v_mfma_f32_16x16x32_bf16 v[28:31], v[128:131], v[200:203], v[28:31]
	v_mfma_f32_16x16x32_bf16 v[24:27], v[136:139], v[200:203], v[24:27]
	v_mfma_f32_16x16x32_bf16 v[12:15], v[128:131], v[208:211], v[12:15]
	v_mfma_f32_16x16x32_bf16 v[8:11], v[136:139], v[208:211], v[8:11]
	v_mfma_f32_16x16x32_bf16 v[60:63], v[132:135], v[188:191], v[60:63]
	v_mfma_f32_16x16x32_bf16 v[56:59], v[140:143], v[188:191], v[56:59]
	v_mfma_f32_16x16x32_bf16 v[44:47], v[132:135], v[196:199], v[44:47]
	v_mfma_f32_16x16x32_bf16 v[40:43], v[140:143], v[196:199], v[40:43]
	v_mfma_f32_16x16x32_bf16 v[28:31], v[132:135], v[204:207], v[28:31]
	v_mfma_f32_16x16x32_bf16 v[24:27], v[140:143], v[204:207], v[24:27]
	v_mfma_f32_16x16x32_bf16 v[12:15], v[132:135], v[212:215], v[12:15]
	v_mfma_f32_16x16x32_bf16 v[8:11], v[140:143], v[212:215], v[8:11]
	v_mfma_f32_16x16x32_bf16 v[52:55], v[160:163], v[184:187], v[52:55]
	v_mfma_f32_16x16x32_bf16 v[48:51], v[176:179], v[184:187], v[48:51]
	v_mfma_f32_16x16x32_bf16 v[36:39], v[160:163], v[192:195], v[36:39]
	v_mfma_f32_16x16x32_bf16 v[32:35], v[176:179], v[192:195], v[32:35]
	v_mfma_f32_16x16x32_bf16 v[20:23], v[160:163], v[200:203], v[20:23]
	v_mfma_f32_16x16x32_bf16 v[16:19], v[176:179], v[200:203], v[16:19]
	v_mfma_f32_16x16x32_bf16 v[4:7], v[160:163], v[208:211], v[4:7]
	v_mfma_f32_16x16x32_bf16 v[0:3], v[176:179], v[208:211], v[0:3]
	v_mfma_f32_16x16x32_bf16 v[52:55], v[172:175], v[188:191], v[52:55]
	v_mfma_f32_16x16x32_bf16 v[48:51], v[180:183], v[188:191], v[48:51]
	v_mfma_f32_16x16x32_bf16 v[36:39], v[172:175], v[196:199], v[36:39]
	v_mfma_f32_16x16x32_bf16 v[32:35], v[180:183], v[196:199], v[32:35]
	v_mfma_f32_16x16x32_bf16 v[20:23], v[172:175], v[204:207], v[20:23]
	v_mfma_f32_16x16x32_bf16 v[16:19], v[180:183], v[204:207], v[16:19]
	v_mfma_f32_16x16x32_bf16 v[4:7], v[172:175], v[212:215], v[4:7]
	v_mfma_f32_16x16x32_bf16 v[0:3], v[180:183], v[212:215], v[0:3]
	s_setprio 0
	s_barrier
	s_add_u32 s36, s36, 0x100
	s_addc_u32 s37, s37, 0
	s_add_u32 s61, s61, 0x100
	s_addc_u32 s62, s62, 0
	s_cmp_ge_i32 s63, s52
	s_mov_b32 s38, s63
	s_cbranch_scc0 .LBB0_1897
